# c2 + one static s_setprio 1 for waves 4-7 around each GEMM K-loop, per-segment setprio flips deleted
# speedup vs baseline: 1.0174x; 1.0060x over previous
; #define PG8_LAS __attribute__((address_space(3)))
; template <class Epi>
; __device__ __forceinline__ void gemm_phase(PG8_LAS unsigned char* lds, const Gemm g, const StaticOrder& S, const Epi& E) {
;     const int tid = threadIdx.x, wid = __builtin_amdgcn_readfirstlane(tid >> 6), lane = tid & 63, wr = wid >> 2, wc = wid & 3, fr = lane & 15, fq = lane >> 4;
; __global__ void __launch_bounds__(512, 2) fwd_megakernel(Params P, int ph_lo, int ph_hi) {
;     extern __shared__ __attribute__((aligned(16))) unsigned char lds[];
;     cg::grid_group grid = cg::this_grid();
;     unsigned char* ws = P.ws;
;     PG8_LAS unsigned char* lds3 = (PG8_LAS unsigned char*)lds;
;     const int G = gridDim.x, c = blockIdx.x;
;     bf16_t* WGU2 = (bf16_t*)(ws + WS_WGU2); bf16_t* WD2 = (bf16_t*)(ws + WS_WD2);
;     bf16_t* WGU = (bf16_t*)(ws + WS_WGU); bf16_t* WD = (bf16_t*)(ws + WS_WD); bf16_t* WIN = (bf16_t*)(ws + WS_WIN);
;     bf16_t* WA = (bf16_t*)(ws + WS_WA); bf16_t* WC = (bf16_t*)(ws + WS_WC); bf16_t* WO = (bf16_t*)(ws + WS_WO);
;     bf16_t* HB = (bf16_t*)(ws + WS_HB); bf16_t* ACT = (bf16_t*)(ws + WS_Z1); bf16_t* Z1 = (bf16_t*)(ws + WS_Z1);
;     bf16_t* XCC = (bf16_t*)(ws + WS_XCC); bf16_t* BB = (bf16_t*)(ws + WS_BB); bf16_t* GG = (bf16_t*)(ws + WS_G);
;     float* part0 = (float*)(ws + WS_PART); float* part1 = (float*)(ws + WS_PART + PART_SZ); float* part2 = (float*)(ws + WS_PART + 2 * PART_SZ);
;     float* hmeta = (float*)(ws + WS_HMETA);
;     ...
;     volatile PG8_LAS unsigned* bst = (volatile PG8_LAS unsigned*)(lds3 + 147456);
;     if (threadIdx.x == 0) { bst[0] = 0u; bst[1] = 0u; }
;     __syncthreads();
_Z14fwd_megakernel6Paramsii:
	s_load_dwordx8 s[4:11], s[0:1], 0x80
	s_load_dwordx2 s[80:81], s[0:1], 0xa0
	s_load_dword s33, s[0:1], 0xb8
	s_load_dwordx2 s[26:27], s[0:1], 0xb0
	s_mov_b32 s24, s2
	s_add_u32 s2, s0, 0xb0
	s_addc_u32 s3, s1, 0
	s_waitcnt lgkmcnt(0)
	v_writelane_b32 v253, s4, 0
	v_and_b32_e32 v168, 0x3ff, v0
	s_nop 0
	v_writelane_b32 v253, s5, 1
	v_readfirstlane_b32 s101, v168
	s_nop 3
	s_lshr_b32 s101, s101, 8
	v_writelane_b32 v253, s6, 2
	v_writelane_b32 v253, s7, 3
	v_writelane_b32 v253, s8, 4
	v_writelane_b32 v253, s9, 5
	v_writelane_b32 v253, s10, 6
	v_writelane_b32 v253, s11, 7
	v_cmp_eq_u32_e64 s[6:7], 0, v168
	s_mov_b64 s[4:5], exec
	s_nop 0
	v_writelane_b32 v253, s6, 8
	s_nop 1
	v_writelane_b32 v253, s7, 9
	s_and_b64 s[6:7], s[4:5], s[6:7]
	s_mov_b64 exec, s[6:7]
	s_cbranch_execz .LBB0_2
	s_add_i32 s6, 0, 0x24000
	v_mov_b32_e32 v1, 0
	v_mov_b32_e32 v2, s6
	s_add_i32 s6, 0, 0x24004
	ds_write_b32 v2, v1
	v_mov_b32_e32 v2, s6
	ds_write_b32 v2, v1

; #define PG8_STAGE(bufoff, gbase, voff) do { _Pragma("unroll") for (int _i = 0; _i < 2; ++_i) \
;         __builtin_amdgcn_global_load_lds((const unsigned*)((const char*)(gbase) + (voff)[_i]), (PG8_LAS unsigned*)(lds + (bufoff) + ldsw + _i * 8192), 16, 0, 0); } while (0)
; #define PG8_LDA(dst, b, h) do { _Pragma("unroll") for (int m = 0; m < 4; ++m) _Pragma("unroll") for (int k = 0; k < 2; ++k) dst[m][k] = *(const PG8_LAS bf16x8*)(lds + PG8_SA(b, h) + aoff + m * 2048 + k * 1024); } while (0)
; #define PG8_LDB(dst, b, h) do { _Pragma("unroll") for (int n = 0; n < 2; ++n) _Pragma("unroll") for (int k = 0; k < 2; ++k) dst[n][k] = *(const PG8_LAS bf16x8*)(lds + PG8_SB(b, h) + boff + n * 2048 + k * 1024); } while (0)
; #define PG8_MMA(ai, bj, At, Bt) do { __builtin_amdgcn_s_setprio(1); _Pragma("unroll") for (int m = 0; m < 4; ++m) _Pragma("unroll") for (int n = 0; n < 2; ++n) _Pragma("unroll") for (int k = 0; k < 2; ++k) \
;         acc[ai][bj][m][n] = __builtin_amdgcn_mfma_f32_16x16x32_bf16(Bt[n][k], At[m][k], acc[ai][bj][m][n], 0, 0, 0); __builtin_amdgcn_s_setprio(0); } while (0)
; #define PG8_WAIT_L(n) asm volatile("s_waitcnt lgkmcnt(" #n ")" ::: "memory")
; template <class Epi>
; __device__ __forceinline__ void gemm_phase(PG8_LAS unsigned char* lds, const Gemm g, const StaticOrder& S, const Epi& E) {
;     ...
;         const bool has_next = S.next(ui + 1, nxt);
;         const char* nA = has_next ? (const char*)g.A + (size_t)nxt.pm * tstepA : cA; const char* nB = has_next ? (const char*)g.Bt + (size_t)nxt.pn * tstepB : cB;
;         for (int t = 0; t < nt; t += 2) {
;             const bool last = (t == nt - 2);
;             const char* a1 = cA + (size_t)(t + 1) * kstep;
;             const char* a2 = last ? nA : cA + (size_t)(t + 2) * kstep; const char* b2 = last ? nB : cB + (size_t)(t + 2) * kstep;
;             const char* a3 = a2 + kstep; const char* b3 = b2 + kstep;
;             PG8_LDB(B0, 0, 0); PG8_SCHED; PG8_LDA(At, 0, 0); PG8_STAGE(PG8_SA(1, 1), a1 + hstepA, voffA);
;             PG8_WAIT_L(8); PG8_BAR; PG8_WAIT_L(0); PG8_MMA(0, 0, At, B0); PG8_BAR; PG8_SCHED;
;     ...
; #pragma unroll
;         for (int a = 0; a < 2; ++a)
; #pragma unroll
;             for (int b = 0; b < 2; ++b)
; #pragma unroll
;                 for (int m = 0; m < 4; ++m)
; #pragma unroll
;                     for (int n = 0; n < 2; ++n) acc[a][b][m][n] = (f32x4){0.f, 0.f, 0.f, 0.f};
.LBB0_225:
	s_ashr_i32 s53, s52, 31
	v_cmp_lt_i64_e32 vcc, s[6:7], v[152:153]
	s_lshl_b64 s[6:7], s[52:53], 20
	s_add_u32 s56, s76, s6
	s_addc_u32 s57, s77, s7
	s_and_b64 s[6:7], vcc, exec
	s_cselect_b32 s47, s57, s1
	s_cselect_b32 s49, s56, s0
	s_ashr_i32 s51, s50, 31
	s_lshl_b64 s[6:7], s[50:51], 20
	s_add_u32 s58, s80, s6
	s_addc_u32 s59, s81, s7
	s_and_b64 s[6:7], vcc, exec
	s_cselect_b32 s51, s59, s5
	s_cselect_b32 s53, s58, s4
	s_add_u32 s0, s0, 0x80080
	s_addc_u32 s1, s1, 0
	s_add_u32 s60, s4, 0x100
	v_mov_b32_e32 v8, 0
	s_addc_u32 s61, s5, 0
	s_mov_b32 s62, -2
	v_mov_b32_e32 v9, v8
	v_mov_b32_e32 v10, v8
	v_mov_b32_e32 v11, v8
	v_mov_b32_e32 v16, v8
	v_mov_b32_e32 v17, v8
	v_mov_b32_e32 v18, v8
	v_mov_b32_e32 v19, v8
	v_mov_b32_e32 v24, v8
	v_mov_b32_e32 v25, v8
	v_mov_b32_e32 v26, v8
	v_mov_b32_e32 v27, v8
	v_mov_b32_e32 v32, v8
	v_mov_b32_e32 v33, v8
	v_mov_b32_e32 v34, v8
	v_mov_b32_e32 v35, v8
	v_mov_b32_e32 v40, v8
	v_mov_b32_e32 v41, v8
	v_mov_b32_e32 v42, v8
	v_mov_b32_e32 v43, v8
	v_mov_b32_e32 v48, v8
	v_mov_b32_e32 v49, v8
	v_mov_b32_e32 v50, v8
	v_mov_b32_e32 v51, v8
	v_mov_b32_e32 v56, v8
	v_mov_b32_e32 v57, v8
	v_mov_b32_e32 v58, v8
	v_mov_b32_e32 v59, v8
	v_mov_b32_e32 v64, v8
	v_mov_b32_e32 v65, v8
	v_mov_b32_e32 v66, v8
	v_mov_b32_e32 v67, v8
	v_mov_b32_e32 v12, v8
	v_mov_b32_e32 v13, v8
	v_mov_b32_e32 v14, v8
	v_mov_b32_e32 v15, v8
	v_mov_b32_e32 v20, v8
	v_mov_b32_e32 v21, v8
	v_mov_b32_e32 v22, v8
	v_mov_b32_e32 v23, v8
	v_mov_b32_e32 v28, v8
	v_mov_b32_e32 v29, v8
	v_mov_b32_e32 v30, v8
	v_mov_b32_e32 v31, v8
	v_mov_b32_e32 v36, v8
	v_mov_b32_e32 v37, v8
	v_mov_b32_e32 v38, v8
	v_mov_b32_e32 v39, v8
	v_mov_b32_e32 v44, v8
	v_mov_b32_e32 v45, v8
	v_mov_b32_e32 v46, v8
	v_mov_b32_e32 v47, v8
	v_mov_b32_e32 v52, v8
	v_mov_b32_e32 v53, v8
	v_mov_b32_e32 v54, v8
	v_mov_b32_e32 v55, v8
	v_mov_b32_e32 v60, v8
	v_mov_b32_e32 v61, v8
	v_mov_b32_e32 v62, v8
	v_mov_b32_e32 v63, v8
	v_mov_b32_e32 v68, v8
	v_mov_b32_e32 v69, v8
	v_mov_b32_e32 v70, v8
	v_mov_b32_e32 v71, v8
	v_mov_b32_e32 v72, v8
	v_mov_b32_e32 v73, v8
	v_mov_b32_e32 v74, v8
	v_mov_b32_e32 v75, v8
	v_mov_b32_e32 v80, v8
	v_mov_b32_e32 v81, v8
	v_mov_b32_e32 v82, v8
	v_mov_b32_e32 v83, v8
	v_mov_b32_e32 v88, v8
	v_mov_b32_e32 v89, v8
	v_mov_b32_e32 v90, v8
	v_mov_b32_e32 v91, v8
	v_mov_b32_e32 v96, v8
	v_mov_b32_e32 v97, v8
	v_mov_b32_e32 v98, v8
	v_mov_b32_e32 v99, v8
	v_mov_b32_e32 v104, v8
	v_mov_b32_e32 v105, v8
	v_mov_b32_e32 v106, v8
	v_mov_b32_e32 v107, v8
	v_mov_b32_e32 v112, v8
	v_mov_b32_e32 v113, v8
	v_mov_b32_e32 v114, v8
	v_mov_b32_e32 v115, v8
	v_mov_b32_e32 v120, v8
	v_mov_b32_e32 v121, v8
	v_mov_b32_e32 v122, v8
	v_mov_b32_e32 v123, v8
	v_mov_b32_e32 v128, v8
	v_mov_b32_e32 v129, v8
	v_mov_b32_e32 v130, v8
	v_mov_b32_e32 v131, v8
	v_mov_b32_e32 v76, v8
	v_mov_b32_e32 v77, v8
	v_mov_b32_e32 v78, v8
	v_mov_b32_e32 v79, v8
	v_mov_b32_e32 v84, v8
	v_mov_b32_e32 v85, v8
	v_mov_b32_e32 v86, v8
	v_mov_b32_e32 v87, v8
	v_mov_b32_e32 v92, v8
	v_mov_b32_e32 v93, v8
	v_mov_b32_e32 v94, v8
	v_mov_b32_e32 v95, v8
	v_mov_b32_e32 v100, v8
	v_mov_b32_e32 v101, v8
	v_mov_b32_e32 v102, v8
	v_mov_b32_e32 v103, v8
	v_mov_b32_e32 v108, v8
	v_mov_b32_e32 v109, v8
	v_mov_b32_e32 v110, v8
	v_mov_b32_e32 v111, v8
	v_mov_b32_e32 v116, v8
	v_mov_b32_e32 v117, v8
	v_mov_b32_e32 v118, v8
	v_mov_b32_e32 v119, v8
	v_mov_b32_e32 v124, v8
	v_mov_b32_e32 v125, v8
	v_mov_b32_e32 v126, v8
	v_mov_b32_e32 v127, v8
	v_mov_b32_e32 v132, v8
	v_mov_b32_e32 v133, v8
	v_mov_b32_e32 v134, v8
	v_mov_b32_e32 v135, v8
	s_cmp_eq_u32 s101, 1
	s_cbranch_scc0 .Lsp_0
	s_setprio 1
.Lsp_0:
.LBB0_226:
	ds_read_b128 v[0:3], v174
	ds_read_b128 v[4:7], v174 offset:1024
	ds_read_b128 v[156:159], v174 offset:2048
	ds_read_b128 v[160:163], v174 offset:3072
	ds_read_b128 v[164:167], v175
	ds_read_b128 v[178:181], v175 offset:1024
	ds_read_b128 v[182:185], v175 offset:2048
	ds_read_b128 v[186:189], v175 offset:3072
	ds_read_b128 v[190:193], v175 offset:4096
	ds_read_b128 v[194:197], v175 offset:5120
	ds_read_b128 v[198:201], v175 offset:6144
	ds_read_b128 v[202:205], v175 offset:7168
	ds_read_b128 v[206:209], v176
	ds_read_b128 v[210:213], v176 offset:1024
	ds_read_b128 v[214:217], v176 offset:2048
	ds_read_b128 v[218:221], v176 offset:3072
	s_add_u32 s4, s0, 0xfff80080
	s_addc_u32 s5, s1, -1
	s_cmp_eq_u32 s62, 28
	s_cselect_b32 s7, s47, s5
	s_cselect_b32 s6, s49, s4
	s_cselect_b32 s5, s51, s61
	s_cselect_b32 s4, s53, s60
	v_lshl_add_u64 v[170:171], s[0:1], 0, v[148:149]
	s_add_i32 m0, s14, 0xc000
	s_nop 0
	global_load_lds_dwordx4 v[170:171], off
	v_lshl_add_u64 v[170:171], s[0:1], 0, v[150:151]
	s_add_i32 m0, s14, 0xe000
	s_nop 0
	global_load_lds_dwordx4 v[170:171], off
	s_waitcnt lgkmcnt(0)
	s_waitcnt vmcnt(8)
	s_barrier
; #define PG8_STAGE(bufoff, gbase, voff) do { _Pragma("unroll") for (int _i = 0; _i < 2; ++_i) \
;         __builtin_amdgcn_global_load_lds((const unsigned*)((const char*)(gbase) + (voff)[_i]), (PG8_LAS unsigned*)(lds + (bufoff) + ldsw + _i * 8192), 16, 0, 0); } while (0)
; #define PG8_LDA(dst, b, h) do { _Pragma("unroll") for (int m = 0; m < 4; ++m) _Pragma("unroll") for (int k = 0; k < 2; ++k) dst[m][k] = *(const PG8_LAS bf16x8*)(lds + PG8_SA(b, h) + aoff + m * 2048 + k * 1024); } while (0)
; #define PG8_LDB(dst, b, h) do { _Pragma("unroll") for (int n = 0; n < 2; ++n) _Pragma("unroll") for (int k = 0; k < 2; ++k) dst[n][k] = *(const PG8_LAS bf16x8*)(lds + PG8_SB(b, h) + boff + n * 2048 + k * 1024); } while (0)
; #define PG8_MMA(ai, bj, At, Bt) do { __builtin_amdgcn_s_setprio(1); _Pragma("unroll") for (int m = 0; m < 4; ++m) _Pragma("unroll") for (int n = 0; n < 2; ++n) _Pragma("unroll") for (int k = 0; k < 2; ++k) \
;         acc[ai][bj][m][n] = __builtin_amdgcn_mfma_f32_16x16x32_bf16(Bt[n][k], At[m][k], acc[ai][bj][m][n], 0, 0, 0); __builtin_amdgcn_s_setprio(0); } while (0)
; #define PG8_WAIT_V(n) asm volatile("s_waitcnt vmcnt(" #n ")" ::: "memory")
; #define PG8_WAIT_L(n) asm volatile("s_waitcnt lgkmcnt(" #n ")" ::: "memory")
; #define PG8_BAR __builtin_amdgcn_s_barrier()
; #define PG8_SCHED __builtin_amdgcn_sched_barrier(0)
; template <class Epi>
; __device__ __forceinline__ void gemm_phase(PG8_LAS unsigned char* lds, const Gemm g, const StaticOrder& S, const Epi& E) {
;     ...
;             PG8_WAIT_L(8); PG8_BAR; PG8_WAIT_L(0); PG8_MMA(0, 0, At, B0); PG8_BAR; PG8_SCHED;
;             PG8_LDB(B1, 0, 1); PG8_STAGE(PG8_SB(0, 0), b2, voffB);
;             PG8_BAR; PG8_WAIT_L(0); PG8_MMA(0, 1, At, B1); PG8_BAR;
;             PG8_LDA(At, 0, 1); PG8_STAGE(PG8_SA(0, 0), a2, voffA);
;             PG8_BAR; PG8_WAIT_L(0); PG8_MMA(1, 0, At, B0); PG8_BAR; PG8_SCHED;
;             PG8_STAGE(PG8_SB(0, 1), b2 + hstepB, voffB);
;             PG8_WAIT_V(6); PG8_BAR; PG8_MMA(1, 1, At, B1); PG8_BAR;
	v_mfma_f32_16x16x32_bf16 v[132:135], v[0:3], v[164:167], v[132:135]
	v_mfma_f32_16x16x32_bf16 v[124:127], v[156:159], v[164:167], v[124:127]
	v_mfma_f32_16x16x32_bf16 v[116:119], v[0:3], v[182:185], v[116:119]
	v_mfma_f32_16x16x32_bf16 v[108:111], v[156:159], v[182:185], v[108:111]
	v_mfma_f32_16x16x32_bf16 v[100:103], v[0:3], v[190:193], v[100:103]
	v_mfma_f32_16x16x32_bf16 v[92:95], v[156:159], v[190:193], v[92:95]
	v_mfma_f32_16x16x32_bf16 v[84:87], v[0:3], v[198:201], v[84:87]
	v_mfma_f32_16x16x32_bf16 v[76:79], v[156:159], v[198:201], v[76:79]
	v_mfma_f32_16x16x32_bf16 v[132:135], v[4:7], v[178:181], v[132:135]
	v_mfma_f32_16x16x32_bf16 v[124:127], v[160:163], v[178:181], v[124:127]
	v_mfma_f32_16x16x32_bf16 v[116:119], v[4:7], v[186:189], v[116:119]
	v_mfma_f32_16x16x32_bf16 v[108:111], v[160:163], v[186:189], v[108:111]
	v_mfma_f32_16x16x32_bf16 v[100:103], v[4:7], v[194:197], v[100:103]
	v_mfma_f32_16x16x32_bf16 v[92:95], v[160:163], v[194:197], v[92:95]
	v_mfma_f32_16x16x32_bf16 v[84:87], v[4:7], v[202:205], v[84:87]
	v_mfma_f32_16x16x32_bf16 v[76:79], v[160:163], v[202:205], v[76:79]
	v_mfma_f32_16x16x32_bf16 v[128:131], v[206:209], v[164:167], v[128:131]
	v_mfma_f32_16x16x32_bf16 v[120:123], v[214:217], v[164:167], v[120:123]
	v_mfma_f32_16x16x32_bf16 v[112:115], v[206:209], v[182:185], v[112:115]
	v_mfma_f32_16x16x32_bf16 v[104:107], v[214:217], v[182:185], v[104:107]
	v_mfma_f32_16x16x32_bf16 v[96:99], v[206:209], v[190:193], v[96:99]
	v_mfma_f32_16x16x32_bf16 v[88:91], v[214:217], v[190:193], v[88:91]
	v_mfma_f32_16x16x32_bf16 v[80:83], v[206:209], v[198:201], v[80:83]
	v_mfma_f32_16x16x32_bf16 v[72:75], v[214:217], v[198:201], v[72:75]
	v_mfma_f32_16x16x32_bf16 v[128:131], v[210:213], v[178:181], v[128:131]
	v_mfma_f32_16x16x32_bf16 v[120:123], v[218:221], v[178:181], v[120:123]
	v_mfma_f32_16x16x32_bf16 v[112:115], v[210:213], v[186:189], v[112:115]
	v_mfma_f32_16x16x32_bf16 v[104:107], v[218:221], v[186:189], v[104:107]
	v_mfma_f32_16x16x32_bf16 v[96:99], v[210:213], v[194:197], v[96:99]
	v_mfma_f32_16x16x32_bf16 v[88:91], v[218:221], v[194:197], v[88:91]
	v_mfma_f32_16x16x32_bf16 v[80:83], v[210:213], v[202:205], v[80:83]
	v_mfma_f32_16x16x32_bf16 v[72:75], v[218:221], v[202:205], v[72:75]
	s_barrier
	ds_read_b128 v[164:167], v175 offset:16384
	ds_read_b128 v[178:181], v175 offset:17408
	ds_read_b128 v[182:185], v175 offset:18432
	ds_read_b128 v[186:189], v175 offset:19456
	ds_read_b128 v[190:193], v175 offset:20480
	ds_read_b128 v[194:197], v175 offset:21504
	ds_read_b128 v[198:201], v175 offset:22528
	ds_read_b128 v[202:205], v175 offset:23552
	s_add_i32 s63, s37, s11
	v_lshl_add_u64 v[170:171], s[4:5], 0, v[142:143]
	s_mov_b32 m0, s63
	s_nop 0
	global_load_lds_dwordx4 v[170:171], off
	v_lshl_add_u64 v[222:223], s[4:5], 0, v[138:139]
	s_add_i32 m0, s63, 0x2000
	s_nop 0
	global_load_lds_dwordx4 v[222:223], off
	s_mov_b32 m0, s14
	v_lshl_add_u64 v[224:225], s[6:7], 0, v[144:145]
	global_load_lds_dwordx4 v[224:225], off
	v_lshl_add_u64 v[226:227], s[6:7], 0, v[140:141]
	s_mov_b32 m0, s15
	s_nop 0
	global_load_lds_dwordx4 v[226:227], off
	s_add_u32 s64, s4, 0x80000
	s_addc_u32 s65, s5, 0
	s_add_i32 s63, s38, s11
	v_lshl_add_u64 v[228:229], s[64:65], 0, v[142:143]
	s_mov_b32 m0, s63
	s_nop 0
	global_load_lds_dwordx4 v[228:229], off
	v_lshl_add_u64 v[228:229], s[64:65], 0, v[138:139]
	s_add_i32 m0, s63, 0x2000
	s_nop 0
	global_load_lds_dwordx4 v[228:229], off
	s_waitcnt lgkmcnt(0)
	s_waitcnt vmcnt(8)
	s_barrier
	v_mfma_f32_16x16x32_bf16 v[68:71], v[0:3], v[164:167], v[68:71]
	v_mfma_f32_16x16x32_bf16 v[60:63], v[156:159], v[164:167], v[60:63]
	v_mfma_f32_16x16x32_bf16 v[52:55], v[0:3], v[182:185], v[52:55]
	v_mfma_f32_16x16x32_bf16 v[44:47], v[156:159], v[182:185], v[44:47]
	v_mfma_f32_16x16x32_bf16 v[36:39], v[0:3], v[190:193], v[36:39]
	v_mfma_f32_16x16x32_bf16 v[28:31], v[156:159], v[190:193], v[28:31]
	v_mfma_f32_16x16x32_bf16 v[0:3], v[0:3], v[198:201], v[20:23]
	v_mfma_f32_16x16x32_bf16 v[68:71], v[4:7], v[178:181], v[68:71]
	v_mfma_f32_16x16x32_bf16 v[60:63], v[160:163], v[178:181], v[60:63]
	v_mfma_f32_16x16x32_bf16 v[52:55], v[4:7], v[186:189], v[52:55]
	v_mfma_f32_16x16x32_bf16 v[44:47], v[160:163], v[186:189], v[44:47]
	v_mfma_f32_16x16x32_bf16 v[36:39], v[4:7], v[194:197], v[36:39]
	v_mfma_f32_16x16x32_bf16 v[28:31], v[160:163], v[194:197], v[28:31]
	v_mfma_f32_16x16x32_bf16 v[0:3], v[4:7], v[202:205], v[0:3]
	v_mfma_f32_16x16x32_bf16 v[4:7], v[156:159], v[198:201], v[12:15]
	v_mfma_f32_16x16x32_bf16 v[4:7], v[160:163], v[202:205], v[4:7]
	v_mfma_f32_16x16x32_bf16 v[12:15], v[206:209], v[164:167], v[64:67]
	v_mfma_f32_16x16x32_bf16 v[64:67], v[210:213], v[178:181], v[12:15]
	v_mfma_f32_16x16x32_bf16 v[12:15], v[214:217], v[164:167], v[56:59]
	v_mfma_f32_16x16x32_bf16 v[56:59], v[218:221], v[178:181], v[12:15]
	v_mfma_f32_16x16x32_bf16 v[12:15], v[206:209], v[182:185], v[48:51]
	v_mfma_f32_16x16x32_bf16 v[48:51], v[210:213], v[186:189], v[12:15]
	v_mfma_f32_16x16x32_bf16 v[12:15], v[214:217], v[182:185], v[40:43]
	v_mfma_f32_16x16x32_bf16 v[40:43], v[218:221], v[186:189], v[12:15]
	v_mfma_f32_16x16x32_bf16 v[12:15], v[206:209], v[190:193], v[32:35]
	v_mfma_f32_16x16x32_bf16 v[32:35], v[210:213], v[194:197], v[12:15]
	v_mfma_f32_16x16x32_bf16 v[12:15], v[214:217], v[190:193], v[24:27]
	v_mfma_f32_16x16x32_bf16 v[24:27], v[218:221], v[194:197], v[12:15]
	v_mfma_f32_16x16x32_bf16 v[12:15], v[206:209], v[198:201], v[16:19]
	v_mfma_f32_16x16x32_bf16 v[8:11], v[214:217], v[198:201], v[8:11]
	v_mfma_f32_16x16x32_bf16 v[16:19], v[210:213], v[202:205], v[12:15]
	v_mfma_f32_16x16x32_bf16 v[8:11], v[218:221], v[202:205], v[8:11]
	s_add_i32 s63, 0, 0x18000
	v_add_u32_e32 v160, s63, v169
	s_barrier
; #define PG8_STAGE(bufoff, gbase, voff) do { _Pragma("unroll") for (int _i = 0; _i < 2; ++_i) \
;         __builtin_amdgcn_global_load_lds((const unsigned*)((const char*)(gbase) + (voff)[_i]), (PG8_LAS unsigned*)(lds + (bufoff) + ldsw + _i * 8192), 16, 0, 0); } while (0)
; #define PG8_LDA(dst, b, h) do { _Pragma("unroll") for (int m = 0; m < 4; ++m) _Pragma("unroll") for (int k = 0; k < 2; ++k) dst[m][k] = *(const PG8_LAS bf16x8*)(lds + PG8_SA(b, h) + aoff + m * 2048 + k * 1024); } while (0)
; #define PG8_LDB(dst, b, h) do { _Pragma("unroll") for (int n = 0; n < 2; ++n) _Pragma("unroll") for (int k = 0; k < 2; ++k) dst[n][k] = *(const PG8_LAS bf16x8*)(lds + PG8_SB(b, h) + boff + n * 2048 + k * 1024); } while (0)
; #define PG8_MMA(ai, bj, At, Bt) do { __builtin_amdgcn_s_setprio(1); _Pragma("unroll") for (int m = 0; m < 4; ++m) _Pragma("unroll") for (int n = 0; n < 2; ++n) _Pragma("unroll") for (int k = 0; k < 2; ++k) \
;         acc[ai][bj][m][n] = __builtin_amdgcn_mfma_f32_16x16x32_bf16(Bt[n][k], At[m][k], acc[ai][bj][m][n], 0, 0, 0); __builtin_amdgcn_s_setprio(0); } while (0)
; #define PG8_WAIT_L(n) asm volatile("s_waitcnt lgkmcnt(" #n ")" ::: "memory")
; #define PG8_BAR __builtin_amdgcn_s_barrier()
; #define PG8_SCHED __builtin_amdgcn_sched_barrier(0)
; template <class Epi>
; __device__ __forceinline__ void gemm_phase(PG8_LAS unsigned char* lds, const Gemm g, const StaticOrder& S, const Epi& E) {
;     ...
;             PG8_LDB(B0, 1, 0); PG8_SCHED; PG8_LDA(At, 1, 0); PG8_STAGE(PG8_SA(0, 1), a2 + hstepA, voffA);
;             PG8_WAIT_L(8); PG8_BAR; PG8_WAIT_L(0); PG8_MMA(0, 0, At, B0); PG8_BAR; PG8_SCHED;
;             PG8_LDB(B1, 1, 1); PG8_STAGE(PG8_SB(1, 0), b3, voffB);
;             PG8_BAR; PG8_WAIT_L(0); PG8_MMA(0, 1, At, B1); PG8_BAR;
;             PG8_LDA(At, 1, 1); PG8_STAGE(PG8_SA(1, 0), a3, voffA);
;             PG8_BAR; PG8_WAIT_L(0); PG8_MMA(1, 0, At, B0); PG8_BAR; PG8_SCHED;
	s_nop 0
	s_nop 0
	ds_read_b128 v[12:15], v160
	ds_read_b128 v[20:23], v160 offset:1024
	ds_read_b128 v[156:159], v160 offset:2048
	ds_read_b128 v[160:163], v160 offset:3072
	ds_read_b128 v[164:167], v175 offset:32768
	ds_read_b128 v[178:181], v175 offset:33792
	ds_read_b128 v[182:185], v175 offset:34816
	ds_read_b128 v[186:189], v175 offset:35840
	ds_read_b128 v[190:193], v175 offset:36864
	ds_read_b128 v[194:197], v175 offset:37888
	ds_read_b128 v[198:201], v175 offset:38912
	ds_read_b128 v[202:205], v175 offset:39936
	v_add_u32_e32 v218, 0x1c000, v169
	ds_read_b128 v[206:209], v218
	ds_read_b128 v[210:213], v218 offset:1024
	ds_read_b128 v[214:217], v218 offset:2048
	ds_read_b128 v[218:221], v218 offset:3072
	s_add_u32 s6, s6, 0x80000
	s_addc_u32 s7, s7, 0
	s_mov_b32 m0, s17
	v_lshl_add_u64 v[228:229], s[6:7], 0, v[144:145]
	global_load_lds_dwordx4 v[228:229], off
	v_lshl_add_u64 v[228:229], s[6:7], 0, v[140:141]
	s_mov_b32 m0, s22
	s_nop 0
	global_load_lds_dwordx4 v[228:229], off
	s_waitcnt lgkmcnt(0)
	s_waitcnt vmcnt(8)
	s_barrier
	v_mfma_f32_16x16x32_bf16 v[132:135], v[12:15], v[164:167], v[132:135]
	v_mfma_f32_16x16x32_bf16 v[124:127], v[156:159], v[164:167], v[124:127]
	v_mfma_f32_16x16x32_bf16 v[116:119], v[12:15], v[182:185], v[116:119]
	v_mfma_f32_16x16x32_bf16 v[108:111], v[156:159], v[182:185], v[108:111]
	v_mfma_f32_16x16x32_bf16 v[100:103], v[12:15], v[190:193], v[100:103]
	v_mfma_f32_16x16x32_bf16 v[92:95], v[156:159], v[190:193], v[92:95]
	v_mfma_f32_16x16x32_bf16 v[84:87], v[12:15], v[198:201], v[84:87]
	v_mfma_f32_16x16x32_bf16 v[76:79], v[156:159], v[198:201], v[76:79]
	v_mfma_f32_16x16x32_bf16 v[132:135], v[20:23], v[178:181], v[132:135]
	v_mfma_f32_16x16x32_bf16 v[124:127], v[160:163], v[178:181], v[124:127]
	v_mfma_f32_16x16x32_bf16 v[116:119], v[20:23], v[186:189], v[116:119]
	v_mfma_f32_16x16x32_bf16 v[108:111], v[160:163], v[186:189], v[108:111]
	v_mfma_f32_16x16x32_bf16 v[100:103], v[20:23], v[194:197], v[100:103]
	v_mfma_f32_16x16x32_bf16 v[92:95], v[160:163], v[194:197], v[92:95]
	v_mfma_f32_16x16x32_bf16 v[84:87], v[20:23], v[202:205], v[84:87]
	v_mfma_f32_16x16x32_bf16 v[76:79], v[160:163], v[202:205], v[76:79]
	v_mfma_f32_16x16x32_bf16 v[128:131], v[206:209], v[164:167], v[128:131]
	v_mfma_f32_16x16x32_bf16 v[120:123], v[214:217], v[164:167], v[120:123]
	v_mfma_f32_16x16x32_bf16 v[112:115], v[206:209], v[182:185], v[112:115]
	v_mfma_f32_16x16x32_bf16 v[104:107], v[214:217], v[182:185], v[104:107]
	v_mfma_f32_16x16x32_bf16 v[96:99], v[206:209], v[190:193], v[96:99]
	v_mfma_f32_16x16x32_bf16 v[88:91], v[214:217], v[190:193], v[88:91]
	v_mfma_f32_16x16x32_bf16 v[80:83], v[206:209], v[198:201], v[80:83]
	v_mfma_f32_16x16x32_bf16 v[72:75], v[214:217], v[198:201], v[72:75]
	v_mfma_f32_16x16x32_bf16 v[128:131], v[210:213], v[178:181], v[128:131]
	v_mfma_f32_16x16x32_bf16 v[120:123], v[218:221], v[178:181], v[120:123]
	v_mfma_f32_16x16x32_bf16 v[112:115], v[210:213], v[186:189], v[112:115]
	v_mfma_f32_16x16x32_bf16 v[104:107], v[218:221], v[186:189], v[104:107]
	v_mfma_f32_16x16x32_bf16 v[96:99], v[210:213], v[194:197], v[96:99]
	v_mfma_f32_16x16x32_bf16 v[88:91], v[218:221], v[194:197], v[88:91]
	v_mfma_f32_16x16x32_bf16 v[80:83], v[210:213], v[202:205], v[80:83]
	v_mfma_f32_16x16x32_bf16 v[72:75], v[218:221], v[202:205], v[72:75]
	s_barrier
	ds_read_b128 v[164:167], v175 offset:49152
	ds_read_b128 v[178:181], v175 offset:50176
	ds_read_b128 v[182:185], v175 offset:51200
	ds_read_b128 v[186:189], v175 offset:52224
	ds_read_b128 v[190:193], v175 offset:53248
	ds_read_b128 v[194:197], v175 offset:54272
	ds_read_b128 v[198:201], v175 offset:55296
	ds_read_b128 v[202:205], v175 offset:56320
	s_add_i32 s6, 0, 0x1c000
	s_add_i32 s7, s63, s11
	v_lshl_add_u64 v[170:171], v[170:171], 0, s[18:19]
	s_mov_b32 m0, s7
	s_nop 0
	global_load_lds_dwordx4 v[170:171], off
	v_lshl_add_u64 v[170:171], v[222:223], 0, s[18:19]
	s_add_i32 m0, s7, 0x2000
	s_nop 0
	global_load_lds_dwordx4 v[170:171], off
	s_mov_b32 m0, s31
	v_lshl_add_u64 v[170:171], v[224:225], 0, s[18:19]
	global_load_lds_dwordx4 v[170:171], off
	v_lshl_add_u64 v[170:171], v[226:227], 0, s[18:19]
	s_mov_b32 m0, s34
	s_nop 0
	global_load_lds_dwordx4 v[170:171], off
	s_add_u32 s4, s4, 0x80080
	s_addc_u32 s5, s5, 0
	s_add_i32 s6, s6, s11
	v_lshl_add_u64 v[228:229], s[4:5], 0, v[142:143]
	s_mov_b32 m0, s6
	s_nop 0
	global_load_lds_dwordx4 v[228:229], off
	v_lshl_add_u64 v[228:229], s[4:5], 0, v[138:139]
	s_add_i32 m0, s6, 0x2000
	s_nop 0
	global_load_lds_dwordx4 v[228:229], off
	s_waitcnt lgkmcnt(0)
	s_waitcnt vmcnt(8)
	s_barrier
; #define PG8_STAGE(bufoff, gbase, voff) do { _Pragma("unroll") for (int _i = 0; _i < 2; ++_i) \
;         __builtin_amdgcn_global_load_lds((const unsigned*)((const char*)(gbase) + (voff)[_i]), (PG8_LAS unsigned*)(lds + (bufoff) + ldsw + _i * 8192), 16, 0, 0); } while (0)
; #define PG8_MMA(ai, bj, At, Bt) do { __builtin_amdgcn_s_setprio(1); _Pragma("unroll") for (int m = 0; m < 4; ++m) _Pragma("unroll") for (int n = 0; n < 2; ++n) _Pragma("unroll") for (int k = 0; k < 2; ++k) \
;         acc[ai][bj][m][n] = __builtin_amdgcn_mfma_f32_16x16x32_bf16(Bt[n][k], At[m][k], acc[ai][bj][m][n], 0, 0, 0); __builtin_amdgcn_s_setprio(0); } while (0)
; #define PG8_WAIT_V(n) asm volatile("s_waitcnt vmcnt(" #n ")" ::: "memory")
; #define PG8_WAIT_L(n) asm volatile("s_waitcnt lgkmcnt(" #n ")" ::: "memory")
; #define PG8_BAR __builtin_amdgcn_s_barrier()
; #define PG8_SCHED __builtin_amdgcn_sched_barrier(0)
; __device__ __forceinline__ void rstd8(const float* part, int row0, int fq, float (&rs)[8]) {
;     f32x4 v[8][2];
; #pragma unroll
;     for (int k = 0; k < 8; ++k) { const f32x4* p = (const f32x4*)(part + (size_t)(row0 + (k >> 2) * 128 + (k & 3) * 16) * 32 + fq * 8); v[k][0] = p[0]; v[k][1] = p[1]; }
; #pragma unroll
;     for (int k = 0; k < 8; ++k) { float s = ((v[k][0][0] + v[k][0][1]) + (v[k][0][2] + v[k][0][3])) + ((v[k][1][0] + v[k][1][1]) + (v[k][1][2] + v[k][1][3]));
;         s += __shfl_xor(s, 16); s += __shfl_xor(s, 32); rs[k] = rsqrtf(s * (1.0f / 2048.0f) + EPS); }
; template <class Epi>
; __device__ __forceinline__ void gemm_phase(PG8_LAS unsigned char* lds, const Gemm g, const StaticOrder& S, const Epi& E) {
;     ...
;             PG8_BAR; PG8_WAIT_L(0); PG8_MMA(1, 0, At, B0); PG8_BAR; PG8_SCHED;
;             PG8_STAGE(PG8_SB(1, 1), b3 + hstepB, voffB);
;             PG8_WAIT_V(6); PG8_BAR; PG8_MMA(1, 1, At, B1); PG8_BAR;
;         }
;         E(acc, cur, wr, wc, fr, fq);
	v_mfma_f32_16x16x32_bf16 v[68:71], v[12:15], v[164:167], v[68:71]
	v_mfma_f32_16x16x32_bf16 v[52:55], v[12:15], v[182:185], v[52:55]
	v_mfma_f32_16x16x32_bf16 v[36:39], v[12:15], v[190:193], v[36:39]
	v_mfma_f32_16x16x32_bf16 v[0:3], v[12:15], v[198:201], v[0:3]
	v_mfma_f32_16x16x32_bf16 v[68:71], v[20:23], v[178:181], v[68:71]
	v_mfma_f32_16x16x32_bf16 v[60:63], v[156:159], v[164:167], v[60:63]
	v_mfma_f32_16x16x32_bf16 v[52:55], v[20:23], v[186:189], v[52:55]
	v_mfma_f32_16x16x32_bf16 v[44:47], v[156:159], v[182:185], v[44:47]
	v_mfma_f32_16x16x32_bf16 v[36:39], v[20:23], v[194:197], v[36:39]
	v_mfma_f32_16x16x32_bf16 v[28:31], v[156:159], v[190:193], v[28:31]
	v_mfma_f32_16x16x32_bf16 v[20:23], v[20:23], v[202:205], v[0:3]
	v_mfma_f32_16x16x32_bf16 v[0:3], v[156:159], v[198:201], v[4:7]
	v_mfma_f32_16x16x32_bf16 v[60:63], v[160:163], v[178:181], v[60:63]
	v_mfma_f32_16x16x32_bf16 v[44:47], v[160:163], v[186:189], v[44:47]
	v_mfma_f32_16x16x32_bf16 v[28:31], v[160:163], v[194:197], v[28:31]
	v_mfma_f32_16x16x32_bf16 v[12:15], v[160:163], v[202:205], v[0:3]
	v_mfma_f32_16x16x32_bf16 v[0:3], v[206:209], v[164:167], v[64:67]
	v_mfma_f32_16x16x32_bf16 v[64:67], v[210:213], v[178:181], v[0:3]
	v_mfma_f32_16x16x32_bf16 v[0:3], v[214:217], v[164:167], v[56:59]
	v_mfma_f32_16x16x32_bf16 v[56:59], v[218:221], v[178:181], v[0:3]
	v_mfma_f32_16x16x32_bf16 v[0:3], v[206:209], v[182:185], v[48:51]
	v_mfma_f32_16x16x32_bf16 v[48:51], v[210:213], v[186:189], v[0:3]
	v_mfma_f32_16x16x32_bf16 v[0:3], v[214:217], v[182:185], v[40:43]
	v_mfma_f32_16x16x32_bf16 v[40:43], v[218:221], v[186:189], v[0:3]
	v_mfma_f32_16x16x32_bf16 v[0:3], v[206:209], v[190:193], v[32:35]
	v_mfma_f32_16x16x32_bf16 v[32:35], v[210:213], v[194:197], v[0:3]
	v_mfma_f32_16x16x32_bf16 v[0:3], v[214:217], v[190:193], v[24:27]
	v_mfma_f32_16x16x32_bf16 v[24:27], v[218:221], v[194:197], v[0:3]
	v_mfma_f32_16x16x32_bf16 v[0:3], v[206:209], v[198:201], v[16:19]
	v_mfma_f32_16x16x32_bf16 v[16:19], v[210:213], v[202:205], v[0:3]
	v_mfma_f32_16x16x32_bf16 v[0:3], v[214:217], v[198:201], v[8:11]
	v_mfma_f32_16x16x32_bf16 v[8:11], v[218:221], v[202:205], v[0:3]
	s_add_i32 s62, s62, 2
	s_add_u32 s0, s0, 0x100
	s_addc_u32 s1, s1, 0
	s_add_u32 s60, s60, 0x100
	s_addc_u32 s61, s61, 0
	s_cmp_gt_u32 s62, 29
	s_barrier
	s_cbranch_scc0 .LBB0_226
	s_setprio 0
	v_lshl_add_u32 v166, s16, 8, v137
	v_or_b32_e32 v162, 16, v166
	v_or_b32_e32 v160, 32, v166
	v_or_b32_e32 v158, 48, v166
	s_mov_b64 s[0:1], -1
	s_cmp_lg_u32 s16, s43
	v_ashrrev_i32_e32 v167, 31, v166
	v_ashrrev_i32_e32 v163, 31, v162
	v_ashrrev_i32_e32 v161, 31, v160
	v_ashrrev_i32_e32 v159, 31, v158
	v_add_u32_e32 v170, 0x80, v166
	s_cbranch_scc0 .LBB0_229
	v_lshlrev_b64 v[0:1], 7, v[166:167]
	v_lshlrev_b64 v[4:5], 7, v[162:163]
	v_lshl_add_u64 v[6:7], v[146:147], 0, v[0:1]
	v_lshl_add_u64 v[4:5], v[146:147], 0, v[4:5]
	global_load_dwordx4 v[0:3], v[6:7], off
	global_load_dwordx4 v[178:181], v[4:5], off
	global_load_dwordx4 v[182:185], v[6:7], off offset:16
	global_load_dwordx4 v[186:189], v[4:5], off offset:16
	v_lshlrev_b64 v[4:5], 7, v[160:161]
	v_lshlrev_b64 v[156:157], 7, v[158:159]
	v_lshl_add_u64 v[4:5], v[146:147], 0, v[4:5]
	v_lshl_add_u64 v[156:157], v[146:147], 0, v[156:157]
	global_load_dwordx4 v[190:193], v[4:5], off
	global_load_dwordx4 v[194:197], v[156:157], off
	global_load_dwordx4 v[198:201], v[4:5], off offset:16
	global_load_dwordx4 v[202:205], v[156:157], off offset:16
	v_add_u32_e32 v156, 0x80, v166
	s_movk_i32 s4, 0x4000
	v_and_b32_e32 v164, 64, v177
	v_ashrrev_i32_e32 v157, 31, v156
	v_add_co_u32_e32 v206, vcc, s4, v6
	v_add_u32_e32 v221, 64, v164
	v_lshlrev_b64 v[164:165], 7, v[156:157]
	v_addc_co_u32_e32 v207, vcc, 0, v7, vcc
	v_lshl_add_u64 v[164:165], v[146:147], 0, v[164:165]
	global_load_dwordx4 v[206:209], v[206:207], off offset:2048
	s_nop 0
	global_load_dwordx4 v[210:213], v[164:165], off offset:16
	global_load_dwordx4 v[214:217], v[164:165], off
	v_add_co_u32_e32 v230, vcc, s39, v6
	v_xor_b32_e32 v171, 16, v177
	s_nop 0
	v_addc_co_u32_e32 v231, vcc, 0, v7, vcc
	v_xor_b32_e32 v220, 32, v177
	s_mov_b64 s[0:1], 0x4800
	v_cmp_lt_i32_e32 vcc, v171, v221
	v_lshl_add_u64 v[218:219], v[6:7], 0, s[0:1]
	v_lshl_add_u64 v[226:227], v[6:7], 0, s[20:21]
	v_cndmask_b32_e32 v164, v177, v171, vcc
	v_cmp_lt_i32_e32 vcc, v220, v221
	v_lshl_add_u64 v[6:7], v[6:7], 0, s[28:29]
	v_lshlrev_b32_e32 v171, 2, v164
	v_cndmask_b32_e32 v165, v177, v220, vcc
	global_load_dwordx4 v[218:221], v[218:219], off offset:16
	s_nop 0
	global_load_dwordx4 v[222:225], v[230:231], off
	s_nop 0
	global_load_dwordx4 v[226:229], v[226:227], off offset:16
	s_nop 0
	global_load_dwordx4 v[230:233], v[230:231], off offset:2048
	s_nop 0
	global_load_dwordx4 v[234:237], v[6:7], off offset:16
	v_lshlrev_b32_e32 v238, 2, v165
	v_mov_b64_e32 v[4:5], s[46:47]
	s_waitcnt vmcnt(0)
; __device__ __forceinline__ void rstd8(const float* part, int row0, int fq, float (&rs)[8]) {
;     f32x4 v[8][2];
; #pragma unroll
;     for (int k = 0; k < 8; ++k) { const f32x4* p = (const f32x4*)(part + (size_t)(row0 + (k >> 2) * 128 + (k & 3) * 16) * 32 + fq * 8); v[k][0] = p[0]; v[k][1] = p[1]; }
; #pragma unroll
;     for (int k = 0; k < 8; ++k) { float s = ((v[k][0][0] + v[k][0][1]) + (v[k][0][2] + v[k][0][3])) + ((v[k][1][0] + v[k][1][1]) + (v[k][1][2] + v[k][1][3]));
;         s += __shfl_xor(s, 16); s += __shfl_xor(s, 32); rs[k] = rsqrtf(s * (1.0f / 2048.0f) + EPS); }
;     __device__ __forceinline__ void operator()(const f32x4 (&acc)[2][2][4][2], const pg8::Unit& u, int wr, int wc, int fr, int fq) const {
;     ...
;         if (u.pm != cached_pm) { rstd8(part, row0, fq, rsv);
; #pragma unroll
;             for (int k = 0; k < 8; ++k) mine[k * 64] = rsv[k];
;             cached_pm = u.pm; }
	v_mov_b32_e32 v7, v178
	v_mov_b32_e32 v6, v0
	v_mov_b32_e32 v178, v1
	v_mov_b32_e32 v0, v2
	v_mov_b32_e32 v1, v180
	v_mov_b32_e32 v180, v3
	v_mov_b32_e32 v2, v182
	v_mov_b32_e32 v3, v186
	v_mov_b32_e32 v186, v183
	v_mov_b32_e32 v164, v184
	v_mov_b32_e32 v165, v188
	v_mov_b32_e32 v188, v185
	v_pk_add_f32 v[6:7], v[6:7], v[178:179]
	v_pk_add_f32 v[0:1], v[0:1], v[180:181]
	v_pk_add_f32 v[2:3], v[2:3], v[186:187]
	v_pk_add_f32 v[164:165], v[164:165], v[188:189]
	v_pk_add_f32 v[0:1], v[6:7], v[0:1]
	v_pk_add_f32 v[2:3], v[2:3], v[164:165]
	v_mov_b32_e32 v182, v190
	v_pk_add_f32 v[0:1], v[0:1], v[2:3]
	ds_bpermute_b32 v2, v171, v0
	ds_bpermute_b32 v3, v171, v1
	v_mov_b32_e32 v183, v194
	v_mov_b32_e32 v194, v191
	v_mov_b32_e32 v184, v192
	v_mov_b32_e32 v185, v196
	v_mov_b32_e32 v196, v193
	v_mov_b32_e32 v190, v198
	v_mov_b32_e32 v191, v202
	v_mov_b32_e32 v202, v199
	v_mov_b32_e32 v192, v200
	v_mov_b32_e32 v193, v204
	v_mov_b32_e32 v204, v201
	s_waitcnt lgkmcnt(0)
	v_pk_add_f32 v[0:1], v[0:1], v[2:3]
	v_pk_add_f32 v[178:179], v[182:183], v[194:195]
	v_pk_add_f32 v[6:7], v[184:185], v[196:197]
	v_pk_add_f32 v[164:165], v[190:191], v[202:203]
	v_pk_add_f32 v[180:181], v[192:193], v[204:205]
	ds_bpermute_b32 v2, v238, v0
	ds_bpermute_b32 v3, v238, v1
	v_pk_add_f32 v[6:7], v[178:179], v[6:7]
	v_pk_add_f32 v[164:165], v[164:165], v[180:181]
	v_mov_b32_e32 v178, v216
	v_pk_add_f32 v[6:7], v[6:7], v[164:165]
	ds_bpermute_b32 v164, v171, v6
	ds_bpermute_b32 v165, v171, v7
	s_waitcnt lgkmcnt(2)
	v_pk_add_f32 v[0:1], v[0:1], v[2:3]
	v_mov_b32_e32 v179, v208
	v_pk_fma_f32 v[0:1], v[0:1], s[30:31], v[4:5] op_sel_hi:[1,0,0]
	v_mov_b32_e32 v208, v217
	v_mul_f32_e32 v2, 0x4b800000, v0
	v_mul_f32_e32 v3, 0x4b800000, v1
	v_cmp_gt_f32_e32 vcc, s40, v0
	v_cmp_gt_f32_e64 s[0:1], s40, v1
	v_pk_add_f32 v[178:179], v[178:179], v[208:209]
	v_cndmask_b32_e32 v0, v0, v2, vcc
	v_cndmask_b32_e64 v1, v1, v3, s[0:1]
	s_waitcnt lgkmcnt(0)
	v_pk_add_f32 v[2:3], v[6:7], v[164:165]
	ds_bpermute_b32 v6, v238, v2
	ds_bpermute_b32 v7, v238, v3
	v_rsq_f32_e32 v0, v0
	v_rsq_f32_e32 v1, v1
	v_mov_b32_e32 v180, v212
	v_mov_b32_e32 v181, v220
	s_waitcnt lgkmcnt(0)
	v_pk_add_f32 v[2:3], v[2:3], v[6:7]
	v_pk_mul_f32 v[164:165], v[0:1], s[48:49] op_sel_hi:[1,0]
	v_pk_fma_f32 v[2:3], v[2:3], s[30:31], v[4:5] op_sel_hi:[1,0,0]
	v_cndmask_b32_e64 v1, v1, v165, s[0:1]
	v_mul_f32_e32 v6, 0x4b800000, v2
	v_cmp_gt_f32_e64 s[0:1], s40, v2
	v_mov_b32_e32 v7, v206
	v_mov_b32_e32 v206, v215
	v_cndmask_b32_e64 v2, v2, v6, s[0:1]
	v_mov_b32_e32 v6, v214
	v_pk_add_f32 v[6:7], v[6:7], v[206:207]
	v_mov_b32_e32 v220, v213
	v_pk_add_f32 v[6:7], v[6:7], v[178:179]
	v_mov_b32_e32 v178, v210
	v_mov_b32_e32 v179, v218
	v_mov_b32_e32 v218, v211
	v_pk_add_f32 v[178:179], v[178:179], v[218:219]
	v_pk_add_f32 v[180:181], v[180:181], v[220:221]
	v_mul_f32_e32 v165, 0x4b800000, v3
	v_pk_add_f32 v[178:179], v[178:179], v[180:181]
	v_cmp_gt_f32_e64 s[4:5], s40, v3
	v_pk_add_f32 v[6:7], v[6:7], v[178:179]
	ds_bpermute_b32 v178, v171, v6
	ds_bpermute_b32 v179, v171, v7
	v_cndmask_b32_e64 v3, v3, v165, s[4:5]
	v_rsq_f32_e32 v2, v2
	v_rsq_f32_e32 v3, v3
	v_cndmask_b32_e32 v0, v0, v164, vcc
	s_waitcnt lgkmcnt(0)
	v_pk_add_f32 v[6:7], v[6:7], v[178:179]
	ds_bpermute_b32 v178, v238, v6
	ds_bpermute_b32 v179, v238, v7
	v_pk_mul_f32 v[164:165], v[2:3], s[48:49] op_sel_hi:[1,0]
	v_mov_b32_e32 v180, v230
	v_cndmask_b32_e64 v3, v3, v165, s[4:5]
	v_cndmask_b32_e64 v2, v2, v164, s[0:1]
	s_waitcnt lgkmcnt(0)
	v_pk_add_f32 v[6:7], v[6:7], v[178:179]
	v_mov_b32_e32 v164, v223
	v_mov_b32_e32 v165, v224
	v_mov_b32_e32 v223, v225
	v_mov_b32_e32 v178, v227
	v_mov_b32_e32 v179, v228
	v_mov_b32_e32 v227, v229
	v_mov_b32_e32 v181, v234
	v_mov_b32_e32 v234, v231
	v_mov_b32_e32 v182, v232
	v_mov_b32_e32 v183, v236
	v_mov_b32_e32 v236, v233
	v_pk_add_f32 v[164:165], v[164:165], v[222:223]
	v_pk_add_f32 v[178:179], v[178:179], v[226:227]
	v_pk_add_f32 v[180:181], v[180:181], v[234:235]
	v_pk_add_f32 v[182:183], v[182:183], v[236:237]
	v_pk_add_f32 v[164:165], v[164:165], v[164:165] op_sel:[0,1] op_sel_hi:[1,0]
	v_pk_add_f32 v[178:179], v[178:179], v[178:179] op_sel:[0,1] op_sel_hi:[1,0]
	v_pk_add_f32 v[180:181], v[180:181], v[182:183]
	v_pk_fma_f32 v[6:7], v[6:7], s[30:31], v[4:5] op_sel_hi:[1,0,0]
	v_mov_b32_e32 v165, v180
	v_mov_b32_e32 v179, v181
	v_pk_add_f32 v[164:165], v[164:165], v[178:179]
	ds_bpermute_b32 v178, v171, v164
	ds_bpermute_b32 v179, v171, v165
	v_mul_f32_e32 v171, 0x4b800000, v6
	v_cmp_gt_f32_e32 vcc, s40, v6
	v_cmp_gt_f32_e64 s[0:1], s40, v7
	s_waitcnt lgkmcnt(0)
	v_pk_add_f32 v[164:165], v[164:165], v[178:179]
	ds_bpermute_b32 v178, v238, v164
	ds_bpermute_b32 v179, v238, v165
	v_cndmask_b32_e32 v6, v6, v171, vcc
	v_mul_f32_e32 v171, 0x4b800000, v7
	v_cndmask_b32_e64 v7, v7, v171, s[0:1]
	v_rsq_f32_e32 v6, v6
	s_waitcnt lgkmcnt(0)
	v_pk_add_f32 v[164:165], v[164:165], v[178:179]
	v_rsq_f32_e32 v7, v7
	v_pk_fma_f32 v[4:5], v[164:165], s[30:31], v[4:5] op_sel_hi:[1,0,0]
	s_nop 0
	v_mul_f32_e32 v164, 0x4b800000, v4
	v_cmp_gt_f32_e64 s[4:5], s40, v4
	v_cmp_gt_f32_e64 s[6:7], s40, v5
	s_nop 0
	v_cndmask_b32_e64 v4, v4, v164, s[4:5]
	v_rsq_f32_e32 v164, v4
	v_mul_f32_e32 v4, 0x4b800000, v5
	v_cndmask_b32_e64 v4, v5, v4, s[6:7]
	v_rsq_f32_e32 v165, v4
	v_pk_mul_f32 v[4:5], v[6:7], s[48:49] op_sel_hi:[1,0]
	s_nop 0
	v_cndmask_b32_e64 v5, v7, v5, s[0:1]
	v_cndmask_b32_e32 v4, v6, v4, vcc
	v_pk_mul_f32 v[6:7], v[164:165], s[48:49] op_sel_hi:[1,0]
	s_mov_b64 s[0:1], 0
	v_cndmask_b32_e64 v7, v165, v7, s[6:7]
	v_cndmask_b32_e64 v6, v164, v6, s[4:5]
	ds_write2st64_b32 v172, v0, v1 offset1:1
	ds_write2st64_b32 v172, v2, v3 offset0:2 offset1:3
	ds_write2st64_b32 v172, v4, v5 offset0:4 offset1:5
	ds_write2st64_b32 v172, v6, v7 offset0:6 offset1:7
	v_mov_b64_e32 v[164:165], v[156:157]

; #define PG8_STAGE(bufoff, gbase, voff) do { _Pragma("unroll") for (int _i = 0; _i < 2; ++_i) \
;         __builtin_amdgcn_global_load_lds((const unsigned*)((const char*)(gbase) + (voff)[_i]), (PG8_LAS unsigned*)(lds + (bufoff) + ldsw + _i * 8192), 16, 0, 0); } while (0)
; #define PG8_LDA(dst, b, h) do { _Pragma("unroll") for (int m = 0; m < 4; ++m) _Pragma("unroll") for (int k = 0; k < 2; ++k) dst[m][k] = *(const PG8_LAS bf16x8*)(lds + PG8_SA(b, h) + aoff + m * 2048 + k * 1024); } while (0)
; #define PG8_LDB(dst, b, h) do { _Pragma("unroll") for (int n = 0; n < 2; ++n) _Pragma("unroll") for (int k = 0; k < 2; ++k) dst[n][k] = *(const PG8_LAS bf16x8*)(lds + PG8_SB(b, h) + boff + n * 2048 + k * 1024); } while (0)
; #define PG8_MMA(ai, bj, At, Bt) do { __builtin_amdgcn_s_setprio(1); _Pragma("unroll") for (int m = 0; m < 4; ++m) _Pragma("unroll") for (int n = 0; n < 2; ++n) _Pragma("unroll") for (int k = 0; k < 2; ++k) \
;         acc[ai][bj][m][n] = __builtin_amdgcn_mfma_f32_16x16x32_bf16(Bt[n][k], At[m][k], acc[ai][bj][m][n], 0, 0, 0); __builtin_amdgcn_s_setprio(0); } while (0)
; #define PG8_WAIT_L(n) asm volatile("s_waitcnt lgkmcnt(" #n ")" ::: "memory")
; template <class Epi>
; __device__ __forceinline__ void gemm_phase(PG8_LAS unsigned char* lds, const Gemm g, const StaticOrder& S, const Epi& E) {
;     ...
;         const bool has_next = S.next(ui + 1, nxt);
;         const char* nA = has_next ? (const char*)g.A + (size_t)nxt.pm * tstepA : cA; const char* nB = has_next ? (const char*)g.Bt + (size_t)nxt.pn * tstepB : cB;
;         for (int t = 0; t < nt; t += 2) {
;             const bool last = (t == nt - 2);
;             const char* a1 = cA + (size_t)(t + 1) * kstep;
;             const char* a2 = last ? nA : cA + (size_t)(t + 2) * kstep; const char* b2 = last ? nB : cB + (size_t)(t + 2) * kstep;
;             const char* a3 = a2 + kstep; const char* b3 = b2 + kstep;
;             PG8_LDB(B0, 0, 0); PG8_SCHED; PG8_LDA(At, 0, 0); PG8_STAGE(PG8_SA(1, 1), a1 + hstepA, voffA);
;             PG8_WAIT_L(8); PG8_BAR; PG8_WAIT_L(0); PG8_MMA(0, 0, At, B0); PG8_BAR; PG8_SCHED;
;     ...
; #pragma unroll
;         for (int a = 0; a < 2; ++a)
; #pragma unroll
;             for (int b = 0; b < 2; ++b)
; #pragma unroll
;                 for (int m = 0; m < 4; ++m)
; #pragma unroll
;                     for (int n = 0; n < 2; ++n) acc[a][b][m][n] = (f32x4){0.f, 0.f, 0.f, 0.f};
.LBB0_316:
	s_add_u32 s20, s12, 0x160080
	s_addc_u32 s21, s13, 0
	s_add_u32 s48, s10, 0x100
	v_mov_b32_e32 v0, 0
	s_addc_u32 s49, s11, 0
	s_mov_b32 s50, -2
	s_waitcnt lgkmcnt(0)
	v_mov_b32_e32 v1, v0
	v_mov_b32_e32 v2, v0
	v_mov_b32_e32 v3, v0
	v_mov_b32_e32 v4, v0
	v_mov_b32_e32 v5, v0
	v_mov_b32_e32 v6, v0
	v_mov_b32_e32 v7, v0
	v_mov_b32_e32 v16, v0
	v_mov_b32_e32 v17, v0
	v_mov_b32_e32 v18, v0
	v_mov_b32_e32 v19, v0
	v_mov_b32_e32 v20, v0
	v_mov_b32_e32 v21, v0
	v_mov_b32_e32 v22, v0
	v_mov_b32_e32 v23, v0
	v_mov_b32_e32 v32, v0
	v_mov_b32_e32 v33, v0
	v_mov_b32_e32 v34, v0
	v_mov_b32_e32 v35, v0
	v_mov_b32_e32 v36, v0
	v_mov_b32_e32 v37, v0
	v_mov_b32_e32 v38, v0
	v_mov_b32_e32 v39, v0
	v_mov_b32_e32 v48, v0
	v_mov_b32_e32 v49, v0
	v_mov_b32_e32 v50, v0
	v_mov_b32_e32 v51, v0
	v_mov_b32_e32 v52, v0
	v_mov_b32_e32 v53, v0
	v_mov_b32_e32 v54, v0
	v_mov_b32_e32 v55, v0
	v_mov_b32_e32 v12, v0
	v_mov_b32_e32 v13, v0
	v_mov_b32_e32 v14, v0
	v_mov_b32_e32 v15, v0
	v_mov_b32_e32 v8, v0
	v_mov_b32_e32 v9, v0
	v_mov_b32_e32 v10, v0
	v_mov_b32_e32 v11, v0
	v_mov_b32_e32 v28, v0
	v_mov_b32_e32 v29, v0
	v_mov_b32_e32 v30, v0
	v_mov_b32_e32 v31, v0
	v_mov_b32_e32 v24, v0
	v_mov_b32_e32 v25, v0
	v_mov_b32_e32 v26, v0
	v_mov_b32_e32 v27, v0
	v_mov_b32_e32 v44, v0
	v_mov_b32_e32 v45, v0
	v_mov_b32_e32 v46, v0
	v_mov_b32_e32 v47, v0
	v_mov_b32_e32 v40, v0
	v_mov_b32_e32 v41, v0
	v_mov_b32_e32 v42, v0
	v_mov_b32_e32 v43, v0
	v_mov_b32_e32 v56, v0
	v_mov_b32_e32 v57, v0
	v_mov_b32_e32 v58, v0
	v_mov_b32_e32 v59, v0
	v_mov_b32_e32 v60, v0
	v_mov_b32_e32 v61, v0
	v_mov_b32_e32 v62, v0
	v_mov_b32_e32 v63, v0
	v_mov_b32_e32 v64, v0
	v_mov_b32_e32 v65, v0
	v_mov_b32_e32 v66, v0
	v_mov_b32_e32 v67, v0
	v_mov_b32_e32 v68, v0
	v_mov_b32_e32 v69, v0
	v_mov_b32_e32 v70, v0
	v_mov_b32_e32 v71, v0
	v_mov_b32_e32 v80, v0
	v_mov_b32_e32 v81, v0
	v_mov_b32_e32 v82, v0
	v_mov_b32_e32 v83, v0
	v_mov_b32_e32 v84, v0
	v_mov_b32_e32 v85, v0
	v_mov_b32_e32 v86, v0
	v_mov_b32_e32 v87, v0
	v_mov_b32_e32 v96, v0
	v_mov_b32_e32 v97, v0
	v_mov_b32_e32 v98, v0
	v_mov_b32_e32 v99, v0
	v_mov_b32_e32 v100, v0
	v_mov_b32_e32 v101, v0
	v_mov_b32_e32 v102, v0
	v_mov_b32_e32 v103, v0
	v_mov_b32_e32 v112, v0
	v_mov_b32_e32 v113, v0
	v_mov_b32_e32 v114, v0
	v_mov_b32_e32 v115, v0
	v_mov_b32_e32 v116, v0
	v_mov_b32_e32 v117, v0
	v_mov_b32_e32 v118, v0
	v_mov_b32_e32 v119, v0
	v_mov_b32_e32 v76, v0
	v_mov_b32_e32 v77, v0
	v_mov_b32_e32 v78, v0
	v_mov_b32_e32 v79, v0
	v_mov_b32_e32 v72, v0
	v_mov_b32_e32 v73, v0
	v_mov_b32_e32 v74, v0
	v_mov_b32_e32 v75, v0
	v_mov_b32_e32 v92, v0
	v_mov_b32_e32 v93, v0
	v_mov_b32_e32 v94, v0
	v_mov_b32_e32 v95, v0
	v_mov_b32_e32 v88, v0
	v_mov_b32_e32 v89, v0
	v_mov_b32_e32 v90, v0
	v_mov_b32_e32 v91, v0
	v_mov_b32_e32 v108, v0
	v_mov_b32_e32 v109, v0
	v_mov_b32_e32 v110, v0
	v_mov_b32_e32 v111, v0
	v_mov_b32_e32 v104, v0
	v_mov_b32_e32 v105, v0
	v_mov_b32_e32 v106, v0
	v_mov_b32_e32 v107, v0
	v_mov_b32_e32 v120, v0
	v_mov_b32_e32 v121, v0
	v_mov_b32_e32 v122, v0
	v_mov_b32_e32 v123, v0
	v_mov_b32_e32 v124, v0
	v_mov_b32_e32 v125, v0
	v_mov_b32_e32 v126, v0
	v_mov_b32_e32 v127, v0
	s_cmp_eq_u32 s101, 1
	s_cbranch_scc0 .Lsp_1
	s_setprio 1
.Lsp_1:
.LBB0_317:
	ds_read_b128 v[128:131], v191
	ds_read_b128 v[132:135], v191 offset:1024
	ds_read_b128 v[136:139], v191 offset:2048
	ds_read_b128 v[140:143], v191 offset:3072
	ds_read_b128 v[144:147], v192
	ds_read_b128 v[148:151], v192 offset:1024
	ds_read_b128 v[170:173], v192 offset:2048
	ds_read_b128 v[174:177], v192 offset:3072
	ds_read_b128 v[178:181], v192 offset:4096
	ds_read_b128 v[182:185], v192 offset:5120
	ds_read_b128 v[196:199], v192 offset:6144
	ds_read_b128 v[200:203], v192 offset:7168
	ds_read_b128 v[204:207], v193
	ds_read_b128 v[208:211], v193 offset:1024
	ds_read_b128 v[212:215], v193 offset:2048
	ds_read_b128 v[216:219], v193 offset:3072
	s_add_u32 s10, s20, 0xffea0080
	s_addc_u32 s11, s21, -1
	s_cmpk_eq_i32 s50, 0x54
	s_cselect_b32 s13, s1, s11
	s_cselect_b32 s12, s0, s10
	s_cselect_b32 s11, s7, s49
	s_cselect_b32 s10, s6, s48
	v_lshl_add_u64 v[186:187], s[20:21], 0, v[160:161]
	s_add_i32 m0, s28, 0xc000
	s_nop 0
	global_load_lds_dwordx4 v[186:187], off
	v_lshl_add_u64 v[186:187], s[20:21], 0, v[162:163]
	s_add_i32 m0, s28, 0xe000
	s_nop 0
	global_load_lds_dwordx4 v[186:187], off
	s_waitcnt lgkmcnt(0)
	s_waitcnt vmcnt(8)
	s_barrier
	v_mfma_f32_16x16x32_bf16 v[124:127], v[128:131], v[144:147], v[124:127]
	v_mfma_f32_16x16x32_bf16 v[120:123], v[136:139], v[144:147], v[120:123]
	v_mfma_f32_16x16x32_bf16 v[104:107], v[128:131], v[170:173], v[104:107]
	v_mfma_f32_16x16x32_bf16 v[108:111], v[136:139], v[170:173], v[108:111]
	v_mfma_f32_16x16x32_bf16 v[88:91], v[128:131], v[178:181], v[88:91]
	v_mfma_f32_16x16x32_bf16 v[92:95], v[136:139], v[178:181], v[92:95]
	v_mfma_f32_16x16x32_bf16 v[72:75], v[128:131], v[196:199], v[72:75]
	v_mfma_f32_16x16x32_bf16 v[76:79], v[136:139], v[196:199], v[76:79]
	v_mfma_f32_16x16x32_bf16 v[124:127], v[132:135], v[148:151], v[124:127]
	v_mfma_f32_16x16x32_bf16 v[120:123], v[140:143], v[148:151], v[120:123]
	v_mfma_f32_16x16x32_bf16 v[104:107], v[132:135], v[174:177], v[104:107]
	v_mfma_f32_16x16x32_bf16 v[108:111], v[140:143], v[174:177], v[108:111]
	v_mfma_f32_16x16x32_bf16 v[88:91], v[132:135], v[182:185], v[88:91]
	v_mfma_f32_16x16x32_bf16 v[92:95], v[140:143], v[182:185], v[92:95]
	v_mfma_f32_16x16x32_bf16 v[72:75], v[132:135], v[200:203], v[72:75]
	v_mfma_f32_16x16x32_bf16 v[76:79], v[140:143], v[200:203], v[76:79]
	v_mfma_f32_16x16x32_bf16 v[116:119], v[204:207], v[144:147], v[116:119]
	v_mfma_f32_16x16x32_bf16 v[112:115], v[212:215], v[144:147], v[112:115]
	v_mfma_f32_16x16x32_bf16 v[100:103], v[204:207], v[170:173], v[100:103]
	v_mfma_f32_16x16x32_bf16 v[96:99], v[212:215], v[170:173], v[96:99]
	v_mfma_f32_16x16x32_bf16 v[84:87], v[204:207], v[178:181], v[84:87]
	v_mfma_f32_16x16x32_bf16 v[80:83], v[212:215], v[178:181], v[80:83]
	v_mfma_f32_16x16x32_bf16 v[68:71], v[204:207], v[196:199], v[68:71]
	v_mfma_f32_16x16x32_bf16 v[64:67], v[212:215], v[196:199], v[64:67]
	v_mfma_f32_16x16x32_bf16 v[116:119], v[208:211], v[148:151], v[116:119]
	v_mfma_f32_16x16x32_bf16 v[112:115], v[216:219], v[148:151], v[112:115]
	v_mfma_f32_16x16x32_bf16 v[100:103], v[208:211], v[174:177], v[100:103]
	v_mfma_f32_16x16x32_bf16 v[96:99], v[216:219], v[174:177], v[96:99]
	v_mfma_f32_16x16x32_bf16 v[84:87], v[208:211], v[182:185], v[84:87]
	v_mfma_f32_16x16x32_bf16 v[80:83], v[216:219], v[182:185], v[80:83]
	v_mfma_f32_16x16x32_bf16 v[68:71], v[208:211], v[200:203], v[68:71]
	v_mfma_f32_16x16x32_bf16 v[64:67], v[216:219], v[200:203], v[64:67]
	s_barrier
; #define PG8_STAGE(bufoff, gbase, voff) do { _Pragma("unroll") for (int _i = 0; _i < 2; ++_i) \
;         __builtin_amdgcn_global_load_lds((const unsigned*)((const char*)(gbase) + (voff)[_i]), (PG8_LAS unsigned*)(lds + (bufoff) + ldsw + _i * 8192), 16, 0, 0); } while (0)
; #define PG8_LDA(dst, b, h) do { _Pragma("unroll") for (int m = 0; m < 4; ++m) _Pragma("unroll") for (int k = 0; k < 2; ++k) dst[m][k] = *(const PG8_LAS bf16x8*)(lds + PG8_SA(b, h) + aoff + m * 2048 + k * 1024); } while (0)
; #define PG8_LDB(dst, b, h) do { _Pragma("unroll") for (int n = 0; n < 2; ++n) _Pragma("unroll") for (int k = 0; k < 2; ++k) dst[n][k] = *(const PG8_LAS bf16x8*)(lds + PG8_SB(b, h) + boff + n * 2048 + k * 1024); } while (0)
; #define PG8_MMA(ai, bj, At, Bt) do { __builtin_amdgcn_s_setprio(1); _Pragma("unroll") for (int m = 0; m < 4; ++m) _Pragma("unroll") for (int n = 0; n < 2; ++n) _Pragma("unroll") for (int k = 0; k < 2; ++k) \
;         acc[ai][bj][m][n] = __builtin_amdgcn_mfma_f32_16x16x32_bf16(Bt[n][k], At[m][k], acc[ai][bj][m][n], 0, 0, 0); __builtin_amdgcn_s_setprio(0); } while (0)
; #define PG8_WAIT_V(n) asm volatile("s_waitcnt vmcnt(" #n ")" ::: "memory")
; #define PG8_WAIT_L(n) asm volatile("s_waitcnt lgkmcnt(" #n ")" ::: "memory")
; #define PG8_BAR __builtin_amdgcn_s_barrier()
; #define PG8_SCHED __builtin_amdgcn_sched_barrier(0)
; template <class Epi>
; __device__ __forceinline__ void gemm_phase(PG8_LAS unsigned char* lds, const Gemm g, const StaticOrder& S, const Epi& E) {
;     ...
;             PG8_WAIT_L(8); PG8_BAR; PG8_WAIT_L(0); PG8_MMA(0, 0, At, B0); PG8_BAR; PG8_SCHED;
;             PG8_LDB(B1, 0, 1); PG8_STAGE(PG8_SB(0, 0), b2, voffB);
;             PG8_BAR; PG8_WAIT_L(0); PG8_MMA(0, 1, At, B1); PG8_BAR;
;             PG8_LDA(At, 0, 1); PG8_STAGE(PG8_SA(0, 0), a2, voffA);
;             PG8_BAR; PG8_WAIT_L(0); PG8_MMA(1, 0, At, B0); PG8_BAR; PG8_SCHED;
;             PG8_STAGE(PG8_SB(0, 1), b2 + hstepB, voffB);
;             PG8_WAIT_V(6); PG8_BAR; PG8_MMA(1, 1, At, B1); PG8_BAR;
;             PG8_LDB(B0, 1, 0); PG8_SCHED; PG8_LDA(At, 1, 0); PG8_STAGE(PG8_SA(0, 1), a2 + hstepA, voffA);
;             PG8_WAIT_L(8); PG8_BAR; PG8_WAIT_L(0); PG8_MMA(0, 0, At, B0); PG8_BAR; PG8_SCHED;
	ds_read_b128 v[144:147], v192 offset:16384
	ds_read_b128 v[148:151], v192 offset:17408
	ds_read_b128 v[170:173], v192 offset:18432
	ds_read_b128 v[174:177], v192 offset:19456
	ds_read_b128 v[178:181], v192 offset:20480
	ds_read_b128 v[182:185], v192 offset:21504
	ds_read_b128 v[196:199], v192 offset:22528
	ds_read_b128 v[200:203], v192 offset:23552
	s_add_i32 s51, s40, s23
	v_lshl_add_u64 v[186:187], s[10:11], 0, v[154:155]
	s_mov_b32 m0, s51
	s_nop 0
	global_load_lds_dwordx4 v[186:187], off
	v_lshl_add_u64 v[220:221], s[10:11], 0, v[158:159]
	s_add_i32 m0, s51, 0x2000
	s_nop 0
	global_load_lds_dwordx4 v[220:221], off
	s_mov_b32 m0, s28
	v_lshl_add_u64 v[222:223], s[12:13], 0, v[152:153]
	global_load_lds_dwordx4 v[222:223], off
	v_lshl_add_u64 v[224:225], s[12:13], 0, v[156:157]
	s_mov_b32 m0, s29
	s_nop 0
	global_load_lds_dwordx4 v[224:225], off
	s_add_u32 s52, s10, 0x160000
	s_addc_u32 s53, s11, 0
	s_add_i32 s51, s41, s23
	v_lshl_add_u64 v[226:227], s[52:53], 0, v[154:155]
	s_mov_b32 m0, s51
	s_nop 0
	global_load_lds_dwordx4 v[226:227], off
	v_lshl_add_u64 v[226:227], s[52:53], 0, v[158:159]
	s_add_i32 m0, s51, 0x2000
	s_nop 0
	global_load_lds_dwordx4 v[226:227], off
	s_waitcnt lgkmcnt(0)
	s_waitcnt vmcnt(8)
	s_barrier
	v_mfma_f32_16x16x32_bf16 v[60:63], v[128:131], v[144:147], v[60:63]
	v_mfma_f32_16x16x32_bf16 v[56:59], v[136:139], v[144:147], v[56:59]
	v_mfma_f32_16x16x32_bf16 v[40:43], v[128:131], v[170:173], v[40:43]
	v_mfma_f32_16x16x32_bf16 v[44:47], v[136:139], v[170:173], v[44:47]
	v_mfma_f32_16x16x32_bf16 v[24:27], v[128:131], v[178:181], v[24:27]
	v_mfma_f32_16x16x32_bf16 v[28:31], v[136:139], v[178:181], v[28:31]
	v_mfma_f32_16x16x32_bf16 v[8:11], v[128:131], v[196:199], v[8:11]
	v_mfma_f32_16x16x32_bf16 v[12:15], v[136:139], v[196:199], v[12:15]
	v_mfma_f32_16x16x32_bf16 v[60:63], v[132:135], v[148:151], v[60:63]
	v_mfma_f32_16x16x32_bf16 v[56:59], v[140:143], v[148:151], v[56:59]
	v_mfma_f32_16x16x32_bf16 v[40:43], v[132:135], v[174:177], v[40:43]
	v_mfma_f32_16x16x32_bf16 v[44:47], v[140:143], v[174:177], v[44:47]
	v_mfma_f32_16x16x32_bf16 v[24:27], v[132:135], v[182:185], v[24:27]
	v_mfma_f32_16x16x32_bf16 v[28:31], v[140:143], v[182:185], v[28:31]
	v_mfma_f32_16x16x32_bf16 v[8:11], v[132:135], v[200:203], v[8:11]
	v_mfma_f32_16x16x32_bf16 v[12:15], v[140:143], v[200:203], v[12:15]
	v_mfma_f32_16x16x32_bf16 v[52:55], v[204:207], v[144:147], v[52:55]
	v_mfma_f32_16x16x32_bf16 v[48:51], v[212:215], v[144:147], v[48:51]
	v_mfma_f32_16x16x32_bf16 v[36:39], v[204:207], v[170:173], v[36:39]
	v_mfma_f32_16x16x32_bf16 v[32:35], v[212:215], v[170:173], v[32:35]
	v_mfma_f32_16x16x32_bf16 v[20:23], v[204:207], v[178:181], v[20:23]
	v_mfma_f32_16x16x32_bf16 v[16:19], v[212:215], v[178:181], v[16:19]
	v_mfma_f32_16x16x32_bf16 v[4:7], v[204:207], v[196:199], v[4:7]
	v_mfma_f32_16x16x32_bf16 v[0:3], v[212:215], v[196:199], v[0:3]
	v_mfma_f32_16x16x32_bf16 v[52:55], v[208:211], v[148:151], v[52:55]
	v_mfma_f32_16x16x32_bf16 v[48:51], v[216:219], v[148:151], v[48:51]
	v_mfma_f32_16x16x32_bf16 v[36:39], v[208:211], v[174:177], v[36:39]
	v_mfma_f32_16x16x32_bf16 v[32:35], v[216:219], v[174:177], v[32:35]
	v_mfma_f32_16x16x32_bf16 v[20:23], v[208:211], v[182:185], v[20:23]
	v_mfma_f32_16x16x32_bf16 v[16:19], v[216:219], v[182:185], v[16:19]
	v_mfma_f32_16x16x32_bf16 v[4:7], v[208:211], v[200:203], v[4:7]
	v_mfma_f32_16x16x32_bf16 v[0:3], v[216:219], v[200:203], v[0:3]
	s_add_i32 s51, 0, 0x18000
	v_add_u32_e32 v140, s51, v189
	s_barrier
	ds_read_b128 v[128:131], v140
	ds_read_b128 v[132:135], v140 offset:1024
	ds_read_b128 v[136:139], v140 offset:2048
	ds_read_b128 v[140:143], v140 offset:3072
	ds_read_b128 v[144:147], v192 offset:32768
	ds_read_b128 v[148:151], v192 offset:33792
	ds_read_b128 v[170:173], v192 offset:34816
	ds_read_b128 v[174:177], v192 offset:35840
	ds_read_b128 v[178:181], v192 offset:36864
	ds_read_b128 v[182:185], v192 offset:37888
	ds_read_b128 v[196:199], v192 offset:38912
	ds_read_b128 v[200:203], v192 offset:39936
	v_add_u32_e32 v195, 0x1c000, v189
	ds_read_b128 v[204:207], v195
	ds_read_b128 v[208:211], v195 offset:1024
	ds_read_b128 v[212:215], v195 offset:2048
	ds_read_b128 v[216:219], v195 offset:3072
	s_add_u32 s12, s12, 0x160000
	s_addc_u32 s13, s13, 0
	s_mov_b32 m0, s30
	v_lshl_add_u64 v[226:227], s[12:13], 0, v[152:153]
	global_load_lds_dwordx4 v[226:227], off
	v_lshl_add_u64 v[226:227], s[12:13], 0, v[156:157]
	s_mov_b32 m0, s31
	s_nop 0
	global_load_lds_dwordx4 v[226:227], off
	s_waitcnt lgkmcnt(0)
	s_waitcnt vmcnt(8)
	s_barrier
; #define PG8_STAGE(bufoff, gbase, voff) do { _Pragma("unroll") for (int _i = 0; _i < 2; ++_i) \
;         __builtin_amdgcn_global_load_lds((const unsigned*)((const char*)(gbase) + (voff)[_i]), (PG8_LAS unsigned*)(lds + (bufoff) + ldsw + _i * 8192), 16, 0, 0); } while (0)
; #define PG8_LDA(dst, b, h) do { _Pragma("unroll") for (int m = 0; m < 4; ++m) _Pragma("unroll") for (int k = 0; k < 2; ++k) dst[m][k] = *(const PG8_LAS bf16x8*)(lds + PG8_SA(b, h) + aoff + m * 2048 + k * 1024); } while (0)
; #define PG8_LDB(dst, b, h) do { _Pragma("unroll") for (int n = 0; n < 2; ++n) _Pragma("unroll") for (int k = 0; k < 2; ++k) dst[n][k] = *(const PG8_LAS bf16x8*)(lds + PG8_SB(b, h) + boff + n * 2048 + k * 1024); } while (0)
; #define PG8_MMA(ai, bj, At, Bt) do { __builtin_amdgcn_s_setprio(1); _Pragma("unroll") for (int m = 0; m < 4; ++m) _Pragma("unroll") for (int n = 0; n < 2; ++n) _Pragma("unroll") for (int k = 0; k < 2; ++k) \
;         acc[ai][bj][m][n] = __builtin_amdgcn_mfma_f32_16x16x32_bf16(Bt[n][k], At[m][k], acc[ai][bj][m][n], 0, 0, 0); __builtin_amdgcn_s_setprio(0); } while (0)
; #define PG8_WAIT_V(n) asm volatile("s_waitcnt vmcnt(" #n ")" ::: "memory")
; #define PG8_WAIT_L(n) asm volatile("s_waitcnt lgkmcnt(" #n ")" ::: "memory")
; #define PG8_BAR __builtin_amdgcn_s_barrier()
; #define PG8_SCHED __builtin_amdgcn_sched_barrier(0)
; template <class Epi>
; __device__ __forceinline__ void gemm_phase(PG8_LAS unsigned char* lds, const Gemm g, const StaticOrder& S, const Epi& E) {
;     ...
;             PG8_WAIT_L(8); PG8_BAR; PG8_WAIT_L(0); PG8_MMA(0, 0, At, B0); PG8_BAR; PG8_SCHED;
;             PG8_LDB(B1, 1, 1); PG8_STAGE(PG8_SB(1, 0), b3, voffB);
;             PG8_BAR; PG8_WAIT_L(0); PG8_MMA(0, 1, At, B1); PG8_BAR;
;             PG8_LDA(At, 1, 1); PG8_STAGE(PG8_SA(1, 0), a3, voffA);
;             PG8_BAR; PG8_WAIT_L(0); PG8_MMA(1, 0, At, B0); PG8_BAR; PG8_SCHED;
;             PG8_STAGE(PG8_SB(1, 1), b3 + hstepB, voffB);
;             PG8_WAIT_V(6); PG8_BAR; PG8_MMA(1, 1, At, B1); PG8_BAR;
	v_mfma_f32_16x16x32_bf16 v[124:127], v[128:131], v[144:147], v[124:127]
	v_mfma_f32_16x16x32_bf16 v[120:123], v[136:139], v[144:147], v[120:123]
	v_mfma_f32_16x16x32_bf16 v[104:107], v[128:131], v[170:173], v[104:107]
	v_mfma_f32_16x16x32_bf16 v[108:111], v[136:139], v[170:173], v[108:111]
	v_mfma_f32_16x16x32_bf16 v[88:91], v[128:131], v[178:181], v[88:91]
	v_mfma_f32_16x16x32_bf16 v[92:95], v[136:139], v[178:181], v[92:95]
	v_mfma_f32_16x16x32_bf16 v[72:75], v[128:131], v[196:199], v[72:75]
	v_mfma_f32_16x16x32_bf16 v[76:79], v[136:139], v[196:199], v[76:79]
	v_mfma_f32_16x16x32_bf16 v[124:127], v[132:135], v[148:151], v[124:127]
	v_mfma_f32_16x16x32_bf16 v[120:123], v[140:143], v[148:151], v[120:123]
	v_mfma_f32_16x16x32_bf16 v[104:107], v[132:135], v[174:177], v[104:107]
	v_mfma_f32_16x16x32_bf16 v[108:111], v[140:143], v[174:177], v[108:111]
	v_mfma_f32_16x16x32_bf16 v[88:91], v[132:135], v[182:185], v[88:91]
	v_mfma_f32_16x16x32_bf16 v[92:95], v[140:143], v[182:185], v[92:95]
	v_mfma_f32_16x16x32_bf16 v[72:75], v[132:135], v[200:203], v[72:75]
	v_mfma_f32_16x16x32_bf16 v[76:79], v[140:143], v[200:203], v[76:79]
	v_mfma_f32_16x16x32_bf16 v[116:119], v[204:207], v[144:147], v[116:119]
	v_mfma_f32_16x16x32_bf16 v[112:115], v[212:215], v[144:147], v[112:115]
	v_mfma_f32_16x16x32_bf16 v[100:103], v[204:207], v[170:173], v[100:103]
	v_mfma_f32_16x16x32_bf16 v[96:99], v[212:215], v[170:173], v[96:99]
	v_mfma_f32_16x16x32_bf16 v[84:87], v[204:207], v[178:181], v[84:87]
	v_mfma_f32_16x16x32_bf16 v[80:83], v[212:215], v[178:181], v[80:83]
	v_mfma_f32_16x16x32_bf16 v[68:71], v[204:207], v[196:199], v[68:71]
	v_mfma_f32_16x16x32_bf16 v[64:67], v[212:215], v[196:199], v[64:67]
	v_mfma_f32_16x16x32_bf16 v[116:119], v[208:211], v[148:151], v[116:119]
	v_mfma_f32_16x16x32_bf16 v[112:115], v[216:219], v[148:151], v[112:115]
	v_mfma_f32_16x16x32_bf16 v[100:103], v[208:211], v[174:177], v[100:103]
	v_mfma_f32_16x16x32_bf16 v[96:99], v[216:219], v[174:177], v[96:99]
	v_mfma_f32_16x16x32_bf16 v[84:87], v[208:211], v[182:185], v[84:87]
	v_mfma_f32_16x16x32_bf16 v[80:83], v[216:219], v[182:185], v[80:83]
	v_mfma_f32_16x16x32_bf16 v[68:71], v[208:211], v[200:203], v[68:71]
	v_mfma_f32_16x16x32_bf16 v[64:67], v[216:219], v[200:203], v[64:67]
	s_barrier
	ds_read_b128 v[144:147], v192 offset:49152
	ds_read_b128 v[148:151], v192 offset:50176
	ds_read_b128 v[170:173], v192 offset:51200
	ds_read_b128 v[174:177], v192 offset:52224
	ds_read_b128 v[178:181], v192 offset:53248
	ds_read_b128 v[182:185], v192 offset:54272
	ds_read_b128 v[196:199], v192 offset:55296
	ds_read_b128 v[200:203], v192 offset:56320
	s_add_i32 s12, 0, 0x1c000
	s_add_i32 s13, s51, s23
	v_lshl_add_u64 v[186:187], v[186:187], 0, s[18:19]
	s_mov_b32 m0, s13
	s_nop 0
	global_load_lds_dwordx4 v[186:187], off
	v_lshl_add_u64 v[186:187], v[220:221], 0, s[18:19]
	s_add_i32 m0, s13, 0x2000
	s_nop 0
	global_load_lds_dwordx4 v[186:187], off
	s_mov_b32 m0, s35
	v_lshl_add_u64 v[186:187], v[222:223], 0, s[18:19]
	global_load_lds_dwordx4 v[186:187], off
	v_lshl_add_u64 v[186:187], v[224:225], 0, s[18:19]
	s_mov_b32 m0, s36
	s_nop 0
	global_load_lds_dwordx4 v[186:187], off
	s_add_u32 s10, s10, 0x160080
	s_addc_u32 s11, s11, 0
	s_add_i32 s12, s12, s23
	v_lshl_add_u64 v[226:227], s[10:11], 0, v[154:155]
	s_mov_b32 m0, s12
	s_nop 0
	global_load_lds_dwordx4 v[226:227], off
	v_lshl_add_u64 v[226:227], s[10:11], 0, v[158:159]
	s_add_i32 m0, s12, 0x2000
	s_nop 0
	global_load_lds_dwordx4 v[226:227], off
	s_waitcnt lgkmcnt(0)
	s_waitcnt vmcnt(8)
	s_barrier
	v_mfma_f32_16x16x32_bf16 v[60:63], v[128:131], v[144:147], v[60:63]
	v_mfma_f32_16x16x32_bf16 v[56:59], v[136:139], v[144:147], v[56:59]
	v_mfma_f32_16x16x32_bf16 v[40:43], v[128:131], v[170:173], v[40:43]
	v_mfma_f32_16x16x32_bf16 v[44:47], v[136:139], v[170:173], v[44:47]
	v_mfma_f32_16x16x32_bf16 v[24:27], v[128:131], v[178:181], v[24:27]
	v_mfma_f32_16x16x32_bf16 v[28:31], v[136:139], v[178:181], v[28:31]
	v_mfma_f32_16x16x32_bf16 v[8:11], v[128:131], v[196:199], v[8:11]
	v_mfma_f32_16x16x32_bf16 v[12:15], v[136:139], v[196:199], v[12:15]
	v_mfma_f32_16x16x32_bf16 v[60:63], v[132:135], v[148:151], v[60:63]
	v_mfma_f32_16x16x32_bf16 v[56:59], v[140:143], v[148:151], v[56:59]
	v_mfma_f32_16x16x32_bf16 v[40:43], v[132:135], v[174:177], v[40:43]
	v_mfma_f32_16x16x32_bf16 v[44:47], v[140:143], v[174:177], v[44:47]
	v_mfma_f32_16x16x32_bf16 v[24:27], v[132:135], v[182:185], v[24:27]
	v_mfma_f32_16x16x32_bf16 v[28:31], v[140:143], v[182:185], v[28:31]
	v_mfma_f32_16x16x32_bf16 v[8:11], v[132:135], v[200:203], v[8:11]
	v_mfma_f32_16x16x32_bf16 v[12:15], v[140:143], v[200:203], v[12:15]
	v_mfma_f32_16x16x32_bf16 v[52:55], v[204:207], v[144:147], v[52:55]
	v_mfma_f32_16x16x32_bf16 v[48:51], v[212:215], v[144:147], v[48:51]
	v_mfma_f32_16x16x32_bf16 v[36:39], v[204:207], v[170:173], v[36:39]
	v_mfma_f32_16x16x32_bf16 v[32:35], v[212:215], v[170:173], v[32:35]
	v_mfma_f32_16x16x32_bf16 v[20:23], v[204:207], v[178:181], v[20:23]
	v_mfma_f32_16x16x32_bf16 v[16:19], v[212:215], v[178:181], v[16:19]
	v_mfma_f32_16x16x32_bf16 v[4:7], v[204:207], v[196:199], v[4:7]
	v_mfma_f32_16x16x32_bf16 v[0:3], v[212:215], v[196:199], v[0:3]
	v_mfma_f32_16x16x32_bf16 v[52:55], v[208:211], v[148:151], v[52:55]
	v_mfma_f32_16x16x32_bf16 v[48:51], v[216:219], v[148:151], v[48:51]
	v_mfma_f32_16x16x32_bf16 v[36:39], v[208:211], v[174:177], v[36:39]
	v_mfma_f32_16x16x32_bf16 v[32:35], v[216:219], v[174:177], v[32:35]
	v_mfma_f32_16x16x32_bf16 v[20:23], v[208:211], v[182:185], v[20:23]
	v_mfma_f32_16x16x32_bf16 v[16:19], v[216:219], v[182:185], v[16:19]
	v_mfma_f32_16x16x32_bf16 v[4:7], v[208:211], v[200:203], v[4:7]
	v_mfma_f32_16x16x32_bf16 v[0:3], v[216:219], v[200:203], v[0:3]
	s_add_i32 s50, s50, 2
	s_add_u32 s20, s20, 0x100
	s_addc_u32 s21, s21, 0
	s_add_u32 s48, s48, 0x100
	s_addc_u32 s49, s49, 0
	s_cmpk_gt_u32 s50, 0x55
	s_barrier
; __device__ __forceinline__ u32x4 pack8(const float (&f)[8]) { u32x4 w; w.x = cvt_pk_bf16(f[0], f[1]); w.y = cvt_pk_bf16(f[2], f[3]); w.z = cvt_pk_bf16(f[4], f[5]); w.w = cvt_pk_bf16(f[6], f[7]); return w; }
;     __device__ __forceinline__ void operator()(const f32x4 (&acc)[2][2][4][2], const pg8::Unit& u, int wr, int wc, int fr, int fq) const {
;         const int row0 = u.pm * 256 + wr * 64 + fr, col0 = u.pn * 256 + wc * 32 + 8 * fq;
; #pragma unroll
;         for (int ai = 0; ai < 2; ++ai) {
;             u32x4 rb[4][2];
; #pragma unroll
;             for (int m = 0; m < 4; ++m)
; #pragma unroll
;                 for (int bj = 0; bj < 2; ++bj) rb[m][bj] = *(const u32x4*)(resb + (size_t)(row0 + ai * 128 + m * 16) * DM + col0 + bj * 128);
; #pragma unroll
;             for (int m = 0; m < 4; ++m) {
;                 const int r = row0 + ai * 128 + m * 16; float ss = 0.f;
; #pragma unroll
;                 for (int bj = 0; bj < 2; ++bj) {
;                     const size_t off = (size_t)r * DM + col0 + bj * 128;
;                     float rv[8], o[8]; unpack8(rb[m][bj], rv);
; #pragma unroll
;                     for (int n = 0; n < 2; ++n)
; #pragma unroll
;                         for (int i = 0; i < 4; ++i) o[n * 4 + i] = rv[n * 4 + i] + coef * acc[ai][bj][m][n][i];
;                     if (outf) { *(f32x4*)(outf + off) = (f32x4){o[0], o[1], o[2], o[3]}; *(f32x4*)(outf + off + 4) = (f32x4){o[4], o[5], o[6], o[7]}; }
;                     if (hb) { *(u32x4*)(hb + off) = pack8(o);
; #pragma unroll
;                         for (int i = 0; i < 8; ++i) ss += o[i] * o[i]; }
;                 }
;                 if (hb) { ss += __shfl_xor(ss, 16); ss += __shfl_xor(ss, 32); if (fq == 0) part[(size_t)r * 32 + u.pn * 4 + wc] = ss; }
	s_cbranch_scc0 .LBB0_317
	s_setprio 0
	v_lshl_or_b32 v170, s16, 8, v190
	v_lshl_add_u32 v172, s47, 8, v188
	v_ashrrev_i32_e32 v171, 31, v170
	v_lshlrev_b64 v[204:205], 1, v[170:171]
	v_ashrrev_i32_e32 v173, 31, v172
	v_lshl_add_u64 v[174:175], s[76:77], 0, v[204:205]
	v_lshlrev_b64 v[206:207], 12, v[172:173]
	v_lshl_add_u64 v[128:129], v[174:175], 0, v[206:207]
	global_load_dwordx4 v[196:199], v[128:129], off
	global_load_dwordx4 v[200:203], v[128:129], off offset:256
	v_or_b32_e32 v184, 16, v172
	v_or_b32_e32 v180, 32, v172
	v_or_b32_e32 v176, 48, v172
	v_ashrrev_i32_e32 v185, 31, v184
	v_ashrrev_i32_e32 v181, 31, v180
	v_ashrrev_i32_e32 v177, 31, v176
	v_lshlrev_b64 v[186:187], 12, v[184:185]
	v_lshlrev_b64 v[182:183], 12, v[180:181]
	v_lshlrev_b64 v[178:179], 12, v[176:177]
	v_lshl_add_u64 v[128:129], v[174:175], 0, v[186:187]
	v_lshl_add_u64 v[130:131], v[174:175], 0, v[182:183]
	v_lshl_add_u64 v[208:209], v[174:175], 0, v[178:179]
	global_load_dwordx4 v[148:151], v[128:129], off
	global_load_dwordx4 v[144:147], v[128:129], off offset:256
	global_load_dwordx4 v[140:143], v[130:131], off
	global_load_dwordx4 v[136:139], v[130:131], off offset:256
	global_load_dwordx4 v[132:135], v[208:209], off
	s_nop 0
	global_load_dwordx4 v[128:131], v[208:209], off offset:256
	v_lshl_add_u64 v[206:207], s[76:77], 0, v[206:207]
	v_and_b32_e32 v208, 64, v194
	v_lshl_add_u64 v[204:205], v[206:207], 0, v[204:205]
	v_xor_b32_e32 v195, 16, v194
	v_add_u32_e32 v208, 64, v208
	v_xor_b32_e32 v209, 32, v194
	v_cmp_lt_i32_e32 vcc, v195, v208
	s_lshl_b32 s20, s16, 2
	s_ashr_i32 s21, s20, 31
	v_cndmask_b32_e32 v195, v194, v195, vcc
	v_cmp_lt_i32_e32 vcc, v209, v208
	v_lshlrev_b32_e32 v195, 2, v195
	s_waitcnt vmcnt(0)
	v_lshlrev_b32_e32 v206, 16, v196
	v_and_b32_e32 v196, 0xffff0000, v196
	v_lshlrev_b32_e32 v211, 16, v200
	v_and_b32_e32 v200, 0xffff0000, v200
	v_fmac_f32_e32 v196, 0.5, v125
	v_lshlrev_b32_e32 v207, 16, v197
	v_fmac_f32_e32 v206, 0.5, v124
	v_fmac_f32_e32 v200, 0.5, v117
	v_mul_f32_e32 v117, v196, v196
	v_and_b32_e32 v197, 0xffff0000, v197
	v_fmac_f32_e32 v207, 0.5, v126
	v_fmac_f32_e32 v117, v206, v206
	v_cndmask_b32_e32 v208, v194, v209, vcc
	v_lshlrev_b32_e32 v209, 16, v198
	v_fmac_f32_e32 v197, 0.5, v127
	v_fmac_f32_e32 v117, v207, v207
	v_and_b32_e32 v198, 0xffff0000, v198
	v_fmac_f32_e32 v209, 0.5, v120
	v_fmac_f32_e32 v117, v197, v197
	v_lshlrev_b32_e32 v210, 16, v199
	v_fmac_f32_e32 v198, 0.5, v121
	v_fmac_f32_e32 v117, v209, v209
	v_and_b32_e32 v199, 0xffff0000, v199
	v_fmac_f32_e32 v210, 0.5, v122
	v_fmac_f32_e32 v117, v198, v198
	v_fmac_f32_e32 v199, 0.5, v123
	v_fmac_f32_e32 v117, v210, v210
	v_fmac_f32_e32 v211, 0.5, v116
	v_fmac_f32_e32 v117, v199, v199
	v_lshlrev_b32_e32 v212, 16, v201
	v_fmac_f32_e32 v117, v211, v211
	v_and_b32_e32 v201, 0xffff0000, v201
	v_fmac_f32_e32 v212, 0.5, v118
	v_fmac_f32_e32 v117, v200, v200
	v_lshlrev_b32_e32 v213, 16, v202
	v_fmac_f32_e32 v201, 0.5, v119
	v_fmac_f32_e32 v117, v212, v212
	v_and_b32_e32 v202, 0xffff0000, v202
	v_fmac_f32_e32 v213, 0.5, v112
	v_fmac_f32_e32 v117, v201, v201
	v_lshlrev_b32_e32 v214, 16, v203
	v_fmac_f32_e32 v202, 0.5, v113
	v_fmac_f32_e32 v117, v213, v213
	v_and_b32_e32 v203, 0xffff0000, v203
	v_fmac_f32_e32 v214, 0.5, v114
	v_fmac_f32_e32 v117, v202, v202
	v_fmac_f32_e32 v203, 0.5, v115
	v_fmac_f32_e32 v117, v214, v214
	v_fmac_f32_e32 v117, v203, v203
	ds_bpermute_b32 v118, v195, v117
	v_cvt_pk_bf16_f32 v112, v206, v196
	v_cvt_pk_bf16_f32 v113, v207, v197
	v_cvt_pk_bf16_f32 v114, v209, v198
	v_cvt_pk_bf16_f32 v115, v210, v199
	global_store_dwordx4 v[204:205], v[112:115], off
	v_cvt_pk_bf16_f32 v116, v211, v200
	s_waitcnt lgkmcnt(0)
	s_nop 0
	v_add_f32_e32 v113, v117, v118
	v_lshlrev_b32_e32 v112, 2, v208
	ds_bpermute_b32 v114, v112, v113
	v_cvt_pk_bf16_f32 v117, v212, v201
	v_cvt_pk_bf16_f32 v118, v213, v202
	v_cvt_pk_bf16_f32 v119, v214, v203
	global_store_dwordx4 v[204:205], v[116:119], off offset:256
	s_and_saveexec_b64 s[10:11], s[2:3]
	s_cbranch_execz .LBB0_320
	v_lshlrev_b64 v[116:117], 7, v[172:173]
	v_lshl_add_u64 v[116:117], s[8:9], 0, v[116:117]
	v_lshl_add_u64 v[116:117], s[20:21], 2, v[116:117]
	s_lshl_b32 s16, s34, 2
	v_lshl_add_u64 v[116:117], v[116:117], 0, s[16:17]
	s_waitcnt lgkmcnt(0)
	v_add_f32_e32 v113, v113, v114
	global_store_dword v[116:117], v113, off

; #define PG8_STAGE(bufoff, gbase, voff) do { _Pragma("unroll") for (int _i = 0; _i < 2; ++_i) \
;         __builtin_amdgcn_global_load_lds((const unsigned*)((const char*)(gbase) + (voff)[_i]), (PG8_LAS unsigned*)(lds + (bufoff) + ldsw + _i * 8192), 16, 0, 0); } while (0)
; #define PG8_LDA(dst, b, h) do { _Pragma("unroll") for (int m = 0; m < 4; ++m) _Pragma("unroll") for (int k = 0; k < 2; ++k) dst[m][k] = *(const PG8_LAS bf16x8*)(lds + PG8_SA(b, h) + aoff + m * 2048 + k * 1024); } while (0)
; #define PG8_LDB(dst, b, h) do { _Pragma("unroll") for (int n = 0; n < 2; ++n) _Pragma("unroll") for (int k = 0; k < 2; ++k) dst[n][k] = *(const PG8_LAS bf16x8*)(lds + PG8_SB(b, h) + boff + n * 2048 + k * 1024); } while (0)
; #define PG8_MMA(ai, bj, At, Bt) do { __builtin_amdgcn_s_setprio(1); _Pragma("unroll") for (int m = 0; m < 4; ++m) _Pragma("unroll") for (int n = 0; n < 2; ++n) _Pragma("unroll") for (int k = 0; k < 2; ++k) \
;         acc[ai][bj][m][n] = __builtin_amdgcn_mfma_f32_16x16x32_bf16(Bt[n][k], At[m][k], acc[ai][bj][m][n], 0, 0, 0); __builtin_amdgcn_s_setprio(0); } while (0)
; #define PG8_WAIT_L(n) asm volatile("s_waitcnt lgkmcnt(" #n ")" ::: "memory")
; template <class Epi>
; __device__ __forceinline__ void gemm_phase(PG8_LAS unsigned char* lds, const Gemm g, const StaticOrder& S, const Epi& E) {
;     ...
;         const bool has_next = S.next(ui + 1, nxt);
;         const char* nA = has_next ? (const char*)g.A + (size_t)nxt.pm * tstepA : cA; const char* nB = has_next ? (const char*)g.Bt + (size_t)nxt.pn * tstepB : cB;
;         for (int t = 0; t < nt; t += 2) {
;             const bool last = (t == nt - 2);
;             const char* a1 = cA + (size_t)(t + 1) * kstep;
;             const char* a2 = last ? nA : cA + (size_t)(t + 2) * kstep; const char* b2 = last ? nB : cB + (size_t)(t + 2) * kstep;
;             const char* a3 = a2 + kstep; const char* b3 = b2 + kstep;
;             PG8_LDB(B0, 0, 0); PG8_SCHED; PG8_LDA(At, 0, 0); PG8_STAGE(PG8_SA(1, 1), a1 + hstepA, voffA);
;             PG8_WAIT_L(8); PG8_BAR; PG8_WAIT_L(0); PG8_MMA(0, 0, At, B0); PG8_BAR; PG8_SCHED;
;     ...
; #pragma unroll
;         for (int a = 0; a < 2; ++a)
; #pragma unroll
;             for (int b = 0; b < 2; ++b)
; #pragma unroll
;                 for (int m = 0; m < 4; ++m)
; #pragma unroll
;                     for (int n = 0; n < 2; ++n) acc[a][b][m][n] = (f32x4){0.f, 0.f, 0.f, 0.f};
.LBB0_412:
	s_ashr_i32 s57, s56, 31
	v_cmp_lt_i64_e32 vcc, s[6:7], v[144:145]
	s_lshl_b64 s[6:7], s[56:57], 20
	s_add_u32 s58, s76, s6
	s_addc_u32 s59, s77, s7
	s_and_b64 s[6:7], vcc, exec
	s_cselect_b32 s53, s59, s1
	s_cselect_b32 s57, s58, s0
	s_ashr_i32 s55, s54, 31
	s_lshl_b64 s[6:7], s[54:55], 20
	v_readlane_b32 s48, v253, 34
	v_readlane_b32 s49, v253, 35
	s_add_u32 s60, s48, s6
	s_addc_u32 s61, s49, s7
	s_and_b64 s[6:7], vcc, exec
	s_cselect_b32 s55, s61, s5
	s_cselect_b32 s63, s60, s4
	s_add_u32 s0, s0, 0x80080
	s_addc_u32 s1, s1, 0
	s_add_u32 s65, s4, 0x100
	v_mov_b32_e32 v0, 0
	s_addc_u32 s66, s5, 0
	s_mov_b32 s67, -2
	v_mov_b32_e32 v1, v0
	v_mov_b32_e32 v2, v0
	v_mov_b32_e32 v3, v0
	v_mov_b32_e32 v4, v0
	v_mov_b32_e32 v5, v0
	v_mov_b32_e32 v6, v0
	v_mov_b32_e32 v7, v0
	v_mov_b32_e32 v16, v0
	v_mov_b32_e32 v17, v0
	v_mov_b32_e32 v18, v0
	v_mov_b32_e32 v19, v0
	v_mov_b32_e32 v20, v0
	v_mov_b32_e32 v21, v0
	v_mov_b32_e32 v22, v0
	v_mov_b32_e32 v23, v0
	v_mov_b32_e32 v32, v0
	v_mov_b32_e32 v33, v0
	v_mov_b32_e32 v34, v0
	v_mov_b32_e32 v35, v0
	v_mov_b32_e32 v36, v0
	v_mov_b32_e32 v37, v0
	v_mov_b32_e32 v38, v0
	v_mov_b32_e32 v39, v0
	v_mov_b32_e32 v48, v0
	v_mov_b32_e32 v49, v0
	v_mov_b32_e32 v50, v0
	v_mov_b32_e32 v51, v0
	v_mov_b32_e32 v52, v0
	v_mov_b32_e32 v53, v0
	v_mov_b32_e32 v54, v0
	v_mov_b32_e32 v55, v0
	v_mov_b32_e32 v8, v0
	v_mov_b32_e32 v9, v0
	v_mov_b32_e32 v10, v0
	v_mov_b32_e32 v11, v0
	v_mov_b32_e32 v12, v0
	v_mov_b32_e32 v13, v0
	v_mov_b32_e32 v14, v0
	v_mov_b32_e32 v15, v0
	v_mov_b32_e32 v24, v0
	v_mov_b32_e32 v25, v0
	v_mov_b32_e32 v26, v0
	v_mov_b32_e32 v27, v0
	v_mov_b32_e32 v28, v0
	v_mov_b32_e32 v29, v0
	v_mov_b32_e32 v30, v0
	v_mov_b32_e32 v31, v0
	v_mov_b32_e32 v40, v0
	v_mov_b32_e32 v41, v0
	v_mov_b32_e32 v42, v0
	v_mov_b32_e32 v43, v0
	v_mov_b32_e32 v44, v0
	v_mov_b32_e32 v45, v0
	v_mov_b32_e32 v46, v0
	v_mov_b32_e32 v47, v0
	v_mov_b32_e32 v56, v0
	v_mov_b32_e32 v57, v0
	v_mov_b32_e32 v58, v0
	v_mov_b32_e32 v59, v0
	v_mov_b32_e32 v60, v0
	v_mov_b32_e32 v61, v0
	v_mov_b32_e32 v62, v0
	v_mov_b32_e32 v63, v0
	v_mov_b32_e32 v64, v0
	v_mov_b32_e32 v65, v0
	v_mov_b32_e32 v66, v0
	v_mov_b32_e32 v67, v0
	v_mov_b32_e32 v68, v0
	v_mov_b32_e32 v69, v0
	v_mov_b32_e32 v70, v0
	v_mov_b32_e32 v71, v0
	v_mov_b32_e32 v80, v0
	v_mov_b32_e32 v81, v0
	v_mov_b32_e32 v82, v0
	v_mov_b32_e32 v83, v0
	v_mov_b32_e32 v84, v0
	v_mov_b32_e32 v85, v0
	v_mov_b32_e32 v86, v0
	v_mov_b32_e32 v87, v0
	v_mov_b32_e32 v96, v0
	v_mov_b32_e32 v97, v0
	v_mov_b32_e32 v98, v0
	v_mov_b32_e32 v99, v0
	v_mov_b32_e32 v100, v0
	v_mov_b32_e32 v101, v0
	v_mov_b32_e32 v102, v0
	v_mov_b32_e32 v103, v0
	v_mov_b32_e32 v112, v0
	v_mov_b32_e32 v113, v0
	v_mov_b32_e32 v114, v0
	v_mov_b32_e32 v115, v0
	v_mov_b32_e32 v116, v0
	v_mov_b32_e32 v117, v0
	v_mov_b32_e32 v118, v0
	v_mov_b32_e32 v119, v0
	v_mov_b32_e32 v72, v0
	v_mov_b32_e32 v73, v0
	v_mov_b32_e32 v74, v0
	v_mov_b32_e32 v75, v0
	v_mov_b32_e32 v76, v0
	v_mov_b32_e32 v77, v0
	v_mov_b32_e32 v78, v0
	v_mov_b32_e32 v79, v0
	v_mov_b32_e32 v88, v0
	v_mov_b32_e32 v89, v0
	v_mov_b32_e32 v90, v0
	v_mov_b32_e32 v91, v0
	v_mov_b32_e32 v92, v0
	v_mov_b32_e32 v93, v0
	v_mov_b32_e32 v94, v0
	v_mov_b32_e32 v95, v0
	v_mov_b32_e32 v104, v0
	v_mov_b32_e32 v105, v0
	v_mov_b32_e32 v106, v0
	v_mov_b32_e32 v107, v0
	v_mov_b32_e32 v108, v0
	v_mov_b32_e32 v109, v0
	v_mov_b32_e32 v110, v0
	v_mov_b32_e32 v111, v0
	v_mov_b32_e32 v120, v0
	v_mov_b32_e32 v121, v0
	v_mov_b32_e32 v122, v0
	v_mov_b32_e32 v123, v0
	v_mov_b32_e32 v124, v0
	v_mov_b32_e32 v125, v0
	v_mov_b32_e32 v126, v0
	v_mov_b32_e32 v127, v0
	s_cmp_eq_u32 s101, 1
	s_cbranch_scc0 .Lsp_2
	s_setprio 1
.Lsp_2:
.LBB0_413:
	ds_read_b128 v[148:151], v166
	ds_read_b128 v[152:155], v166 offset:1024
	ds_read_b128 v[156:159], v166 offset:2048
	ds_read_b128 v[172:175], v166 offset:3072
	ds_read_b128 v[176:179], v167
	ds_read_b128 v[180:183], v167 offset:1024
	ds_read_b128 v[184:187], v167 offset:2048
	ds_read_b128 v[188:191], v167 offset:3072
	ds_read_b128 v[192:195], v167 offset:4096
	ds_read_b128 v[196:199], v167 offset:5120
	ds_read_b128 v[200:203], v167 offset:6144
	ds_read_b128 v[204:207], v167 offset:7168
	ds_read_b128 v[208:211], v169
	ds_read_b128 v[212:215], v169 offset:1024
	ds_read_b128 v[216:219], v169 offset:2048
	ds_read_b128 v[220:223], v169 offset:3072
	s_add_u32 s4, s0, 0xfff80080
	s_addc_u32 s5, s1, -1
	s_cmp_eq_u32 s67, 28
	s_cselect_b32 s7, s53, s5
	s_cselect_b32 s6, s57, s4
	s_cselect_b32 s5, s55, s66
	s_cselect_b32 s4, s63, s65
	v_lshl_add_u64 v[160:161], s[0:1], 0, v[140:141]
	s_add_i32 m0, s11, 0xc000
	s_nop 0
	global_load_lds_dwordx4 v[160:161], off
	v_lshl_add_u64 v[160:161], s[0:1], 0, v[142:143]
	s_add_i32 m0, s11, 0xe000
	s_nop 0
	global_load_lds_dwordx4 v[160:161], off
	s_waitcnt lgkmcnt(0)
	s_waitcnt vmcnt(8)
	s_barrier
; #define PG8_STAGE(bufoff, gbase, voff) do { _Pragma("unroll") for (int _i = 0; _i < 2; ++_i) \
;         __builtin_amdgcn_global_load_lds((const unsigned*)((const char*)(gbase) + (voff)[_i]), (PG8_LAS unsigned*)(lds + (bufoff) + ldsw + _i * 8192), 16, 0, 0); } while (0)
; #define PG8_LDA(dst, b, h) do { _Pragma("unroll") for (int m = 0; m < 4; ++m) _Pragma("unroll") for (int k = 0; k < 2; ++k) dst[m][k] = *(const PG8_LAS bf16x8*)(lds + PG8_SA(b, h) + aoff + m * 2048 + k * 1024); } while (0)
; #define PG8_LDB(dst, b, h) do { _Pragma("unroll") for (int n = 0; n < 2; ++n) _Pragma("unroll") for (int k = 0; k < 2; ++k) dst[n][k] = *(const PG8_LAS bf16x8*)(lds + PG8_SB(b, h) + boff + n * 2048 + k * 1024); } while (0)
; #define PG8_MMA(ai, bj, At, Bt) do { __builtin_amdgcn_s_setprio(1); _Pragma("unroll") for (int m = 0; m < 4; ++m) _Pragma("unroll") for (int n = 0; n < 2; ++n) _Pragma("unroll") for (int k = 0; k < 2; ++k) \
;         acc[ai][bj][m][n] = __builtin_amdgcn_mfma_f32_16x16x32_bf16(Bt[n][k], At[m][k], acc[ai][bj][m][n], 0, 0, 0); __builtin_amdgcn_s_setprio(0); } while (0)
; #define PG8_WAIT_V(n) asm volatile("s_waitcnt vmcnt(" #n ")" ::: "memory")
; #define PG8_WAIT_L(n) asm volatile("s_waitcnt lgkmcnt(" #n ")" ::: "memory")
; #define PG8_BAR __builtin_amdgcn_s_barrier()
; #define PG8_SCHED __builtin_amdgcn_sched_barrier(0)
; template <class Epi>
; __device__ __forceinline__ void gemm_phase(PG8_LAS unsigned char* lds, const Gemm g, const StaticOrder& S, const Epi& E) {
;     ...
;             PG8_WAIT_L(8); PG8_BAR; PG8_WAIT_L(0); PG8_MMA(0, 0, At, B0); PG8_BAR; PG8_SCHED;
;             PG8_LDB(B1, 0, 1); PG8_STAGE(PG8_SB(0, 0), b2, voffB);
;             PG8_BAR; PG8_WAIT_L(0); PG8_MMA(0, 1, At, B1); PG8_BAR;
;             PG8_LDA(At, 0, 1); PG8_STAGE(PG8_SA(0, 0), a2, voffA);
;             PG8_BAR; PG8_WAIT_L(0); PG8_MMA(1, 0, At, B0); PG8_BAR; PG8_SCHED;
;             PG8_STAGE(PG8_SB(0, 1), b2 + hstepB, voffB);
;             PG8_WAIT_V(6); PG8_BAR; PG8_MMA(1, 1, At, B1); PG8_BAR;
	v_mfma_f32_16x16x32_bf16 v[124:127], v[148:151], v[176:179], v[124:127]
	v_mfma_f32_16x16x32_bf16 v[120:123], v[156:159], v[176:179], v[120:123]
	v_mfma_f32_16x16x32_bf16 v[108:111], v[148:151], v[184:187], v[108:111]
	v_mfma_f32_16x16x32_bf16 v[104:107], v[156:159], v[184:187], v[104:107]
	v_mfma_f32_16x16x32_bf16 v[92:95], v[148:151], v[192:195], v[92:95]
	v_mfma_f32_16x16x32_bf16 v[88:91], v[156:159], v[192:195], v[88:91]
	v_mfma_f32_16x16x32_bf16 v[76:79], v[148:151], v[200:203], v[76:79]
	v_mfma_f32_16x16x32_bf16 v[72:75], v[156:159], v[200:203], v[72:75]
	v_mfma_f32_16x16x32_bf16 v[124:127], v[152:155], v[180:183], v[124:127]
	v_mfma_f32_16x16x32_bf16 v[120:123], v[172:175], v[180:183], v[120:123]
	v_mfma_f32_16x16x32_bf16 v[108:111], v[152:155], v[188:191], v[108:111]
	v_mfma_f32_16x16x32_bf16 v[104:107], v[172:175], v[188:191], v[104:107]
	v_mfma_f32_16x16x32_bf16 v[92:95], v[152:155], v[196:199], v[92:95]
	v_mfma_f32_16x16x32_bf16 v[88:91], v[172:175], v[196:199], v[88:91]
	v_mfma_f32_16x16x32_bf16 v[76:79], v[152:155], v[204:207], v[76:79]
	v_mfma_f32_16x16x32_bf16 v[72:75], v[172:175], v[204:207], v[72:75]
	v_mfma_f32_16x16x32_bf16 v[116:119], v[208:211], v[176:179], v[116:119]
	v_mfma_f32_16x16x32_bf16 v[112:115], v[216:219], v[176:179], v[112:115]
	v_mfma_f32_16x16x32_bf16 v[100:103], v[208:211], v[184:187], v[100:103]
	v_mfma_f32_16x16x32_bf16 v[96:99], v[216:219], v[184:187], v[96:99]
	v_mfma_f32_16x16x32_bf16 v[84:87], v[208:211], v[192:195], v[84:87]
	v_mfma_f32_16x16x32_bf16 v[80:83], v[216:219], v[192:195], v[80:83]
	v_mfma_f32_16x16x32_bf16 v[68:71], v[208:211], v[200:203], v[68:71]
	v_mfma_f32_16x16x32_bf16 v[64:67], v[216:219], v[200:203], v[64:67]
	v_mfma_f32_16x16x32_bf16 v[116:119], v[212:215], v[180:183], v[116:119]
	v_mfma_f32_16x16x32_bf16 v[112:115], v[220:223], v[180:183], v[112:115]
	v_mfma_f32_16x16x32_bf16 v[100:103], v[212:215], v[188:191], v[100:103]
	v_mfma_f32_16x16x32_bf16 v[96:99], v[220:223], v[188:191], v[96:99]
	v_mfma_f32_16x16x32_bf16 v[84:87], v[212:215], v[196:199], v[84:87]
	v_mfma_f32_16x16x32_bf16 v[80:83], v[220:223], v[196:199], v[80:83]
	v_mfma_f32_16x16x32_bf16 v[68:71], v[212:215], v[204:207], v[68:71]
	v_mfma_f32_16x16x32_bf16 v[64:67], v[220:223], v[204:207], v[64:67]
	s_barrier
	ds_read_b128 v[176:179], v167 offset:16384
	ds_read_b128 v[180:183], v167 offset:17408
	ds_read_b128 v[184:187], v167 offset:18432
	ds_read_b128 v[188:191], v167 offset:19456
	ds_read_b128 v[192:195], v167 offset:20480
	ds_read_b128 v[196:199], v167 offset:21504
	ds_read_b128 v[200:203], v167 offset:22528
	ds_read_b128 v[204:207], v167 offset:23552
	s_add_i32 s68, s9, s10
	v_lshl_add_u64 v[160:161], s[4:5], 0, v[130:131]
	s_mov_b32 m0, s68
	s_nop 0
	global_load_lds_dwordx4 v[160:161], off
	v_lshl_add_u64 v[224:225], s[4:5], 0, v[134:135]
	s_add_i32 m0, s68, 0x2000
	s_nop 0
	global_load_lds_dwordx4 v[224:225], off
	s_mov_b32 m0, s11
	v_lshl_add_u64 v[226:227], s[6:7], 0, v[128:129]
	global_load_lds_dwordx4 v[226:227], off
	v_lshl_add_u64 v[228:229], s[6:7], 0, v[132:133]
	s_mov_b32 m0, s19
	s_nop 0
	global_load_lds_dwordx4 v[228:229], off
	s_add_u32 s68, s4, 0x80000
	s_addc_u32 s69, s5, 0
	s_add_i32 s70, s40, s10
	v_lshl_add_u64 v[230:231], s[68:69], 0, v[130:131]
	s_mov_b32 m0, s70
	s_nop 0
	global_load_lds_dwordx4 v[230:231], off
	v_lshl_add_u64 v[230:231], s[68:69], 0, v[134:135]
	s_add_i32 m0, s70, 0x2000
	s_nop 0
	global_load_lds_dwordx4 v[230:231], off
	s_waitcnt lgkmcnt(0)
	s_waitcnt vmcnt(8)
	s_barrier
	v_mfma_f32_16x16x32_bf16 v[60:63], v[148:151], v[176:179], v[60:63]
	v_mfma_f32_16x16x32_bf16 v[56:59], v[156:159], v[176:179], v[56:59]
	v_mfma_f32_16x16x32_bf16 v[44:47], v[148:151], v[184:187], v[44:47]
	v_mfma_f32_16x16x32_bf16 v[40:43], v[156:159], v[184:187], v[40:43]
	v_mfma_f32_16x16x32_bf16 v[28:31], v[148:151], v[192:195], v[28:31]
	v_mfma_f32_16x16x32_bf16 v[24:27], v[156:159], v[192:195], v[24:27]
	v_mfma_f32_16x16x32_bf16 v[12:15], v[148:151], v[200:203], v[12:15]
	v_mfma_f32_16x16x32_bf16 v[8:11], v[156:159], v[200:203], v[8:11]
	v_mfma_f32_16x16x32_bf16 v[60:63], v[152:155], v[180:183], v[60:63]
	v_mfma_f32_16x16x32_bf16 v[56:59], v[172:175], v[180:183], v[56:59]
	v_mfma_f32_16x16x32_bf16 v[44:47], v[152:155], v[188:191], v[44:47]
	v_mfma_f32_16x16x32_bf16 v[40:43], v[172:175], v[188:191], v[40:43]
	v_mfma_f32_16x16x32_bf16 v[28:31], v[152:155], v[196:199], v[28:31]
	v_mfma_f32_16x16x32_bf16 v[24:27], v[172:175], v[196:199], v[24:27]
	v_mfma_f32_16x16x32_bf16 v[12:15], v[152:155], v[204:207], v[12:15]
	v_mfma_f32_16x16x32_bf16 v[8:11], v[172:175], v[204:207], v[8:11]
	v_mfma_f32_16x16x32_bf16 v[52:55], v[208:211], v[176:179], v[52:55]
	v_mfma_f32_16x16x32_bf16 v[48:51], v[216:219], v[176:179], v[48:51]
	v_mfma_f32_16x16x32_bf16 v[36:39], v[208:211], v[184:187], v[36:39]
	v_mfma_f32_16x16x32_bf16 v[32:35], v[216:219], v[184:187], v[32:35]
	v_mfma_f32_16x16x32_bf16 v[20:23], v[208:211], v[192:195], v[20:23]
	v_mfma_f32_16x16x32_bf16 v[16:19], v[216:219], v[192:195], v[16:19]
	v_mfma_f32_16x16x32_bf16 v[4:7], v[208:211], v[200:203], v[4:7]
	v_mfma_f32_16x16x32_bf16 v[0:3], v[216:219], v[200:203], v[0:3]
	v_mfma_f32_16x16x32_bf16 v[52:55], v[212:215], v[180:183], v[52:55]
	v_mfma_f32_16x16x32_bf16 v[48:51], v[220:223], v[180:183], v[48:51]
	v_mfma_f32_16x16x32_bf16 v[36:39], v[212:215], v[188:191], v[36:39]
	v_mfma_f32_16x16x32_bf16 v[32:35], v[220:223], v[188:191], v[32:35]
	v_mfma_f32_16x16x32_bf16 v[20:23], v[212:215], v[196:199], v[20:23]
	v_mfma_f32_16x16x32_bf16 v[16:19], v[220:223], v[196:199], v[16:19]
	v_mfma_f32_16x16x32_bf16 v[4:7], v[212:215], v[204:207], v[4:7]
	v_mfma_f32_16x16x32_bf16 v[0:3], v[220:223], v[204:207], v[0:3]
	s_add_i32 s68, 0, 0x18000
	v_add_u32_e32 v172, s68, v163
	s_barrier
; #define PG8_STAGE(bufoff, gbase, voff) do { _Pragma("unroll") for (int _i = 0; _i < 2; ++_i) \
;         __builtin_amdgcn_global_load_lds((const unsigned*)((const char*)(gbase) + (voff)[_i]), (PG8_LAS unsigned*)(lds + (bufoff) + ldsw + _i * 8192), 16, 0, 0); } while (0)
; #define PG8_LDA(dst, b, h) do { _Pragma("unroll") for (int m = 0; m < 4; ++m) _Pragma("unroll") for (int k = 0; k < 2; ++k) dst[m][k] = *(const PG8_LAS bf16x8*)(lds + PG8_SA(b, h) + aoff + m * 2048 + k * 1024); } while (0)
; #define PG8_LDB(dst, b, h) do { _Pragma("unroll") for (int n = 0; n < 2; ++n) _Pragma("unroll") for (int k = 0; k < 2; ++k) dst[n][k] = *(const PG8_LAS bf16x8*)(lds + PG8_SB(b, h) + boff + n * 2048 + k * 1024); } while (0)
; #define PG8_MMA(ai, bj, At, Bt) do { __builtin_amdgcn_s_setprio(1); _Pragma("unroll") for (int m = 0; m < 4; ++m) _Pragma("unroll") for (int n = 0; n < 2; ++n) _Pragma("unroll") for (int k = 0; k < 2; ++k) \
;         acc[ai][bj][m][n] = __builtin_amdgcn_mfma_f32_16x16x32_bf16(Bt[n][k], At[m][k], acc[ai][bj][m][n], 0, 0, 0); __builtin_amdgcn_s_setprio(0); } while (0)
; #define PG8_WAIT_L(n) asm volatile("s_waitcnt lgkmcnt(" #n ")" ::: "memory")
; #define PG8_BAR __builtin_amdgcn_s_barrier()
; #define PG8_SCHED __builtin_amdgcn_sched_barrier(0)
; template <class Epi>
; __device__ __forceinline__ void gemm_phase(PG8_LAS unsigned char* lds, const Gemm g, const StaticOrder& S, const Epi& E) {
;     ...
;             PG8_LDB(B0, 1, 0); PG8_SCHED; PG8_LDA(At, 1, 0); PG8_STAGE(PG8_SA(0, 1), a2 + hstepA, voffA);
;             PG8_WAIT_L(8); PG8_BAR; PG8_WAIT_L(0); PG8_MMA(0, 0, At, B0); PG8_BAR; PG8_SCHED;
;             PG8_LDB(B1, 1, 1); PG8_STAGE(PG8_SB(1, 0), b3, voffB);
;             PG8_BAR; PG8_WAIT_L(0); PG8_MMA(0, 1, At, B1); PG8_BAR;
	ds_read_b128 v[148:151], v172
	ds_read_b128 v[152:155], v172 offset:1024
	ds_read_b128 v[156:159], v172 offset:2048
	ds_read_b128 v[172:175], v172 offset:3072
	ds_read_b128 v[176:179], v167 offset:32768
	ds_read_b128 v[180:183], v167 offset:33792
	ds_read_b128 v[184:187], v167 offset:34816
	ds_read_b128 v[188:191], v167 offset:35840
	ds_read_b128 v[192:195], v167 offset:36864
	ds_read_b128 v[196:199], v167 offset:37888
	ds_read_b128 v[200:203], v167 offset:38912
	ds_read_b128 v[204:207], v167 offset:39936
	v_add_u32_e32 v220, 0x1c000, v163
	ds_read_b128 v[208:211], v220
	ds_read_b128 v[212:215], v220 offset:1024
	ds_read_b128 v[216:219], v220 offset:2048
	ds_read_b128 v[220:223], v220 offset:3072
	s_add_u32 s6, s6, 0x80000
	s_addc_u32 s7, s7, 0
	s_mov_b32 m0, s22
	v_lshl_add_u64 v[230:231], s[6:7], 0, v[128:129]
	global_load_lds_dwordx4 v[230:231], off
	v_lshl_add_u64 v[230:231], s[6:7], 0, v[132:133]
	s_mov_b32 m0, s23
	s_nop 0
	global_load_lds_dwordx4 v[230:231], off
	s_waitcnt lgkmcnt(0)
	s_waitcnt vmcnt(8)
	s_barrier
	v_mfma_f32_16x16x32_bf16 v[124:127], v[148:151], v[176:179], v[124:127]
	v_mfma_f32_16x16x32_bf16 v[120:123], v[156:159], v[176:179], v[120:123]
	v_mfma_f32_16x16x32_bf16 v[108:111], v[148:151], v[184:187], v[108:111]
	v_mfma_f32_16x16x32_bf16 v[104:107], v[156:159], v[184:187], v[104:107]
	v_mfma_f32_16x16x32_bf16 v[92:95], v[148:151], v[192:195], v[92:95]
	v_mfma_f32_16x16x32_bf16 v[88:91], v[156:159], v[192:195], v[88:91]
	v_mfma_f32_16x16x32_bf16 v[76:79], v[148:151], v[200:203], v[76:79]
	v_mfma_f32_16x16x32_bf16 v[72:75], v[156:159], v[200:203], v[72:75]
	v_mfma_f32_16x16x32_bf16 v[124:127], v[152:155], v[180:183], v[124:127]
	v_mfma_f32_16x16x32_bf16 v[120:123], v[172:175], v[180:183], v[120:123]
	v_mfma_f32_16x16x32_bf16 v[108:111], v[152:155], v[188:191], v[108:111]
	v_mfma_f32_16x16x32_bf16 v[104:107], v[172:175], v[188:191], v[104:107]
	v_mfma_f32_16x16x32_bf16 v[92:95], v[152:155], v[196:199], v[92:95]
	v_mfma_f32_16x16x32_bf16 v[88:91], v[172:175], v[196:199], v[88:91]
	v_mfma_f32_16x16x32_bf16 v[76:79], v[152:155], v[204:207], v[76:79]
	v_mfma_f32_16x16x32_bf16 v[72:75], v[172:175], v[204:207], v[72:75]
	v_mfma_f32_16x16x32_bf16 v[116:119], v[208:211], v[176:179], v[116:119]
	v_mfma_f32_16x16x32_bf16 v[112:115], v[216:219], v[176:179], v[112:115]
	v_mfma_f32_16x16x32_bf16 v[100:103], v[208:211], v[184:187], v[100:103]
	v_mfma_f32_16x16x32_bf16 v[96:99], v[216:219], v[184:187], v[96:99]
	v_mfma_f32_16x16x32_bf16 v[84:87], v[208:211], v[192:195], v[84:87]
	v_mfma_f32_16x16x32_bf16 v[80:83], v[216:219], v[192:195], v[80:83]
	v_mfma_f32_16x16x32_bf16 v[68:71], v[208:211], v[200:203], v[68:71]
	v_mfma_f32_16x16x32_bf16 v[64:67], v[216:219], v[200:203], v[64:67]
	v_mfma_f32_16x16x32_bf16 v[116:119], v[212:215], v[180:183], v[116:119]
	v_mfma_f32_16x16x32_bf16 v[112:115], v[220:223], v[180:183], v[112:115]
	v_mfma_f32_16x16x32_bf16 v[100:103], v[212:215], v[188:191], v[100:103]
	v_mfma_f32_16x16x32_bf16 v[96:99], v[220:223], v[188:191], v[96:99]
	v_mfma_f32_16x16x32_bf16 v[84:87], v[212:215], v[196:199], v[84:87]
	v_mfma_f32_16x16x32_bf16 v[80:83], v[220:223], v[196:199], v[80:83]
	v_mfma_f32_16x16x32_bf16 v[68:71], v[212:215], v[204:207], v[68:71]
	v_mfma_f32_16x16x32_bf16 v[64:67], v[220:223], v[204:207], v[64:67]
	s_barrier
; #define PG8_STAGE(bufoff, gbase, voff) do { _Pragma("unroll") for (int _i = 0; _i < 2; ++_i) \
;         __builtin_amdgcn_global_load_lds((const unsigned*)((const char*)(gbase) + (voff)[_i]), (PG8_LAS unsigned*)(lds + (bufoff) + ldsw + _i * 8192), 16, 0, 0); } while (0)
; #define PG8_MMA(ai, bj, At, Bt) do { __builtin_amdgcn_s_setprio(1); _Pragma("unroll") for (int m = 0; m < 4; ++m) _Pragma("unroll") for (int n = 0; n < 2; ++n) _Pragma("unroll") for (int k = 0; k < 2; ++k) \
;         acc[ai][bj][m][n] = __builtin_amdgcn_mfma_f32_16x16x32_bf16(Bt[n][k], At[m][k], acc[ai][bj][m][n], 0, 0, 0); __builtin_amdgcn_s_setprio(0); } while (0)
; #define PG8_WAIT_V(n) asm volatile("s_waitcnt vmcnt(" #n ")" ::: "memory")
; #define PG8_WAIT_L(n) asm volatile("s_waitcnt lgkmcnt(" #n ")" ::: "memory")
; #define PG8_BAR __builtin_amdgcn_s_barrier()
; #define PG8_SCHED __builtin_amdgcn_sched_barrier(0)
; template <class Epi>
; __device__ __forceinline__ void gemm_phase(PG8_LAS unsigned char* lds, const Gemm g, const StaticOrder& S, const Epi& E) {
;     ...
;             PG8_BAR; PG8_WAIT_L(0); PG8_MMA(1, 0, At, B0); PG8_BAR; PG8_SCHED;
;             PG8_STAGE(PG8_SB(1, 1), b3 + hstepB, voffB);
;             PG8_WAIT_V(6); PG8_BAR; PG8_MMA(1, 1, At, B1); PG8_BAR;
;         }
;         E(acc, cur, wr, wc, fr, fq);
;     __device__ __forceinline__ void operator()(const f32x4 (&acc)[2][2][4][2], const pg8::Unit& u, int wr, int wc, int fr, int fq) const {
;         const int row0 = u.pm * 256 + wr * 64 + fr; const int pn = u.pn;
;         bf16_t* base; int ld, cb; const bool paired = (pn >= 11 && pn < 19);
;         if (pn < 11) { base = Z1; ld = LDZ; cb = pn * 256; } else if (pn < 19) { base = XCC; ld = LDX; cb = (pn - 11) * 128; } else if (pn < 23) { base = BB; ld = LDX; cb = (pn - 19) * 256; } else { base = G; ld = LDG; cb = (pn - 23) * 256; }
;         cb += wc * 32 + 8 * fq;
	ds_read_b128 v[176:179], v167 offset:49152
	ds_read_b128 v[180:183], v167 offset:50176
	ds_read_b128 v[184:187], v167 offset:51200
	ds_read_b128 v[188:191], v167 offset:52224
	ds_read_b128 v[192:195], v167 offset:53248
	ds_read_b128 v[196:199], v167 offset:54272
	ds_read_b128 v[200:203], v167 offset:55296
	ds_read_b128 v[204:207], v167 offset:56320
	s_add_i32 s6, 0, 0x1c000
	s_add_i32 s7, s68, s10
	v_lshl_add_u64 v[160:161], v[160:161], 0, s[14:15]
	s_mov_b32 m0, s7
	s_nop 0
	global_load_lds_dwordx4 v[160:161], off
	v_lshl_add_u64 v[160:161], v[224:225], 0, s[14:15]
	s_add_i32 m0, s7, 0x2000
	s_nop 0
	global_load_lds_dwordx4 v[160:161], off
	s_mov_b32 m0, s35
	v_lshl_add_u64 v[160:161], v[226:227], 0, s[14:15]
	global_load_lds_dwordx4 v[160:161], off
	v_lshl_add_u64 v[160:161], v[228:229], 0, s[14:15]
	s_mov_b32 m0, s36
	s_nop 0
	global_load_lds_dwordx4 v[160:161], off
	s_add_u32 s4, s4, 0x80080
	s_addc_u32 s5, s5, 0
	s_add_i32 s6, s6, s10
	v_lshl_add_u64 v[230:231], s[4:5], 0, v[130:131]
	s_mov_b32 m0, s6
	s_nop 0
	global_load_lds_dwordx4 v[230:231], off
	v_lshl_add_u64 v[230:231], s[4:5], 0, v[134:135]
	s_add_i32 m0, s6, 0x2000
	s_nop 0
	global_load_lds_dwordx4 v[230:231], off
	s_waitcnt lgkmcnt(0)
	s_waitcnt vmcnt(8)
	s_barrier
	v_mfma_f32_16x16x32_bf16 v[60:63], v[148:151], v[176:179], v[60:63]
	v_mfma_f32_16x16x32_bf16 v[56:59], v[156:159], v[176:179], v[56:59]
	v_mfma_f32_16x16x32_bf16 v[44:47], v[148:151], v[184:187], v[44:47]
	v_mfma_f32_16x16x32_bf16 v[40:43], v[156:159], v[184:187], v[40:43]
	v_mfma_f32_16x16x32_bf16 v[28:31], v[148:151], v[192:195], v[28:31]
	v_mfma_f32_16x16x32_bf16 v[24:27], v[156:159], v[192:195], v[24:27]
	v_mfma_f32_16x16x32_bf16 v[12:15], v[148:151], v[200:203], v[12:15]
	v_mfma_f32_16x16x32_bf16 v[8:11], v[156:159], v[200:203], v[8:11]
	v_mfma_f32_16x16x32_bf16 v[60:63], v[152:155], v[180:183], v[60:63]
	v_mfma_f32_16x16x32_bf16 v[56:59], v[172:175], v[180:183], v[56:59]
	v_mfma_f32_16x16x32_bf16 v[44:47], v[152:155], v[188:191], v[44:47]
	v_mfma_f32_16x16x32_bf16 v[40:43], v[172:175], v[188:191], v[40:43]
	v_mfma_f32_16x16x32_bf16 v[28:31], v[152:155], v[196:199], v[28:31]
	v_mfma_f32_16x16x32_bf16 v[24:27], v[172:175], v[196:199], v[24:27]
	v_mfma_f32_16x16x32_bf16 v[12:15], v[152:155], v[204:207], v[12:15]
	v_mfma_f32_16x16x32_bf16 v[8:11], v[172:175], v[204:207], v[8:11]
	v_mfma_f32_16x16x32_bf16 v[52:55], v[208:211], v[176:179], v[52:55]
	v_mfma_f32_16x16x32_bf16 v[48:51], v[216:219], v[176:179], v[48:51]
	v_mfma_f32_16x16x32_bf16 v[36:39], v[208:211], v[184:187], v[36:39]
	v_mfma_f32_16x16x32_bf16 v[32:35], v[216:219], v[184:187], v[32:35]
	v_mfma_f32_16x16x32_bf16 v[20:23], v[208:211], v[192:195], v[20:23]
	v_mfma_f32_16x16x32_bf16 v[16:19], v[216:219], v[192:195], v[16:19]
	v_mfma_f32_16x16x32_bf16 v[4:7], v[208:211], v[200:203], v[4:7]
	v_mfma_f32_16x16x32_bf16 v[0:3], v[216:219], v[200:203], v[0:3]
	v_mfma_f32_16x16x32_bf16 v[52:55], v[212:215], v[180:183], v[52:55]
	v_mfma_f32_16x16x32_bf16 v[48:51], v[220:223], v[180:183], v[48:51]
	v_mfma_f32_16x16x32_bf16 v[36:39], v[212:215], v[188:191], v[36:39]
	v_mfma_f32_16x16x32_bf16 v[32:35], v[220:223], v[188:191], v[32:35]
	v_mfma_f32_16x16x32_bf16 v[20:23], v[212:215], v[196:199], v[20:23]
	v_mfma_f32_16x16x32_bf16 v[16:19], v[220:223], v[196:199], v[16:19]
	v_mfma_f32_16x16x32_bf16 v[4:7], v[212:215], v[204:207], v[4:7]
	v_mfma_f32_16x16x32_bf16 v[0:3], v[220:223], v[204:207], v[0:3]
	s_add_i32 s67, s67, 2
	s_add_u32 s0, s0, 0x100
	s_addc_u32 s1, s1, 0
	s_add_u32 s65, s65, 0x100
	s_addc_u32 s66, s66, 0
	s_cmp_gt_u32 s67, 29
	s_barrier
	s_cbranch_scc0 .LBB0_413
	s_setprio 0
	s_cmp_gt_i32 s62, 10
	s_mov_b64 s[0:1], -1
	s_cbranch_scc0 .LBB0_424
	s_cmp_gt_u32 s62, 18
	s_cbranch_scc0 .LBB0_421
	s_lshl_b32 s4, s62, 8
	s_cmp_gt_u32 s62, 22
	s_cbranch_scc0 .LBB0_418
	s_add_i32 s53, s4, 0xffffe900
	s_mov_b64 s[0:1], 0

; #define PG8_STAGE(bufoff, gbase, voff) do { _Pragma("unroll") for (int _i = 0; _i < 2; ++_i) \
;         __builtin_amdgcn_global_load_lds((const unsigned*)((const char*)(gbase) + (voff)[_i]), (PG8_LAS unsigned*)(lds + (bufoff) + ldsw + _i * 8192), 16, 0, 0); } while (0)
; #define PG8_LDA(dst, b, h) do { _Pragma("unroll") for (int m = 0; m < 4; ++m) _Pragma("unroll") for (int k = 0; k < 2; ++k) dst[m][k] = *(const PG8_LAS bf16x8*)(lds + PG8_SA(b, h) + aoff + m * 2048 + k * 1024); } while (0)
; #define PG8_LDB(dst, b, h) do { _Pragma("unroll") for (int n = 0; n < 2; ++n) _Pragma("unroll") for (int k = 0; k < 2; ++k) dst[n][k] = *(const PG8_LAS bf16x8*)(lds + PG8_SB(b, h) + boff + n * 2048 + k * 1024); } while (0)
; #define PG8_MMA(ai, bj, At, Bt) do { __builtin_amdgcn_s_setprio(1); _Pragma("unroll") for (int m = 0; m < 4; ++m) _Pragma("unroll") for (int n = 0; n < 2; ++n) _Pragma("unroll") for (int k = 0; k < 2; ++k) \
;         acc[ai][bj][m][n] = __builtin_amdgcn_mfma_f32_16x16x32_bf16(Bt[n][k], At[m][k], acc[ai][bj][m][n], 0, 0, 0); __builtin_amdgcn_s_setprio(0); } while (0)
; #define PG8_WAIT_L(n) asm volatile("s_waitcnt lgkmcnt(" #n ")" ::: "memory")
; template <class Epi>
; __device__ __forceinline__ void gemm_phase(PG8_LAS unsigned char* lds, const Gemm g, const StaticOrder& S, const Epi& E) {
;     ...
;         const bool has_next = S.next(ui + 1, nxt);
;         const char* nA = has_next ? (const char*)g.A + (size_t)nxt.pm * tstepA : cA; const char* nB = has_next ? (const char*)g.Bt + (size_t)nxt.pn * tstepB : cB;
;         for (int t = 0; t < nt; t += 2) {
;             const bool last = (t == nt - 2);
;             const char* a1 = cA + (size_t)(t + 1) * kstep;
;             const char* a2 = last ? nA : cA + (size_t)(t + 2) * kstep; const char* b2 = last ? nB : cB + (size_t)(t + 2) * kstep;
;             const char* a3 = a2 + kstep; const char* b3 = b2 + kstep;
;             PG8_LDB(B0, 0, 0); PG8_SCHED; PG8_LDA(At, 0, 0); PG8_STAGE(PG8_SA(1, 1), a1 + hstepA, voffA);
;             PG8_WAIT_L(8); PG8_BAR; PG8_WAIT_L(0); PG8_MMA(0, 0, At, B0); PG8_BAR; PG8_SCHED;
;     ...
; #pragma unroll
;         for (int a = 0; a < 2; ++a)
; #pragma unroll
;             for (int b = 0; b < 2; ++b)
; #pragma unroll
;                 for (int m = 0; m < 4; ++m)
; #pragma unroll
;                     for (int n = 0; n < 2; ++n) acc[a][b][m][n] = (f32x4){0.f, 0.f, 0.f, 0.f};
.LBB0_903:
	s_ashr_i32 s15, s14, 31
	v_cmp_lt_i64_e32 vcc, s[16:17], v[160:161]
	s_lshl_b64 s[16:17], s[14:15], 19
	s_add_u32 s16, s80, s16
	s_addc_u32 s17, s81, s17
	s_and_b64 s[18:19], vcc, exec
	s_cselect_b32 s15, s17, s29
	s_cselect_b32 s54, s16, s28
	s_ashr_i32 s13, s12, 31
	s_lshl_b64 s[18:19], s[12:13], 19
	s_add_u32 s18, s64, s18
	s_addc_u32 s19, s65, s19
	s_and_b64 s[30:31], vcc, exec
	s_cselect_b32 s13, s19, s23
	s_cselect_b32 s55, s18, s22
	s_add_u32 s28, s28, 0x40080
	s_addc_u32 s29, s29, 0
	s_add_u32 s56, s22, 0x100
	v_mov_b32_e32 v0, 0
	s_addc_u32 s57, s23, 0
	s_mov_b32 s58, -2
	v_mov_b32_e32 v1, v0
	v_mov_b32_e32 v2, v0
	v_mov_b32_e32 v3, v0
	v_mov_b32_e32 v4, v0
	v_mov_b32_e32 v5, v0
	v_mov_b32_e32 v6, v0
	v_mov_b32_e32 v7, v0
	v_mov_b32_e32 v16, v0
	v_mov_b32_e32 v17, v0
	v_mov_b32_e32 v18, v0
	v_mov_b32_e32 v19, v0
	v_mov_b32_e32 v20, v0
	v_mov_b32_e32 v21, v0
	v_mov_b32_e32 v22, v0
	v_mov_b32_e32 v23, v0
	v_mov_b32_e32 v32, v0
	v_mov_b32_e32 v33, v0
	v_mov_b32_e32 v34, v0
	v_mov_b32_e32 v35, v0
	v_mov_b32_e32 v36, v0
	v_mov_b32_e32 v37, v0
	v_mov_b32_e32 v38, v0
	v_mov_b32_e32 v39, v0
	v_mov_b32_e32 v48, v0
	v_mov_b32_e32 v49, v0
	v_mov_b32_e32 v50, v0
	v_mov_b32_e32 v51, v0
	v_mov_b32_e32 v52, v0
	v_mov_b32_e32 v53, v0
	v_mov_b32_e32 v54, v0
	v_mov_b32_e32 v55, v0
	v_mov_b32_e32 v8, v0
	v_mov_b32_e32 v9, v0
	v_mov_b32_e32 v10, v0
	v_mov_b32_e32 v11, v0
	v_mov_b32_e32 v12, v0
	v_mov_b32_e32 v13, v0
	v_mov_b32_e32 v14, v0
	v_mov_b32_e32 v15, v0
	v_mov_b32_e32 v24, v0
	v_mov_b32_e32 v25, v0
	v_mov_b32_e32 v26, v0
	v_mov_b32_e32 v27, v0
	v_mov_b32_e32 v28, v0
	v_mov_b32_e32 v29, v0
	v_mov_b32_e32 v30, v0
	v_mov_b32_e32 v31, v0
	v_mov_b32_e32 v40, v0
	v_mov_b32_e32 v41, v0
	v_mov_b32_e32 v42, v0
	v_mov_b32_e32 v43, v0
	v_mov_b32_e32 v44, v0
	v_mov_b32_e32 v45, v0
	v_mov_b32_e32 v46, v0
	v_mov_b32_e32 v47, v0
	v_mov_b32_e32 v56, v0
	v_mov_b32_e32 v57, v0
	v_mov_b32_e32 v58, v0
	v_mov_b32_e32 v59, v0
	v_mov_b32_e32 v60, v0
	v_mov_b32_e32 v61, v0
	v_mov_b32_e32 v62, v0
	v_mov_b32_e32 v63, v0
	v_mov_b32_e32 v64, v0
	v_mov_b32_e32 v65, v0
	v_mov_b32_e32 v66, v0
	v_mov_b32_e32 v67, v0
	v_mov_b32_e32 v68, v0
	v_mov_b32_e32 v69, v0
	v_mov_b32_e32 v70, v0
	v_mov_b32_e32 v71, v0
	v_mov_b32_e32 v80, v0
	v_mov_b32_e32 v81, v0
	v_mov_b32_e32 v82, v0
	v_mov_b32_e32 v83, v0
	v_mov_b32_e32 v84, v0
	v_mov_b32_e32 v85, v0
	v_mov_b32_e32 v86, v0
	v_mov_b32_e32 v87, v0
	v_mov_b32_e32 v96, v0
	v_mov_b32_e32 v97, v0
	v_mov_b32_e32 v98, v0
	v_mov_b32_e32 v99, v0
	v_mov_b32_e32 v100, v0
	v_mov_b32_e32 v101, v0
	v_mov_b32_e32 v102, v0
	v_mov_b32_e32 v103, v0
	v_mov_b32_e32 v112, v0
	v_mov_b32_e32 v113, v0
	v_mov_b32_e32 v114, v0
	v_mov_b32_e32 v115, v0
	v_mov_b32_e32 v116, v0
	v_mov_b32_e32 v117, v0
	v_mov_b32_e32 v118, v0
	v_mov_b32_e32 v119, v0
	v_mov_b32_e32 v72, v0
	v_mov_b32_e32 v73, v0
	v_mov_b32_e32 v74, v0
	v_mov_b32_e32 v75, v0
	v_mov_b32_e32 v76, v0
	v_mov_b32_e32 v77, v0
	v_mov_b32_e32 v78, v0
	v_mov_b32_e32 v79, v0
	v_mov_b32_e32 v88, v0
	v_mov_b32_e32 v89, v0
	v_mov_b32_e32 v90, v0
	v_mov_b32_e32 v91, v0
	v_mov_b32_e32 v92, v0
	v_mov_b32_e32 v93, v0
	v_mov_b32_e32 v94, v0
	v_mov_b32_e32 v95, v0
	v_mov_b32_e32 v104, v0
	v_mov_b32_e32 v105, v0
	v_mov_b32_e32 v106, v0
	v_mov_b32_e32 v107, v0
	v_mov_b32_e32 v108, v0
	v_mov_b32_e32 v109, v0
	v_mov_b32_e32 v110, v0
	v_mov_b32_e32 v111, v0
	v_mov_b32_e32 v120, v0
	v_mov_b32_e32 v121, v0
	v_mov_b32_e32 v122, v0
	v_mov_b32_e32 v123, v0
	v_mov_b32_e32 v124, v0
	v_mov_b32_e32 v125, v0
	v_mov_b32_e32 v126, v0
	v_mov_b32_e32 v127, v0
	s_cmp_eq_u32 s101, 1
	s_cbranch_scc0 .Lsp_3
	s_setprio 1
.Lsp_3:
.LBB0_904:
	ds_read_b128 v[128:131], v178
	ds_read_b128 v[132:135], v178 offset:1024
	ds_read_b128 v[136:139], v178 offset:2048
	ds_read_b128 v[140:143], v178 offset:3072
	ds_read_b128 v[144:147], v179
	ds_read_b128 v[164:167], v179 offset:1024
	ds_read_b128 v[170:173], v179 offset:2048
	ds_read_b128 v[182:185], v179 offset:3072
	ds_read_b128 v[186:189], v179 offset:4096
	ds_read_b128 v[190:193], v179 offset:5120
	ds_read_b128 v[194:197], v179 offset:6144
	ds_read_b128 v[198:201], v179 offset:7168
	ds_read_b128 v[202:205], v180
	ds_read_b128 v[206:209], v180 offset:1024
	ds_read_b128 v[210:213], v180 offset:2048
	ds_read_b128 v[214:217], v180 offset:3072
	s_add_u32 s22, s28, 0xfffc0080
	s_addc_u32 s23, s29, -1
	s_cmp_eq_u32 s58, 12
	s_cselect_b32 s31, s15, s23
	s_cselect_b32 s30, s54, s22
	s_cselect_b32 s23, s13, s57
	s_cselect_b32 s22, s55, s56
	v_lshl_add_u64 v[174:175], s[28:29], 0, v[156:157]
	s_add_i32 m0, s21, 0xc000
	s_nop 0
	global_load_lds_dwordx4 v[174:175], off
	v_lshl_add_u64 v[174:175], s[28:29], 0, v[158:159]
	s_add_i32 m0, s21, 0xe000
	s_nop 0
	global_load_lds_dwordx4 v[174:175], off
	s_waitcnt lgkmcnt(0)
	s_waitcnt vmcnt(8)
	s_barrier
; #define PG8_STAGE(bufoff, gbase, voff) do { _Pragma("unroll") for (int _i = 0; _i < 2; ++_i) \
;         __builtin_amdgcn_global_load_lds((const unsigned*)((const char*)(gbase) + (voff)[_i]), (PG8_LAS unsigned*)(lds + (bufoff) + ldsw + _i * 8192), 16, 0, 0); } while (0)
; #define PG8_LDA(dst, b, h) do { _Pragma("unroll") for (int m = 0; m < 4; ++m) _Pragma("unroll") for (int k = 0; k < 2; ++k) dst[m][k] = *(const PG8_LAS bf16x8*)(lds + PG8_SA(b, h) + aoff + m * 2048 + k * 1024); } while (0)
; #define PG8_LDB(dst, b, h) do { _Pragma("unroll") for (int n = 0; n < 2; ++n) _Pragma("unroll") for (int k = 0; k < 2; ++k) dst[n][k] = *(const PG8_LAS bf16x8*)(lds + PG8_SB(b, h) + boff + n * 2048 + k * 1024); } while (0)
; #define PG8_MMA(ai, bj, At, Bt) do { __builtin_amdgcn_s_setprio(1); _Pragma("unroll") for (int m = 0; m < 4; ++m) _Pragma("unroll") for (int n = 0; n < 2; ++n) _Pragma("unroll") for (int k = 0; k < 2; ++k) \
;         acc[ai][bj][m][n] = __builtin_amdgcn_mfma_f32_16x16x32_bf16(Bt[n][k], At[m][k], acc[ai][bj][m][n], 0, 0, 0); __builtin_amdgcn_s_setprio(0); } while (0)
; #define PG8_WAIT_V(n) asm volatile("s_waitcnt vmcnt(" #n ")" ::: "memory")
; #define PG8_WAIT_L(n) asm volatile("s_waitcnt lgkmcnt(" #n ")" ::: "memory")
; #define PG8_BAR __builtin_amdgcn_s_barrier()
; #define PG8_SCHED __builtin_amdgcn_sched_barrier(0)
; template <class Epi>
; __device__ __forceinline__ void gemm_phase(PG8_LAS unsigned char* lds, const Gemm g, const StaticOrder& S, const Epi& E) {
;     ...
;             PG8_WAIT_L(8); PG8_BAR; PG8_WAIT_L(0); PG8_MMA(0, 0, At, B0); PG8_BAR; PG8_SCHED;
;             PG8_LDB(B1, 0, 1); PG8_STAGE(PG8_SB(0, 0), b2, voffB);
;             PG8_BAR; PG8_WAIT_L(0); PG8_MMA(0, 1, At, B1); PG8_BAR;
;             PG8_LDA(At, 0, 1); PG8_STAGE(PG8_SA(0, 0), a2, voffA);
;             PG8_BAR; PG8_WAIT_L(0); PG8_MMA(1, 0, At, B0); PG8_BAR; PG8_SCHED;
;             PG8_STAGE(PG8_SB(0, 1), b2 + hstepB, voffB);
;             PG8_WAIT_V(6); PG8_BAR; PG8_MMA(1, 1, At, B1); PG8_BAR;
	v_mfma_f32_16x16x32_bf16 v[124:127], v[128:131], v[144:147], v[124:127]
	v_mfma_f32_16x16x32_bf16 v[120:123], v[136:139], v[144:147], v[120:123]
	v_mfma_f32_16x16x32_bf16 v[108:111], v[128:131], v[170:173], v[108:111]
	v_mfma_f32_16x16x32_bf16 v[104:107], v[136:139], v[170:173], v[104:107]
	v_mfma_f32_16x16x32_bf16 v[92:95], v[128:131], v[186:189], v[92:95]
	v_mfma_f32_16x16x32_bf16 v[88:91], v[136:139], v[186:189], v[88:91]
	v_mfma_f32_16x16x32_bf16 v[76:79], v[128:131], v[194:197], v[76:79]
	v_mfma_f32_16x16x32_bf16 v[72:75], v[136:139], v[194:197], v[72:75]
	v_mfma_f32_16x16x32_bf16 v[124:127], v[132:135], v[164:167], v[124:127]
	v_mfma_f32_16x16x32_bf16 v[120:123], v[140:143], v[164:167], v[120:123]
	v_mfma_f32_16x16x32_bf16 v[108:111], v[132:135], v[182:185], v[108:111]
	v_mfma_f32_16x16x32_bf16 v[104:107], v[140:143], v[182:185], v[104:107]
	v_mfma_f32_16x16x32_bf16 v[92:95], v[132:135], v[190:193], v[92:95]
	v_mfma_f32_16x16x32_bf16 v[88:91], v[140:143], v[190:193], v[88:91]
	v_mfma_f32_16x16x32_bf16 v[76:79], v[132:135], v[198:201], v[76:79]
	v_mfma_f32_16x16x32_bf16 v[72:75], v[140:143], v[198:201], v[72:75]
	v_mfma_f32_16x16x32_bf16 v[116:119], v[202:205], v[144:147], v[116:119]
	v_mfma_f32_16x16x32_bf16 v[112:115], v[210:213], v[144:147], v[112:115]
	v_mfma_f32_16x16x32_bf16 v[100:103], v[202:205], v[170:173], v[100:103]
	v_mfma_f32_16x16x32_bf16 v[96:99], v[210:213], v[170:173], v[96:99]
	v_mfma_f32_16x16x32_bf16 v[84:87], v[202:205], v[186:189], v[84:87]
	v_mfma_f32_16x16x32_bf16 v[80:83], v[210:213], v[186:189], v[80:83]
	v_mfma_f32_16x16x32_bf16 v[68:71], v[202:205], v[194:197], v[68:71]
	v_mfma_f32_16x16x32_bf16 v[64:67], v[210:213], v[194:197], v[64:67]
	v_mfma_f32_16x16x32_bf16 v[116:119], v[206:209], v[164:167], v[116:119]
	v_mfma_f32_16x16x32_bf16 v[112:115], v[214:217], v[164:167], v[112:115]
	v_mfma_f32_16x16x32_bf16 v[100:103], v[206:209], v[182:185], v[100:103]
	v_mfma_f32_16x16x32_bf16 v[96:99], v[214:217], v[182:185], v[96:99]
	v_mfma_f32_16x16x32_bf16 v[84:87], v[206:209], v[190:193], v[84:87]
	v_mfma_f32_16x16x32_bf16 v[80:83], v[214:217], v[190:193], v[80:83]
	v_mfma_f32_16x16x32_bf16 v[68:71], v[206:209], v[198:201], v[68:71]
	v_mfma_f32_16x16x32_bf16 v[64:67], v[214:217], v[198:201], v[64:67]
	s_barrier
	ds_read_b128 v[144:147], v179 offset:16384
	ds_read_b128 v[164:167], v179 offset:17408
	ds_read_b128 v[170:173], v179 offset:18432
	ds_read_b128 v[182:185], v179 offset:19456
	ds_read_b128 v[186:189], v179 offset:20480
	ds_read_b128 v[190:193], v179 offset:21504
	ds_read_b128 v[194:197], v179 offset:22528
	ds_read_b128 v[198:201], v179 offset:23552
	s_add_i32 s59, s51, s36
	v_lshl_add_u64 v[174:175], s[22:23], 0, v[150:151]
	s_mov_b32 m0, s59
	s_nop 0
	global_load_lds_dwordx4 v[174:175], off
	v_lshl_add_u64 v[218:219], s[22:23], 0, v[154:155]
	s_add_i32 m0, s59, 0x2000
	s_nop 0
	global_load_lds_dwordx4 v[218:219], off
	s_mov_b32 m0, s21
	v_lshl_add_u64 v[220:221], s[30:31], 0, v[148:149]
	global_load_lds_dwordx4 v[220:221], off
	v_lshl_add_u64 v[222:223], s[30:31], 0, v[152:153]
	s_mov_b32 m0, s37
	s_nop 0
	global_load_lds_dwordx4 v[222:223], off
	s_add_u32 s60, s22, 0x40000
	s_addc_u32 s61, s23, 0
	s_add_i32 s59, s52, s36
	v_lshl_add_u64 v[224:225], s[60:61], 0, v[150:151]
	s_mov_b32 m0, s59
	s_nop 0
	global_load_lds_dwordx4 v[224:225], off
	v_lshl_add_u64 v[224:225], s[60:61], 0, v[154:155]
	s_add_i32 m0, s59, 0x2000
	s_nop 0
	global_load_lds_dwordx4 v[224:225], off
	s_waitcnt lgkmcnt(0)
	s_waitcnt vmcnt(8)
	s_barrier
	v_mfma_f32_16x16x32_bf16 v[60:63], v[128:131], v[144:147], v[60:63]
	v_mfma_f32_16x16x32_bf16 v[56:59], v[136:139], v[144:147], v[56:59]
	v_mfma_f32_16x16x32_bf16 v[44:47], v[128:131], v[170:173], v[44:47]
	v_mfma_f32_16x16x32_bf16 v[40:43], v[136:139], v[170:173], v[40:43]
	v_mfma_f32_16x16x32_bf16 v[28:31], v[128:131], v[186:189], v[28:31]
	v_mfma_f32_16x16x32_bf16 v[24:27], v[136:139], v[186:189], v[24:27]
	v_mfma_f32_16x16x32_bf16 v[12:15], v[128:131], v[194:197], v[12:15]
	v_mfma_f32_16x16x32_bf16 v[8:11], v[136:139], v[194:197], v[8:11]
	v_mfma_f32_16x16x32_bf16 v[60:63], v[132:135], v[164:167], v[60:63]
	v_mfma_f32_16x16x32_bf16 v[56:59], v[140:143], v[164:167], v[56:59]
	v_mfma_f32_16x16x32_bf16 v[44:47], v[132:135], v[182:185], v[44:47]
	v_mfma_f32_16x16x32_bf16 v[40:43], v[140:143], v[182:185], v[40:43]
	v_mfma_f32_16x16x32_bf16 v[28:31], v[132:135], v[190:193], v[28:31]
	v_mfma_f32_16x16x32_bf16 v[24:27], v[140:143], v[190:193], v[24:27]
	v_mfma_f32_16x16x32_bf16 v[12:15], v[132:135], v[198:201], v[12:15]
	v_mfma_f32_16x16x32_bf16 v[8:11], v[140:143], v[198:201], v[8:11]
	v_mfma_f32_16x16x32_bf16 v[52:55], v[202:205], v[144:147], v[52:55]
	v_mfma_f32_16x16x32_bf16 v[48:51], v[210:213], v[144:147], v[48:51]
	v_mfma_f32_16x16x32_bf16 v[36:39], v[202:205], v[170:173], v[36:39]
	v_mfma_f32_16x16x32_bf16 v[32:35], v[210:213], v[170:173], v[32:35]
	v_mfma_f32_16x16x32_bf16 v[20:23], v[202:205], v[186:189], v[20:23]
	v_mfma_f32_16x16x32_bf16 v[16:19], v[210:213], v[186:189], v[16:19]
	v_mfma_f32_16x16x32_bf16 v[4:7], v[202:205], v[194:197], v[4:7]
	v_mfma_f32_16x16x32_bf16 v[0:3], v[210:213], v[194:197], v[0:3]
	v_mfma_f32_16x16x32_bf16 v[52:55], v[206:209], v[164:167], v[52:55]
	v_mfma_f32_16x16x32_bf16 v[48:51], v[214:217], v[164:167], v[48:51]
	v_mfma_f32_16x16x32_bf16 v[36:39], v[206:209], v[182:185], v[36:39]
	v_mfma_f32_16x16x32_bf16 v[32:35], v[214:217], v[182:185], v[32:35]
	v_mfma_f32_16x16x32_bf16 v[20:23], v[206:209], v[190:193], v[20:23]
	v_mfma_f32_16x16x32_bf16 v[16:19], v[214:217], v[190:193], v[16:19]
	v_mfma_f32_16x16x32_bf16 v[4:7], v[206:209], v[198:201], v[4:7]
	v_mfma_f32_16x16x32_bf16 v[0:3], v[214:217], v[198:201], v[0:3]
	s_add_i32 s59, 0, 0x18000
	v_add_u32_e32 v140, s59, v176
	s_barrier
; #define PG8_STAGE(bufoff, gbase, voff) do { _Pragma("unroll") for (int _i = 0; _i < 2; ++_i) \
;         __builtin_amdgcn_global_load_lds((const unsigned*)((const char*)(gbase) + (voff)[_i]), (PG8_LAS unsigned*)(lds + (bufoff) + ldsw + _i * 8192), 16, 0, 0); } while (0)
; #define PG8_LDA(dst, b, h) do { _Pragma("unroll") for (int m = 0; m < 4; ++m) _Pragma("unroll") for (int k = 0; k < 2; ++k) dst[m][k] = *(const PG8_LAS bf16x8*)(lds + PG8_SA(b, h) + aoff + m * 2048 + k * 1024); } while (0)
; #define PG8_LDB(dst, b, h) do { _Pragma("unroll") for (int n = 0; n < 2; ++n) _Pragma("unroll") for (int k = 0; k < 2; ++k) dst[n][k] = *(const PG8_LAS bf16x8*)(lds + PG8_SB(b, h) + boff + n * 2048 + k * 1024); } while (0)
; #define PG8_MMA(ai, bj, At, Bt) do { __builtin_amdgcn_s_setprio(1); _Pragma("unroll") for (int m = 0; m < 4; ++m) _Pragma("unroll") for (int n = 0; n < 2; ++n) _Pragma("unroll") for (int k = 0; k < 2; ++k) \
;         acc[ai][bj][m][n] = __builtin_amdgcn_mfma_f32_16x16x32_bf16(Bt[n][k], At[m][k], acc[ai][bj][m][n], 0, 0, 0); __builtin_amdgcn_s_setprio(0); } while (0)
; #define PG8_WAIT_L(n) asm volatile("s_waitcnt lgkmcnt(" #n ")" ::: "memory")
; #define PG8_BAR __builtin_amdgcn_s_barrier()
; #define PG8_SCHED __builtin_amdgcn_sched_barrier(0)
; template <class Epi>
; __device__ __forceinline__ void gemm_phase(PG8_LAS unsigned char* lds, const Gemm g, const StaticOrder& S, const Epi& E) {
;     ...
;             PG8_LDB(B0, 1, 0); PG8_SCHED; PG8_LDA(At, 1, 0); PG8_STAGE(PG8_SA(0, 1), a2 + hstepA, voffA);
;             PG8_WAIT_L(8); PG8_BAR; PG8_WAIT_L(0); PG8_MMA(0, 0, At, B0); PG8_BAR; PG8_SCHED;
;             PG8_LDB(B1, 1, 1); PG8_STAGE(PG8_SB(1, 0), b3, voffB);
;             PG8_BAR; PG8_WAIT_L(0); PG8_MMA(0, 1, At, B1); PG8_BAR;
;             PG8_LDA(At, 1, 1); PG8_STAGE(PG8_SA(1, 0), a3, voffA);
;             PG8_BAR; PG8_WAIT_L(0); PG8_MMA(1, 0, At, B0); PG8_BAR; PG8_SCHED;
	ds_read_b128 v[128:131], v140
	ds_read_b128 v[132:135], v140 offset:1024
	ds_read_b128 v[136:139], v140 offset:2048
	ds_read_b128 v[140:143], v140 offset:3072
	ds_read_b128 v[144:147], v179 offset:32768
	ds_read_b128 v[164:167], v179 offset:33792
	ds_read_b128 v[170:173], v179 offset:34816
	ds_read_b128 v[182:185], v179 offset:35840
	ds_read_b128 v[186:189], v179 offset:36864
	ds_read_b128 v[190:193], v179 offset:37888
	ds_read_b128 v[194:197], v179 offset:38912
	ds_read_b128 v[198:201], v179 offset:39936
	v_add_u32_e32 v181, 0x1c000, v176
	ds_read_b128 v[202:205], v181
	ds_read_b128 v[206:209], v181 offset:1024
	ds_read_b128 v[210:213], v181 offset:2048
	ds_read_b128 v[214:217], v181 offset:3072
	s_add_u32 s30, s30, 0x40000
	s_addc_u32 s31, s31, 0
	s_mov_b32 m0, s38
	v_lshl_add_u64 v[224:225], s[30:31], 0, v[148:149]
	global_load_lds_dwordx4 v[224:225], off
	v_lshl_add_u64 v[224:225], s[30:31], 0, v[152:153]
	s_mov_b32 m0, s39
	s_nop 0
	global_load_lds_dwordx4 v[224:225], off
	s_waitcnt lgkmcnt(0)
	s_waitcnt vmcnt(8)
	s_barrier
	v_mfma_f32_16x16x32_bf16 v[124:127], v[128:131], v[144:147], v[124:127]
	v_mfma_f32_16x16x32_bf16 v[120:123], v[136:139], v[144:147], v[120:123]
	v_mfma_f32_16x16x32_bf16 v[108:111], v[128:131], v[170:173], v[108:111]
	v_mfma_f32_16x16x32_bf16 v[104:107], v[136:139], v[170:173], v[104:107]
	v_mfma_f32_16x16x32_bf16 v[92:95], v[128:131], v[186:189], v[92:95]
	v_mfma_f32_16x16x32_bf16 v[88:91], v[136:139], v[186:189], v[88:91]
	v_mfma_f32_16x16x32_bf16 v[76:79], v[128:131], v[194:197], v[76:79]
	v_mfma_f32_16x16x32_bf16 v[72:75], v[136:139], v[194:197], v[72:75]
	v_mfma_f32_16x16x32_bf16 v[124:127], v[132:135], v[164:167], v[124:127]
	v_mfma_f32_16x16x32_bf16 v[120:123], v[140:143], v[164:167], v[120:123]
	v_mfma_f32_16x16x32_bf16 v[108:111], v[132:135], v[182:185], v[108:111]
	v_mfma_f32_16x16x32_bf16 v[104:107], v[140:143], v[182:185], v[104:107]
	v_mfma_f32_16x16x32_bf16 v[92:95], v[132:135], v[190:193], v[92:95]
	v_mfma_f32_16x16x32_bf16 v[88:91], v[140:143], v[190:193], v[88:91]
	v_mfma_f32_16x16x32_bf16 v[76:79], v[132:135], v[198:201], v[76:79]
	v_mfma_f32_16x16x32_bf16 v[72:75], v[140:143], v[198:201], v[72:75]
	v_mfma_f32_16x16x32_bf16 v[116:119], v[202:205], v[144:147], v[116:119]
	v_mfma_f32_16x16x32_bf16 v[112:115], v[210:213], v[144:147], v[112:115]
	v_mfma_f32_16x16x32_bf16 v[100:103], v[202:205], v[170:173], v[100:103]
	v_mfma_f32_16x16x32_bf16 v[96:99], v[210:213], v[170:173], v[96:99]
	v_mfma_f32_16x16x32_bf16 v[84:87], v[202:205], v[186:189], v[84:87]
	v_mfma_f32_16x16x32_bf16 v[80:83], v[210:213], v[186:189], v[80:83]
	v_mfma_f32_16x16x32_bf16 v[68:71], v[202:205], v[194:197], v[68:71]
	v_mfma_f32_16x16x32_bf16 v[64:67], v[210:213], v[194:197], v[64:67]
	v_mfma_f32_16x16x32_bf16 v[116:119], v[206:209], v[164:167], v[116:119]
	v_mfma_f32_16x16x32_bf16 v[112:115], v[214:217], v[164:167], v[112:115]
	v_mfma_f32_16x16x32_bf16 v[100:103], v[206:209], v[182:185], v[100:103]
	v_mfma_f32_16x16x32_bf16 v[96:99], v[214:217], v[182:185], v[96:99]
	v_mfma_f32_16x16x32_bf16 v[84:87], v[206:209], v[190:193], v[84:87]
	v_mfma_f32_16x16x32_bf16 v[80:83], v[214:217], v[190:193], v[80:83]
	v_mfma_f32_16x16x32_bf16 v[68:71], v[206:209], v[198:201], v[68:71]
	v_mfma_f32_16x16x32_bf16 v[64:67], v[214:217], v[198:201], v[64:67]
	s_barrier
	ds_read_b128 v[144:147], v179 offset:49152
	ds_read_b128 v[164:167], v179 offset:50176
	ds_read_b128 v[170:173], v179 offset:51200
	ds_read_b128 v[182:185], v179 offset:52224
	ds_read_b128 v[186:189], v179 offset:53248
	ds_read_b128 v[190:193], v179 offset:54272
	ds_read_b128 v[194:197], v179 offset:55296
	ds_read_b128 v[198:201], v179 offset:56320
	s_add_i32 s30, 0, 0x1c000
	s_add_i32 s31, s59, s36
	v_lshl_add_u64 v[174:175], v[174:175], 0, s[0:1]
	s_mov_b32 m0, s31
	s_nop 0
	global_load_lds_dwordx4 v[174:175], off
	v_lshl_add_u64 v[174:175], v[218:219], 0, s[0:1]
	s_add_i32 m0, s31, 0x2000
	s_nop 0
	global_load_lds_dwordx4 v[174:175], off
	s_mov_b32 m0, s41
	v_lshl_add_u64 v[174:175], v[220:221], 0, s[0:1]
	global_load_lds_dwordx4 v[174:175], off
	v_lshl_add_u64 v[174:175], v[222:223], 0, s[0:1]
	s_mov_b32 m0, s42
	s_nop 0
	global_load_lds_dwordx4 v[174:175], off
	s_add_u32 s22, s22, 0x40080
	s_addc_u32 s23, s23, 0
	s_add_i32 s30, s30, s36
	v_lshl_add_u64 v[224:225], s[22:23], 0, v[150:151]
	s_mov_b32 m0, s30
	s_nop 0
	global_load_lds_dwordx4 v[224:225], off
	v_lshl_add_u64 v[224:225], s[22:23], 0, v[154:155]
	s_add_i32 m0, s30, 0x2000
	s_nop 0
	global_load_lds_dwordx4 v[224:225], off
	s_waitcnt lgkmcnt(0)
	s_waitcnt vmcnt(8)
	s_barrier
; __device__ __forceinline__ float sigmoidf_(float x) { return __builtin_amdgcn_rcpf(1.0f + __expf(-x)); }
;     __device__ __forceinline__ void operator()(const f32x4 (&acc)[2][2][4][2], const pg8::Unit& u, int wr, int wc, int fr, int fq) const {
;         const int row0 = u.pm * 256 + wr * 64 + fr, col0 = u.pn * 256 + wc * 32 + 8 * fq;
; #pragma unroll
;         for (int ai = 0; ai < 2; ++ai) {
;             u32x4 la[4][2], lg[4][2];
; #pragma unroll
;             for (int m = 0; m < 4; ++m)
; #pragma unroll
;                 for (int bj = 0; bj < 2; ++bj) { const bf16_t* p = G + (size_t)(row0 + ai * 128 + m * 16) * LDG + col0 + bj * 128;
;                     la[m][bj] = *(const u32x4*)p; if (mode != 0) lg[m][bj] = *(const u32x4*)(p + 2048); else lg[m][bj] = la[m][bj]; }
; #pragma unroll
;             for (int m = 0; m < 4; ++m)
; #pragma unroll
;                 for (int bj = 0; bj < 2; ++bj) {
;                     bf16_t* p = G + (size_t)(row0 + ai * 128 + m * 16) * LDG + col0 + bj * 128;
;                     float a[8], gt[8], o[8];
;                     unpack8(la[m][bj], a);
;                     if (mode == 0) {
; #pragma unroll
;                         for (int n = 0; n < 2; ++n)
; #pragma unroll
;                             for (int i = 0; i < 4; ++i) o[n * 4 + i] = sigmoidf_(a[n * 4 + i]) * acc[ai][bj][m][n][i];
	v_mfma_f32_16x16x32_bf16 v[60:63], v[128:131], v[144:147], v[60:63]
	v_mfma_f32_16x16x32_bf16 v[56:59], v[136:139], v[144:147], v[56:59]
	v_mfma_f32_16x16x32_bf16 v[44:47], v[128:131], v[170:173], v[44:47]
	v_mfma_f32_16x16x32_bf16 v[40:43], v[136:139], v[170:173], v[40:43]
	v_mfma_f32_16x16x32_bf16 v[28:31], v[128:131], v[186:189], v[28:31]
	v_mfma_f32_16x16x32_bf16 v[24:27], v[136:139], v[186:189], v[24:27]
	v_mfma_f32_16x16x32_bf16 v[12:15], v[128:131], v[194:197], v[12:15]
	v_mfma_f32_16x16x32_bf16 v[8:11], v[136:139], v[194:197], v[8:11]
	v_mfma_f32_16x16x32_bf16 v[60:63], v[132:135], v[164:167], v[60:63]
	v_mfma_f32_16x16x32_bf16 v[56:59], v[140:143], v[164:167], v[56:59]
	v_mfma_f32_16x16x32_bf16 v[44:47], v[132:135], v[182:185], v[44:47]
	v_mfma_f32_16x16x32_bf16 v[40:43], v[140:143], v[182:185], v[40:43]
	v_mfma_f32_16x16x32_bf16 v[28:31], v[132:135], v[190:193], v[28:31]
	v_mfma_f32_16x16x32_bf16 v[24:27], v[140:143], v[190:193], v[24:27]
	v_mfma_f32_16x16x32_bf16 v[12:15], v[132:135], v[198:201], v[12:15]
	v_mfma_f32_16x16x32_bf16 v[8:11], v[140:143], v[198:201], v[8:11]
	v_mfma_f32_16x16x32_bf16 v[52:55], v[202:205], v[144:147], v[52:55]
	v_mfma_f32_16x16x32_bf16 v[48:51], v[210:213], v[144:147], v[48:51]
	v_mfma_f32_16x16x32_bf16 v[36:39], v[202:205], v[170:173], v[36:39]
	v_mfma_f32_16x16x32_bf16 v[32:35], v[210:213], v[170:173], v[32:35]
	v_mfma_f32_16x16x32_bf16 v[20:23], v[202:205], v[186:189], v[20:23]
	v_mfma_f32_16x16x32_bf16 v[16:19], v[210:213], v[186:189], v[16:19]
	v_mfma_f32_16x16x32_bf16 v[4:7], v[202:205], v[194:197], v[4:7]
	v_mfma_f32_16x16x32_bf16 v[0:3], v[210:213], v[194:197], v[0:3]
	v_mfma_f32_16x16x32_bf16 v[52:55], v[206:209], v[164:167], v[52:55]
	v_mfma_f32_16x16x32_bf16 v[48:51], v[214:217], v[164:167], v[48:51]
	v_mfma_f32_16x16x32_bf16 v[36:39], v[206:209], v[182:185], v[36:39]
	v_mfma_f32_16x16x32_bf16 v[32:35], v[214:217], v[182:185], v[32:35]
	v_mfma_f32_16x16x32_bf16 v[20:23], v[206:209], v[190:193], v[20:23]
	v_mfma_f32_16x16x32_bf16 v[16:19], v[214:217], v[190:193], v[16:19]
	v_mfma_f32_16x16x32_bf16 v[4:7], v[206:209], v[198:201], v[4:7]
	v_mfma_f32_16x16x32_bf16 v[0:3], v[214:217], v[198:201], v[0:3]
	s_add_i32 s58, s58, 2
	s_add_u32 s28, s28, 0x100
	s_addc_u32 s29, s29, 0
	s_add_u32 s56, s56, 0x100
	s_addc_u32 s57, s57, 0
	s_cmp_gt_u32 s58, 13
	s_barrier
	s_cbranch_scc0 .LBB0_904
	s_setprio 0
	v_lshl_or_b32 v130, s53, 8, v177
	v_lshl_add_u32 v128, s20, 8, v169
	v_ashrrev_i32_e32 v131, 31, v130
	v_lshlrev_b64 v[164:165], 1, v[130:131]
	v_ashrrev_i32_e32 v129, 31, v128
	v_lshl_add_u64 v[166:167], s[46:47], 0, v[164:165]
	v_lshlrev_b64 v[170:171], 13, v[128:129]
	v_lshl_add_u64 v[130:131], v[166:167], 0, v[170:171]
	global_load_dwordx4 v[182:185], v[130:131], off
	global_load_dwordx4 v[186:189], v[130:131], off offset:256
	v_or_b32_e32 v130, 16, v128
	v_or_b32_e32 v132, 32, v128
	v_or_b32_e32 v128, 48, v128
	v_ashrrev_i32_e32 v131, 31, v130
	v_ashrrev_i32_e32 v133, 31, v132
	v_ashrrev_i32_e32 v129, 31, v128
	v_lshlrev_b64 v[194:195], 13, v[130:131]
	v_lshlrev_b64 v[174:175], 13, v[132:133]
	v_lshlrev_b64 v[172:173], 13, v[128:129]
	v_lshl_add_u64 v[128:129], s[46:47], 0, v[170:171]
	v_lshl_add_u64 v[130:131], v[166:167], 0, v[194:195]
	v_lshl_add_u64 v[132:133], v[166:167], 0, v[174:175]
	v_lshl_add_u64 v[196:197], v[166:167], 0, v[172:173]
	v_lshl_add_u64 v[198:199], v[128:129], 0, v[164:165]
	global_load_dwordx4 v[190:193], v[130:131], off
	global_load_dwordx4 v[144:147], v[130:131], off offset:256
	global_load_dwordx4 v[140:143], v[132:133], off
	global_load_dwordx4 v[136:139], v[132:133], off offset:256
	s_nop 0
	global_load_dwordx4 v[132:135], v[196:197], off
	global_load_dwordx4 v[128:131], v[196:197], off offset:256
	s_and_b64 vcc, exec, s[2:3]
	s_mov_b32 s53, s12
	s_mov_b32 s20, s14
	s_mov_b64 s[22:23], s[18:19]
	s_mov_b64 s[28:29], s[16:17]
	s_waitcnt vmcnt(0)
	v_lshlrev_b32_e32 v181, 16, v182
	v_and_b32_e32 v182, 0xffff0000, v182
	v_lshlrev_b32_e32 v196, 16, v183
	v_and_b32_e32 v183, 0xffff0000, v183
	v_lshlrev_b32_e32 v197, 16, v184
	v_and_b32_e32 v184, 0xffff0000, v184
	v_lshlrev_b32_e32 v200, 16, v185
	v_and_b32_e32 v185, 0xffff0000, v185
	v_mul_f32_e32 v181, 0xbfb8aa3b, v181
	v_mul_f32_e32 v182, 0xbfb8aa3b, v182
	v_mul_f32_e32 v196, 0xbfb8aa3b, v196
	v_mul_f32_e32 v183, 0xbfb8aa3b, v183
	v_mul_f32_e32 v197, 0xbfb8aa3b, v197
	v_mul_f32_e32 v184, 0xbfb8aa3b, v184
	v_mul_f32_e32 v200, 0xbfb8aa3b, v200
	v_mul_f32_e32 v185, 0xbfb8aa3b, v185
	v_exp_f32_e32 v181, v181
	v_exp_f32_e32 v182, v182
	v_exp_f32_e32 v196, v196
	v_exp_f32_e32 v183, v183
	v_exp_f32_e32 v197, v197
	v_exp_f32_e32 v184, v184
	v_exp_f32_e32 v200, v200
	v_exp_f32_e32 v185, v185
	v_lshlrev_b32_e32 v201, 16, v186
	v_and_b32_e32 v186, 0xffff0000, v186
	v_lshlrev_b32_e32 v202, 16, v187
	v_add_f32_e32 v181, 1.0, v181
	v_add_f32_e32 v182, 1.0, v182
	v_add_f32_e32 v196, 1.0, v196
	v_add_f32_e32 v183, 1.0, v183
	v_add_f32_e32 v197, 1.0, v197
	v_add_f32_e32 v184, 1.0, v184
	v_add_f32_e32 v200, 1.0, v200
	v_add_f32_e32 v185, 1.0, v185
	v_mul_f32_e32 v186, 0xbfb8aa3b, v186
	v_mul_f32_e32 v202, 0xbfb8aa3b, v202
	v_rcp_f32_e32 v181, v181
	v_rcp_f32_e32 v182, v182
	v_rcp_f32_e32 v196, v196
	v_rcp_f32_e32 v183, v183
	v_rcp_f32_e32 v197, v197
	v_rcp_f32_e32 v184, v184
	v_rcp_f32_e32 v200, v200
	v_rcp_f32_e32 v185, v185
	v_exp_f32_e32 v186, v186
	v_exp_f32_e32 v202, v202
	v_and_b32_e32 v187, 0xffff0000, v187
	v_mul_f32_e32 v124, v124, v181
	v_mul_f32_e32 v125, v125, v182
	v_mul_f32_e32 v126, v126, v196
	v_mul_f32_e32 v127, v127, v183
	v_mul_f32_e32 v181, v120, v197
	v_mul_f32_e32 v182, v121, v184
	v_mul_f32_e32 v183, v122, v200
; __device__ __forceinline__ float sigmoidf_(float x) { return __builtin_amdgcn_rcpf(1.0f + __expf(-x)); }
; __device__ __forceinline__ u32x4 pack8(const float (&f)[8]) { u32x4 w; w.x = cvt_pk_bf16(f[0], f[1]); w.y = cvt_pk_bf16(f[2], f[3]); w.z = cvt_pk_bf16(f[4], f[5]); w.w = cvt_pk_bf16(f[6], f[7]); return w; }
;     __device__ __forceinline__ void operator()(const f32x4 (&acc)[2][2][4][2], const pg8::Unit& u, int wr, int wc, int fr, int fq) const {
;     ...
;             for (int m = 0; m < 4; ++m)
; #pragma unroll
;                 for (int bj = 0; bj < 2; ++bj) {
;                     bf16_t* p = G + (size_t)(row0 + ai * 128 + m * 16) * LDG + col0 + bj * 128;
;                     float a[8], gt[8], o[8];
;                     unpack8(la[m][bj], a);
;                     if (mode == 0) {
; #pragma unroll
;                         for (int n = 0; n < 2; ++n)
; #pragma unroll
;                             for (int i = 0; i < 4; ++i) o[n * 4 + i] = sigmoidf_(a[n * 4 + i]) * acc[ai][bj][m][n][i];
;                     } else {
;                         unpack8(lg[m][bj], gt);
; #pragma unroll
;                         for (int n = 0; n < 2; ++n)
; #pragma unroll
;                             for (int i = 0; i < 4; ++i) o[n * 4 + i] = a[n * 4 + i] + sigmoidf_(gt[n * 4 + i]) * acc[ai][bj][m][n][i];
;                     }
;                     *(u32x4*)p = pack8(o);
	v_mul_f32_e32 v123, v123, v185
	v_cvt_pk_bf16_f32 v120, v124, v125
	v_cvt_pk_bf16_f32 v121, v126, v127
	v_cvt_pk_bf16_f32 v122, v181, v182
	v_cvt_pk_bf16_f32 v123, v183, v123
	global_store_dwordx4 v[198:199], v[120:123], off
	v_lshlrev_b32_e32 v203, 16, v188
	v_and_b32_e32 v188, 0xffff0000, v188
	v_add_f32_e32 v120, 1.0, v186
	v_add_f32_e32 v121, 1.0, v202
	v_mul_f32_e32 v122, 0xbfb8aa3b, v187
	v_rcp_f32_e32 v120, v120
	v_rcp_f32_e32 v121, v121
	v_exp_f32_e32 v122, v122
	v_lshlrev_b32_e32 v204, 16, v189
	v_mul_f32_e32 v117, v117, v120
	v_mul_f32_e32 v118, v118, v121
	v_add_f32_e32 v120, 1.0, v122
	v_mul_f32_e32 v121, 0xbfb8aa3b, v203
	v_mul_f32_e32 v122, 0xbfb8aa3b, v188
	v_rcp_f32_e32 v120, v120
	v_exp_f32_e32 v121, v121
	v_exp_f32_e32 v122, v122
	v_and_b32_e32 v189, 0xffff0000, v189
	v_mul_f32_e32 v123, 0xbfb8aa3b, v189
	v_mul_f32_e32 v201, 0xbfb8aa3b, v201
	v_mul_f32_e32 v119, v119, v120
	v_add_f32_e32 v120, 1.0, v121
	v_add_f32_e32 v121, 1.0, v122
	v_mul_f32_e32 v122, 0xbfb8aa3b, v204
	v_exp_f32_e32 v123, v123
	v_exp_f32_e32 v201, v201
	v_exp_f32_e32 v122, v122
	v_rcp_f32_e32 v120, v120
	v_add_f32_e32 v123, 1.0, v123
	v_add_f32_e32 v201, 1.0, v201
	v_add_f32_e32 v122, 1.0, v122
	v_rcp_f32_e32 v123, v123
	v_rcp_f32_e32 v201, v201
	v_rcp_f32_e32 v121, v121
	v_rcp_f32_e32 v122, v122
	v_mul_f32_e32 v115, v115, v123
	v_mul_f32_e32 v116, v116, v201
	v_mul_f32_e32 v120, v112, v120
	v_mul_f32_e32 v121, v113, v121
	v_mul_f32_e32 v122, v114, v122
	v_cvt_pk_bf16_f32 v112, v116, v117
	v_cvt_pk_bf16_f32 v113, v118, v119
	v_cvt_pk_bf16_f32 v114, v120, v121
	v_cvt_pk_bf16_f32 v115, v122, v115
	global_store_dwordx4 v[198:199], v[112:115], off offset:256
	v_lshlrev_b32_e32 v116, 16, v191
	v_mul_f32_e32 v116, 0xbfb8aa3b, v116
	v_lshlrev_b32_e32 v114, 16, v190
	v_and_b32_e32 v115, 0xffff0000, v190
	v_mul_f32_e32 v114, 0xbfb8aa3b, v114
	v_mul_f32_e32 v115, 0xbfb8aa3b, v115
	v_exp_f32_e32 v114, v114
	v_exp_f32_e32 v115, v115
	v_exp_f32_e32 v116, v116
	v_and_b32_e32 v117, 0xffff0000, v191
	v_add_f32_e32 v114, 1.0, v114
	v_add_f32_e32 v115, 1.0, v115
	v_add_f32_e32 v116, 1.0, v116
	v_mul_f32_e32 v117, 0xbfb8aa3b, v117
	v_rcp_f32_e32 v114, v114
	v_rcp_f32_e32 v115, v115
	v_rcp_f32_e32 v116, v116
	v_exp_f32_e32 v117, v117
	v_lshlrev_b32_e32 v118, 16, v192
	v_and_b32_e32 v119, 0xffff0000, v192
	v_mul_f32_e32 v108, v108, v114
	v_mul_f32_e32 v109, v109, v115
	v_mul_f32_e32 v110, v110, v116
	v_add_f32_e32 v114, 1.0, v117
	v_mul_f32_e32 v115, 0xbfb8aa3b, v118
	v_mul_f32_e32 v116, 0xbfb8aa3b, v119
	v_rcp_f32_e32 v114, v114
	v_exp_f32_e32 v115, v115
	v_exp_f32_e32 v116, v116
	v_lshlrev_b32_e32 v120, 16, v193
	v_and_b32_e32 v121, 0xffff0000, v193
	v_mul_f32_e32 v111, v111, v114
	v_add_f32_e32 v114, 1.0, v115
	v_add_f32_e32 v115, 1.0, v116
	v_mul_f32_e32 v116, 0xbfb8aa3b, v120
	v_mul_f32_e32 v117, 0xbfb8aa3b, v121
	v_exp_f32_e32 v116, v116
	v_exp_f32_e32 v117, v117
	v_rcp_f32_e32 v114, v114
	v_rcp_f32_e32 v115, v115
	v_add_f32_e32 v116, 1.0, v116
	v_add_f32_e32 v117, 1.0, v117
	v_rcp_f32_e32 v116, v116
	v_rcp_f32_e32 v117, v117
	v_lshl_add_u64 v[112:113], s[46:47], 0, v[194:195]
	v_lshl_add_u64 v[112:113], v[112:113], 0, v[164:165]
	v_mul_f32_e32 v114, v104, v114
	v_mul_f32_e32 v115, v105, v115
	v_mul_f32_e32 v116, v106, v116
	v_mul_f32_e32 v107, v107, v117
	v_cvt_pk_bf16_f32 v104, v108, v109
	v_cvt_pk_bf16_f32 v105, v110, v111
	v_cvt_pk_bf16_f32 v106, v114, v115
	v_cvt_pk_bf16_f32 v107, v116, v107
	global_store_dwordx4 v[112:113], v[104:107], off
	v_lshlrev_b32_e32 v108, 16, v146
	v_and_b32_e32 v109, 0xffff0000, v146
	v_lshlrev_b32_e32 v104, 16, v144
	v_and_b32_e32 v105, 0xffff0000, v144
	v_lshlrev_b32_e32 v106, 16, v145
	v_mul_f32_e32 v104, 0xbfb8aa3b, v104
	v_mul_f32_e32 v105, 0xbfb8aa3b, v105
	v_mul_f32_e32 v106, 0xbfb8aa3b, v106
	v_exp_f32_e32 v104, v104
	v_exp_f32_e32 v105, v105
	v_exp_f32_e32 v106, v106
	v_and_b32_e32 v107, 0xffff0000, v145
	v_add_f32_e32 v104, 1.0, v104
	v_add_f32_e32 v105, 1.0, v105
	v_add_f32_e32 v106, 1.0, v106
	v_mul_f32_e32 v107, 0xbfb8aa3b, v107
	v_rcp_f32_e32 v104, v104
	v_rcp_f32_e32 v105, v105
	v_rcp_f32_e32 v106, v106
	v_exp_f32_e32 v107, v107
	v_mul_f32_e32 v100, v100, v104
	v_mul_f32_e32 v101, v101, v105
	v_mul_f32_e32 v102, v102, v106
	v_add_f32_e32 v104, 1.0, v107
	v_mul_f32_e32 v105, 0xbfb8aa3b, v108
	v_mul_f32_e32 v106, 0xbfb8aa3b, v109
	v_rcp_f32_e32 v104, v104
	v_exp_f32_e32 v105, v105
	v_exp_f32_e32 v106, v106
	v_and_b32_e32 v111, 0xffff0000, v147
	v_lshlrev_b32_e32 v110, 16, v147
	v_mul_f32_e32 v107, 0xbfb8aa3b, v111
	v_mul_f32_e32 v103, v103, v104
	v_add_f32_e32 v104, 1.0, v105
	v_add_f32_e32 v105, 1.0, v106
	v_mul_f32_e32 v106, 0xbfb8aa3b, v110
	v_exp_f32_e32 v107, v107
	v_exp_f32_e32 v106, v106
	v_rcp_f32_e32 v104, v104
	v_rcp_f32_e32 v105, v105
	v_add_f32_e32 v107, 1.0, v107
	v_add_f32_e32 v106, 1.0, v106
	v_rcp_f32_e32 v107, v107
	v_rcp_f32_e32 v106, v106
	v_mul_f32_e32 v104, v96, v104
	v_mul_f32_e32 v105, v97, v105
	v_mul_f32_e32 v99, v99, v107
	v_mul_f32_e32 v106, v98, v106
	v_cvt_pk_bf16_f32 v96, v100, v101
	v_cvt_pk_bf16_f32 v97, v102, v103
	v_cvt_pk_bf16_f32 v98, v104, v105
	v_cvt_pk_bf16_f32 v99, v106, v99
	global_store_dwordx4 v[112:113], v[96:99], off offset:256
	v_lshlrev_b32_e32 v100, 16, v141
	v_mul_f32_e32 v100, 0xbfb8aa3b, v100
	v_lshlrev_b32_e32 v98, 16, v140
	v_and_b32_e32 v99, 0xffff0000, v140
	v_mul_f32_e32 v98, 0xbfb8aa3b, v98
	v_mul_f32_e32 v99, 0xbfb8aa3b, v99
	v_exp_f32_e32 v98, v98
	v_exp_f32_e32 v99, v99
	v_exp_f32_e32 v100, v100
	v_and_b32_e32 v101, 0xffff0000, v141
	v_add_f32_e32 v98, 1.0, v98
	v_add_f32_e32 v99, 1.0, v99
	v_add_f32_e32 v100, 1.0, v100
	v_mul_f32_e32 v101, 0xbfb8aa3b, v101
; __device__ __forceinline__ float sigmoidf_(float x) { return __builtin_amdgcn_rcpf(1.0f + __expf(-x)); }
; __device__ __forceinline__ u32x4 pack8(const float (&f)[8]) { u32x4 w; w.x = cvt_pk_bf16(f[0], f[1]); w.y = cvt_pk_bf16(f[2], f[3]); w.z = cvt_pk_bf16(f[4], f[5]); w.w = cvt_pk_bf16(f[6], f[7]); return w; }
;     __device__ __forceinline__ void operator()(const f32x4 (&acc)[2][2][4][2], const pg8::Unit& u, int wr, int wc, int fr, int fq) const {
;     ...
;             for (int m = 0; m < 4; ++m)
; #pragma unroll
;                 for (int bj = 0; bj < 2; ++bj) {
;                     bf16_t* p = G + (size_t)(row0 + ai * 128 + m * 16) * LDG + col0 + bj * 128;
;                     float a[8], gt[8], o[8];
;                     unpack8(la[m][bj], a);
;                     if (mode == 0) {
; #pragma unroll
;                         for (int n = 0; n < 2; ++n)
; #pragma unroll
;                             for (int i = 0; i < 4; ++i) o[n * 4 + i] = sigmoidf_(a[n * 4 + i]) * acc[ai][bj][m][n][i];
;                     } else {
;                         unpack8(lg[m][bj], gt);
; #pragma unroll
;                         for (int n = 0; n < 2; ++n)
; #pragma unroll
;                             for (int i = 0; i < 4; ++i) o[n * 4 + i] = a[n * 4 + i] + sigmoidf_(gt[n * 4 + i]) * acc[ai][bj][m][n][i];
;                     }
;                     *(u32x4*)p = pack8(o);
	v_rcp_f32_e32 v98, v98
	v_rcp_f32_e32 v99, v99
	v_rcp_f32_e32 v100, v100
	v_exp_f32_e32 v101, v101
	v_lshlrev_b32_e32 v102, 16, v142
	v_and_b32_e32 v103, 0xffff0000, v142
	v_mul_f32_e32 v92, v92, v98
	v_mul_f32_e32 v93, v93, v99
	v_mul_f32_e32 v94, v94, v100
	v_add_f32_e32 v98, 1.0, v101
	v_mul_f32_e32 v99, 0xbfb8aa3b, v102
	v_mul_f32_e32 v100, 0xbfb8aa3b, v103
	v_rcp_f32_e32 v98, v98
	v_exp_f32_e32 v99, v99
	v_exp_f32_e32 v100, v100
	v_lshlrev_b32_e32 v104, 16, v143
	v_and_b32_e32 v105, 0xffff0000, v143
	v_mul_f32_e32 v95, v95, v98
	v_add_f32_e32 v98, 1.0, v99
	v_add_f32_e32 v99, 1.0, v100
	v_mul_f32_e32 v100, 0xbfb8aa3b, v104
	v_mul_f32_e32 v101, 0xbfb8aa3b, v105
	v_exp_f32_e32 v100, v100
	v_exp_f32_e32 v101, v101
	v_rcp_f32_e32 v98, v98
	v_rcp_f32_e32 v99, v99
	v_add_f32_e32 v100, 1.0, v100
	v_add_f32_e32 v101, 1.0, v101
	v_rcp_f32_e32 v100, v100
	v_rcp_f32_e32 v101, v101
	v_lshl_add_u64 v[96:97], s[46:47], 0, v[174:175]
	v_lshl_add_u64 v[96:97], v[96:97], 0, v[164:165]
	v_mul_f32_e32 v98, v88, v98
	v_mul_f32_e32 v99, v89, v99
	v_mul_f32_e32 v100, v90, v100
	v_mul_f32_e32 v91, v91, v101
	v_cvt_pk_bf16_f32 v88, v92, v93
	v_cvt_pk_bf16_f32 v89, v94, v95
	v_cvt_pk_bf16_f32 v90, v98, v99
	v_cvt_pk_bf16_f32 v91, v100, v91
	global_store_dwordx4 v[96:97], v[88:91], off
	v_lshlrev_b32_e32 v92, 16, v138
	v_and_b32_e32 v93, 0xffff0000, v138
	v_lshlrev_b32_e32 v88, 16, v136
	v_and_b32_e32 v89, 0xffff0000, v136
	v_lshlrev_b32_e32 v90, 16, v137
	v_mul_f32_e32 v88, 0xbfb8aa3b, v88
	v_mul_f32_e32 v89, 0xbfb8aa3b, v89
	v_mul_f32_e32 v90, 0xbfb8aa3b, v90
	v_exp_f32_e32 v88, v88
	v_exp_f32_e32 v89, v89
	v_exp_f32_e32 v90, v90
	v_and_b32_e32 v91, 0xffff0000, v137
	v_add_f32_e32 v88, 1.0, v88
	v_add_f32_e32 v89, 1.0, v89
	v_add_f32_e32 v90, 1.0, v90
	v_mul_f32_e32 v91, 0xbfb8aa3b, v91
	v_rcp_f32_e32 v88, v88
	v_rcp_f32_e32 v89, v89
	v_rcp_f32_e32 v90, v90
	v_exp_f32_e32 v91, v91
	v_mul_f32_e32 v84, v84, v88
	v_mul_f32_e32 v85, v85, v89
	v_mul_f32_e32 v86, v86, v90
	v_add_f32_e32 v88, 1.0, v91
	v_mul_f32_e32 v89, 0xbfb8aa3b, v92
	v_mul_f32_e32 v90, 0xbfb8aa3b, v93
	v_rcp_f32_e32 v88, v88
	v_exp_f32_e32 v89, v89
	v_exp_f32_e32 v90, v90
	v_and_b32_e32 v95, 0xffff0000, v139
	v_lshlrev_b32_e32 v94, 16, v139
	v_mul_f32_e32 v91, 0xbfb8aa3b, v95
	v_mul_f32_e32 v87, v87, v88
	v_add_f32_e32 v88, 1.0, v89
	v_add_f32_e32 v89, 1.0, v90
	v_mul_f32_e32 v90, 0xbfb8aa3b, v94
	v_exp_f32_e32 v91, v91
	v_exp_f32_e32 v90, v90
	v_rcp_f32_e32 v88, v88
	v_rcp_f32_e32 v89, v89
	v_add_f32_e32 v91, 1.0, v91
	v_add_f32_e32 v90, 1.0, v90
	v_rcp_f32_e32 v91, v91
	v_rcp_f32_e32 v90, v90
	v_mul_f32_e32 v88, v80, v88
	v_mul_f32_e32 v89, v81, v89
	v_mul_f32_e32 v83, v83, v91
	v_mul_f32_e32 v90, v82, v90
	v_cvt_pk_bf16_f32 v80, v84, v85
	v_cvt_pk_bf16_f32 v81, v86, v87
	v_cvt_pk_bf16_f32 v82, v88, v89
	v_cvt_pk_bf16_f32 v83, v90, v83
	global_store_dwordx4 v[96:97], v[80:83], off offset:256
	v_lshlrev_b32_e32 v84, 16, v133
	v_mul_f32_e32 v84, 0xbfb8aa3b, v84
	v_lshlrev_b32_e32 v82, 16, v132
	v_and_b32_e32 v83, 0xffff0000, v132
	v_mul_f32_e32 v82, 0xbfb8aa3b, v82
	v_mul_f32_e32 v83, 0xbfb8aa3b, v83
	v_exp_f32_e32 v82, v82
	v_exp_f32_e32 v83, v83
	v_exp_f32_e32 v84, v84
	v_and_b32_e32 v85, 0xffff0000, v133
	v_add_f32_e32 v82, 1.0, v82
	v_add_f32_e32 v83, 1.0, v83
	v_add_f32_e32 v84, 1.0, v84
	v_mul_f32_e32 v85, 0xbfb8aa3b, v85
	v_rcp_f32_e32 v82, v82
	v_rcp_f32_e32 v83, v83
	v_rcp_f32_e32 v84, v84
	v_exp_f32_e32 v85, v85
	v_lshlrev_b32_e32 v86, 16, v134
	v_and_b32_e32 v87, 0xffff0000, v134
	v_mul_f32_e32 v76, v76, v82
	v_mul_f32_e32 v77, v77, v83
	v_mul_f32_e32 v78, v78, v84
	v_add_f32_e32 v82, 1.0, v85
	v_mul_f32_e32 v83, 0xbfb8aa3b, v86
	v_mul_f32_e32 v84, 0xbfb8aa3b, v87
	v_rcp_f32_e32 v82, v82
	v_exp_f32_e32 v83, v83
	v_exp_f32_e32 v84, v84
	v_lshlrev_b32_e32 v88, 16, v135
	v_and_b32_e32 v89, 0xffff0000, v135
	v_mul_f32_e32 v79, v79, v82
	v_add_f32_e32 v82, 1.0, v83
	v_add_f32_e32 v83, 1.0, v84
	v_mul_f32_e32 v84, 0xbfb8aa3b, v88
	v_mul_f32_e32 v85, 0xbfb8aa3b, v89
	v_exp_f32_e32 v84, v84
	v_exp_f32_e32 v85, v85
	v_rcp_f32_e32 v82, v82
	v_rcp_f32_e32 v83, v83
	v_add_f32_e32 v84, 1.0, v84
	v_add_f32_e32 v85, 1.0, v85
	v_rcp_f32_e32 v84, v84
	v_rcp_f32_e32 v85, v85
	v_lshl_add_u64 v[80:81], s[46:47], 0, v[172:173]
	v_lshl_add_u64 v[80:81], v[80:81], 0, v[164:165]
	v_mul_f32_e32 v82, v72, v82
	v_mul_f32_e32 v83, v73, v83
	v_mul_f32_e32 v84, v74, v84
	v_mul_f32_e32 v75, v75, v85
	v_cvt_pk_bf16_f32 v72, v76, v77
	v_cvt_pk_bf16_f32 v73, v78, v79
	v_cvt_pk_bf16_f32 v74, v82, v83
	v_cvt_pk_bf16_f32 v75, v84, v75
	global_store_dwordx4 v[80:81], v[72:75], off
	v_lshlrev_b32_e32 v76, 16, v130
	v_and_b32_e32 v77, 0xffff0000, v130
	v_lshlrev_b32_e32 v72, 16, v128
	v_and_b32_e32 v73, 0xffff0000, v128
	v_lshlrev_b32_e32 v74, 16, v129
	v_mul_f32_e32 v72, 0xbfb8aa3b, v72
	v_mul_f32_e32 v73, 0xbfb8aa3b, v73
	v_mul_f32_e32 v74, 0xbfb8aa3b, v74
	v_exp_f32_e32 v72, v72
	v_exp_f32_e32 v73, v73
	v_exp_f32_e32 v74, v74
	v_and_b32_e32 v75, 0xffff0000, v129
	v_add_f32_e32 v72, 1.0, v72
	v_add_f32_e32 v73, 1.0, v73
	v_add_f32_e32 v74, 1.0, v74
	v_mul_f32_e32 v75, 0xbfb8aa3b, v75
	v_rcp_f32_e32 v72, v72
	v_rcp_f32_e32 v73, v73
	v_rcp_f32_e32 v74, v74
	v_exp_f32_e32 v75, v75
	v_mul_f32_e32 v68, v68, v72
	v_mul_f32_e32 v69, v69, v73
	v_mul_f32_e32 v70, v70, v74
	v_add_f32_e32 v72, 1.0, v75
	v_mul_f32_e32 v73, 0xbfb8aa3b, v76
	v_mul_f32_e32 v74, 0xbfb8aa3b, v77
	v_rcp_f32_e32 v72, v72
	v_exp_f32_e32 v73, v73
	v_exp_f32_e32 v74, v74
	v_and_b32_e32 v79, 0xffff0000, v131
	v_lshlrev_b32_e32 v78, 16, v131
	v_mul_f32_e32 v75, 0xbfb8aa3b, v79
	v_mul_f32_e32 v71, v71, v72
	v_add_f32_e32 v72, 1.0, v73
	v_add_f32_e32 v73, 1.0, v74
; __device__ __forceinline__ float sigmoidf_(float x) { return __builtin_amdgcn_rcpf(1.0f + __expf(-x)); }
; __device__ __forceinline__ u32x4 pack8(const float (&f)[8]) { u32x4 w; w.x = cvt_pk_bf16(f[0], f[1]); w.y = cvt_pk_bf16(f[2], f[3]); w.z = cvt_pk_bf16(f[4], f[5]); w.w = cvt_pk_bf16(f[6], f[7]); return w; }
;     __device__ __forceinline__ void operator()(const f32x4 (&acc)[2][2][4][2], const pg8::Unit& u, int wr, int wc, int fr, int fq) const {
;     ...
;         for (int ai = 0; ai < 2; ++ai) {
;             u32x4 la[4][2], lg[4][2];
; #pragma unroll
;             for (int m = 0; m < 4; ++m)
; #pragma unroll
;                 for (int bj = 0; bj < 2; ++bj) { const bf16_t* p = G + (size_t)(row0 + ai * 128 + m * 16) * LDG + col0 + bj * 128;
;                     la[m][bj] = *(const u32x4*)p; if (mode != 0) lg[m][bj] = *(const u32x4*)(p + 2048); else lg[m][bj] = la[m][bj]; }
; #pragma unroll
;             for (int m = 0; m < 4; ++m)
; #pragma unroll
;                 for (int bj = 0; bj < 2; ++bj) {
;                     bf16_t* p = G + (size_t)(row0 + ai * 128 + m * 16) * LDG + col0 + bj * 128;
;                     float a[8], gt[8], o[8];
;                     unpack8(la[m][bj], a);
;                     if (mode == 0) {
; #pragma unroll
;                         for (int n = 0; n < 2; ++n)
; #pragma unroll
;                             for (int i = 0; i < 4; ++i) o[n * 4 + i] = sigmoidf_(a[n * 4 + i]) * acc[ai][bj][m][n][i];
;                     } else {
;                         unpack8(lg[m][bj], gt);
; #pragma unroll
;                         for (int n = 0; n < 2; ++n)
; #pragma unroll
;                             for (int i = 0; i < 4; ++i) o[n * 4 + i] = a[n * 4 + i] + sigmoidf_(gt[n * 4 + i]) * acc[ai][bj][m][n][i];
;                     }
;                     *(u32x4*)p = pack8(o);
	v_mul_f32_e32 v74, 0xbfb8aa3b, v78
	v_exp_f32_e32 v75, v75
	v_exp_f32_e32 v74, v74
	v_rcp_f32_e32 v72, v72
	v_rcp_f32_e32 v73, v73
	v_add_f32_e32 v75, 1.0, v75
	v_add_f32_e32 v74, 1.0, v74
	v_rcp_f32_e32 v75, v75
	v_rcp_f32_e32 v74, v74
	v_lshl_add_u64 v[100:101], v[170:171], 0, s[4:5]
	v_mul_f32_e32 v72, v64, v72
	v_mul_f32_e32 v67, v67, v75
	v_cvt_pk_bf16_f32 v64, v68, v69
	v_lshl_add_u64 v[68:69], v[166:167], 0, v[100:101]
	v_mul_f32_e32 v73, v65, v73
	v_mul_f32_e32 v74, v66, v74
	v_cvt_pk_bf16_f32 v65, v70, v71
	v_cvt_pk_bf16_f32 v66, v72, v73
	v_cvt_pk_bf16_f32 v67, v74, v67
	global_load_dwordx4 v[84:87], v[68:69], off
	global_load_dwordx4 v[88:91], v[68:69], off offset:256
	v_lshl_add_u64 v[102:103], v[170:171], 0, s[6:7]
	global_store_dwordx4 v[80:81], v[64:67], off offset:256
	v_lshl_add_u64 v[82:83], v[170:171], 0, s[8:9]
	v_lshl_add_u64 v[80:81], v[170:171], 0, s[10:11]
	v_lshl_add_u64 v[64:65], v[166:167], 0, v[102:103]
	global_load_dwordx4 v[92:95], v[64:65], off
	global_load_dwordx4 v[96:99], v[64:65], off offset:256
	v_lshl_add_u64 v[64:65], v[166:167], 0, v[82:83]
	global_load_dwordx4 v[76:79], v[64:65], off
	global_load_dwordx4 v[72:75], v[64:65], off offset:256
	v_lshl_add_u64 v[64:65], v[166:167], 0, v[80:81]
	v_lshl_add_u64 v[100:101], s[46:47], 0, v[100:101]
	global_load_dwordx4 v[68:71], v[64:65], off
	s_nop 0
	global_load_dwordx4 v[64:67], v[64:65], off offset:256
	v_lshl_add_u64 v[100:101], v[100:101], 0, v[164:165]
	s_waitcnt vmcnt(0)
	v_lshlrev_b32_e32 v104, 16, v84
	v_and_b32_e32 v84, 0xffff0000, v84
	v_mul_f32_e32 v84, 0xbfb8aa3b, v84
	v_exp_f32_e32 v84, v84
	v_lshlrev_b32_e32 v105, 16, v85
	v_and_b32_e32 v85, 0xffff0000, v85
	v_mul_f32_e32 v85, 0xbfb8aa3b, v85
	v_add_f32_e32 v84, 1.0, v84
	v_rcp_f32_e32 v84, v84
	v_exp_f32_e32 v85, v85
	v_lshlrev_b32_e32 v106, 16, v86
	v_and_b32_e32 v86, 0xffff0000, v86
	v_mul_f32_e32 v61, v61, v84
	v_add_f32_e32 v84, 1.0, v85
	v_mul_f32_e32 v85, 0xbfb8aa3b, v106
	v_mul_f32_e32 v86, 0xbfb8aa3b, v86
	v_rcp_f32_e32 v84, v84
	v_exp_f32_e32 v85, v85
	v_exp_f32_e32 v86, v86
	v_lshlrev_b32_e32 v107, 16, v87
	v_and_b32_e32 v87, 0xffff0000, v87
	v_mul_f32_e32 v104, 0xbfb8aa3b, v104
	v_mul_f32_e32 v105, 0xbfb8aa3b, v105
	v_mul_f32_e32 v63, v63, v84
	v_add_f32_e32 v84, 1.0, v85
	v_add_f32_e32 v85, 1.0, v86
	v_mul_f32_e32 v86, 0xbfb8aa3b, v107
	v_mul_f32_e32 v87, 0xbfb8aa3b, v87
	v_exp_f32_e32 v104, v104
	v_exp_f32_e32 v105, v105
	v_exp_f32_e32 v86, v86
	v_exp_f32_e32 v87, v87
	v_add_f32_e32 v104, 1.0, v104
	v_add_f32_e32 v105, 1.0, v105
	v_add_f32_e32 v86, 1.0, v86
	v_add_f32_e32 v87, 1.0, v87
	v_rcp_f32_e32 v104, v104
	v_rcp_f32_e32 v105, v105
	v_rcp_f32_e32 v84, v84
	v_rcp_f32_e32 v85, v85
	v_rcp_f32_e32 v86, v86
	v_rcp_f32_e32 v87, v87
	v_mul_f32_e32 v60, v60, v104
	v_mul_f32_e32 v62, v62, v105
	v_mul_f32_e32 v84, v56, v84
	v_mul_f32_e32 v85, v57, v85
	v_mul_f32_e32 v86, v58, v86
	v_mul_f32_e32 v59, v59, v87
	v_cvt_pk_bf16_f32 v56, v60, v61
	v_cvt_pk_bf16_f32 v57, v62, v63
	v_cvt_pk_bf16_f32 v58, v84, v85
	v_cvt_pk_bf16_f32 v59, v86, v59
	global_store_dwordx4 v[100:101], v[56:59], off
	v_lshlrev_b32_e32 v60, 16, v90
	v_and_b32_e32 v61, 0xffff0000, v90
	v_lshlrev_b32_e32 v56, 16, v88
	v_and_b32_e32 v57, 0xffff0000, v88
	v_lshlrev_b32_e32 v58, 16, v89
	v_mul_f32_e32 v56, 0xbfb8aa3b, v56
	v_mul_f32_e32 v57, 0xbfb8aa3b, v57
	v_mul_f32_e32 v58, 0xbfb8aa3b, v58
	v_exp_f32_e32 v56, v56
	v_exp_f32_e32 v57, v57
	v_exp_f32_e32 v58, v58
	v_and_b32_e32 v59, 0xffff0000, v89
	v_add_f32_e32 v56, 1.0, v56
	v_add_f32_e32 v57, 1.0, v57
	v_add_f32_e32 v58, 1.0, v58
	v_mul_f32_e32 v59, 0xbfb8aa3b, v59
	v_rcp_f32_e32 v56, v56
	v_rcp_f32_e32 v57, v57
	v_rcp_f32_e32 v58, v58
	v_exp_f32_e32 v59, v59
	v_mul_f32_e32 v52, v52, v56
	v_mul_f32_e32 v53, v53, v57
	v_mul_f32_e32 v54, v54, v58
	v_add_f32_e32 v56, 1.0, v59
	v_mul_f32_e32 v57, 0xbfb8aa3b, v60
	v_mul_f32_e32 v58, 0xbfb8aa3b, v61
	v_rcp_f32_e32 v56, v56
	v_exp_f32_e32 v57, v57
	v_exp_f32_e32 v58, v58
	v_and_b32_e32 v63, 0xffff0000, v91
	v_lshlrev_b32_e32 v62, 16, v91
	v_mul_f32_e32 v59, 0xbfb8aa3b, v63
	v_mul_f32_e32 v55, v55, v56
	v_add_f32_e32 v56, 1.0, v57
	v_add_f32_e32 v57, 1.0, v58
	v_mul_f32_e32 v58, 0xbfb8aa3b, v62
	v_exp_f32_e32 v59, v59
	v_exp_f32_e32 v58, v58
	v_rcp_f32_e32 v56, v56
	v_rcp_f32_e32 v57, v57
	v_add_f32_e32 v59, 1.0, v59
	v_add_f32_e32 v58, 1.0, v58
	v_rcp_f32_e32 v59, v59
	v_rcp_f32_e32 v58, v58
	v_mul_f32_e32 v56, v48, v56
	v_mul_f32_e32 v57, v49, v57
	v_mul_f32_e32 v51, v51, v59
	v_mul_f32_e32 v58, v50, v58
	v_cvt_pk_bf16_f32 v48, v52, v53
	v_cvt_pk_bf16_f32 v49, v54, v55
	v_cvt_pk_bf16_f32 v50, v56, v57
	v_cvt_pk_bf16_f32 v51, v58, v51
	global_store_dwordx4 v[100:101], v[48:51], off offset:256
	v_lshlrev_b32_e32 v52, 16, v93
	v_mul_f32_e32 v52, 0xbfb8aa3b, v52
	v_lshlrev_b32_e32 v50, 16, v92
	v_and_b32_e32 v51, 0xffff0000, v92
	v_mul_f32_e32 v50, 0xbfb8aa3b, v50
	v_mul_f32_e32 v51, 0xbfb8aa3b, v51
	v_exp_f32_e32 v50, v50
	v_exp_f32_e32 v51, v51
	v_exp_f32_e32 v52, v52
	v_and_b32_e32 v53, 0xffff0000, v93
	v_add_f32_e32 v50, 1.0, v50
	v_add_f32_e32 v51, 1.0, v51
	v_add_f32_e32 v52, 1.0, v52
	v_mul_f32_e32 v53, 0xbfb8aa3b, v53
	v_rcp_f32_e32 v50, v50
	v_rcp_f32_e32 v51, v51
	v_rcp_f32_e32 v52, v52
	v_exp_f32_e32 v53, v53
	v_lshlrev_b32_e32 v54, 16, v94
	v_and_b32_e32 v55, 0xffff0000, v94
	v_mul_f32_e32 v44, v44, v50
	v_mul_f32_e32 v45, v45, v51
	v_mul_f32_e32 v46, v46, v52
	v_add_f32_e32 v50, 1.0, v53
	v_mul_f32_e32 v51, 0xbfb8aa3b, v54
	v_mul_f32_e32 v52, 0xbfb8aa3b, v55
	v_rcp_f32_e32 v50, v50
	v_exp_f32_e32 v51, v51
	v_exp_f32_e32 v52, v52
	v_lshlrev_b32_e32 v56, 16, v95
	v_and_b32_e32 v57, 0xffff0000, v95
; __device__ __forceinline__ float sigmoidf_(float x) { return __builtin_amdgcn_rcpf(1.0f + __expf(-x)); }
; __device__ __forceinline__ u32x4 pack8(const float (&f)[8]) { u32x4 w; w.x = cvt_pk_bf16(f[0], f[1]); w.y = cvt_pk_bf16(f[2], f[3]); w.z = cvt_pk_bf16(f[4], f[5]); w.w = cvt_pk_bf16(f[6], f[7]); return w; }
;     __device__ __forceinline__ void operator()(const f32x4 (&acc)[2][2][4][2], const pg8::Unit& u, int wr, int wc, int fr, int fq) const {
;     ...
;             for (int m = 0; m < 4; ++m)
; #pragma unroll
;                 for (int bj = 0; bj < 2; ++bj) {
;                     bf16_t* p = G + (size_t)(row0 + ai * 128 + m * 16) * LDG + col0 + bj * 128;
;                     float a[8], gt[8], o[8];
;                     unpack8(la[m][bj], a);
;                     if (mode == 0) {
; #pragma unroll
;                         for (int n = 0; n < 2; ++n)
; #pragma unroll
;                             for (int i = 0; i < 4; ++i) o[n * 4 + i] = sigmoidf_(a[n * 4 + i]) * acc[ai][bj][m][n][i];
;                     } else {
;                         unpack8(lg[m][bj], gt);
; #pragma unroll
;                         for (int n = 0; n < 2; ++n)
; #pragma unroll
;                             for (int i = 0; i < 4; ++i) o[n * 4 + i] = a[n * 4 + i] + sigmoidf_(gt[n * 4 + i]) * acc[ai][bj][m][n][i];
;                     }
;                     *(u32x4*)p = pack8(o);
	v_mul_f32_e32 v47, v47, v50
	v_add_f32_e32 v50, 1.0, v51
	v_add_f32_e32 v51, 1.0, v52
	v_mul_f32_e32 v52, 0xbfb8aa3b, v56
	v_mul_f32_e32 v53, 0xbfb8aa3b, v57
	v_exp_f32_e32 v52, v52
	v_exp_f32_e32 v53, v53
	v_rcp_f32_e32 v50, v50
	v_rcp_f32_e32 v51, v51
	v_add_f32_e32 v52, 1.0, v52
	v_add_f32_e32 v53, 1.0, v53
	v_rcp_f32_e32 v52, v52
	v_rcp_f32_e32 v53, v53
	v_lshl_add_u64 v[48:49], s[46:47], 0, v[102:103]
	v_lshl_add_u64 v[48:49], v[48:49], 0, v[164:165]
	v_mul_f32_e32 v50, v40, v50
	v_mul_f32_e32 v51, v41, v51
	v_mul_f32_e32 v52, v42, v52
	v_mul_f32_e32 v43, v43, v53
	v_cvt_pk_bf16_f32 v40, v44, v45
	v_cvt_pk_bf16_f32 v41, v46, v47
	v_cvt_pk_bf16_f32 v42, v50, v51
	v_cvt_pk_bf16_f32 v43, v52, v43
	global_store_dwordx4 v[48:49], v[40:43], off
	v_lshlrev_b32_e32 v44, 16, v98
	v_and_b32_e32 v45, 0xffff0000, v98
	v_lshlrev_b32_e32 v40, 16, v96
	v_and_b32_e32 v41, 0xffff0000, v96
	v_lshlrev_b32_e32 v42, 16, v97
	v_mul_f32_e32 v40, 0xbfb8aa3b, v40
	v_mul_f32_e32 v41, 0xbfb8aa3b, v41
	v_mul_f32_e32 v42, 0xbfb8aa3b, v42
	v_exp_f32_e32 v40, v40
	v_exp_f32_e32 v41, v41
	v_exp_f32_e32 v42, v42
	v_and_b32_e32 v43, 0xffff0000, v97
	v_add_f32_e32 v40, 1.0, v40
	v_add_f32_e32 v41, 1.0, v41
	v_add_f32_e32 v42, 1.0, v42
	v_mul_f32_e32 v43, 0xbfb8aa3b, v43
	v_rcp_f32_e32 v40, v40
	v_rcp_f32_e32 v41, v41
	v_rcp_f32_e32 v42, v42
	v_exp_f32_e32 v43, v43
	v_mul_f32_e32 v36, v36, v40
	v_mul_f32_e32 v37, v37, v41
	v_mul_f32_e32 v38, v38, v42
	v_add_f32_e32 v40, 1.0, v43
	v_mul_f32_e32 v41, 0xbfb8aa3b, v44
	v_mul_f32_e32 v42, 0xbfb8aa3b, v45
	v_rcp_f32_e32 v40, v40
	v_exp_f32_e32 v41, v41
	v_exp_f32_e32 v42, v42
	v_and_b32_e32 v47, 0xffff0000, v99
	v_lshlrev_b32_e32 v46, 16, v99
	v_mul_f32_e32 v43, 0xbfb8aa3b, v47
	v_mul_f32_e32 v39, v39, v40
	v_add_f32_e32 v40, 1.0, v41
	v_add_f32_e32 v41, 1.0, v42
	v_mul_f32_e32 v42, 0xbfb8aa3b, v46
	v_exp_f32_e32 v43, v43
	v_exp_f32_e32 v42, v42
	v_rcp_f32_e32 v40, v40
	v_rcp_f32_e32 v41, v41
	v_add_f32_e32 v43, 1.0, v43
	v_add_f32_e32 v42, 1.0, v42
	v_rcp_f32_e32 v43, v43
	v_rcp_f32_e32 v42, v42
	v_mul_f32_e32 v40, v32, v40
	v_mul_f32_e32 v41, v33, v41
	v_mul_f32_e32 v35, v35, v43
	v_mul_f32_e32 v42, v34, v42
	v_cvt_pk_bf16_f32 v32, v36, v37
	v_cvt_pk_bf16_f32 v33, v38, v39
	v_cvt_pk_bf16_f32 v34, v40, v41
	v_cvt_pk_bf16_f32 v35, v42, v35
	global_store_dwordx4 v[48:49], v[32:35], off offset:256
	v_lshlrev_b32_e32 v36, 16, v77
	v_mul_f32_e32 v36, 0xbfb8aa3b, v36
	v_lshlrev_b32_e32 v34, 16, v76
	v_and_b32_e32 v35, 0xffff0000, v76
	v_mul_f32_e32 v34, 0xbfb8aa3b, v34
	v_mul_f32_e32 v35, 0xbfb8aa3b, v35
	v_exp_f32_e32 v34, v34
	v_exp_f32_e32 v35, v35
	v_exp_f32_e32 v36, v36
	v_and_b32_e32 v37, 0xffff0000, v77
	v_add_f32_e32 v34, 1.0, v34
	v_add_f32_e32 v35, 1.0, v35
	v_add_f32_e32 v36, 1.0, v36
	v_mul_f32_e32 v37, 0xbfb8aa3b, v37
	v_rcp_f32_e32 v34, v34
	v_rcp_f32_e32 v35, v35
	v_rcp_f32_e32 v36, v36
	v_exp_f32_e32 v37, v37
	v_lshlrev_b32_e32 v38, 16, v78
	v_and_b32_e32 v39, 0xffff0000, v78
	v_mul_f32_e32 v28, v28, v34
	v_mul_f32_e32 v29, v29, v35
	v_mul_f32_e32 v30, v30, v36
	v_add_f32_e32 v34, 1.0, v37
	v_mul_f32_e32 v35, 0xbfb8aa3b, v38
	v_mul_f32_e32 v36, 0xbfb8aa3b, v39
	v_rcp_f32_e32 v34, v34
	v_exp_f32_e32 v35, v35
	v_exp_f32_e32 v36, v36
	v_lshlrev_b32_e32 v40, 16, v79
	v_and_b32_e32 v41, 0xffff0000, v79
	v_mul_f32_e32 v31, v31, v34
	v_add_f32_e32 v34, 1.0, v35
	v_add_f32_e32 v35, 1.0, v36
	v_mul_f32_e32 v36, 0xbfb8aa3b, v40
	v_mul_f32_e32 v37, 0xbfb8aa3b, v41
	v_exp_f32_e32 v36, v36
	v_exp_f32_e32 v37, v37
	v_rcp_f32_e32 v34, v34
	v_rcp_f32_e32 v35, v35
	v_add_f32_e32 v36, 1.0, v36
	v_add_f32_e32 v37, 1.0, v37
	v_rcp_f32_e32 v36, v36
	v_rcp_f32_e32 v37, v37
	v_lshl_add_u64 v[32:33], s[46:47], 0, v[82:83]
	v_lshl_add_u64 v[32:33], v[32:33], 0, v[164:165]
	v_mul_f32_e32 v34, v24, v34
	v_mul_f32_e32 v35, v25, v35
	v_mul_f32_e32 v36, v26, v36
	v_mul_f32_e32 v27, v27, v37
	v_cvt_pk_bf16_f32 v24, v28, v29
	v_cvt_pk_bf16_f32 v25, v30, v31
	v_cvt_pk_bf16_f32 v26, v34, v35
	v_cvt_pk_bf16_f32 v27, v36, v27
	global_store_dwordx4 v[32:33], v[24:27], off
	v_lshlrev_b32_e32 v28, 16, v74
	v_and_b32_e32 v29, 0xffff0000, v74
	v_lshlrev_b32_e32 v24, 16, v72
	v_and_b32_e32 v25, 0xffff0000, v72
	v_lshlrev_b32_e32 v26, 16, v73
	v_mul_f32_e32 v24, 0xbfb8aa3b, v24
	v_mul_f32_e32 v25, 0xbfb8aa3b, v25
	v_mul_f32_e32 v26, 0xbfb8aa3b, v26
	v_exp_f32_e32 v24, v24
	v_exp_f32_e32 v25, v25
	v_exp_f32_e32 v26, v26
	v_and_b32_e32 v27, 0xffff0000, v73
	v_add_f32_e32 v24, 1.0, v24
	v_add_f32_e32 v25, 1.0, v25
; __device__ __forceinline__ float sigmoidf_(float x) { return __builtin_amdgcn_rcpf(1.0f + __expf(-x)); }
; __device__ __forceinline__ u32x4 pack8(const float (&f)[8]) { u32x4 w; w.x = cvt_pk_bf16(f[0], f[1]); w.y = cvt_pk_bf16(f[2], f[3]); w.z = cvt_pk_bf16(f[4], f[5]); w.w = cvt_pk_bf16(f[6], f[7]); return w; }
; #define PG8_WAIT_V(n) asm volatile("s_waitcnt vmcnt(" #n ")" ::: "memory")
; #define PG8_BAR __builtin_amdgcn_s_barrier()
; template <class Epi>
; __device__ __forceinline__ void gemm_phase(PG8_LAS unsigned char* lds, const Gemm g, const StaticOrder& S, const Epi& E) {
;     ...
;         if (!has_next) break;
; #pragma unroll
;         for (int a = 0; a < 2; ++a)
; #pragma unroll
;             for (int b = 0; b < 2; ++b)
; #pragma unroll
;                 for (int m = 0; m < 4; ++m)
; #pragma unroll
;                     for (int n = 0; n < 2; ++n) acc[a][b][m][n] = (f32x4){0.f, 0.f, 0.f, 0.f};
;         cur = nxt; cA = nA; cB = nB; ++ui;
;     }
;     PG8_WAIT_V(0);
;     if (wr == 0) PG8_BAR;
;     __device__ __forceinline__ void operator()(const f32x4 (&acc)[2][2][4][2], const pg8::Unit& u, int wr, int wc, int fr, int fq) const {
;     ...
;             for (int m = 0; m < 4; ++m)
; #pragma unroll
;                 for (int bj = 0; bj < 2; ++bj) {
;                     bf16_t* p = G + (size_t)(row0 + ai * 128 + m * 16) * LDG + col0 + bj * 128;
;                     float a[8], gt[8], o[8];
;                     unpack8(la[m][bj], a);
;                     if (mode == 0) {
; #pragma unroll
;                         for (int n = 0; n < 2; ++n)
; #pragma unroll
;                             for (int i = 0; i < 4; ++i) o[n * 4 + i] = sigmoidf_(a[n * 4 + i]) * acc[ai][bj][m][n][i];
;                     } else {
;                         unpack8(lg[m][bj], gt);
; #pragma unroll
;                         for (int n = 0; n < 2; ++n)
; #pragma unroll
;                             for (int i = 0; i < 4; ++i) o[n * 4 + i] = a[n * 4 + i] + sigmoidf_(gt[n * 4 + i]) * acc[ai][bj][m][n][i];
;                     }
;                     *(u32x4*)p = pack8(o);
	v_add_f32_e32 v26, 1.0, v26
	v_mul_f32_e32 v27, 0xbfb8aa3b, v27
	v_rcp_f32_e32 v24, v24
	v_rcp_f32_e32 v25, v25
	v_rcp_f32_e32 v26, v26
	v_exp_f32_e32 v27, v27
	v_mul_f32_e32 v20, v20, v24
	v_mul_f32_e32 v21, v21, v25
	v_mul_f32_e32 v22, v22, v26
	v_add_f32_e32 v24, 1.0, v27
	v_mul_f32_e32 v25, 0xbfb8aa3b, v28
	v_mul_f32_e32 v26, 0xbfb8aa3b, v29
	v_rcp_f32_e32 v24, v24
	v_exp_f32_e32 v25, v25
	v_exp_f32_e32 v26, v26
	v_and_b32_e32 v31, 0xffff0000, v75
	v_lshlrev_b32_e32 v30, 16, v75
	v_mul_f32_e32 v27, 0xbfb8aa3b, v31
	v_mul_f32_e32 v23, v23, v24
	v_add_f32_e32 v24, 1.0, v25
	v_add_f32_e32 v25, 1.0, v26
	v_mul_f32_e32 v26, 0xbfb8aa3b, v30
	v_exp_f32_e32 v27, v27
	v_exp_f32_e32 v26, v26
	v_rcp_f32_e32 v24, v24
	v_rcp_f32_e32 v25, v25
	v_add_f32_e32 v27, 1.0, v27
	v_add_f32_e32 v26, 1.0, v26
	v_rcp_f32_e32 v27, v27
	v_rcp_f32_e32 v26, v26
	v_mul_f32_e32 v24, v16, v24
	v_mul_f32_e32 v25, v17, v25
	v_mul_f32_e32 v19, v19, v27
	v_mul_f32_e32 v26, v18, v26
	v_cvt_pk_bf16_f32 v16, v20, v21
	v_cvt_pk_bf16_f32 v17, v22, v23
	v_cvt_pk_bf16_f32 v18, v24, v25
	v_cvt_pk_bf16_f32 v19, v26, v19
	global_store_dwordx4 v[32:33], v[16:19], off offset:256
	v_lshlrev_b32_e32 v20, 16, v69
	v_mul_f32_e32 v20, 0xbfb8aa3b, v20
	v_lshlrev_b32_e32 v18, 16, v68
	v_and_b32_e32 v19, 0xffff0000, v68
	v_mul_f32_e32 v18, 0xbfb8aa3b, v18
	v_mul_f32_e32 v19, 0xbfb8aa3b, v19
	v_exp_f32_e32 v18, v18
	v_exp_f32_e32 v19, v19
	v_exp_f32_e32 v20, v20
	v_and_b32_e32 v21, 0xffff0000, v69
	v_add_f32_e32 v18, 1.0, v18
	v_add_f32_e32 v19, 1.0, v19
	v_add_f32_e32 v20, 1.0, v20
	v_mul_f32_e32 v21, 0xbfb8aa3b, v21
	v_rcp_f32_e32 v18, v18
	v_rcp_f32_e32 v19, v19
	v_rcp_f32_e32 v20, v20
	v_exp_f32_e32 v21, v21
	v_lshlrev_b32_e32 v22, 16, v70
	v_and_b32_e32 v23, 0xffff0000, v70
	v_mul_f32_e32 v12, v12, v18
	v_mul_f32_e32 v13, v13, v19
	v_mul_f32_e32 v14, v14, v20
	v_add_f32_e32 v18, 1.0, v21
	v_mul_f32_e32 v19, 0xbfb8aa3b, v22
	v_mul_f32_e32 v20, 0xbfb8aa3b, v23
	v_rcp_f32_e32 v18, v18
	v_exp_f32_e32 v19, v19
	v_exp_f32_e32 v20, v20
	v_lshlrev_b32_e32 v24, 16, v71
	v_and_b32_e32 v25, 0xffff0000, v71
	v_mul_f32_e32 v15, v15, v18
	v_add_f32_e32 v18, 1.0, v19
	v_add_f32_e32 v19, 1.0, v20
	v_mul_f32_e32 v20, 0xbfb8aa3b, v24
	v_mul_f32_e32 v21, 0xbfb8aa3b, v25
	v_exp_f32_e32 v20, v20
	v_exp_f32_e32 v21, v21
	v_rcp_f32_e32 v18, v18
	v_rcp_f32_e32 v19, v19
	v_add_f32_e32 v20, 1.0, v20
	v_add_f32_e32 v21, 1.0, v21
	v_rcp_f32_e32 v20, v20
	v_rcp_f32_e32 v21, v21
	v_lshl_add_u64 v[16:17], s[46:47], 0, v[80:81]
	v_lshl_add_u64 v[16:17], v[16:17], 0, v[164:165]
	v_mul_f32_e32 v18, v8, v18
	v_mul_f32_e32 v19, v9, v19
	v_mul_f32_e32 v20, v10, v20
	v_mul_f32_e32 v11, v11, v21
	v_cvt_pk_bf16_f32 v8, v12, v13
	v_cvt_pk_bf16_f32 v9, v14, v15
	v_cvt_pk_bf16_f32 v10, v18, v19
	v_cvt_pk_bf16_f32 v11, v20, v11
	global_store_dwordx4 v[16:17], v[8:11], off
	v_lshlrev_b32_e32 v12, 16, v66
	v_and_b32_e32 v13, 0xffff0000, v66
	v_lshlrev_b32_e32 v8, 16, v64
	v_and_b32_e32 v9, 0xffff0000, v64
	v_lshlrev_b32_e32 v10, 16, v65
	v_mul_f32_e32 v8, 0xbfb8aa3b, v8
	v_mul_f32_e32 v9, 0xbfb8aa3b, v9
	v_mul_f32_e32 v10, 0xbfb8aa3b, v10
	v_exp_f32_e32 v8, v8
	v_exp_f32_e32 v9, v9
	v_exp_f32_e32 v10, v10
	v_and_b32_e32 v11, 0xffff0000, v65
	v_add_f32_e32 v8, 1.0, v8
	v_add_f32_e32 v9, 1.0, v9
	v_add_f32_e32 v10, 1.0, v10
	v_mul_f32_e32 v11, 0xbfb8aa3b, v11
	v_rcp_f32_e32 v8, v8
	v_rcp_f32_e32 v9, v9
	v_rcp_f32_e32 v10, v10
	v_exp_f32_e32 v11, v11
	v_mul_f32_e32 v4, v4, v8
	v_mul_f32_e32 v5, v5, v9
	v_mul_f32_e32 v6, v6, v10
	v_add_f32_e32 v8, 1.0, v11
	v_mul_f32_e32 v9, 0xbfb8aa3b, v12
	v_mul_f32_e32 v10, 0xbfb8aa3b, v13
	v_rcp_f32_e32 v8, v8
	v_exp_f32_e32 v9, v9
	v_exp_f32_e32 v10, v10
	v_and_b32_e32 v15, 0xffff0000, v67
	v_lshlrev_b32_e32 v14, 16, v67
	v_mul_f32_e32 v11, 0xbfb8aa3b, v15
	v_mul_f32_e32 v7, v7, v8
	v_add_f32_e32 v8, 1.0, v9
	v_add_f32_e32 v9, 1.0, v10
	v_mul_f32_e32 v10, 0xbfb8aa3b, v14
	v_exp_f32_e32 v11, v11
	v_exp_f32_e32 v10, v10
	v_rcp_f32_e32 v8, v8
	v_rcp_f32_e32 v9, v9
	v_add_f32_e32 v11, 1.0, v11
	v_add_f32_e32 v10, 1.0, v10
	v_rcp_f32_e32 v11, v11
	v_rcp_f32_e32 v10, v10
	v_mul_f32_e32 v8, v0, v8
	v_mul_f32_e32 v9, v1, v9
	v_mul_f32_e32 v3, v3, v11
	v_mul_f32_e32 v10, v2, v10
	v_cvt_pk_bf16_f32 v0, v4, v5
	v_cvt_pk_bf16_f32 v1, v6, v7
	v_cvt_pk_bf16_f32 v2, v8, v9
	v_cvt_pk_bf16_f32 v3, v10, v3
	global_store_dwordx4 v[16:17], v[0:3], off offset:256
	s_cbranch_vccz .LBB0_897
	s_waitcnt vmcnt(0)
	s_cmpk_gt_u32 s34, 0xff
	s_cbranch_scc1 .LBB0_908
	s_barrier

; #define PG8_STAGE(bufoff, gbase, voff) do { _Pragma("unroll") for (int _i = 0; _i < 2; ++_i) \
;         __builtin_amdgcn_global_load_lds((const unsigned*)((const char*)(gbase) + (voff)[_i]), (PG8_LAS unsigned*)(lds + (bufoff) + ldsw + _i * 8192), 16, 0, 0); } while (0)
; #define PG8_LDA(dst, b, h) do { _Pragma("unroll") for (int m = 0; m < 4; ++m) _Pragma("unroll") for (int k = 0; k < 2; ++k) dst[m][k] = *(const PG8_LAS bf16x8*)(lds + PG8_SA(b, h) + aoff + m * 2048 + k * 1024); } while (0)
; #define PG8_LDB(dst, b, h) do { _Pragma("unroll") for (int n = 0; n < 2; ++n) _Pragma("unroll") for (int k = 0; k < 2; ++k) dst[n][k] = *(const PG8_LAS bf16x8*)(lds + PG8_SB(b, h) + boff + n * 2048 + k * 1024); } while (0)
; #define PG8_MMA(ai, bj, At, Bt) do { __builtin_amdgcn_s_setprio(1); _Pragma("unroll") for (int m = 0; m < 4; ++m) _Pragma("unroll") for (int n = 0; n < 2; ++n) _Pragma("unroll") for (int k = 0; k < 2; ++k) \
;         acc[ai][bj][m][n] = __builtin_amdgcn_mfma_f32_16x16x32_bf16(Bt[n][k], At[m][k], acc[ai][bj][m][n], 0, 0, 0); __builtin_amdgcn_s_setprio(0); } while (0)
; template <class Epi>
; __device__ __forceinline__ void gemm_phase(PG8_LAS unsigned char* lds, const Gemm g, const StaticOrder& S, const Epi& E) {
;     ...
;         const bool has_next = S.next(ui + 1, nxt);
;         const char* nA = has_next ? (const char*)g.A + (size_t)nxt.pm * tstepA : cA; const char* nB = has_next ? (const char*)g.Bt + (size_t)nxt.pn * tstepB : cB;
;         for (int t = 0; t < nt; t += 2) {
;             const bool last = (t == nt - 2);
;             const char* a1 = cA + (size_t)(t + 1) * kstep;
;             const char* a2 = last ? nA : cA + (size_t)(t + 2) * kstep; const char* b2 = last ? nB : cB + (size_t)(t + 2) * kstep;
;             const char* a3 = a2 + kstep; const char* b3 = b2 + kstep;
;             PG8_LDB(B0, 0, 0); PG8_SCHED; PG8_LDA(At, 0, 0); PG8_STAGE(PG8_SA(1, 1), a1 + hstepA, voffA);
;             PG8_WAIT_L(8); PG8_BAR; PG8_WAIT_L(0); PG8_MMA(0, 0, At, B0); PG8_BAR; PG8_SCHED;
;     ...
; #pragma unroll
;         for (int a = 0; a < 2; ++a)
; #pragma unroll
;             for (int b = 0; b < 2; ++b)
; #pragma unroll
;                 for (int m = 0; m < 4; ++m)
; #pragma unroll
;                     for (int n = 0; n < 2; ++n) acc[a][b][m][n] = (f32x4){0.f, 0.f, 0.f, 0.f};
;         cur = nxt; cA = nA; cB = nB; ++ui;
.LBB0_924:
	s_ashr_i32 s17, s16, 31
	v_cmp_lt_i64_e32 vcc, s[18:19], v[182:183]
	s_lshl_b64 s[18:19], s[16:17], 19
	s_add_u32 s18, s90, s18
	s_addc_u32 s19, s91, s19
	s_and_b64 s[20:21], vcc, exec
	s_cselect_b32 s17, s19, s31
	s_cselect_b32 s57, s18, s30
	s_ashr_i32 s15, s14, 31
	s_lshl_b64 s[20:21], s[14:15], 19
	v_readlane_b32 s34, v253, 38
	v_readlane_b32 s35, v253, 39
	s_add_u32 s20, s34, s20
	s_addc_u32 s21, s35, s21
	s_and_b64 s[34:35], vcc, exec
	s_cselect_b32 s15, s21, s23
	s_cselect_b32 s58, s20, s22
	s_add_u32 s30, s30, 0x40080
	s_addc_u32 s31, s31, 0
	s_add_u32 s59, s22, 0x100
	v_mov_b32_e32 v0, 0
	s_addc_u32 s60, s23, 0
	s_mov_b32 s61, -2
	v_mov_b32_e32 v1, v0
	v_mov_b32_e32 v2, v0
	v_mov_b32_e32 v3, v0
	v_mov_b32_e32 v4, v0
	v_mov_b32_e32 v5, v0
	v_mov_b32_e32 v6, v0
	v_mov_b32_e32 v7, v0
	v_mov_b32_e32 v16, v0
	v_mov_b32_e32 v17, v0
	v_mov_b32_e32 v18, v0
	v_mov_b32_e32 v19, v0
	v_mov_b32_e32 v20, v0
	v_mov_b32_e32 v21, v0
	v_mov_b32_e32 v22, v0
	v_mov_b32_e32 v23, v0
	v_mov_b32_e32 v32, v0
	v_mov_b32_e32 v33, v0
	v_mov_b32_e32 v34, v0
	v_mov_b32_e32 v35, v0
	v_mov_b32_e32 v36, v0
	v_mov_b32_e32 v37, v0
	v_mov_b32_e32 v38, v0
	v_mov_b32_e32 v39, v0
	v_mov_b32_e32 v48, v0
	v_mov_b32_e32 v49, v0
	v_mov_b32_e32 v50, v0
	v_mov_b32_e32 v51, v0
	v_mov_b32_e32 v52, v0
	v_mov_b32_e32 v53, v0
	v_mov_b32_e32 v54, v0
	v_mov_b32_e32 v55, v0
	v_mov_b32_e32 v8, v0
	v_mov_b32_e32 v9, v0
	v_mov_b32_e32 v10, v0
	v_mov_b32_e32 v11, v0
	v_mov_b32_e32 v12, v0
	v_mov_b32_e32 v13, v0
	v_mov_b32_e32 v14, v0
	v_mov_b32_e32 v15, v0
	v_mov_b32_e32 v24, v0
	v_mov_b32_e32 v25, v0
	v_mov_b32_e32 v26, v0
	v_mov_b32_e32 v27, v0
	v_mov_b32_e32 v28, v0
	v_mov_b32_e32 v29, v0
	v_mov_b32_e32 v30, v0
	v_mov_b32_e32 v31, v0
	v_mov_b32_e32 v40, v0
	v_mov_b32_e32 v41, v0
	v_mov_b32_e32 v42, v0
	v_mov_b32_e32 v43, v0
	v_mov_b32_e32 v44, v0
	v_mov_b32_e32 v45, v0
	v_mov_b32_e32 v46, v0
	v_mov_b32_e32 v47, v0
	v_mov_b32_e32 v56, v0
	v_mov_b32_e32 v57, v0
	v_mov_b32_e32 v58, v0
	v_mov_b32_e32 v59, v0
	v_mov_b32_e32 v60, v0
	v_mov_b32_e32 v61, v0
	v_mov_b32_e32 v62, v0
	v_mov_b32_e32 v63, v0
	v_mov_b32_e32 v64, v0
	v_mov_b32_e32 v65, v0
	v_mov_b32_e32 v66, v0
	v_mov_b32_e32 v67, v0
	v_mov_b32_e32 v68, v0
	v_mov_b32_e32 v69, v0
	v_mov_b32_e32 v70, v0
	v_mov_b32_e32 v71, v0
	v_mov_b32_e32 v80, v0
	v_mov_b32_e32 v81, v0
	v_mov_b32_e32 v82, v0
	v_mov_b32_e32 v83, v0
	v_mov_b32_e32 v84, v0
	v_mov_b32_e32 v85, v0
	v_mov_b32_e32 v86, v0
	v_mov_b32_e32 v87, v0
	v_mov_b32_e32 v96, v0
	v_mov_b32_e32 v97, v0
	v_mov_b32_e32 v98, v0
	v_mov_b32_e32 v99, v0
	v_mov_b32_e32 v100, v0
	v_mov_b32_e32 v101, v0
	v_mov_b32_e32 v102, v0
	v_mov_b32_e32 v103, v0
	v_mov_b32_e32 v112, v0
	v_mov_b32_e32 v113, v0
	v_mov_b32_e32 v114, v0
	v_mov_b32_e32 v115, v0
	v_mov_b32_e32 v116, v0
	v_mov_b32_e32 v117, v0
	v_mov_b32_e32 v118, v0
	v_mov_b32_e32 v119, v0
	v_mov_b32_e32 v72, v0
	v_mov_b32_e32 v73, v0
	v_mov_b32_e32 v74, v0
	v_mov_b32_e32 v75, v0
	v_mov_b32_e32 v76, v0
	v_mov_b32_e32 v77, v0
	v_mov_b32_e32 v78, v0
	v_mov_b32_e32 v79, v0
	v_mov_b32_e32 v88, v0
	v_mov_b32_e32 v89, v0
	v_mov_b32_e32 v90, v0
	v_mov_b32_e32 v91, v0
	v_mov_b32_e32 v92, v0
	v_mov_b32_e32 v93, v0
	v_mov_b32_e32 v94, v0
	v_mov_b32_e32 v95, v0
	v_mov_b32_e32 v104, v0
	v_mov_b32_e32 v105, v0
	v_mov_b32_e32 v106, v0
	v_mov_b32_e32 v107, v0
	v_mov_b32_e32 v108, v0
	v_mov_b32_e32 v109, v0
	v_mov_b32_e32 v110, v0
	v_mov_b32_e32 v111, v0
	v_mov_b32_e32 v120, v0
	v_mov_b32_e32 v121, v0
	v_mov_b32_e32 v122, v0
	v_mov_b32_e32 v123, v0
	v_mov_b32_e32 v124, v0
	v_mov_b32_e32 v125, v0
	v_mov_b32_e32 v126, v0
	v_mov_b32_e32 v127, v0
	s_waitcnt vmcnt(0)
	s_cmp_eq_u32 s101, 1
	s_cbranch_scc0 .Lsp_4
	s_setprio 1
.Lsp_4:
.LBB0_925:
	ds_read_b128 v[128:131], v198
	ds_read_b128 v[132:135], v198 offset:1024
	ds_read_b128 v[136:139], v198 offset:2048
	ds_read_b128 v[140:143], v198 offset:3072
	ds_read_b128 v[144:147], v199
	ds_read_b128 v[148:151], v199 offset:1024
	ds_read_b128 v[152:155], v199 offset:2048
	ds_read_b128 v[156:159], v199 offset:3072
	ds_read_b128 v[160:163], v199 offset:4096
	ds_read_b128 v[164:167], v199 offset:5120
	ds_read_b128 v[186:189], v199 offset:6144
	ds_read_b128 v[190:193], v199 offset:7168
	ds_read_b128 v[202:205], v200
	ds_read_b128 v[206:209], v200 offset:1024
	ds_read_b128 v[210:213], v200 offset:2048
	ds_read_b128 v[214:217], v200 offset:3072
	s_add_u32 s22, s30, 0xfffc0080
	s_addc_u32 s23, s31, -1
	s_cmp_eq_u32 s61, 12
	s_cselect_b32 s35, s17, s23
	s_cselect_b32 s34, s57, s22
	s_cselect_b32 s23, s15, s60
	s_cselect_b32 s22, s58, s59
	v_lshl_add_u64 v[194:195], s[30:31], 0, v[178:179]
	s_add_i32 m0, s29, 0xc000
	s_nop 0
	global_load_lds_dwordx4 v[194:195], off
	v_lshl_add_u64 v[194:195], s[30:31], 0, v[180:181]
	s_add_i32 m0, s29, 0xe000
	s_nop 0
	global_load_lds_dwordx4 v[194:195], off
	s_waitcnt lgkmcnt(0)
	s_waitcnt vmcnt(8)
	s_barrier
; #define PG8_STAGE(bufoff, gbase, voff) do { _Pragma("unroll") for (int _i = 0; _i < 2; ++_i) \
;         __builtin_amdgcn_global_load_lds((const unsigned*)((const char*)(gbase) + (voff)[_i]), (PG8_LAS unsigned*)(lds + (bufoff) + ldsw + _i * 8192), 16, 0, 0); } while (0)
; #define PG8_LDA(dst, b, h) do { _Pragma("unroll") for (int m = 0; m < 4; ++m) _Pragma("unroll") for (int k = 0; k < 2; ++k) dst[m][k] = *(const PG8_LAS bf16x8*)(lds + PG8_SA(b, h) + aoff + m * 2048 + k * 1024); } while (0)
; #define PG8_LDB(dst, b, h) do { _Pragma("unroll") for (int n = 0; n < 2; ++n) _Pragma("unroll") for (int k = 0; k < 2; ++k) dst[n][k] = *(const PG8_LAS bf16x8*)(lds + PG8_SB(b, h) + boff + n * 2048 + k * 1024); } while (0)
; #define PG8_MMA(ai, bj, At, Bt) do { __builtin_amdgcn_s_setprio(1); _Pragma("unroll") for (int m = 0; m < 4; ++m) _Pragma("unroll") for (int n = 0; n < 2; ++n) _Pragma("unroll") for (int k = 0; k < 2; ++k) \
;         acc[ai][bj][m][n] = __builtin_amdgcn_mfma_f32_16x16x32_bf16(Bt[n][k], At[m][k], acc[ai][bj][m][n], 0, 0, 0); __builtin_amdgcn_s_setprio(0); } while (0)
; #define PG8_WAIT_V(n) asm volatile("s_waitcnt vmcnt(" #n ")" ::: "memory")
; #define PG8_WAIT_L(n) asm volatile("s_waitcnt lgkmcnt(" #n ")" ::: "memory")
; #define PG8_BAR __builtin_amdgcn_s_barrier()
; #define PG8_SCHED __builtin_amdgcn_sched_barrier(0)
; template <class Epi>
; __device__ __forceinline__ void gemm_phase(PG8_LAS unsigned char* lds, const Gemm g, const StaticOrder& S, const Epi& E) {
;     ...
;             PG8_WAIT_L(8); PG8_BAR; PG8_WAIT_L(0); PG8_MMA(0, 0, At, B0); PG8_BAR; PG8_SCHED;
;             PG8_LDB(B1, 0, 1); PG8_STAGE(PG8_SB(0, 0), b2, voffB);
;             PG8_BAR; PG8_WAIT_L(0); PG8_MMA(0, 1, At, B1); PG8_BAR;
;             PG8_LDA(At, 0, 1); PG8_STAGE(PG8_SA(0, 0), a2, voffA);
;             PG8_BAR; PG8_WAIT_L(0); PG8_MMA(1, 0, At, B0); PG8_BAR; PG8_SCHED;
;             PG8_STAGE(PG8_SB(0, 1), b2 + hstepB, voffB);
;             PG8_WAIT_V(6); PG8_BAR; PG8_MMA(1, 1, At, B1); PG8_BAR;
	v_mfma_f32_16x16x32_bf16 v[124:127], v[128:131], v[144:147], v[124:127]
	v_mfma_f32_16x16x32_bf16 v[120:123], v[136:139], v[144:147], v[120:123]
	v_mfma_f32_16x16x32_bf16 v[108:111], v[128:131], v[152:155], v[108:111]
	v_mfma_f32_16x16x32_bf16 v[104:107], v[136:139], v[152:155], v[104:107]
	v_mfma_f32_16x16x32_bf16 v[92:95], v[128:131], v[160:163], v[92:95]
	v_mfma_f32_16x16x32_bf16 v[88:91], v[136:139], v[160:163], v[88:91]
	v_mfma_f32_16x16x32_bf16 v[76:79], v[128:131], v[186:189], v[76:79]
	v_mfma_f32_16x16x32_bf16 v[72:75], v[136:139], v[186:189], v[72:75]
	v_mfma_f32_16x16x32_bf16 v[124:127], v[132:135], v[148:151], v[124:127]
	v_mfma_f32_16x16x32_bf16 v[120:123], v[140:143], v[148:151], v[120:123]
	v_mfma_f32_16x16x32_bf16 v[108:111], v[132:135], v[156:159], v[108:111]
	v_mfma_f32_16x16x32_bf16 v[104:107], v[140:143], v[156:159], v[104:107]
	v_mfma_f32_16x16x32_bf16 v[92:95], v[132:135], v[164:167], v[92:95]
	v_mfma_f32_16x16x32_bf16 v[88:91], v[140:143], v[164:167], v[88:91]
	v_mfma_f32_16x16x32_bf16 v[76:79], v[132:135], v[190:193], v[76:79]
	v_mfma_f32_16x16x32_bf16 v[72:75], v[140:143], v[190:193], v[72:75]
	v_mfma_f32_16x16x32_bf16 v[116:119], v[202:205], v[144:147], v[116:119]
	v_mfma_f32_16x16x32_bf16 v[112:115], v[210:213], v[144:147], v[112:115]
	v_mfma_f32_16x16x32_bf16 v[100:103], v[202:205], v[152:155], v[100:103]
	v_mfma_f32_16x16x32_bf16 v[96:99], v[210:213], v[152:155], v[96:99]
	v_mfma_f32_16x16x32_bf16 v[84:87], v[202:205], v[160:163], v[84:87]
	v_mfma_f32_16x16x32_bf16 v[80:83], v[210:213], v[160:163], v[80:83]
	v_mfma_f32_16x16x32_bf16 v[68:71], v[202:205], v[186:189], v[68:71]
	v_mfma_f32_16x16x32_bf16 v[64:67], v[210:213], v[186:189], v[64:67]
	v_mfma_f32_16x16x32_bf16 v[116:119], v[206:209], v[148:151], v[116:119]
	v_mfma_f32_16x16x32_bf16 v[112:115], v[214:217], v[148:151], v[112:115]
	v_mfma_f32_16x16x32_bf16 v[100:103], v[206:209], v[156:159], v[100:103]
	v_mfma_f32_16x16x32_bf16 v[96:99], v[214:217], v[156:159], v[96:99]
	v_mfma_f32_16x16x32_bf16 v[84:87], v[206:209], v[164:167], v[84:87]
	v_mfma_f32_16x16x32_bf16 v[80:83], v[214:217], v[164:167], v[80:83]
	v_mfma_f32_16x16x32_bf16 v[68:71], v[206:209], v[190:193], v[68:71]
	v_mfma_f32_16x16x32_bf16 v[64:67], v[214:217], v[190:193], v[64:67]
	s_barrier
	ds_read_b128 v[144:147], v199 offset:16384
	ds_read_b128 v[148:151], v199 offset:17408
	ds_read_b128 v[152:155], v199 offset:18432
	ds_read_b128 v[156:159], v199 offset:19456
	ds_read_b128 v[160:163], v199 offset:20480
	ds_read_b128 v[164:167], v199 offset:21504
	ds_read_b128 v[186:189], v199 offset:22528
	ds_read_b128 v[190:193], v199 offset:23552
	s_add_i32 s62, s53, s38
	v_lshl_add_u64 v[194:195], s[22:23], 0, v[172:173]
	s_mov_b32 m0, s62
	s_nop 0
	global_load_lds_dwordx4 v[194:195], off
	v_lshl_add_u64 v[218:219], s[22:23], 0, v[176:177]
	s_add_i32 m0, s62, 0x2000
	s_nop 0
	global_load_lds_dwordx4 v[218:219], off
	s_mov_b32 m0, s29
	v_lshl_add_u64 v[220:221], s[34:35], 0, v[170:171]
	global_load_lds_dwordx4 v[220:221], off
	v_lshl_add_u64 v[222:223], s[34:35], 0, v[174:175]
	s_mov_b32 m0, s39
	s_nop 0
	global_load_lds_dwordx4 v[222:223], off
	s_add_u32 s62, s22, 0x40000
	s_addc_u32 s63, s23, 0
	s_add_i32 s64, s54, s38
	v_lshl_add_u64 v[224:225], s[62:63], 0, v[172:173]
	s_mov_b32 m0, s64
	s_nop 0
	global_load_lds_dwordx4 v[224:225], off
	v_lshl_add_u64 v[224:225], s[62:63], 0, v[176:177]
	s_add_i32 m0, s64, 0x2000
	s_nop 0
	global_load_lds_dwordx4 v[224:225], off
	s_waitcnt lgkmcnt(0)
	s_waitcnt vmcnt(8)
	s_barrier
	v_mfma_f32_16x16x32_bf16 v[60:63], v[128:131], v[144:147], v[60:63]
	v_mfma_f32_16x16x32_bf16 v[56:59], v[136:139], v[144:147], v[56:59]
	v_mfma_f32_16x16x32_bf16 v[44:47], v[128:131], v[152:155], v[44:47]
	v_mfma_f32_16x16x32_bf16 v[40:43], v[136:139], v[152:155], v[40:43]
	v_mfma_f32_16x16x32_bf16 v[28:31], v[128:131], v[160:163], v[28:31]
	v_mfma_f32_16x16x32_bf16 v[24:27], v[136:139], v[160:163], v[24:27]
	v_mfma_f32_16x16x32_bf16 v[12:15], v[128:131], v[186:189], v[12:15]
	v_mfma_f32_16x16x32_bf16 v[8:11], v[136:139], v[186:189], v[8:11]
	v_mfma_f32_16x16x32_bf16 v[60:63], v[132:135], v[148:151], v[60:63]
	v_mfma_f32_16x16x32_bf16 v[56:59], v[140:143], v[148:151], v[56:59]
	v_mfma_f32_16x16x32_bf16 v[44:47], v[132:135], v[156:159], v[44:47]
	v_mfma_f32_16x16x32_bf16 v[40:43], v[140:143], v[156:159], v[40:43]
	v_mfma_f32_16x16x32_bf16 v[28:31], v[132:135], v[164:167], v[28:31]
	v_mfma_f32_16x16x32_bf16 v[24:27], v[140:143], v[164:167], v[24:27]
	v_mfma_f32_16x16x32_bf16 v[12:15], v[132:135], v[190:193], v[12:15]
	v_mfma_f32_16x16x32_bf16 v[8:11], v[140:143], v[190:193], v[8:11]
	v_mfma_f32_16x16x32_bf16 v[52:55], v[202:205], v[144:147], v[52:55]
	v_mfma_f32_16x16x32_bf16 v[48:51], v[210:213], v[144:147], v[48:51]
	v_mfma_f32_16x16x32_bf16 v[36:39], v[202:205], v[152:155], v[36:39]
	v_mfma_f32_16x16x32_bf16 v[32:35], v[210:213], v[152:155], v[32:35]
	v_mfma_f32_16x16x32_bf16 v[20:23], v[202:205], v[160:163], v[20:23]
	v_mfma_f32_16x16x32_bf16 v[16:19], v[210:213], v[160:163], v[16:19]
	v_mfma_f32_16x16x32_bf16 v[4:7], v[202:205], v[186:189], v[4:7]
	v_mfma_f32_16x16x32_bf16 v[0:3], v[210:213], v[186:189], v[0:3]
	v_mfma_f32_16x16x32_bf16 v[52:55], v[206:209], v[148:151], v[52:55]
	v_mfma_f32_16x16x32_bf16 v[48:51], v[214:217], v[148:151], v[48:51]
	v_mfma_f32_16x16x32_bf16 v[36:39], v[206:209], v[156:159], v[36:39]
	v_mfma_f32_16x16x32_bf16 v[32:35], v[214:217], v[156:159], v[32:35]
	v_mfma_f32_16x16x32_bf16 v[20:23], v[206:209], v[164:167], v[20:23]
	v_mfma_f32_16x16x32_bf16 v[16:19], v[214:217], v[164:167], v[16:19]
	v_mfma_f32_16x16x32_bf16 v[4:7], v[206:209], v[190:193], v[4:7]
	v_mfma_f32_16x16x32_bf16 v[0:3], v[214:217], v[190:193], v[0:3]
	s_add_i32 s62, 0, 0x18000
	v_add_u32_e32 v140, s62, v196
	s_barrier
; #define PG8_STAGE(bufoff, gbase, voff) do { _Pragma("unroll") for (int _i = 0; _i < 2; ++_i) \
;         __builtin_amdgcn_global_load_lds((const unsigned*)((const char*)(gbase) + (voff)[_i]), (PG8_LAS unsigned*)(lds + (bufoff) + ldsw + _i * 8192), 16, 0, 0); } while (0)
; #define PG8_LDA(dst, b, h) do { _Pragma("unroll") for (int m = 0; m < 4; ++m) _Pragma("unroll") for (int k = 0; k < 2; ++k) dst[m][k] = *(const PG8_LAS bf16x8*)(lds + PG8_SA(b, h) + aoff + m * 2048 + k * 1024); } while (0)
; #define PG8_LDB(dst, b, h) do { _Pragma("unroll") for (int n = 0; n < 2; ++n) _Pragma("unroll") for (int k = 0; k < 2; ++k) dst[n][k] = *(const PG8_LAS bf16x8*)(lds + PG8_SB(b, h) + boff + n * 2048 + k * 1024); } while (0)
; #define PG8_MMA(ai, bj, At, Bt) do { __builtin_amdgcn_s_setprio(1); _Pragma("unroll") for (int m = 0; m < 4; ++m) _Pragma("unroll") for (int n = 0; n < 2; ++n) _Pragma("unroll") for (int k = 0; k < 2; ++k) \
;         acc[ai][bj][m][n] = __builtin_amdgcn_mfma_f32_16x16x32_bf16(Bt[n][k], At[m][k], acc[ai][bj][m][n], 0, 0, 0); __builtin_amdgcn_s_setprio(0); } while (0)
; #define PG8_WAIT_L(n) asm volatile("s_waitcnt lgkmcnt(" #n ")" ::: "memory")
; #define PG8_BAR __builtin_amdgcn_s_barrier()
; #define PG8_SCHED __builtin_amdgcn_sched_barrier(0)
; template <class Epi>
; __device__ __forceinline__ void gemm_phase(PG8_LAS unsigned char* lds, const Gemm g, const StaticOrder& S, const Epi& E) {
;     ...
;             PG8_LDB(B0, 1, 0); PG8_SCHED; PG8_LDA(At, 1, 0); PG8_STAGE(PG8_SA(0, 1), a2 + hstepA, voffA);
;             PG8_WAIT_L(8); PG8_BAR; PG8_WAIT_L(0); PG8_MMA(0, 0, At, B0); PG8_BAR; PG8_SCHED;
;             PG8_LDB(B1, 1, 1); PG8_STAGE(PG8_SB(1, 0), b3, voffB);
;             PG8_BAR; PG8_WAIT_L(0); PG8_MMA(0, 1, At, B1); PG8_BAR;
;             PG8_LDA(At, 1, 1); PG8_STAGE(PG8_SA(1, 0), a3, voffA);
;             PG8_BAR; PG8_WAIT_L(0); PG8_MMA(1, 0, At, B0); PG8_BAR; PG8_SCHED;
	ds_read_b128 v[128:131], v140
	ds_read_b128 v[132:135], v140 offset:1024
	ds_read_b128 v[136:139], v140 offset:2048
	ds_read_b128 v[140:143], v140 offset:3072
	ds_read_b128 v[144:147], v199 offset:32768
	ds_read_b128 v[148:151], v199 offset:33792
	ds_read_b128 v[152:155], v199 offset:34816
	ds_read_b128 v[156:159], v199 offset:35840
	ds_read_b128 v[160:163], v199 offset:36864
	ds_read_b128 v[164:167], v199 offset:37888
	ds_read_b128 v[186:189], v199 offset:38912
	ds_read_b128 v[190:193], v199 offset:39936
	v_add_u32_e32 v201, 0x1c000, v196
	ds_read_b128 v[202:205], v201
	ds_read_b128 v[206:209], v201 offset:1024
	ds_read_b128 v[210:213], v201 offset:2048
	ds_read_b128 v[214:217], v201 offset:3072
	s_add_u32 s34, s34, 0x40000
	s_addc_u32 s35, s35, 0
	s_mov_b32 m0, s40
	v_lshl_add_u64 v[224:225], s[34:35], 0, v[170:171]
	global_load_lds_dwordx4 v[224:225], off
	v_lshl_add_u64 v[224:225], s[34:35], 0, v[174:175]
	s_mov_b32 m0, s41
	s_nop 0
	global_load_lds_dwordx4 v[224:225], off
	s_waitcnt lgkmcnt(0)
	s_waitcnt vmcnt(8)
	s_barrier
	v_mfma_f32_16x16x32_bf16 v[124:127], v[128:131], v[144:147], v[124:127]
	v_mfma_f32_16x16x32_bf16 v[120:123], v[136:139], v[144:147], v[120:123]
	v_mfma_f32_16x16x32_bf16 v[108:111], v[128:131], v[152:155], v[108:111]
	v_mfma_f32_16x16x32_bf16 v[104:107], v[136:139], v[152:155], v[104:107]
	v_mfma_f32_16x16x32_bf16 v[92:95], v[128:131], v[160:163], v[92:95]
	v_mfma_f32_16x16x32_bf16 v[88:91], v[136:139], v[160:163], v[88:91]
	v_mfma_f32_16x16x32_bf16 v[76:79], v[128:131], v[186:189], v[76:79]
	v_mfma_f32_16x16x32_bf16 v[72:75], v[136:139], v[186:189], v[72:75]
	v_mfma_f32_16x16x32_bf16 v[124:127], v[132:135], v[148:151], v[124:127]
	v_mfma_f32_16x16x32_bf16 v[120:123], v[140:143], v[148:151], v[120:123]
	v_mfma_f32_16x16x32_bf16 v[108:111], v[132:135], v[156:159], v[108:111]
	v_mfma_f32_16x16x32_bf16 v[104:107], v[140:143], v[156:159], v[104:107]
	v_mfma_f32_16x16x32_bf16 v[92:95], v[132:135], v[164:167], v[92:95]
	v_mfma_f32_16x16x32_bf16 v[88:91], v[140:143], v[164:167], v[88:91]
	v_mfma_f32_16x16x32_bf16 v[76:79], v[132:135], v[190:193], v[76:79]
	v_mfma_f32_16x16x32_bf16 v[72:75], v[140:143], v[190:193], v[72:75]
	v_mfma_f32_16x16x32_bf16 v[116:119], v[202:205], v[144:147], v[116:119]
	v_mfma_f32_16x16x32_bf16 v[112:115], v[210:213], v[144:147], v[112:115]
	v_mfma_f32_16x16x32_bf16 v[100:103], v[202:205], v[152:155], v[100:103]
	v_mfma_f32_16x16x32_bf16 v[96:99], v[210:213], v[152:155], v[96:99]
	v_mfma_f32_16x16x32_bf16 v[84:87], v[202:205], v[160:163], v[84:87]
	v_mfma_f32_16x16x32_bf16 v[80:83], v[210:213], v[160:163], v[80:83]
	v_mfma_f32_16x16x32_bf16 v[68:71], v[202:205], v[186:189], v[68:71]
	v_mfma_f32_16x16x32_bf16 v[64:67], v[210:213], v[186:189], v[64:67]
	v_mfma_f32_16x16x32_bf16 v[116:119], v[206:209], v[148:151], v[116:119]
	v_mfma_f32_16x16x32_bf16 v[112:115], v[214:217], v[148:151], v[112:115]
	v_mfma_f32_16x16x32_bf16 v[100:103], v[206:209], v[156:159], v[100:103]
	v_mfma_f32_16x16x32_bf16 v[96:99], v[214:217], v[156:159], v[96:99]
	v_mfma_f32_16x16x32_bf16 v[84:87], v[206:209], v[164:167], v[84:87]
	v_mfma_f32_16x16x32_bf16 v[80:83], v[214:217], v[164:167], v[80:83]
	v_mfma_f32_16x16x32_bf16 v[68:71], v[206:209], v[190:193], v[68:71]
	v_mfma_f32_16x16x32_bf16 v[64:67], v[214:217], v[190:193], v[64:67]
	s_barrier
	ds_read_b128 v[144:147], v199 offset:49152
	ds_read_b128 v[148:151], v199 offset:50176
	ds_read_b128 v[152:155], v199 offset:51200
	ds_read_b128 v[156:159], v199 offset:52224
	ds_read_b128 v[160:163], v199 offset:53248
	ds_read_b128 v[164:167], v199 offset:54272
	ds_read_b128 v[186:189], v199 offset:55296
	ds_read_b128 v[190:193], v199 offset:56320
	s_add_i32 s34, 0, 0x1c000
	s_add_i32 s35, s62, s38
	v_lshl_add_u64 v[194:195], v[194:195], 0, s[4:5]
	s_mov_b32 m0, s35
	s_nop 0
	global_load_lds_dwordx4 v[194:195], off
	v_lshl_add_u64 v[194:195], v[218:219], 0, s[4:5]
	s_add_i32 m0, s35, 0x2000
	s_nop 0
	global_load_lds_dwordx4 v[194:195], off
	s_mov_b32 m0, s43
	v_lshl_add_u64 v[194:195], v[220:221], 0, s[4:5]
	global_load_lds_dwordx4 v[194:195], off
	v_lshl_add_u64 v[194:195], v[222:223], 0, s[4:5]
	s_mov_b32 m0, s50
	s_nop 0
	global_load_lds_dwordx4 v[194:195], off
	s_add_u32 s22, s22, 0x40080
	s_addc_u32 s23, s23, 0
	s_add_i32 s34, s34, s38
	v_lshl_add_u64 v[224:225], s[22:23], 0, v[172:173]
	s_mov_b32 m0, s34
	s_nop 0
	global_load_lds_dwordx4 v[224:225], off
	v_lshl_add_u64 v[224:225], s[22:23], 0, v[176:177]
	s_add_i32 m0, s34, 0x2000
	s_nop 0
	global_load_lds_dwordx4 v[224:225], off
	s_waitcnt lgkmcnt(0)
	s_waitcnt vmcnt(8)
	s_barrier
; #define PG8_MMA(ai, bj, At, Bt) do { __builtin_amdgcn_s_setprio(1); _Pragma("unroll") for (int m = 0; m < 4; ++m) _Pragma("unroll") for (int n = 0; n < 2; ++n) _Pragma("unroll") for (int k = 0; k < 2; ++k) \
;         acc[ai][bj][m][n] = __builtin_amdgcn_mfma_f32_16x16x32_bf16(Bt[n][k], At[m][k], acc[ai][bj][m][n], 0, 0, 0); __builtin_amdgcn_s_setprio(0); } while (0)
; #define PG8_WAIT_V(n) asm volatile("s_waitcnt vmcnt(" #n ")" ::: "memory")
; #define PG8_BAR __builtin_amdgcn_s_barrier()
; template <class Epi>
; __device__ __forceinline__ void gemm_phase(PG8_LAS unsigned char* lds, const Gemm g, const StaticOrder& S, const Epi& E) {
;     ...
;             PG8_WAIT_V(6); PG8_BAR; PG8_MMA(1, 1, At, B1); PG8_BAR;
;         }
;         E(acc, cur, wr, wc, fr, fq);
;     __device__ __forceinline__ void operator()(const f32x4 (&acc)[2][2][4][2], const pg8::Unit& u, int wr, int wc, int fr, int fq) const {
;         const int row0 = u.pm * 256 + wr * 64 + fr, col0 = u.pn * 256 + wc * 32 + 8 * fq;
; #pragma unroll
;         for (int ai = 0; ai < 2; ++ai) {
;             u32x4 la[4][2], lg[4][2];
; #pragma unroll
;             for (int m = 0; m < 4; ++m)
; #pragma unroll
;                 for (int bj = 0; bj < 2; ++bj) { const bf16_t* p = G + (size_t)(row0 + ai * 128 + m * 16) * LDG + col0 + bj * 128;
;                     la[m][bj] = *(const u32x4*)p; if (mode != 0) lg[m][bj] = *(const u32x4*)(p + 2048); else lg[m][bj] = la[m][bj]; }
	v_mfma_f32_16x16x32_bf16 v[60:63], v[128:131], v[144:147], v[60:63]
	v_mfma_f32_16x16x32_bf16 v[56:59], v[136:139], v[144:147], v[56:59]
	v_mfma_f32_16x16x32_bf16 v[44:47], v[128:131], v[152:155], v[44:47]
	v_mfma_f32_16x16x32_bf16 v[40:43], v[136:139], v[152:155], v[40:43]
	v_mfma_f32_16x16x32_bf16 v[28:31], v[128:131], v[160:163], v[28:31]
	v_mfma_f32_16x16x32_bf16 v[24:27], v[136:139], v[160:163], v[24:27]
	v_mfma_f32_16x16x32_bf16 v[12:15], v[128:131], v[186:189], v[12:15]
	v_mfma_f32_16x16x32_bf16 v[8:11], v[136:139], v[186:189], v[8:11]
	v_mfma_f32_16x16x32_bf16 v[60:63], v[132:135], v[148:151], v[60:63]
	v_mfma_f32_16x16x32_bf16 v[56:59], v[140:143], v[148:151], v[56:59]
	v_mfma_f32_16x16x32_bf16 v[44:47], v[132:135], v[156:159], v[44:47]
	v_mfma_f32_16x16x32_bf16 v[40:43], v[140:143], v[156:159], v[40:43]
	v_mfma_f32_16x16x32_bf16 v[28:31], v[132:135], v[164:167], v[28:31]
	v_mfma_f32_16x16x32_bf16 v[24:27], v[140:143], v[164:167], v[24:27]
	v_mfma_f32_16x16x32_bf16 v[12:15], v[132:135], v[190:193], v[12:15]
	v_mfma_f32_16x16x32_bf16 v[8:11], v[140:143], v[190:193], v[8:11]
	v_mfma_f32_16x16x32_bf16 v[52:55], v[202:205], v[144:147], v[52:55]
	v_mfma_f32_16x16x32_bf16 v[48:51], v[210:213], v[144:147], v[48:51]
	v_mfma_f32_16x16x32_bf16 v[36:39], v[202:205], v[152:155], v[36:39]
	v_mfma_f32_16x16x32_bf16 v[32:35], v[210:213], v[152:155], v[32:35]
	v_mfma_f32_16x16x32_bf16 v[20:23], v[202:205], v[160:163], v[20:23]
	v_mfma_f32_16x16x32_bf16 v[16:19], v[210:213], v[160:163], v[16:19]
	v_mfma_f32_16x16x32_bf16 v[4:7], v[202:205], v[186:189], v[4:7]
	v_mfma_f32_16x16x32_bf16 v[0:3], v[210:213], v[186:189], v[0:3]
	v_mfma_f32_16x16x32_bf16 v[52:55], v[206:209], v[148:151], v[52:55]
	v_mfma_f32_16x16x32_bf16 v[48:51], v[214:217], v[148:151], v[48:51]
	v_mfma_f32_16x16x32_bf16 v[36:39], v[206:209], v[156:159], v[36:39]
	v_mfma_f32_16x16x32_bf16 v[32:35], v[214:217], v[156:159], v[32:35]
	v_mfma_f32_16x16x32_bf16 v[20:23], v[206:209], v[164:167], v[20:23]
	v_mfma_f32_16x16x32_bf16 v[16:19], v[214:217], v[164:167], v[16:19]
	v_mfma_f32_16x16x32_bf16 v[4:7], v[206:209], v[190:193], v[4:7]
	v_mfma_f32_16x16x32_bf16 v[0:3], v[214:217], v[190:193], v[0:3]
	s_add_i32 s61, s61, 2
	s_add_u32 s30, s30, 0x100
	s_addc_u32 s31, s31, 0
	s_add_u32 s59, s59, 0x100
	s_addc_u32 s60, s60, 0
	s_cmp_gt_u32 s61, 13
	s_barrier
	s_cbranch_scc0 .LBB0_925
	s_setprio 0
	v_lshl_or_b32 v130, s56, 8, v197
	v_lshl_add_u32 v128, s28, 8, v169
	v_ashrrev_i32_e32 v131, 31, v130
	v_lshlrev_b64 v[186:187], 1, v[130:131]
	v_ashrrev_i32_e32 v129, 31, v128
	v_lshl_add_u64 v[188:189], s[46:47], 0, v[186:187]
	v_lshlrev_b64 v[190:191], 13, v[128:129]
	v_lshl_add_u64 v[130:131], v[188:189], 0, v[190:191]
	v_add_co_u32_e32 v132, vcc, 0x1000, v130
	global_load_dwordx4 v[202:205], v[130:131], off
	s_nop 0
	v_addc_co_u32_e32 v133, vcc, 0, v131, vcc
	global_load_dwordx4 v[206:209], v[132:133], off
	v_or_b32_e32 v134, 16, v128
	v_or_b32_e32 v136, 32, v128
	v_or_b32_e32 v128, 48, v128
	v_ashrrev_i32_e32 v135, 31, v134
	v_ashrrev_i32_e32 v137, 31, v136
	v_ashrrev_i32_e32 v129, 31, v128
	v_lshlrev_b64 v[226:227], 13, v[134:135]
	v_lshlrev_b64 v[194:195], 13, v[136:137]
	v_lshlrev_b64 v[192:193], 13, v[128:129]
	v_lshl_add_u64 v[128:129], s[46:47], 0, v[190:191]
	v_lshl_add_u64 v[134:135], v[188:189], 0, v[226:227]
	v_lshl_add_u64 v[140:141], v[188:189], 0, v[194:195]
	v_lshl_add_u64 v[142:143], v[188:189], 0, v[192:193]
	v_lshl_add_u64 v[228:229], v[128:129], 0, v[186:187]
	global_load_dwordx4 v[210:213], v[130:131], off offset:256
	global_load_dwordx4 v[214:217], v[134:135], off
	global_load_dwordx4 v[164:167], v[134:135], off offset:256
	global_load_dwordx4 v[152:155], v[140:141], off
	global_load_dwordx4 v[144:147], v[140:141], off offset:256
	global_load_dwordx4 v[136:139], v[142:143], off
	global_load_dwordx4 v[128:131], v[142:143], off offset:256
	global_load_dwordx4 v[218:221], v[132:133], off offset:256
	v_add_co_u32_e32 v134, vcc, 0x1000, v134
	s_mov_b32 s56, s14
	s_nop 0
	v_addc_co_u32_e32 v135, vcc, 0, v135, vcc
	global_load_dwordx4 v[222:225], v[134:135], off
	global_load_dwordx4 v[160:163], v[134:135], off offset:256
	v_add_co_u32_e32 v132, vcc, 0x1000, v140
	s_mov_b32 s28, s16
	s_nop 0
	v_addc_co_u32_e32 v133, vcc, 0, v141, vcc
	global_load_dwordx4 v[156:159], v[132:133], off
	global_load_dwordx4 v[148:151], v[132:133], off offset:256
	v_add_co_u32_e32 v134, vcc, 0x1000, v142
	s_mov_b64 s[22:23], s[20:21]
	s_nop 0
	v_addc_co_u32_e32 v135, vcc, 0, v143, vcc
	global_load_dwordx4 v[140:143], v[134:135], off
	s_nop 0
	global_load_dwordx4 v[132:135], v[134:135], off offset:256
	s_mov_b64 s[30:31], s[18:19]
	s_waitcnt vmcnt(0)
; __device__ __forceinline__ float sigmoidf_(float x) { return __builtin_amdgcn_rcpf(1.0f + __expf(-x)); }
; __device__ __forceinline__ u32x4 pack8(const float (&f)[8]) { u32x4 w; w.x = cvt_pk_bf16(f[0], f[1]); w.y = cvt_pk_bf16(f[2], f[3]); w.z = cvt_pk_bf16(f[4], f[5]); w.w = cvt_pk_bf16(f[6], f[7]); return w; }
;     __device__ __forceinline__ void operator()(const f32x4 (&acc)[2][2][4][2], const pg8::Unit& u, int wr, int wc, int fr, int fq) const {
;     ...
;                     float a[8], gt[8], o[8];
;                     unpack8(la[m][bj], a);
;                     if (mode == 0) {
; #pragma unroll
;                         for (int n = 0; n < 2; ++n)
; #pragma unroll
;                             for (int i = 0; i < 4; ++i) o[n * 4 + i] = sigmoidf_(a[n * 4 + i]) * acc[ai][bj][m][n][i];
;                     } else {
;                         unpack8(lg[m][bj], gt);
; #pragma unroll
;                         for (int n = 0; n < 2; ++n)
; #pragma unroll
;                             for (int i = 0; i < 4; ++i) o[n * 4 + i] = a[n * 4 + i] + sigmoidf_(gt[n * 4 + i]) * acc[ai][bj][m][n][i];
;                     }
;                     *(u32x4*)p = pack8(o);
	v_lshlrev_b32_e32 v201, 16, v202
	v_and_b32_e32 v202, 0xffff0000, v202
	v_lshlrev_b32_e32 v230, 16, v203
	v_lshlrev_b32_e32 v233, 16, v206
	v_and_b32_e32 v206, 0xffff0000, v206
	v_lshlrev_b32_e32 v234, 16, v207
	v_mul_f32_e32 v206, 0xbfb8aa3b, v206
	v_mul_f32_e32 v234, 0xbfb8aa3b, v234
	v_mul_f32_e32 v233, 0xbfb8aa3b, v233
	v_exp_f32_e32 v206, v206
	v_exp_f32_e32 v234, v234
	v_exp_f32_e32 v233, v233
	v_and_b32_e32 v207, 0xffff0000, v207
	v_lshlrev_b32_e32 v235, 16, v208
	v_and_b32_e32 v208, 0xffff0000, v208
	v_mul_f32_e32 v207, 0xbfb8aa3b, v207
	v_mul_f32_e32 v235, 0xbfb8aa3b, v235
	v_mul_f32_e32 v208, 0xbfb8aa3b, v208
	v_exp_f32_e32 v207, v207
	v_add_f32_e32 v206, 1.0, v206
	v_add_f32_e32 v234, 1.0, v234
	v_exp_f32_e32 v235, v235
	v_exp_f32_e32 v208, v208
	v_add_f32_e32 v233, 1.0, v233
	v_rcp_f32_e32 v206, v206
	v_rcp_f32_e32 v234, v234
	v_rcp_f32_e32 v233, v233
	v_lshlrev_b32_e32 v236, 16, v209
	v_add_f32_e32 v207, 1.0, v207
	v_add_f32_e32 v235, 1.0, v235
	v_rcp_f32_e32 v207, v207
	v_fmac_f32_e32 v202, v125, v206
	v_fmac_f32_e32 v230, v126, v234
	v_add_f32_e32 v125, 1.0, v208
	v_mul_f32_e32 v126, 0xbfb8aa3b, v236
	v_fmac_f32_e32 v201, v124, v233
	v_rcp_f32_e32 v124, v235
	v_exp_f32_e32 v126, v126
	v_rcp_f32_e32 v125, v125
	v_and_b32_e32 v203, 0xffff0000, v203
	v_and_b32_e32 v209, 0xffff0000, v209
	v_lshlrev_b32_e32 v231, 16, v204
	v_and_b32_e32 v204, 0xffff0000, v204
	v_fmac_f32_e32 v203, v127, v207
	v_mul_f32_e32 v127, 0xbfb8aa3b, v209
	v_exp_f32_e32 v127, v127
	v_add_f32_e32 v126, 1.0, v126
	v_fmac_f32_e32 v231, v120, v124
	v_fmac_f32_e32 v204, v121, v125
	v_cvt_pk_bf16_f32 v120, v201, v202
	v_cvt_pk_bf16_f32 v121, v230, v203
	v_lshlrev_b32_e32 v201, 16, v218
	v_and_b32_e32 v202, 0xffff0000, v218
	v_lshlrev_b32_e32 v203, 16, v219
	v_rcp_f32_e32 v126, v126
	v_mul_f32_e32 v201, 0xbfb8aa3b, v201
	v_mul_f32_e32 v202, 0xbfb8aa3b, v202
	v_mul_f32_e32 v203, 0xbfb8aa3b, v203
	v_exp_f32_e32 v201, v201
	v_exp_f32_e32 v202, v202
	v_exp_f32_e32 v203, v203
	v_lshlrev_b32_e32 v232, 16, v205
	v_add_f32_e32 v127, 1.0, v127
	v_rcp_f32_e32 v127, v127
	v_fmac_f32_e32 v232, v122, v126
	v_cvt_pk_bf16_f32 v122, v231, v204
	v_and_b32_e32 v204, 0xffff0000, v219
	v_add_f32_e32 v201, 1.0, v201
	v_add_f32_e32 v202, 1.0, v202
	v_add_f32_e32 v203, 1.0, v203
	v_mul_f32_e32 v204, 0xbfb8aa3b, v204
	v_rcp_f32_e32 v201, v201
	v_rcp_f32_e32 v202, v202
	v_rcp_f32_e32 v203, v203
	v_exp_f32_e32 v204, v204
	v_and_b32_e32 v205, 0xffff0000, v205
	v_fmac_f32_e32 v205, v123, v127
	v_cvt_pk_bf16_f32 v123, v232, v205
	global_store_dwordx4 v[228:229], v[120:123], off
	v_lshlrev_b32_e32 v205, 16, v220
	v_and_b32_e32 v206, 0xffff0000, v220
	v_lshlrev_b32_e32 v120, 16, v210
	v_and_b32_e32 v121, 0xffff0000, v210
	v_lshlrev_b32_e32 v122, 16, v211
	v_fmac_f32_e32 v120, v116, v201
	v_fmac_f32_e32 v121, v117, v202
	v_fmac_f32_e32 v122, v118, v203
	v_add_f32_e32 v116, 1.0, v204
	v_mul_f32_e32 v117, 0xbfb8aa3b, v205
	v_mul_f32_e32 v118, 0xbfb8aa3b, v206
	v_rcp_f32_e32 v116, v116
	v_exp_f32_e32 v117, v117
	v_exp_f32_e32 v118, v118
	v_and_b32_e32 v123, 0xffff0000, v211
	v_lshlrev_b32_e32 v207, 16, v221
	v_fmac_f32_e32 v123, v119, v116
	v_add_f32_e32 v116, 1.0, v117
	v_add_f32_e32 v117, 1.0, v118
	v_mul_f32_e32 v118, 0xbfb8aa3b, v207
	v_exp_f32_e32 v118, v118
	v_rcp_f32_e32 v116, v116
	v_rcp_f32_e32 v117, v117
	v_lshlrev_b32_e32 v124, 16, v212
	v_add_f32_e32 v118, 1.0, v118
	v_rcp_f32_e32 v118, v118
	v_and_b32_e32 v208, 0xffff0000, v221
	v_and_b32_e32 v125, 0xffff0000, v212
	v_lshlrev_b32_e32 v126, 16, v213
	v_mul_f32_e32 v119, 0xbfb8aa3b, v208
	v_fmac_f32_e32 v124, v112, v116
	v_exp_f32_e32 v119, v119
	v_fmac_f32_e32 v125, v113, v117
	v_fmac_f32_e32 v126, v114, v118
	v_cvt_pk_bf16_f32 v112, v120, v121
	v_cvt_pk_bf16_f32 v113, v122, v123
	v_cvt_pk_bf16_f32 v114, v124, v125
	v_lshlrev_b32_e32 v122, 16, v222
	v_and_b32_e32 v123, 0xffff0000, v222
	v_lshlrev_b32_e32 v124, 16, v223
	v_mul_f32_e32 v122, 0xbfb8aa3b, v122
	v_mul_f32_e32 v123, 0xbfb8aa3b, v123
	v_mul_f32_e32 v124, 0xbfb8aa3b, v124
	v_exp_f32_e32 v122, v122
	v_exp_f32_e32 v123, v123
	v_exp_f32_e32 v124, v124
	v_add_f32_e32 v119, 1.0, v119
	v_rcp_f32_e32 v119, v119
	v_and_b32_e32 v125, 0xffff0000, v223
	v_add_f32_e32 v122, 1.0, v122
	v_add_f32_e32 v123, 1.0, v123
	v_add_f32_e32 v124, 1.0, v124
	v_mul_f32_e32 v125, 0xbfb8aa3b, v125
	v_rcp_f32_e32 v122, v122
	v_rcp_f32_e32 v123, v123
	v_rcp_f32_e32 v124, v124
	v_exp_f32_e32 v125, v125
	v_and_b32_e32 v127, 0xffff0000, v213
	v_fmac_f32_e32 v127, v115, v119
	v_cvt_pk_bf16_f32 v115, v126, v127
	global_store_dwordx4 v[228:229], v[112:115], off offset:256
	v_lshlrev_b32_e32 v116, 16, v215
	v_lshlrev_b32_e32 v126, 16, v224
	v_lshlrev_b32_e32 v114, 16, v214
	v_and_b32_e32 v115, 0xffff0000, v214
	v_and_b32_e32 v127, 0xffff0000, v224
	v_fmac_f32_e32 v114, v108, v122
	v_fmac_f32_e32 v115, v109, v123
	v_fmac_f32_e32 v116, v110, v124
	v_add_f32_e32 v108, 1.0, v125
	v_mul_f32_e32 v109, 0xbfb8aa3b, v126
	v_mul_f32_e32 v110, 0xbfb8aa3b, v127
	v_rcp_f32_e32 v108, v108
	v_exp_f32_e32 v109, v109
	v_exp_f32_e32 v110, v110
	v_and_b32_e32 v117, 0xffff0000, v215
	v_fmac_f32_e32 v117, v111, v108
	v_add_f32_e32 v108, 1.0, v109
	v_add_f32_e32 v109, 1.0, v110
	v_rcp_f32_e32 v108, v108
	v_rcp_f32_e32 v109, v109
	v_lshlrev_b32_e32 v201, 16, v225
	v_lshlrev_b32_e32 v118, 16, v216
	v_and_b32_e32 v119, 0xffff0000, v216
	v_and_b32_e32 v202, 0xffff0000, v225
	v_mul_f32_e32 v110, 0xbfb8aa3b, v201
	v_exp_f32_e32 v110, v110
	v_mul_f32_e32 v111, 0xbfb8aa3b, v202
	v_fmac_f32_e32 v118, v104, v108
	v_fmac_f32_e32 v119, v105, v109
	v_cvt_pk_bf16_f32 v104, v114, v115
	v_cvt_pk_bf16_f32 v105, v116, v117
	v_lshlrev_b32_e32 v114, 16, v160
; __device__ __forceinline__ float sigmoidf_(float x) { return __builtin_amdgcn_rcpf(1.0f + __expf(-x)); }
; __device__ __forceinline__ u32x4 pack8(const float (&f)[8]) { u32x4 w; w.x = cvt_pk_bf16(f[0], f[1]); w.y = cvt_pk_bf16(f[2], f[3]); w.z = cvt_pk_bf16(f[4], f[5]); w.w = cvt_pk_bf16(f[6], f[7]); return w; }
;     __device__ __forceinline__ void operator()(const f32x4 (&acc)[2][2][4][2], const pg8::Unit& u, int wr, int wc, int fr, int fq) const {
;     ...
;                     float a[8], gt[8], o[8];
;                     unpack8(la[m][bj], a);
;                     if (mode == 0) {
; #pragma unroll
;                         for (int n = 0; n < 2; ++n)
; #pragma unroll
;                             for (int i = 0; i < 4; ++i) o[n * 4 + i] = sigmoidf_(a[n * 4 + i]) * acc[ai][bj][m][n][i];
;                     } else {
;                         unpack8(lg[m][bj], gt);
; #pragma unroll
;                         for (int n = 0; n < 2; ++n)
; #pragma unroll
;                             for (int i = 0; i < 4; ++i) o[n * 4 + i] = a[n * 4 + i] + sigmoidf_(gt[n * 4 + i]) * acc[ai][bj][m][n][i];
;                     }
;                     *(u32x4*)p = pack8(o);
	v_and_b32_e32 v115, 0xffff0000, v160
	v_lshlrev_b32_e32 v116, 16, v161
	v_exp_f32_e32 v111, v111
	v_mul_f32_e32 v114, 0xbfb8aa3b, v114
	v_mul_f32_e32 v115, 0xbfb8aa3b, v115
	v_mul_f32_e32 v116, 0xbfb8aa3b, v116
	v_exp_f32_e32 v114, v114
	v_exp_f32_e32 v115, v115
	v_exp_f32_e32 v116, v116
	v_add_f32_e32 v110, 1.0, v110
	v_rcp_f32_e32 v110, v110
	v_add_f32_e32 v111, 1.0, v111
	v_and_b32_e32 v117, 0xffff0000, v161
	v_rcp_f32_e32 v111, v111
	v_add_f32_e32 v114, 1.0, v114
	v_add_f32_e32 v115, 1.0, v115
	v_add_f32_e32 v116, 1.0, v116
	v_mul_f32_e32 v117, 0xbfb8aa3b, v117
	v_rcp_f32_e32 v114, v114
	v_rcp_f32_e32 v115, v115
	v_rcp_f32_e32 v116, v116
	v_exp_f32_e32 v117, v117
	v_lshl_add_u64 v[112:113], s[46:47], 0, v[226:227]
	v_lshlrev_b32_e32 v120, 16, v217
	v_lshl_add_u64 v[112:113], v[112:113], 0, v[186:187]
	v_and_b32_e32 v121, 0xffff0000, v217
	v_fmac_f32_e32 v120, v106, v110
	v_cvt_pk_bf16_f32 v106, v118, v119
	v_fmac_f32_e32 v121, v107, v111
	v_cvt_pk_bf16_f32 v107, v120, v121
	global_store_dwordx4 v[112:113], v[104:107], off
	v_lshlrev_b32_e32 v118, 16, v162
	v_and_b32_e32 v119, 0xffff0000, v162
	v_lshlrev_b32_e32 v104, 16, v164
	v_and_b32_e32 v105, 0xffff0000, v164
	v_lshlrev_b32_e32 v106, 16, v165
	v_fmac_f32_e32 v104, v100, v114
	v_fmac_f32_e32 v105, v101, v115
	v_fmac_f32_e32 v106, v102, v116
	v_add_f32_e32 v100, 1.0, v117
	v_mul_f32_e32 v101, 0xbfb8aa3b, v118
	v_mul_f32_e32 v102, 0xbfb8aa3b, v119
	v_rcp_f32_e32 v100, v100
	v_exp_f32_e32 v101, v101
	v_exp_f32_e32 v102, v102
	v_and_b32_e32 v107, 0xffff0000, v165
	v_lshlrev_b32_e32 v120, 16, v163
	v_fmac_f32_e32 v107, v103, v100
	v_add_f32_e32 v100, 1.0, v101
	v_add_f32_e32 v101, 1.0, v102
	v_mul_f32_e32 v102, 0xbfb8aa3b, v120
	v_exp_f32_e32 v102, v102
	v_rcp_f32_e32 v100, v100
	v_rcp_f32_e32 v101, v101
	v_lshlrev_b32_e32 v108, 16, v166
	v_add_f32_e32 v102, 1.0, v102
	v_rcp_f32_e32 v102, v102
	v_and_b32_e32 v121, 0xffff0000, v163
	v_and_b32_e32 v109, 0xffff0000, v166
	v_lshlrev_b32_e32 v110, 16, v167
	v_mul_f32_e32 v103, 0xbfb8aa3b, v121
	v_fmac_f32_e32 v108, v96, v100
	v_exp_f32_e32 v103, v103
	v_fmac_f32_e32 v109, v97, v101
	v_fmac_f32_e32 v110, v98, v102
	v_cvt_pk_bf16_f32 v96, v104, v105
	v_cvt_pk_bf16_f32 v97, v106, v107
	v_cvt_pk_bf16_f32 v98, v108, v109
	v_lshlrev_b32_e32 v106, 16, v156
	v_and_b32_e32 v107, 0xffff0000, v156
	v_lshlrev_b32_e32 v108, 16, v157
	v_mul_f32_e32 v106, 0xbfb8aa3b, v106
	v_mul_f32_e32 v107, 0xbfb8aa3b, v107
	v_mul_f32_e32 v108, 0xbfb8aa3b, v108
	v_exp_f32_e32 v106, v106
	v_exp_f32_e32 v107, v107
	v_exp_f32_e32 v108, v108
	v_add_f32_e32 v103, 1.0, v103
	v_rcp_f32_e32 v103, v103
	v_and_b32_e32 v109, 0xffff0000, v157
	v_add_f32_e32 v106, 1.0, v106
	v_add_f32_e32 v107, 1.0, v107
	v_add_f32_e32 v108, 1.0, v108
	v_mul_f32_e32 v109, 0xbfb8aa3b, v109
	v_rcp_f32_e32 v106, v106
	v_rcp_f32_e32 v107, v107
	v_rcp_f32_e32 v108, v108
	v_exp_f32_e32 v109, v109
	v_and_b32_e32 v111, 0xffff0000, v167
	v_fmac_f32_e32 v111, v99, v103
	v_cvt_pk_bf16_f32 v99, v110, v111
	global_store_dwordx4 v[112:113], v[96:99], off offset:256
	v_lshlrev_b32_e32 v100, 16, v153
	v_lshlrev_b32_e32 v110, 16, v158
	v_lshlrev_b32_e32 v98, 16, v152
	v_and_b32_e32 v99, 0xffff0000, v152
	v_and_b32_e32 v111, 0xffff0000, v158
	v_fmac_f32_e32 v98, v92, v106
	v_fmac_f32_e32 v99, v93, v107
	v_fmac_f32_e32 v100, v94, v108
	v_add_f32_e32 v92, 1.0, v109
	v_mul_f32_e32 v93, 0xbfb8aa3b, v110
	v_mul_f32_e32 v94, 0xbfb8aa3b, v111
	v_rcp_f32_e32 v92, v92
	v_exp_f32_e32 v93, v93
	v_exp_f32_e32 v94, v94
	v_and_b32_e32 v101, 0xffff0000, v153
	v_fmac_f32_e32 v101, v95, v92
	v_add_f32_e32 v92, 1.0, v93
	v_add_f32_e32 v93, 1.0, v94
	v_rcp_f32_e32 v92, v92
	v_rcp_f32_e32 v93, v93
	v_lshlrev_b32_e32 v112, 16, v159
	v_lshlrev_b32_e32 v102, 16, v154
	v_and_b32_e32 v103, 0xffff0000, v154
	v_and_b32_e32 v113, 0xffff0000, v159
	v_mul_f32_e32 v94, 0xbfb8aa3b, v112
	v_exp_f32_e32 v94, v94
	v_mul_f32_e32 v95, 0xbfb8aa3b, v113
	v_fmac_f32_e32 v102, v88, v92
	v_fmac_f32_e32 v103, v89, v93
	v_cvt_pk_bf16_f32 v88, v98, v99
	v_cvt_pk_bf16_f32 v89, v100, v101
	v_lshlrev_b32_e32 v98, 16, v148
	v_and_b32_e32 v99, 0xffff0000, v148
	v_lshlrev_b32_e32 v100, 16, v149
	v_exp_f32_e32 v95, v95
	v_mul_f32_e32 v98, 0xbfb8aa3b, v98
	v_mul_f32_e32 v99, 0xbfb8aa3b, v99
	v_mul_f32_e32 v100, 0xbfb8aa3b, v100
	v_exp_f32_e32 v98, v98
	v_exp_f32_e32 v99, v99
	v_exp_f32_e32 v100, v100
	v_add_f32_e32 v94, 1.0, v94
	v_rcp_f32_e32 v94, v94
	v_add_f32_e32 v95, 1.0, v95
	v_and_b32_e32 v101, 0xffff0000, v149
	v_rcp_f32_e32 v95, v95
	v_add_f32_e32 v98, 1.0, v98
	v_add_f32_e32 v99, 1.0, v99
	v_add_f32_e32 v100, 1.0, v100
	v_mul_f32_e32 v101, 0xbfb8aa3b, v101
	v_rcp_f32_e32 v98, v98
	v_rcp_f32_e32 v99, v99
	v_rcp_f32_e32 v100, v100
	v_exp_f32_e32 v101, v101
	v_lshl_add_u64 v[96:97], s[46:47], 0, v[194:195]
	v_lshlrev_b32_e32 v104, 16, v155
	v_lshl_add_u64 v[96:97], v[96:97], 0, v[186:187]
	v_and_b32_e32 v105, 0xffff0000, v155
	v_fmac_f32_e32 v104, v90, v94
	v_cvt_pk_bf16_f32 v90, v102, v103
	v_fmac_f32_e32 v105, v91, v95
	v_cvt_pk_bf16_f32 v91, v104, v105
	global_store_dwordx4 v[96:97], v[88:91], off
	v_lshlrev_b32_e32 v102, 16, v150
	v_and_b32_e32 v103, 0xffff0000, v150
	v_lshlrev_b32_e32 v88, 16, v144
	v_and_b32_e32 v89, 0xffff0000, v144
	v_lshlrev_b32_e32 v90, 16, v145
	v_fmac_f32_e32 v88, v84, v98
	v_fmac_f32_e32 v89, v85, v99
	v_fmac_f32_e32 v90, v86, v100
	v_add_f32_e32 v84, 1.0, v101
	v_mul_f32_e32 v85, 0xbfb8aa3b, v102
	v_mul_f32_e32 v86, 0xbfb8aa3b, v103
	v_rcp_f32_e32 v84, v84
	v_exp_f32_e32 v85, v85
	v_exp_f32_e32 v86, v86
	v_and_b32_e32 v91, 0xffff0000, v145
	v_lshlrev_b32_e32 v104, 16, v151
	v_fmac_f32_e32 v91, v87, v84
	v_add_f32_e32 v84, 1.0, v85
; __device__ __forceinline__ float sigmoidf_(float x) { return __builtin_amdgcn_rcpf(1.0f + __expf(-x)); }
; __device__ __forceinline__ u32x4 pack8(const float (&f)[8]) { u32x4 w; w.x = cvt_pk_bf16(f[0], f[1]); w.y = cvt_pk_bf16(f[2], f[3]); w.z = cvt_pk_bf16(f[4], f[5]); w.w = cvt_pk_bf16(f[6], f[7]); return w; }
;     __device__ __forceinline__ void operator()(const f32x4 (&acc)[2][2][4][2], const pg8::Unit& u, int wr, int wc, int fr, int fq) const {
;     ...
;         for (int ai = 0; ai < 2; ++ai) {
;             u32x4 la[4][2], lg[4][2];
; #pragma unroll
;             for (int m = 0; m < 4; ++m)
; #pragma unroll
;                 for (int bj = 0; bj < 2; ++bj) { const bf16_t* p = G + (size_t)(row0 + ai * 128 + m * 16) * LDG + col0 + bj * 128;
;                     la[m][bj] = *(const u32x4*)p; if (mode != 0) lg[m][bj] = *(const u32x4*)(p + 2048); else lg[m][bj] = la[m][bj]; }
; #pragma unroll
;             for (int m = 0; m < 4; ++m)
; #pragma unroll
;                 for (int bj = 0; bj < 2; ++bj) {
;                     bf16_t* p = G + (size_t)(row0 + ai * 128 + m * 16) * LDG + col0 + bj * 128;
;                     float a[8], gt[8], o[8];
;                     unpack8(la[m][bj], a);
;                     if (mode == 0) {
; #pragma unroll
;                         for (int n = 0; n < 2; ++n)
; #pragma unroll
;                             for (int i = 0; i < 4; ++i) o[n * 4 + i] = sigmoidf_(a[n * 4 + i]) * acc[ai][bj][m][n][i];
;                     } else {
;                         unpack8(lg[m][bj], gt);
; #pragma unroll
;                         for (int n = 0; n < 2; ++n)
; #pragma unroll
;                             for (int i = 0; i < 4; ++i) o[n * 4 + i] = a[n * 4 + i] + sigmoidf_(gt[n * 4 + i]) * acc[ai][bj][m][n][i];
;                     }
;                     *(u32x4*)p = pack8(o);
	v_add_f32_e32 v85, 1.0, v86
	v_mul_f32_e32 v86, 0xbfb8aa3b, v104
	v_exp_f32_e32 v86, v86
	v_rcp_f32_e32 v84, v84
	v_rcp_f32_e32 v85, v85
	v_lshlrev_b32_e32 v92, 16, v146
	v_add_f32_e32 v86, 1.0, v86
	v_rcp_f32_e32 v86, v86
	v_and_b32_e32 v105, 0xffff0000, v151
	v_and_b32_e32 v93, 0xffff0000, v146
	v_lshlrev_b32_e32 v94, 16, v147
	v_mul_f32_e32 v87, 0xbfb8aa3b, v105
	v_fmac_f32_e32 v92, v80, v84
	v_exp_f32_e32 v87, v87
	v_fmac_f32_e32 v93, v81, v85
	v_fmac_f32_e32 v94, v82, v86
	v_cvt_pk_bf16_f32 v80, v88, v89
	v_cvt_pk_bf16_f32 v81, v90, v91
	v_cvt_pk_bf16_f32 v82, v92, v93
	v_lshlrev_b32_e32 v90, 16, v140
	v_and_b32_e32 v91, 0xffff0000, v140
	v_lshlrev_b32_e32 v92, 16, v141
	v_mul_f32_e32 v90, 0xbfb8aa3b, v90
	v_mul_f32_e32 v91, 0xbfb8aa3b, v91
	v_mul_f32_e32 v92, 0xbfb8aa3b, v92
	v_exp_f32_e32 v90, v90
	v_exp_f32_e32 v91, v91
	v_exp_f32_e32 v92, v92
	v_add_f32_e32 v87, 1.0, v87
	v_rcp_f32_e32 v87, v87
	v_and_b32_e32 v93, 0xffff0000, v141
	v_add_f32_e32 v90, 1.0, v90
	v_add_f32_e32 v91, 1.0, v91
	v_add_f32_e32 v92, 1.0, v92
	v_mul_f32_e32 v93, 0xbfb8aa3b, v93
	v_rcp_f32_e32 v90, v90
	v_rcp_f32_e32 v91, v91
	v_rcp_f32_e32 v92, v92
	v_exp_f32_e32 v93, v93
	v_and_b32_e32 v95, 0xffff0000, v147
	v_fmac_f32_e32 v95, v83, v87
	v_cvt_pk_bf16_f32 v83, v94, v95
	global_store_dwordx4 v[96:97], v[80:83], off offset:256
	v_lshlrev_b32_e32 v84, 16, v137
	v_lshlrev_b32_e32 v94, 16, v142
	v_lshlrev_b32_e32 v82, 16, v136
	v_and_b32_e32 v83, 0xffff0000, v136
	v_and_b32_e32 v95, 0xffff0000, v142
	v_fmac_f32_e32 v82, v76, v90
	v_fmac_f32_e32 v83, v77, v91
	v_fmac_f32_e32 v84, v78, v92
	v_add_f32_e32 v76, 1.0, v93
	v_mul_f32_e32 v77, 0xbfb8aa3b, v94
	v_mul_f32_e32 v78, 0xbfb8aa3b, v95
	v_rcp_f32_e32 v76, v76
	v_exp_f32_e32 v77, v77
	v_exp_f32_e32 v78, v78
	v_and_b32_e32 v85, 0xffff0000, v137
	v_fmac_f32_e32 v85, v79, v76
	v_add_f32_e32 v76, 1.0, v77
	v_add_f32_e32 v77, 1.0, v78
	v_rcp_f32_e32 v76, v76
	v_rcp_f32_e32 v77, v77
	v_lshlrev_b32_e32 v96, 16, v143
	v_lshlrev_b32_e32 v86, 16, v138
	v_and_b32_e32 v87, 0xffff0000, v138
	v_and_b32_e32 v97, 0xffff0000, v143
	v_mul_f32_e32 v78, 0xbfb8aa3b, v96
	v_exp_f32_e32 v78, v78
	v_mul_f32_e32 v79, 0xbfb8aa3b, v97
	v_fmac_f32_e32 v86, v72, v76
	v_fmac_f32_e32 v87, v73, v77
	v_cvt_pk_bf16_f32 v72, v82, v83
	v_cvt_pk_bf16_f32 v73, v84, v85
	v_lshlrev_b32_e32 v82, 16, v132
	v_and_b32_e32 v83, 0xffff0000, v132
	v_lshlrev_b32_e32 v84, 16, v133
	v_exp_f32_e32 v79, v79
	v_mul_f32_e32 v82, 0xbfb8aa3b, v82
	v_mul_f32_e32 v83, 0xbfb8aa3b, v83
	v_mul_f32_e32 v84, 0xbfb8aa3b, v84
	v_exp_f32_e32 v82, v82
	v_exp_f32_e32 v83, v83
	v_exp_f32_e32 v84, v84
	v_add_f32_e32 v78, 1.0, v78
	v_rcp_f32_e32 v78, v78
	v_add_f32_e32 v79, 1.0, v79
	v_and_b32_e32 v85, 0xffff0000, v133
	v_rcp_f32_e32 v79, v79
	v_add_f32_e32 v82, 1.0, v82
	v_add_f32_e32 v83, 1.0, v83
	v_add_f32_e32 v84, 1.0, v84
	v_mul_f32_e32 v85, 0xbfb8aa3b, v85
	v_rcp_f32_e32 v82, v82
	v_rcp_f32_e32 v83, v83
	v_rcp_f32_e32 v84, v84
	v_exp_f32_e32 v85, v85
	v_lshl_add_u64 v[80:81], s[46:47], 0, v[192:193]
	v_lshlrev_b32_e32 v88, 16, v139
	v_lshl_add_u64 v[80:81], v[80:81], 0, v[186:187]
	v_and_b32_e32 v89, 0xffff0000, v139
	v_fmac_f32_e32 v88, v74, v78
	v_cvt_pk_bf16_f32 v74, v86, v87
	v_fmac_f32_e32 v89, v75, v79
	v_cvt_pk_bf16_f32 v75, v88, v89
	global_store_dwordx4 v[80:81], v[72:75], off
	v_lshlrev_b32_e32 v86, 16, v134
	v_and_b32_e32 v87, 0xffff0000, v134
	v_lshlrev_b32_e32 v72, 16, v128
	v_and_b32_e32 v73, 0xffff0000, v128
	v_lshlrev_b32_e32 v74, 16, v129
	v_fmac_f32_e32 v72, v68, v82
	v_fmac_f32_e32 v73, v69, v83
	v_fmac_f32_e32 v74, v70, v84
	v_add_f32_e32 v68, 1.0, v85
	v_mul_f32_e32 v69, 0xbfb8aa3b, v86
	v_mul_f32_e32 v70, 0xbfb8aa3b, v87
	v_rcp_f32_e32 v68, v68
	v_exp_f32_e32 v69, v69
	v_exp_f32_e32 v70, v70
	v_and_b32_e32 v75, 0xffff0000, v129
	v_lshlrev_b32_e32 v88, 16, v135
	v_and_b32_e32 v89, 0xffff0000, v135
	v_fmac_f32_e32 v75, v71, v68
	v_add_f32_e32 v68, 1.0, v69
	v_add_f32_e32 v69, 1.0, v70
	v_mul_f32_e32 v70, 0xbfb8aa3b, v88
	v_exp_f32_e32 v70, v70
	v_mul_f32_e32 v71, 0xbfb8aa3b, v89
	v_exp_f32_e32 v71, v71
	v_rcp_f32_e32 v68, v68
	v_rcp_f32_e32 v69, v69
	v_add_f32_e32 v70, 1.0, v70
	v_rcp_f32_e32 v70, v70
	v_add_f32_e32 v71, 1.0, v71
	v_rcp_f32_e32 v71, v71
	v_lshlrev_b32_e32 v76, 16, v130
	v_and_b32_e32 v77, 0xffff0000, v130
	v_lshl_add_u64 v[132:133], v[190:191], 0, s[6:7]
	v_lshlrev_b32_e32 v78, 16, v131
	v_fmac_f32_e32 v76, v64, v68
	v_fmac_f32_e32 v77, v65, v69
	v_lshl_add_u64 v[68:69], v[188:189], 0, v[132:133]
	v_and_b32_e32 v79, 0xffff0000, v131
	v_fmac_f32_e32 v78, v66, v70
	v_add_co_u32_e32 v70, vcc, s55, v68
	v_fmac_f32_e32 v79, v67, v71
	s_nop 0
	v_addc_co_u32_e32 v71, vcc, 0, v69, vcc
	v_cvt_pk_bf16_f32 v64, v72, v73
	v_cvt_pk_bf16_f32 v65, v74, v75
	v_cvt_pk_bf16_f32 v66, v76, v77
	v_cvt_pk_bf16_f32 v67, v78, v79
	global_load_dwordx4 v[108:111], v[68:69], off
	global_load_dwordx4 v[112:115], v[70:71], off
	v_lshl_add_u64 v[134:135], v[190:191], 0, s[8:9]
	global_store_dwordx4 v[80:81], v[64:67], off offset:256
	global_load_dwordx4 v[116:119], v[68:69], off offset:256
	global_load_dwordx4 v[120:123], v[70:71], off offset:256
	v_lshl_add_u64 v[64:65], v[188:189], 0, v[134:135]
	v_add_co_u32_e32 v66, vcc, s55, v64
	v_lshl_add_u64 v[106:107], v[190:191], 0, s[10:11]
	s_nop 0
	v_addc_co_u32_e32 v67, vcc, 0, v65, vcc
	global_load_dwordx4 v[124:127], v[64:65], off
	global_load_dwordx4 v[100:103], v[64:65], off offset:256
	global_load_dwordx4 v[128:131], v[66:67], off
	global_load_dwordx4 v[96:99], v[66:67], off offset:256
	v_lshl_add_u64 v[64:65], v[188:189], 0, v[106:107]
	v_add_co_u32_e32 v66, vcc, s55, v64
	v_lshl_add_u64 v[104:105], v[190:191], 0, s[12:13]
	s_nop 0
	v_addc_co_u32_e32 v67, vcc, 0, v65, vcc
	global_load_dwordx4 v[92:95], v[64:65], off
	global_load_dwordx4 v[84:87], v[64:65], off offset:256
	global_load_dwordx4 v[88:91], v[66:67], off
	global_load_dwordx4 v[80:83], v[66:67], off offset:256
	v_lshl_add_u64 v[64:65], v[188:189], 0, v[104:105]
	v_add_co_u32_e32 v66, vcc, s55, v64
	v_lshl_add_u64 v[132:133], s[46:47], 0, v[132:133]
	s_nop 0
	v_addc_co_u32_e32 v67, vcc, 0, v65, vcc
	global_load_dwordx4 v[76:79], v[64:65], off
	global_load_dwordx4 v[68:71], v[64:65], off offset:256
	global_load_dwordx4 v[72:75], v[66:67], off
	s_nop 0
	global_load_dwordx4 v[64:67], v[66:67], off offset:256
	v_lshl_add_u64 v[132:133], v[132:133], 0, v[186:187]
	s_and_b64 vcc, exec, s[2:3]
	s_waitcnt vmcnt(0)
; __device__ __forceinline__ float sigmoidf_(float x) { return __builtin_amdgcn_rcpf(1.0f + __expf(-x)); }
; __device__ __forceinline__ u32x4 pack8(const float (&f)[8]) { u32x4 w; w.x = cvt_pk_bf16(f[0], f[1]); w.y = cvt_pk_bf16(f[2], f[3]); w.z = cvt_pk_bf16(f[4], f[5]); w.w = cvt_pk_bf16(f[6], f[7]); return w; }
;     __device__ __forceinline__ void operator()(const f32x4 (&acc)[2][2][4][2], const pg8::Unit& u, int wr, int wc, int fr, int fq) const {
;     ...
;                     float a[8], gt[8], o[8];
;                     unpack8(la[m][bj], a);
;                     if (mode == 0) {
; #pragma unroll
;                         for (int n = 0; n < 2; ++n)
; #pragma unroll
;                             for (int i = 0; i < 4; ++i) o[n * 4 + i] = sigmoidf_(a[n * 4 + i]) * acc[ai][bj][m][n][i];
;                     } else {
;                         unpack8(lg[m][bj], gt);
; #pragma unroll
;                         for (int n = 0; n < 2; ++n)
; #pragma unroll
;                             for (int i = 0; i < 4; ++i) o[n * 4 + i] = a[n * 4 + i] + sigmoidf_(gt[n * 4 + i]) * acc[ai][bj][m][n][i];
;                     }
;                     *(u32x4*)p = pack8(o);
	v_lshlrev_b32_e32 v136, 16, v108
	v_lshlrev_b32_e32 v140, 16, v112
	v_and_b32_e32 v112, 0xffff0000, v112
	v_lshlrev_b32_e32 v141, 16, v113
	v_mul_f32_e32 v140, 0xbfb8aa3b, v140
	v_mul_f32_e32 v112, 0xbfb8aa3b, v112
	v_mul_f32_e32 v141, 0xbfb8aa3b, v141
	v_exp_f32_e32 v140, v140
	v_exp_f32_e32 v112, v112
	v_exp_f32_e32 v141, v141
	v_and_b32_e32 v113, 0xffff0000, v113
	v_add_f32_e32 v140, 1.0, v140
	v_add_f32_e32 v112, 1.0, v112
	v_add_f32_e32 v141, 1.0, v141
	v_mul_f32_e32 v113, 0xbfb8aa3b, v113
	v_rcp_f32_e32 v140, v140
	v_rcp_f32_e32 v112, v112
	v_rcp_f32_e32 v141, v141
	v_exp_f32_e32 v113, v113
	v_and_b32_e32 v108, 0xffff0000, v108
	v_lshlrev_b32_e32 v137, 16, v109
	v_lshlrev_b32_e32 v142, 16, v114
	v_and_b32_e32 v114, 0xffff0000, v114
	v_fmac_f32_e32 v136, v60, v140
	v_fmac_f32_e32 v108, v61, v112
	v_fmac_f32_e32 v137, v62, v141
	v_add_f32_e32 v60, 1.0, v113
	v_mul_f32_e32 v61, 0xbfb8aa3b, v142
	v_mul_f32_e32 v62, 0xbfb8aa3b, v114
	v_rcp_f32_e32 v60, v60
	v_exp_f32_e32 v61, v61
	v_exp_f32_e32 v62, v62
	v_and_b32_e32 v109, 0xffff0000, v109
	v_lshlrev_b32_e32 v143, 16, v115
	v_fmac_f32_e32 v109, v63, v60
	v_add_f32_e32 v60, 1.0, v61
	v_add_f32_e32 v61, 1.0, v62
	v_mul_f32_e32 v62, 0xbfb8aa3b, v143
	v_exp_f32_e32 v62, v62
	v_and_b32_e32 v115, 0xffff0000, v115
	v_mul_f32_e32 v63, 0xbfb8aa3b, v115
	v_exp_f32_e32 v63, v63
	v_rcp_f32_e32 v61, v61
	v_add_f32_e32 v62, 1.0, v62
	v_rcp_f32_e32 v60, v60
	v_rcp_f32_e32 v62, v62
	v_lshlrev_b32_e32 v138, 16, v110
	v_and_b32_e32 v110, 0xffff0000, v110
	v_lshlrev_b32_e32 v139, 16, v111
	v_add_f32_e32 v63, 1.0, v63
	v_fmac_f32_e32 v110, v57, v61
	v_rcp_f32_e32 v63, v63
	v_fmac_f32_e32 v138, v56, v60
	v_fmac_f32_e32 v139, v58, v62
	v_cvt_pk_bf16_f32 v56, v136, v108
	v_cvt_pk_bf16_f32 v57, v137, v109
	v_cvt_pk_bf16_f32 v58, v138, v110
	v_lshlrev_b32_e32 v108, 16, v120
	v_and_b32_e32 v109, 0xffff0000, v120
	v_lshlrev_b32_e32 v110, 16, v121
	v_mul_f32_e32 v108, 0xbfb8aa3b, v108
	v_mul_f32_e32 v109, 0xbfb8aa3b, v109
	v_mul_f32_e32 v110, 0xbfb8aa3b, v110
	v_exp_f32_e32 v108, v108
	v_exp_f32_e32 v109, v109
	v_exp_f32_e32 v110, v110
	v_and_b32_e32 v111, 0xffff0000, v111
	v_fmac_f32_e32 v111, v59, v63
	v_cvt_pk_bf16_f32 v59, v139, v111
	v_and_b32_e32 v111, 0xffff0000, v121
	v_add_f32_e32 v108, 1.0, v108
	v_add_f32_e32 v109, 1.0, v109
	v_add_f32_e32 v110, 1.0, v110
	v_mul_f32_e32 v111, 0xbfb8aa3b, v111
	v_rcp_f32_e32 v108, v108
	v_rcp_f32_e32 v109, v109
	v_rcp_f32_e32 v110, v110
	v_exp_f32_e32 v111, v111
	global_store_dwordx4 v[132:133], v[56:59], off
	v_lshlrev_b32_e32 v112, 16, v122
	v_and_b32_e32 v113, 0xffff0000, v122
	v_lshlrev_b32_e32 v56, 16, v116
	v_and_b32_e32 v57, 0xffff0000, v116
	v_lshlrev_b32_e32 v58, 16, v117
	v_fmac_f32_e32 v56, v52, v108
	v_fmac_f32_e32 v57, v53, v109
	v_fmac_f32_e32 v58, v54, v110
	v_add_f32_e32 v52, 1.0, v111
	v_mul_f32_e32 v53, 0xbfb8aa3b, v112
	v_mul_f32_e32 v54, 0xbfb8aa3b, v113
	v_rcp_f32_e32 v52, v52
	v_exp_f32_e32 v53, v53
	v_exp_f32_e32 v54, v54
	v_and_b32_e32 v59, 0xffff0000, v117
	v_lshlrev_b32_e32 v114, 16, v123
	v_fmac_f32_e32 v59, v55, v52
	v_add_f32_e32 v52, 1.0, v53
	v_add_f32_e32 v53, 1.0, v54
	v_mul_f32_e32 v54, 0xbfb8aa3b, v114
	v_exp_f32_e32 v54, v54
	v_rcp_f32_e32 v52, v52
	v_rcp_f32_e32 v53, v53
	v_lshlrev_b32_e32 v60, 16, v118
	v_add_f32_e32 v54, 1.0, v54
	v_rcp_f32_e32 v54, v54
	v_and_b32_e32 v115, 0xffff0000, v123
	v_and_b32_e32 v61, 0xffff0000, v118
	v_lshlrev_b32_e32 v62, 16, v119
	v_mul_f32_e32 v55, 0xbfb8aa3b, v115
	v_fmac_f32_e32 v60, v48, v52
	v_exp_f32_e32 v55, v55
	v_fmac_f32_e32 v61, v49, v53
	v_fmac_f32_e32 v62, v50, v54
	v_cvt_pk_bf16_f32 v48, v56, v57
	v_cvt_pk_bf16_f32 v49, v58, v59
	v_cvt_pk_bf16_f32 v50, v60, v61
	v_lshlrev_b32_e32 v58, 16, v128
	v_and_b32_e32 v59, 0xffff0000, v128
	v_lshlrev_b32_e32 v60, 16, v129
	v_mul_f32_e32 v58, 0xbfb8aa3b, v58
	v_mul_f32_e32 v59, 0xbfb8aa3b, v59
	v_mul_f32_e32 v60, 0xbfb8aa3b, v60
	v_exp_f32_e32 v58, v58
	v_exp_f32_e32 v59, v59
	v_exp_f32_e32 v60, v60
	v_add_f32_e32 v55, 1.0, v55
	v_rcp_f32_e32 v55, v55
	v_and_b32_e32 v61, 0xffff0000, v129
	v_add_f32_e32 v58, 1.0, v58
	v_add_f32_e32 v59, 1.0, v59
	v_add_f32_e32 v60, 1.0, v60
	v_mul_f32_e32 v61, 0xbfb8aa3b, v61
	v_rcp_f32_e32 v58, v58
	v_rcp_f32_e32 v59, v59
	v_rcp_f32_e32 v60, v60
	v_exp_f32_e32 v61, v61
	v_and_b32_e32 v63, 0xffff0000, v119
	v_fmac_f32_e32 v63, v51, v55
	v_cvt_pk_bf16_f32 v51, v62, v63
	global_store_dwordx4 v[132:133], v[48:51], off offset:256
	v_lshlrev_b32_e32 v52, 16, v125
	v_lshlrev_b32_e32 v62, 16, v130
	v_lshlrev_b32_e32 v50, 16, v124
	v_and_b32_e32 v51, 0xffff0000, v124
	v_and_b32_e32 v63, 0xffff0000, v130
	v_fmac_f32_e32 v50, v44, v58
	v_fmac_f32_e32 v51, v45, v59
	v_fmac_f32_e32 v52, v46, v60
	v_add_f32_e32 v44, 1.0, v61
	v_mul_f32_e32 v45, 0xbfb8aa3b, v62
	v_mul_f32_e32 v46, 0xbfb8aa3b, v63
	v_rcp_f32_e32 v44, v44
	v_exp_f32_e32 v45, v45
	v_exp_f32_e32 v46, v46
	v_and_b32_e32 v53, 0xffff0000, v125
	v_fmac_f32_e32 v53, v47, v44
	v_add_f32_e32 v44, 1.0, v45
	v_add_f32_e32 v45, 1.0, v46
	v_rcp_f32_e32 v44, v44
	v_rcp_f32_e32 v45, v45
	v_lshlrev_b32_e32 v108, 16, v131
	v_lshlrev_b32_e32 v54, 16, v126
	v_and_b32_e32 v55, 0xffff0000, v126
	v_and_b32_e32 v109, 0xffff0000, v131
	v_mul_f32_e32 v46, 0xbfb8aa3b, v108
	v_exp_f32_e32 v46, v46
	v_mul_f32_e32 v47, 0xbfb8aa3b, v109
	v_fmac_f32_e32 v54, v40, v44
	v_fmac_f32_e32 v55, v41, v45
	v_cvt_pk_bf16_f32 v40, v50, v51
	v_cvt_pk_bf16_f32 v41, v52, v53
	v_lshlrev_b32_e32 v50, 16, v96
	v_and_b32_e32 v51, 0xffff0000, v96
	v_lshlrev_b32_e32 v52, 16, v97
	v_exp_f32_e32 v47, v47
	v_mul_f32_e32 v50, 0xbfb8aa3b, v50
	v_mul_f32_e32 v51, 0xbfb8aa3b, v51
	v_mul_f32_e32 v52, 0xbfb8aa3b, v52
; __device__ __forceinline__ float sigmoidf_(float x) { return __builtin_amdgcn_rcpf(1.0f + __expf(-x)); }
; __device__ __forceinline__ u32x4 pack8(const float (&f)[8]) { u32x4 w; w.x = cvt_pk_bf16(f[0], f[1]); w.y = cvt_pk_bf16(f[2], f[3]); w.z = cvt_pk_bf16(f[4], f[5]); w.w = cvt_pk_bf16(f[6], f[7]); return w; }
;     __device__ __forceinline__ void operator()(const f32x4 (&acc)[2][2][4][2], const pg8::Unit& u, int wr, int wc, int fr, int fq) const {
;     ...
;                     float a[8], gt[8], o[8];
;                     unpack8(la[m][bj], a);
;                     if (mode == 0) {
; #pragma unroll
;                         for (int n = 0; n < 2; ++n)
; #pragma unroll
;                             for (int i = 0; i < 4; ++i) o[n * 4 + i] = sigmoidf_(a[n * 4 + i]) * acc[ai][bj][m][n][i];
;                     } else {
;                         unpack8(lg[m][bj], gt);
; #pragma unroll
;                         for (int n = 0; n < 2; ++n)
; #pragma unroll
;                             for (int i = 0; i < 4; ++i) o[n * 4 + i] = a[n * 4 + i] + sigmoidf_(gt[n * 4 + i]) * acc[ai][bj][m][n][i];
;                     }
;                     *(u32x4*)p = pack8(o);
	v_exp_f32_e32 v50, v50
	v_exp_f32_e32 v51, v51
	v_exp_f32_e32 v52, v52
	v_add_f32_e32 v46, 1.0, v46
	v_rcp_f32_e32 v46, v46
	v_add_f32_e32 v47, 1.0, v47
	v_and_b32_e32 v53, 0xffff0000, v97
	v_rcp_f32_e32 v47, v47
	v_add_f32_e32 v50, 1.0, v50
	v_add_f32_e32 v51, 1.0, v51
	v_add_f32_e32 v52, 1.0, v52
	v_mul_f32_e32 v53, 0xbfb8aa3b, v53
	v_rcp_f32_e32 v50, v50
	v_rcp_f32_e32 v51, v51
	v_rcp_f32_e32 v52, v52
	v_exp_f32_e32 v53, v53
	v_lshl_add_u64 v[48:49], s[46:47], 0, v[134:135]
	v_lshlrev_b32_e32 v56, 16, v127
	v_lshl_add_u64 v[48:49], v[48:49], 0, v[186:187]
	v_and_b32_e32 v57, 0xffff0000, v127
	v_fmac_f32_e32 v56, v42, v46
	v_cvt_pk_bf16_f32 v42, v54, v55
	v_fmac_f32_e32 v57, v43, v47
	v_cvt_pk_bf16_f32 v43, v56, v57
	global_store_dwordx4 v[48:49], v[40:43], off
	v_lshlrev_b32_e32 v54, 16, v98
	v_and_b32_e32 v55, 0xffff0000, v98
	v_lshlrev_b32_e32 v40, 16, v100
	v_and_b32_e32 v41, 0xffff0000, v100
	v_lshlrev_b32_e32 v42, 16, v101
	v_fmac_f32_e32 v40, v36, v50
	v_fmac_f32_e32 v41, v37, v51
	v_fmac_f32_e32 v42, v38, v52
	v_add_f32_e32 v36, 1.0, v53
	v_mul_f32_e32 v37, 0xbfb8aa3b, v54
	v_mul_f32_e32 v38, 0xbfb8aa3b, v55
	v_rcp_f32_e32 v36, v36
	v_exp_f32_e32 v37, v37
	v_exp_f32_e32 v38, v38
	v_and_b32_e32 v43, 0xffff0000, v101
	v_lshlrev_b32_e32 v56, 16, v99
	v_fmac_f32_e32 v43, v39, v36
	v_add_f32_e32 v36, 1.0, v37
	v_add_f32_e32 v37, 1.0, v38
	v_mul_f32_e32 v38, 0xbfb8aa3b, v56
	v_exp_f32_e32 v38, v38
	v_rcp_f32_e32 v36, v36
	v_rcp_f32_e32 v37, v37
	v_lshlrev_b32_e32 v44, 16, v102
	v_add_f32_e32 v38, 1.0, v38
	v_rcp_f32_e32 v38, v38
	v_and_b32_e32 v57, 0xffff0000, v99
	v_and_b32_e32 v45, 0xffff0000, v102
	v_lshlrev_b32_e32 v46, 16, v103
	v_mul_f32_e32 v39, 0xbfb8aa3b, v57
	v_fmac_f32_e32 v44, v32, v36
	v_exp_f32_e32 v39, v39
	v_fmac_f32_e32 v45, v33, v37
	v_fmac_f32_e32 v46, v34, v38
	v_cvt_pk_bf16_f32 v32, v40, v41
	v_cvt_pk_bf16_f32 v33, v42, v43
	v_cvt_pk_bf16_f32 v34, v44, v45
	v_lshlrev_b32_e32 v42, 16, v88
	v_and_b32_e32 v43, 0xffff0000, v88
	v_lshlrev_b32_e32 v44, 16, v89
	v_mul_f32_e32 v42, 0xbfb8aa3b, v42
	v_mul_f32_e32 v43, 0xbfb8aa3b, v43
	v_mul_f32_e32 v44, 0xbfb8aa3b, v44
	v_exp_f32_e32 v42, v42
	v_exp_f32_e32 v43, v43
	v_exp_f32_e32 v44, v44
	v_add_f32_e32 v39, 1.0, v39
	v_rcp_f32_e32 v39, v39
	v_and_b32_e32 v45, 0xffff0000, v89
	v_add_f32_e32 v42, 1.0, v42
	v_add_f32_e32 v43, 1.0, v43
	v_add_f32_e32 v44, 1.0, v44
	v_mul_f32_e32 v45, 0xbfb8aa3b, v45
	v_rcp_f32_e32 v42, v42
	v_rcp_f32_e32 v43, v43
	v_rcp_f32_e32 v44, v44
	v_exp_f32_e32 v45, v45
	v_and_b32_e32 v47, 0xffff0000, v103
	v_fmac_f32_e32 v47, v35, v39
	v_cvt_pk_bf16_f32 v35, v46, v47
	global_store_dwordx4 v[48:49], v[32:35], off offset:256
	v_lshlrev_b32_e32 v36, 16, v93
	v_lshlrev_b32_e32 v46, 16, v90
	v_lshlrev_b32_e32 v34, 16, v92
	v_and_b32_e32 v35, 0xffff0000, v92
	v_and_b32_e32 v47, 0xffff0000, v90
	v_fmac_f32_e32 v34, v28, v42
	v_fmac_f32_e32 v35, v29, v43
	v_fmac_f32_e32 v36, v30, v44
	v_add_f32_e32 v28, 1.0, v45
	v_mul_f32_e32 v29, 0xbfb8aa3b, v46
	v_mul_f32_e32 v30, 0xbfb8aa3b, v47
	v_rcp_f32_e32 v28, v28
	v_exp_f32_e32 v29, v29
	v_exp_f32_e32 v30, v30
	v_and_b32_e32 v37, 0xffff0000, v93
	v_fmac_f32_e32 v37, v31, v28
	v_add_f32_e32 v28, 1.0, v29
	v_add_f32_e32 v29, 1.0, v30
	v_rcp_f32_e32 v28, v28
	v_rcp_f32_e32 v29, v29
	v_lshlrev_b32_e32 v48, 16, v91
	v_lshlrev_b32_e32 v38, 16, v94
	v_and_b32_e32 v39, 0xffff0000, v94
	v_and_b32_e32 v49, 0xffff0000, v91
	v_mul_f32_e32 v30, 0xbfb8aa3b, v48
	v_exp_f32_e32 v30, v30
	v_mul_f32_e32 v31, 0xbfb8aa3b, v49
	v_fmac_f32_e32 v38, v24, v28
	v_fmac_f32_e32 v39, v25, v29
	v_cvt_pk_bf16_f32 v24, v34, v35
	v_cvt_pk_bf16_f32 v25, v36, v37
	v_lshlrev_b32_e32 v34, 16, v80
	v_and_b32_e32 v35, 0xffff0000, v80
	v_lshlrev_b32_e32 v36, 16, v81
	v_exp_f32_e32 v31, v31
	v_mul_f32_e32 v34, 0xbfb8aa3b, v34
	v_mul_f32_e32 v35, 0xbfb8aa3b, v35
	v_mul_f32_e32 v36, 0xbfb8aa3b, v36
	v_exp_f32_e32 v34, v34
	v_exp_f32_e32 v35, v35
	v_exp_f32_e32 v36, v36
	v_add_f32_e32 v30, 1.0, v30
	v_rcp_f32_e32 v30, v30
	v_add_f32_e32 v31, 1.0, v31
	v_and_b32_e32 v37, 0xffff0000, v81
	v_rcp_f32_e32 v31, v31
	v_add_f32_e32 v34, 1.0, v34
	v_add_f32_e32 v35, 1.0, v35
	v_add_f32_e32 v36, 1.0, v36
	v_mul_f32_e32 v37, 0xbfb8aa3b, v37
	v_rcp_f32_e32 v34, v34
	v_rcp_f32_e32 v35, v35
	v_rcp_f32_e32 v36, v36
	v_exp_f32_e32 v37, v37
	v_lshl_add_u64 v[32:33], s[46:47], 0, v[106:107]
	v_lshlrev_b32_e32 v40, 16, v95
	v_lshl_add_u64 v[32:33], v[32:33], 0, v[186:187]
	v_and_b32_e32 v41, 0xffff0000, v95
	v_fmac_f32_e32 v40, v26, v30
	v_cvt_pk_bf16_f32 v26, v38, v39
	v_fmac_f32_e32 v41, v27, v31
	v_cvt_pk_bf16_f32 v27, v40, v41
	global_store_dwordx4 v[32:33], v[24:27], off
	v_lshlrev_b32_e32 v38, 16, v82
	v_and_b32_e32 v39, 0xffff0000, v82
	v_lshlrev_b32_e32 v24, 16, v84
	v_and_b32_e32 v25, 0xffff0000, v84
	v_lshlrev_b32_e32 v26, 16, v85
	v_fmac_f32_e32 v24, v20, v34
	v_fmac_f32_e32 v25, v21, v35
	v_fmac_f32_e32 v26, v22, v36
	v_add_f32_e32 v20, 1.0, v37
; __device__ __forceinline__ float sigmoidf_(float x) { return __builtin_amdgcn_rcpf(1.0f + __expf(-x)); }
; __device__ __forceinline__ u32x4 pack8(const float (&f)[8]) { u32x4 w; w.x = cvt_pk_bf16(f[0], f[1]); w.y = cvt_pk_bf16(f[2], f[3]); w.z = cvt_pk_bf16(f[4], f[5]); w.w = cvt_pk_bf16(f[6], f[7]); return w; }
; #define PG8_WAIT_V(n) asm volatile("s_waitcnt vmcnt(" #n ")" ::: "memory")
; #define PG8_BAR __builtin_amdgcn_s_barrier()
; template <class Epi>
; __device__ __forceinline__ void gemm_phase(PG8_LAS unsigned char* lds, const Gemm g, const StaticOrder& S, const Epi& E) {
;     ...
;         if (!has_next) break;
; #pragma unroll
;         for (int a = 0; a < 2; ++a)
; #pragma unroll
;             for (int b = 0; b < 2; ++b)
; #pragma unroll
;                 for (int m = 0; m < 4; ++m)
; #pragma unroll
;                     for (int n = 0; n < 2; ++n) acc[a][b][m][n] = (f32x4){0.f, 0.f, 0.f, 0.f};
;         cur = nxt; cA = nA; cB = nB; ++ui;
;     }
;     PG8_WAIT_V(0);
;     if (wr == 0) PG8_BAR;
;     __device__ __forceinline__ void operator()(const f32x4 (&acc)[2][2][4][2], const pg8::Unit& u, int wr, int wc, int fr, int fq) const {
;     ...
;                     float a[8], gt[8], o[8];
;                     unpack8(la[m][bj], a);
;                     if (mode == 0) {
; #pragma unroll
;                         for (int n = 0; n < 2; ++n)
; #pragma unroll
;                             for (int i = 0; i < 4; ++i) o[n * 4 + i] = sigmoidf_(a[n * 4 + i]) * acc[ai][bj][m][n][i];
;                     } else {
;                         unpack8(lg[m][bj], gt);
; #pragma unroll
;                         for (int n = 0; n < 2; ++n)
; #pragma unroll
;                             for (int i = 0; i < 4; ++i) o[n * 4 + i] = a[n * 4 + i] + sigmoidf_(gt[n * 4 + i]) * acc[ai][bj][m][n][i];
;                     }
;                     *(u32x4*)p = pack8(o);
	v_mul_f32_e32 v21, 0xbfb8aa3b, v38
	v_mul_f32_e32 v22, 0xbfb8aa3b, v39
	v_rcp_f32_e32 v20, v20
	v_exp_f32_e32 v21, v21
	v_exp_f32_e32 v22, v22
	v_and_b32_e32 v27, 0xffff0000, v85
	v_lshlrev_b32_e32 v40, 16, v83
	v_fmac_f32_e32 v27, v23, v20
	v_add_f32_e32 v20, 1.0, v21
	v_add_f32_e32 v21, 1.0, v22
	v_mul_f32_e32 v22, 0xbfb8aa3b, v40
	v_exp_f32_e32 v22, v22
	v_rcp_f32_e32 v20, v20
	v_rcp_f32_e32 v21, v21
	v_lshlrev_b32_e32 v28, 16, v86
	v_add_f32_e32 v22, 1.0, v22
	v_rcp_f32_e32 v22, v22
	v_and_b32_e32 v41, 0xffff0000, v83
	v_and_b32_e32 v29, 0xffff0000, v86
	v_lshlrev_b32_e32 v30, 16, v87
	v_mul_f32_e32 v23, 0xbfb8aa3b, v41
	v_fmac_f32_e32 v28, v16, v20
	v_exp_f32_e32 v23, v23
	v_fmac_f32_e32 v29, v17, v21
	v_fmac_f32_e32 v30, v18, v22
	v_cvt_pk_bf16_f32 v16, v24, v25
	v_cvt_pk_bf16_f32 v17, v26, v27
	v_cvt_pk_bf16_f32 v18, v28, v29
	v_lshlrev_b32_e32 v26, 16, v72
	v_and_b32_e32 v27, 0xffff0000, v72
	v_lshlrev_b32_e32 v28, 16, v73
	v_mul_f32_e32 v26, 0xbfb8aa3b, v26
	v_mul_f32_e32 v27, 0xbfb8aa3b, v27
	v_mul_f32_e32 v28, 0xbfb8aa3b, v28
	v_exp_f32_e32 v26, v26
	v_exp_f32_e32 v27, v27
	v_exp_f32_e32 v28, v28
	v_add_f32_e32 v23, 1.0, v23
	v_rcp_f32_e32 v23, v23
	v_and_b32_e32 v29, 0xffff0000, v73
	v_add_f32_e32 v26, 1.0, v26
	v_add_f32_e32 v27, 1.0, v27
	v_add_f32_e32 v28, 1.0, v28
	v_mul_f32_e32 v29, 0xbfb8aa3b, v29
	v_rcp_f32_e32 v26, v26
	v_rcp_f32_e32 v27, v27
	v_rcp_f32_e32 v28, v28
	v_exp_f32_e32 v29, v29
	v_and_b32_e32 v31, 0xffff0000, v87
	v_fmac_f32_e32 v31, v19, v23
	v_cvt_pk_bf16_f32 v19, v30, v31
	global_store_dwordx4 v[32:33], v[16:19], off offset:256
	v_lshlrev_b32_e32 v20, 16, v77
	v_lshlrev_b32_e32 v30, 16, v74
	v_lshlrev_b32_e32 v18, 16, v76
	v_and_b32_e32 v19, 0xffff0000, v76
	v_and_b32_e32 v31, 0xffff0000, v74
	v_fmac_f32_e32 v18, v12, v26
	v_fmac_f32_e32 v19, v13, v27
	v_fmac_f32_e32 v20, v14, v28
	v_add_f32_e32 v12, 1.0, v29
	v_mul_f32_e32 v13, 0xbfb8aa3b, v30
	v_mul_f32_e32 v14, 0xbfb8aa3b, v31
	v_rcp_f32_e32 v12, v12
	v_exp_f32_e32 v13, v13
	v_exp_f32_e32 v14, v14
	v_and_b32_e32 v21, 0xffff0000, v77
	v_fmac_f32_e32 v21, v15, v12
	v_add_f32_e32 v12, 1.0, v13
	v_add_f32_e32 v13, 1.0, v14
	v_rcp_f32_e32 v12, v12
	v_rcp_f32_e32 v13, v13
	v_lshlrev_b32_e32 v32, 16, v75
	v_lshlrev_b32_e32 v22, 16, v78
	v_and_b32_e32 v23, 0xffff0000, v78
	v_and_b32_e32 v33, 0xffff0000, v75
	v_mul_f32_e32 v14, 0xbfb8aa3b, v32
	v_exp_f32_e32 v14, v14
	v_mul_f32_e32 v15, 0xbfb8aa3b, v33
	v_fmac_f32_e32 v22, v8, v12
	v_fmac_f32_e32 v23, v9, v13
	v_cvt_pk_bf16_f32 v8, v18, v19
	v_cvt_pk_bf16_f32 v9, v20, v21
	v_lshlrev_b32_e32 v18, 16, v64
	v_and_b32_e32 v19, 0xffff0000, v64
	v_lshlrev_b32_e32 v20, 16, v65
	v_exp_f32_e32 v15, v15
	v_mul_f32_e32 v18, 0xbfb8aa3b, v18
	v_mul_f32_e32 v19, 0xbfb8aa3b, v19
	v_mul_f32_e32 v20, 0xbfb8aa3b, v20
	v_exp_f32_e32 v18, v18
	v_exp_f32_e32 v19, v19
	v_exp_f32_e32 v20, v20
	v_add_f32_e32 v14, 1.0, v14
	v_rcp_f32_e32 v14, v14
	v_add_f32_e32 v15, 1.0, v15
	v_and_b32_e32 v21, 0xffff0000, v65
	v_rcp_f32_e32 v15, v15
	v_add_f32_e32 v18, 1.0, v18
	v_add_f32_e32 v19, 1.0, v19
	v_add_f32_e32 v20, 1.0, v20
	v_mul_f32_e32 v21, 0xbfb8aa3b, v21
	v_rcp_f32_e32 v18, v18
	v_rcp_f32_e32 v19, v19
	v_rcp_f32_e32 v20, v20
	v_exp_f32_e32 v21, v21
	v_lshl_add_u64 v[16:17], s[46:47], 0, v[104:105]
	v_lshlrev_b32_e32 v24, 16, v79
	v_lshl_add_u64 v[16:17], v[16:17], 0, v[186:187]
	v_and_b32_e32 v25, 0xffff0000, v79
	v_fmac_f32_e32 v24, v10, v14
	v_cvt_pk_bf16_f32 v10, v22, v23
	v_fmac_f32_e32 v25, v11, v15
	v_cvt_pk_bf16_f32 v11, v24, v25
	global_store_dwordx4 v[16:17], v[8:11], off
	v_lshlrev_b32_e32 v22, 16, v66
	v_and_b32_e32 v23, 0xffff0000, v66
	v_lshlrev_b32_e32 v8, 16, v68
	v_and_b32_e32 v9, 0xffff0000, v68
	v_lshlrev_b32_e32 v10, 16, v69
	v_fmac_f32_e32 v8, v4, v18
	v_fmac_f32_e32 v9, v5, v19
	v_fmac_f32_e32 v10, v6, v20
	v_add_f32_e32 v4, 1.0, v21
	v_mul_f32_e32 v5, 0xbfb8aa3b, v22
	v_mul_f32_e32 v6, 0xbfb8aa3b, v23
	v_rcp_f32_e32 v4, v4
	v_exp_f32_e32 v5, v5
	v_exp_f32_e32 v6, v6
	v_and_b32_e32 v11, 0xffff0000, v69
	v_lshlrev_b32_e32 v24, 16, v67
	v_and_b32_e32 v25, 0xffff0000, v67
	v_fmac_f32_e32 v11, v7, v4
	v_add_f32_e32 v4, 1.0, v5
	v_add_f32_e32 v5, 1.0, v6
	v_mul_f32_e32 v6, 0xbfb8aa3b, v24
	v_mul_f32_e32 v7, 0xbfb8aa3b, v25
	v_exp_f32_e32 v6, v6
	v_exp_f32_e32 v7, v7
	v_rcp_f32_e32 v4, v4
	v_rcp_f32_e32 v5, v5
	v_add_f32_e32 v6, 1.0, v6
	v_add_f32_e32 v7, 1.0, v7
	v_rcp_f32_e32 v6, v6
	v_rcp_f32_e32 v7, v7
	v_lshlrev_b32_e32 v12, 16, v70
	v_and_b32_e32 v13, 0xffff0000, v70
	v_lshlrev_b32_e32 v14, 16, v71
	v_and_b32_e32 v15, 0xffff0000, v71
	v_fmac_f32_e32 v12, v0, v4
	v_fmac_f32_e32 v13, v1, v5
	v_fmac_f32_e32 v14, v2, v6
	v_fmac_f32_e32 v15, v3, v7
	v_cvt_pk_bf16_f32 v0, v8, v9
	v_cvt_pk_bf16_f32 v1, v10, v11
	v_cvt_pk_bf16_f32 v2, v12, v13
	v_cvt_pk_bf16_f32 v3, v14, v15
	global_store_dwordx4 v[16:17], v[0:3], off offset:256
	s_cbranch_vccz .LBB0_918
	s_waitcnt vmcnt(0)
	s_cmpk_gt_u32 s36, 0xff
	s_cbranch_scc1 .LBB0_929
	s_barrier

; #define PG8_STAGE(bufoff, gbase, voff) do { _Pragma("unroll") for (int _i = 0; _i < 2; ++_i) \
;         __builtin_amdgcn_global_load_lds((const unsigned*)((const char*)(gbase) + (voff)[_i]), (PG8_LAS unsigned*)(lds + (bufoff) + ldsw + _i * 8192), 16, 0, 0); } while (0)
; #define PG8_LDA(dst, b, h) do { _Pragma("unroll") for (int m = 0; m < 4; ++m) _Pragma("unroll") for (int k = 0; k < 2; ++k) dst[m][k] = *(const PG8_LAS bf16x8*)(lds + PG8_SA(b, h) + aoff + m * 2048 + k * 1024); } while (0)
; #define PG8_LDB(dst, b, h) do { _Pragma("unroll") for (int n = 0; n < 2; ++n) _Pragma("unroll") for (int k = 0; k < 2; ++k) dst[n][k] = *(const PG8_LAS bf16x8*)(lds + PG8_SB(b, h) + boff + n * 2048 + k * 1024); } while (0)
; #define PG8_MMA(ai, bj, At, Bt) do { __builtin_amdgcn_s_setprio(1); _Pragma("unroll") for (int m = 0; m < 4; ++m) _Pragma("unroll") for (int n = 0; n < 2; ++n) _Pragma("unroll") for (int k = 0; k < 2; ++k) \
;         acc[ai][bj][m][n] = __builtin_amdgcn_mfma_f32_16x16x32_bf16(Bt[n][k], At[m][k], acc[ai][bj][m][n], 0, 0, 0); __builtin_amdgcn_s_setprio(0); } while (0)
; template <class Epi>
; __device__ __forceinline__ void gemm_phase(PG8_LAS unsigned char* lds, const Gemm g, const StaticOrder& S, const Epi& E) {
;     ...
;         const bool has_next = S.next(ui + 1, nxt);
;         const char* nA = has_next ? (const char*)g.A + (size_t)nxt.pm * tstepA : cA; const char* nB = has_next ? (const char*)g.Bt + (size_t)nxt.pn * tstepB : cB;
;         for (int t = 0; t < nt; t += 2) {
;             const bool last = (t == nt - 2);
;             const char* a1 = cA + (size_t)(t + 1) * kstep;
;             const char* a2 = last ? nA : cA + (size_t)(t + 2) * kstep; const char* b2 = last ? nB : cB + (size_t)(t + 2) * kstep;
;             const char* a3 = a2 + kstep; const char* b3 = b2 + kstep;
;             PG8_LDB(B0, 0, 0); PG8_SCHED; PG8_LDA(At, 0, 0); PG8_STAGE(PG8_SA(1, 1), a1 + hstepA, voffA);
;             PG8_WAIT_L(8); PG8_BAR; PG8_WAIT_L(0); PG8_MMA(0, 0, At, B0); PG8_BAR; PG8_SCHED;
;     ...
; #pragma unroll
;         for (int a = 0; a < 2; ++a)
; #pragma unroll
;             for (int b = 0; b < 2; ++b)
; #pragma unroll
;                 for (int m = 0; m < 4; ++m)
; #pragma unroll
;                     for (int n = 0; n < 2; ++n) acc[a][b][m][n] = (f32x4){0.f, 0.f, 0.f, 0.f};
;         cur = nxt; cA = nA; cB = nB; ++ui;
.LBB0_1002:
	s_ashr_i32 s15, s14, 31
	v_cmp_lt_i64_e32 vcc, s[16:17], v[164:165]
	s_lshl_b64 s[16:17], s[14:15], 21
	s_add_u32 s16, s46, s16
	s_addc_u32 s17, s47, s17
	s_and_b64 s[18:19], vcc, exec
	s_cselect_b32 s15, s17, s29
	s_cselect_b32 s21, s16, s28
	s_ashr_i32 s13, s12, 31
	s_lshl_b64 s[18:19], s[12:13], 20
	v_readlane_b32 s30, v253, 40
	v_readlane_b32 s31, v253, 41
	s_add_u32 s18, s30, s18
	s_addc_u32 s19, s31, s19
	s_and_b64 s[30:31], vcc, exec
	s_cselect_b32 s13, s19, s23
	s_cselect_b32 s53, s18, s22
	s_add_u32 s28, s28, 0x100080
	s_addc_u32 s29, s29, 0
	s_add_u32 s54, s22, 0x100
	v_mov_b32_e32 v0, 0
	s_addc_u32 s55, s23, 0
	s_mov_b32 s56, -2
	s_waitcnt lgkmcnt(0)
	v_mov_b32_e32 v1, v0
	v_mov_b32_e32 v2, v0
	v_mov_b32_e32 v3, v0
	v_mov_b32_e32 v4, v0
	v_mov_b32_e32 v5, v0
	v_mov_b32_e32 v6, v0
	v_mov_b32_e32 v7, v0
	v_mov_b32_e32 v16, v0
	v_mov_b32_e32 v17, v0
	v_mov_b32_e32 v18, v0
	v_mov_b32_e32 v19, v0
	v_mov_b32_e32 v20, v0
	v_mov_b32_e32 v21, v0
	v_mov_b32_e32 v22, v0
	v_mov_b32_e32 v23, v0
	v_mov_b32_e32 v32, v0
	v_mov_b32_e32 v33, v0
	v_mov_b32_e32 v34, v0
	v_mov_b32_e32 v35, v0
	v_mov_b32_e32 v36, v0
	v_mov_b32_e32 v37, v0
	v_mov_b32_e32 v38, v0
	v_mov_b32_e32 v39, v0
	v_mov_b32_e32 v48, v0
	v_mov_b32_e32 v49, v0
	v_mov_b32_e32 v50, v0
	v_mov_b32_e32 v51, v0
	v_mov_b32_e32 v52, v0
	v_mov_b32_e32 v53, v0
	v_mov_b32_e32 v54, v0
	v_mov_b32_e32 v55, v0
	v_mov_b32_e32 v12, v0
	v_mov_b32_e32 v13, v0
	v_mov_b32_e32 v14, v0
	v_mov_b32_e32 v15, v0
	v_mov_b32_e32 v8, v0
	v_mov_b32_e32 v9, v0
	v_mov_b32_e32 v10, v0
	v_mov_b32_e32 v11, v0
	v_mov_b32_e32 v28, v0
	v_mov_b32_e32 v29, v0
	v_mov_b32_e32 v30, v0
	v_mov_b32_e32 v31, v0
	v_mov_b32_e32 v24, v0
	v_mov_b32_e32 v25, v0
	v_mov_b32_e32 v26, v0
	v_mov_b32_e32 v27, v0
	v_mov_b32_e32 v44, v0
	v_mov_b32_e32 v45, v0
	v_mov_b32_e32 v46, v0
	v_mov_b32_e32 v47, v0
	v_mov_b32_e32 v40, v0
	v_mov_b32_e32 v41, v0
	v_mov_b32_e32 v42, v0
	v_mov_b32_e32 v43, v0
	v_mov_b32_e32 v56, v0
	v_mov_b32_e32 v57, v0
	v_mov_b32_e32 v58, v0
	v_mov_b32_e32 v59, v0
	v_mov_b32_e32 v60, v0
	v_mov_b32_e32 v61, v0
	v_mov_b32_e32 v62, v0
	v_mov_b32_e32 v63, v0
	v_mov_b32_e32 v64, v0
	v_mov_b32_e32 v65, v0
	v_mov_b32_e32 v66, v0
	v_mov_b32_e32 v67, v0
	v_mov_b32_e32 v68, v0
	v_mov_b32_e32 v69, v0
	v_mov_b32_e32 v70, v0
	v_mov_b32_e32 v71, v0
	v_mov_b32_e32 v80, v0
	v_mov_b32_e32 v81, v0
	v_mov_b32_e32 v82, v0
	v_mov_b32_e32 v83, v0
	v_mov_b32_e32 v84, v0
	v_mov_b32_e32 v85, v0
	v_mov_b32_e32 v86, v0
	v_mov_b32_e32 v87, v0
	v_mov_b32_e32 v96, v0
	v_mov_b32_e32 v97, v0
	v_mov_b32_e32 v98, v0
	v_mov_b32_e32 v99, v0
	v_mov_b32_e32 v100, v0
	v_mov_b32_e32 v101, v0
	v_mov_b32_e32 v102, v0
	v_mov_b32_e32 v103, v0
	v_mov_b32_e32 v112, v0
	v_mov_b32_e32 v113, v0
	v_mov_b32_e32 v114, v0
	v_mov_b32_e32 v115, v0
	v_mov_b32_e32 v116, v0
	v_mov_b32_e32 v117, v0
	v_mov_b32_e32 v118, v0
	v_mov_b32_e32 v119, v0
	v_mov_b32_e32 v76, v0
	v_mov_b32_e32 v77, v0
	v_mov_b32_e32 v78, v0
	v_mov_b32_e32 v79, v0
	v_mov_b32_e32 v72, v0
	v_mov_b32_e32 v73, v0
	v_mov_b32_e32 v74, v0
	v_mov_b32_e32 v75, v0
	v_mov_b32_e32 v92, v0
	v_mov_b32_e32 v93, v0
	v_mov_b32_e32 v94, v0
	v_mov_b32_e32 v95, v0
	v_mov_b32_e32 v88, v0
	v_mov_b32_e32 v89, v0
	v_mov_b32_e32 v90, v0
	v_mov_b32_e32 v91, v0
	v_mov_b32_e32 v108, v0
	v_mov_b32_e32 v109, v0
	v_mov_b32_e32 v110, v0
	v_mov_b32_e32 v111, v0
	v_mov_b32_e32 v104, v0
	v_mov_b32_e32 v105, v0
	v_mov_b32_e32 v106, v0
	v_mov_b32_e32 v107, v0
	v_mov_b32_e32 v120, v0
	v_mov_b32_e32 v121, v0
	v_mov_b32_e32 v122, v0
	v_mov_b32_e32 v123, v0
	v_mov_b32_e32 v124, v0
	v_mov_b32_e32 v125, v0
	v_mov_b32_e32 v126, v0
	v_mov_b32_e32 v127, v0
	s_cmp_eq_u32 s101, 1
	s_cbranch_scc0 .Lsp_5
	s_setprio 1
.Lsp_5:
.LBB0_1003:
	ds_read_b128 v[128:131], v190
	ds_read_b128 v[132:135], v190 offset:1024
	ds_read_b128 v[136:139], v190 offset:2048
	ds_read_b128 v[140:143], v190 offset:3072
	ds_read_b128 v[144:147], v191
	ds_read_b128 v[148:151], v191 offset:1024
	ds_read_b128 v[170:173], v191 offset:2048
	ds_read_b128 v[174:177], v191 offset:3072
	ds_read_b128 v[178:181], v191 offset:4096
	ds_read_b128 v[182:185], v191 offset:5120
	ds_read_b128 v[194:197], v191 offset:6144
	ds_read_b128 v[198:201], v191 offset:7168
	ds_read_b128 v[202:205], v192
	ds_read_b128 v[206:209], v192 offset:1024
	ds_read_b128 v[210:213], v192 offset:2048
	ds_read_b128 v[214:217], v192 offset:3072
	s_add_u32 s22, s28, 0xfff00080
	s_addc_u32 s23, s29, -1
	s_cmp_eq_u32 s56, 28
	s_cselect_b32 s31, s15, s23
	s_cselect_b32 s30, s21, s22
	s_cselect_b32 s23, s13, s55
	s_cselect_b32 s22, s53, s54
	v_lshl_add_u64 v[186:187], s[28:29], 0, v[160:161]
	s_add_i32 m0, s36, 0xc000
	s_nop 0
	global_load_lds_dwordx4 v[186:187], off
	v_lshl_add_u64 v[186:187], s[28:29], 0, v[162:163]
	s_add_i32 m0, s36, 0xe000
	s_nop 0
	global_load_lds_dwordx4 v[186:187], off
	s_waitcnt lgkmcnt(0)
	s_waitcnt vmcnt(8)
	s_barrier
; #define PG8_STAGE(bufoff, gbase, voff) do { _Pragma("unroll") for (int _i = 0; _i < 2; ++_i) \
;         __builtin_amdgcn_global_load_lds((const unsigned*)((const char*)(gbase) + (voff)[_i]), (PG8_LAS unsigned*)(lds + (bufoff) + ldsw + _i * 8192), 16, 0, 0); } while (0)
; #define PG8_LDA(dst, b, h) do { _Pragma("unroll") for (int m = 0; m < 4; ++m) _Pragma("unroll") for (int k = 0; k < 2; ++k) dst[m][k] = *(const PG8_LAS bf16x8*)(lds + PG8_SA(b, h) + aoff + m * 2048 + k * 1024); } while (0)
; #define PG8_LDB(dst, b, h) do { _Pragma("unroll") for (int n = 0; n < 2; ++n) _Pragma("unroll") for (int k = 0; k < 2; ++k) dst[n][k] = *(const PG8_LAS bf16x8*)(lds + PG8_SB(b, h) + boff + n * 2048 + k * 1024); } while (0)
; #define PG8_MMA(ai, bj, At, Bt) do { __builtin_amdgcn_s_setprio(1); _Pragma("unroll") for (int m = 0; m < 4; ++m) _Pragma("unroll") for (int n = 0; n < 2; ++n) _Pragma("unroll") for (int k = 0; k < 2; ++k) \
;         acc[ai][bj][m][n] = __builtin_amdgcn_mfma_f32_16x16x32_bf16(Bt[n][k], At[m][k], acc[ai][bj][m][n], 0, 0, 0); __builtin_amdgcn_s_setprio(0); } while (0)
; #define PG8_WAIT_V(n) asm volatile("s_waitcnt vmcnt(" #n ")" ::: "memory")
; #define PG8_WAIT_L(n) asm volatile("s_waitcnt lgkmcnt(" #n ")" ::: "memory")
; #define PG8_BAR __builtin_amdgcn_s_barrier()
; #define PG8_SCHED __builtin_amdgcn_sched_barrier(0)
; template <class Epi>
; __device__ __forceinline__ void gemm_phase(PG8_LAS unsigned char* lds, const Gemm g, const StaticOrder& S, const Epi& E) {
;     ...
;             PG8_WAIT_L(8); PG8_BAR; PG8_WAIT_L(0); PG8_MMA(0, 0, At, B0); PG8_BAR; PG8_SCHED;
;             PG8_LDB(B1, 0, 1); PG8_STAGE(PG8_SB(0, 0), b2, voffB);
;             PG8_BAR; PG8_WAIT_L(0); PG8_MMA(0, 1, At, B1); PG8_BAR;
;             PG8_LDA(At, 0, 1); PG8_STAGE(PG8_SA(0, 0), a2, voffA);
;             PG8_BAR; PG8_WAIT_L(0); PG8_MMA(1, 0, At, B0); PG8_BAR; PG8_SCHED;
;             PG8_STAGE(PG8_SB(0, 1), b2 + hstepB, voffB);
;             PG8_WAIT_V(6); PG8_BAR; PG8_MMA(1, 1, At, B1); PG8_BAR;
	v_mfma_f32_16x16x32_bf16 v[124:127], v[128:131], v[144:147], v[124:127]
	v_mfma_f32_16x16x32_bf16 v[120:123], v[136:139], v[144:147], v[120:123]
	v_mfma_f32_16x16x32_bf16 v[104:107], v[128:131], v[170:173], v[104:107]
	v_mfma_f32_16x16x32_bf16 v[108:111], v[136:139], v[170:173], v[108:111]
	v_mfma_f32_16x16x32_bf16 v[88:91], v[128:131], v[178:181], v[88:91]
	v_mfma_f32_16x16x32_bf16 v[92:95], v[136:139], v[178:181], v[92:95]
	v_mfma_f32_16x16x32_bf16 v[72:75], v[128:131], v[194:197], v[72:75]
	v_mfma_f32_16x16x32_bf16 v[76:79], v[136:139], v[194:197], v[76:79]
	v_mfma_f32_16x16x32_bf16 v[124:127], v[132:135], v[148:151], v[124:127]
	v_mfma_f32_16x16x32_bf16 v[120:123], v[140:143], v[148:151], v[120:123]
	v_mfma_f32_16x16x32_bf16 v[104:107], v[132:135], v[174:177], v[104:107]
	v_mfma_f32_16x16x32_bf16 v[108:111], v[140:143], v[174:177], v[108:111]
	v_mfma_f32_16x16x32_bf16 v[88:91], v[132:135], v[182:185], v[88:91]
	v_mfma_f32_16x16x32_bf16 v[92:95], v[140:143], v[182:185], v[92:95]
	v_mfma_f32_16x16x32_bf16 v[72:75], v[132:135], v[198:201], v[72:75]
	v_mfma_f32_16x16x32_bf16 v[76:79], v[140:143], v[198:201], v[76:79]
	v_mfma_f32_16x16x32_bf16 v[116:119], v[202:205], v[144:147], v[116:119]
	v_mfma_f32_16x16x32_bf16 v[112:115], v[210:213], v[144:147], v[112:115]
	v_mfma_f32_16x16x32_bf16 v[100:103], v[202:205], v[170:173], v[100:103]
	v_mfma_f32_16x16x32_bf16 v[96:99], v[210:213], v[170:173], v[96:99]
	v_mfma_f32_16x16x32_bf16 v[84:87], v[202:205], v[178:181], v[84:87]
	v_mfma_f32_16x16x32_bf16 v[80:83], v[210:213], v[178:181], v[80:83]
	v_mfma_f32_16x16x32_bf16 v[68:71], v[202:205], v[194:197], v[68:71]
	v_mfma_f32_16x16x32_bf16 v[64:67], v[210:213], v[194:197], v[64:67]
	v_mfma_f32_16x16x32_bf16 v[116:119], v[206:209], v[148:151], v[116:119]
	v_mfma_f32_16x16x32_bf16 v[112:115], v[214:217], v[148:151], v[112:115]
	v_mfma_f32_16x16x32_bf16 v[100:103], v[206:209], v[174:177], v[100:103]
	v_mfma_f32_16x16x32_bf16 v[96:99], v[214:217], v[174:177], v[96:99]
	v_mfma_f32_16x16x32_bf16 v[84:87], v[206:209], v[182:185], v[84:87]
	v_mfma_f32_16x16x32_bf16 v[80:83], v[214:217], v[182:185], v[80:83]
	v_mfma_f32_16x16x32_bf16 v[68:71], v[206:209], v[198:201], v[68:71]
	v_mfma_f32_16x16x32_bf16 v[64:67], v[214:217], v[198:201], v[64:67]
	s_barrier
	ds_read_b128 v[144:147], v191 offset:16384
	ds_read_b128 v[148:151], v191 offset:17408
	ds_read_b128 v[170:173], v191 offset:18432
	ds_read_b128 v[174:177], v191 offset:19456
	ds_read_b128 v[178:181], v191 offset:20480
	ds_read_b128 v[182:185], v191 offset:21504
	ds_read_b128 v[194:197], v191 offset:22528
	ds_read_b128 v[198:201], v191 offset:23552
	s_add_i32 s57, s50, s35
	v_lshl_add_u64 v[186:187], s[22:23], 0, v[154:155]
	s_mov_b32 m0, s57
	s_nop 0
	global_load_lds_dwordx4 v[186:187], off
	v_lshl_add_u64 v[218:219], s[22:23], 0, v[158:159]
	s_add_i32 m0, s57, 0x2000
	s_nop 0
	global_load_lds_dwordx4 v[218:219], off
	s_mov_b32 m0, s36
	v_lshl_add_u64 v[220:221], s[30:31], 0, v[152:153]
	global_load_lds_dwordx4 v[220:221], off
	v_lshl_add_u64 v[222:223], s[30:31], 0, v[156:157]
	s_mov_b32 m0, s37
	s_nop 0
	global_load_lds_dwordx4 v[222:223], off
	s_add_u32 s58, s22, 0x80000
	s_addc_u32 s59, s23, 0
	s_add_i32 s57, s51, s35
	v_lshl_add_u64 v[224:225], s[58:59], 0, v[154:155]
	s_mov_b32 m0, s57
	s_nop 0
	global_load_lds_dwordx4 v[224:225], off
	v_lshl_add_u64 v[224:225], s[58:59], 0, v[158:159]
	s_add_i32 m0, s57, 0x2000
	s_nop 0
	global_load_lds_dwordx4 v[224:225], off
	s_waitcnt lgkmcnt(0)
	s_waitcnt vmcnt(8)
	s_barrier
	v_mfma_f32_16x16x32_bf16 v[60:63], v[128:131], v[144:147], v[60:63]
	v_mfma_f32_16x16x32_bf16 v[56:59], v[136:139], v[144:147], v[56:59]
	v_mfma_f32_16x16x32_bf16 v[40:43], v[128:131], v[170:173], v[40:43]
	v_mfma_f32_16x16x32_bf16 v[44:47], v[136:139], v[170:173], v[44:47]
	v_mfma_f32_16x16x32_bf16 v[24:27], v[128:131], v[178:181], v[24:27]
	v_mfma_f32_16x16x32_bf16 v[28:31], v[136:139], v[178:181], v[28:31]
	v_mfma_f32_16x16x32_bf16 v[8:11], v[128:131], v[194:197], v[8:11]
	v_mfma_f32_16x16x32_bf16 v[12:15], v[136:139], v[194:197], v[12:15]
	v_mfma_f32_16x16x32_bf16 v[60:63], v[132:135], v[148:151], v[60:63]
	v_mfma_f32_16x16x32_bf16 v[56:59], v[140:143], v[148:151], v[56:59]
	v_mfma_f32_16x16x32_bf16 v[40:43], v[132:135], v[174:177], v[40:43]
	v_mfma_f32_16x16x32_bf16 v[44:47], v[140:143], v[174:177], v[44:47]
	v_mfma_f32_16x16x32_bf16 v[24:27], v[132:135], v[182:185], v[24:27]
	v_mfma_f32_16x16x32_bf16 v[28:31], v[140:143], v[182:185], v[28:31]
	v_mfma_f32_16x16x32_bf16 v[8:11], v[132:135], v[198:201], v[8:11]
	v_mfma_f32_16x16x32_bf16 v[12:15], v[140:143], v[198:201], v[12:15]
	v_mfma_f32_16x16x32_bf16 v[52:55], v[202:205], v[144:147], v[52:55]
	v_mfma_f32_16x16x32_bf16 v[48:51], v[210:213], v[144:147], v[48:51]
	v_mfma_f32_16x16x32_bf16 v[36:39], v[202:205], v[170:173], v[36:39]
	v_mfma_f32_16x16x32_bf16 v[32:35], v[210:213], v[170:173], v[32:35]
	v_mfma_f32_16x16x32_bf16 v[20:23], v[202:205], v[178:181], v[20:23]
	v_mfma_f32_16x16x32_bf16 v[16:19], v[210:213], v[178:181], v[16:19]
	v_mfma_f32_16x16x32_bf16 v[4:7], v[202:205], v[194:197], v[4:7]
	v_mfma_f32_16x16x32_bf16 v[0:3], v[210:213], v[194:197], v[0:3]
	v_mfma_f32_16x16x32_bf16 v[52:55], v[206:209], v[148:151], v[52:55]
	v_mfma_f32_16x16x32_bf16 v[48:51], v[214:217], v[148:151], v[48:51]
	v_mfma_f32_16x16x32_bf16 v[36:39], v[206:209], v[174:177], v[36:39]
	v_mfma_f32_16x16x32_bf16 v[32:35], v[214:217], v[174:177], v[32:35]
	v_mfma_f32_16x16x32_bf16 v[20:23], v[206:209], v[182:185], v[20:23]
	v_mfma_f32_16x16x32_bf16 v[16:19], v[214:217], v[182:185], v[16:19]
	v_mfma_f32_16x16x32_bf16 v[4:7], v[206:209], v[198:201], v[4:7]
	v_mfma_f32_16x16x32_bf16 v[0:3], v[214:217], v[198:201], v[0:3]
	s_add_i32 s57, 0, 0x18000
	v_add_u32_e32 v140, s57, v188
	s_barrier
; #define PG8_STAGE(bufoff, gbase, voff) do { _Pragma("unroll") for (int _i = 0; _i < 2; ++_i) \
;         __builtin_amdgcn_global_load_lds((const unsigned*)((const char*)(gbase) + (voff)[_i]), (PG8_LAS unsigned*)(lds + (bufoff) + ldsw + _i * 8192), 16, 0, 0); } while (0)
; #define PG8_LDA(dst, b, h) do { _Pragma("unroll") for (int m = 0; m < 4; ++m) _Pragma("unroll") for (int k = 0; k < 2; ++k) dst[m][k] = *(const PG8_LAS bf16x8*)(lds + PG8_SA(b, h) + aoff + m * 2048 + k * 1024); } while (0)
; #define PG8_LDB(dst, b, h) do { _Pragma("unroll") for (int n = 0; n < 2; ++n) _Pragma("unroll") for (int k = 0; k < 2; ++k) dst[n][k] = *(const PG8_LAS bf16x8*)(lds + PG8_SB(b, h) + boff + n * 2048 + k * 1024); } while (0)
; #define PG8_MMA(ai, bj, At, Bt) do { __builtin_amdgcn_s_setprio(1); _Pragma("unroll") for (int m = 0; m < 4; ++m) _Pragma("unroll") for (int n = 0; n < 2; ++n) _Pragma("unroll") for (int k = 0; k < 2; ++k) \
;         acc[ai][bj][m][n] = __builtin_amdgcn_mfma_f32_16x16x32_bf16(Bt[n][k], At[m][k], acc[ai][bj][m][n], 0, 0, 0); __builtin_amdgcn_s_setprio(0); } while (0)
; #define PG8_WAIT_L(n) asm volatile("s_waitcnt lgkmcnt(" #n ")" ::: "memory")
; #define PG8_BAR __builtin_amdgcn_s_barrier()
; #define PG8_SCHED __builtin_amdgcn_sched_barrier(0)
; template <class Epi>
; __device__ __forceinline__ void gemm_phase(PG8_LAS unsigned char* lds, const Gemm g, const StaticOrder& S, const Epi& E) {
;     ...
;             PG8_LDB(B0, 1, 0); PG8_SCHED; PG8_LDA(At, 1, 0); PG8_STAGE(PG8_SA(0, 1), a2 + hstepA, voffA);
;             PG8_WAIT_L(8); PG8_BAR; PG8_WAIT_L(0); PG8_MMA(0, 0, At, B0); PG8_BAR; PG8_SCHED;
;             PG8_LDB(B1, 1, 1); PG8_STAGE(PG8_SB(1, 0), b3, voffB);
;             PG8_BAR; PG8_WAIT_L(0); PG8_MMA(0, 1, At, B1); PG8_BAR;
;             PG8_LDA(At, 1, 1); PG8_STAGE(PG8_SA(1, 0), a3, voffA);
;             PG8_BAR; PG8_WAIT_L(0); PG8_MMA(1, 0, At, B0); PG8_BAR; PG8_SCHED;
	ds_read_b128 v[128:131], v140
	ds_read_b128 v[132:135], v140 offset:1024
	ds_read_b128 v[136:139], v140 offset:2048
	ds_read_b128 v[140:143], v140 offset:3072
	ds_read_b128 v[144:147], v191 offset:32768
	ds_read_b128 v[148:151], v191 offset:33792
	ds_read_b128 v[170:173], v191 offset:34816
	ds_read_b128 v[174:177], v191 offset:35840
	ds_read_b128 v[178:181], v191 offset:36864
	ds_read_b128 v[182:185], v191 offset:37888
	ds_read_b128 v[194:197], v191 offset:38912
	ds_read_b128 v[198:201], v191 offset:39936
	v_add_u32_e32 v214, 0x1c000, v188
	ds_read_b128 v[202:205], v214
	ds_read_b128 v[206:209], v214 offset:1024
	ds_read_b128 v[210:213], v214 offset:2048
	ds_read_b128 v[214:217], v214 offset:3072
	s_add_u32 s30, s30, 0x100000
	s_addc_u32 s31, s31, 0
	s_mov_b32 m0, s38
	v_lshl_add_u64 v[224:225], s[30:31], 0, v[152:153]
	global_load_lds_dwordx4 v[224:225], off
	v_lshl_add_u64 v[224:225], s[30:31], 0, v[156:157]
	s_mov_b32 m0, s39
	s_nop 0
	global_load_lds_dwordx4 v[224:225], off
	s_waitcnt lgkmcnt(0)
	s_waitcnt vmcnt(8)
	s_barrier
	v_mfma_f32_16x16x32_bf16 v[124:127], v[128:131], v[144:147], v[124:127]
	v_mfma_f32_16x16x32_bf16 v[120:123], v[136:139], v[144:147], v[120:123]
	v_mfma_f32_16x16x32_bf16 v[104:107], v[128:131], v[170:173], v[104:107]
	v_mfma_f32_16x16x32_bf16 v[108:111], v[136:139], v[170:173], v[108:111]
	v_mfma_f32_16x16x32_bf16 v[88:91], v[128:131], v[178:181], v[88:91]
	v_mfma_f32_16x16x32_bf16 v[92:95], v[136:139], v[178:181], v[92:95]
	v_mfma_f32_16x16x32_bf16 v[72:75], v[128:131], v[194:197], v[72:75]
	v_mfma_f32_16x16x32_bf16 v[76:79], v[136:139], v[194:197], v[76:79]
	v_mfma_f32_16x16x32_bf16 v[124:127], v[132:135], v[148:151], v[124:127]
	v_mfma_f32_16x16x32_bf16 v[120:123], v[140:143], v[148:151], v[120:123]
	v_mfma_f32_16x16x32_bf16 v[104:107], v[132:135], v[174:177], v[104:107]
	v_mfma_f32_16x16x32_bf16 v[108:111], v[140:143], v[174:177], v[108:111]
	v_mfma_f32_16x16x32_bf16 v[88:91], v[132:135], v[182:185], v[88:91]
	v_mfma_f32_16x16x32_bf16 v[92:95], v[140:143], v[182:185], v[92:95]
	v_mfma_f32_16x16x32_bf16 v[72:75], v[132:135], v[198:201], v[72:75]
	v_mfma_f32_16x16x32_bf16 v[76:79], v[140:143], v[198:201], v[76:79]
	v_mfma_f32_16x16x32_bf16 v[116:119], v[202:205], v[144:147], v[116:119]
	v_mfma_f32_16x16x32_bf16 v[112:115], v[210:213], v[144:147], v[112:115]
	v_mfma_f32_16x16x32_bf16 v[100:103], v[202:205], v[170:173], v[100:103]
	v_mfma_f32_16x16x32_bf16 v[96:99], v[210:213], v[170:173], v[96:99]
	v_mfma_f32_16x16x32_bf16 v[84:87], v[202:205], v[178:181], v[84:87]
	v_mfma_f32_16x16x32_bf16 v[80:83], v[210:213], v[178:181], v[80:83]
	v_mfma_f32_16x16x32_bf16 v[68:71], v[202:205], v[194:197], v[68:71]
	v_mfma_f32_16x16x32_bf16 v[64:67], v[210:213], v[194:197], v[64:67]
	v_mfma_f32_16x16x32_bf16 v[116:119], v[206:209], v[148:151], v[116:119]
	v_mfma_f32_16x16x32_bf16 v[112:115], v[214:217], v[148:151], v[112:115]
	v_mfma_f32_16x16x32_bf16 v[100:103], v[206:209], v[174:177], v[100:103]
	v_mfma_f32_16x16x32_bf16 v[96:99], v[214:217], v[174:177], v[96:99]
	v_mfma_f32_16x16x32_bf16 v[84:87], v[206:209], v[182:185], v[84:87]
	v_mfma_f32_16x16x32_bf16 v[80:83], v[214:217], v[182:185], v[80:83]
	v_mfma_f32_16x16x32_bf16 v[68:71], v[206:209], v[198:201], v[68:71]
	v_mfma_f32_16x16x32_bf16 v[64:67], v[214:217], v[198:201], v[64:67]
	s_barrier
	ds_read_b128 v[144:147], v191 offset:49152
	ds_read_b128 v[148:151], v191 offset:50176
	ds_read_b128 v[170:173], v191 offset:51200
	ds_read_b128 v[174:177], v191 offset:52224
	ds_read_b128 v[178:181], v191 offset:53248
	ds_read_b128 v[182:185], v191 offset:54272
	ds_read_b128 v[194:197], v191 offset:55296
	ds_read_b128 v[198:201], v191 offset:56320
	s_add_i32 s30, 0, 0x1c000
	s_add_i32 s31, s57, s35
	v_lshl_add_u64 v[186:187], v[186:187], 0, s[10:11]
	s_mov_b32 m0, s31
	s_nop 0
	global_load_lds_dwordx4 v[186:187], off
	v_lshl_add_u64 v[186:187], v[218:219], 0, s[10:11]
	s_add_i32 m0, s31, 0x2000
	s_nop 0
	global_load_lds_dwordx4 v[186:187], off
	s_mov_b32 m0, s41
	v_lshl_add_u64 v[186:187], v[220:221], 0, s[10:11]
	global_load_lds_dwordx4 v[186:187], off
	v_lshl_add_u64 v[186:187], v[222:223], 0, s[10:11]
	s_mov_b32 m0, s42
	s_nop 0
	global_load_lds_dwordx4 v[186:187], off
	s_add_u32 s22, s22, 0x80080
	s_addc_u32 s23, s23, 0
	s_add_i32 s30, s30, s35
	v_lshl_add_u64 v[224:225], s[22:23], 0, v[154:155]
	s_mov_b32 m0, s30
	s_nop 0
	global_load_lds_dwordx4 v[224:225], off
	v_lshl_add_u64 v[224:225], s[22:23], 0, v[158:159]
	s_add_i32 m0, s30, 0x2000
	s_nop 0
	global_load_lds_dwordx4 v[224:225], off
	s_waitcnt lgkmcnt(0)
	s_waitcnt vmcnt(8)
	s_barrier
; __device__ __forceinline__ u32x4 pack8(const float (&f)[8]) { u32x4 w; w.x = cvt_pk_bf16(f[0], f[1]); w.y = cvt_pk_bf16(f[2], f[3]); w.z = cvt_pk_bf16(f[4], f[5]); w.w = cvt_pk_bf16(f[6], f[7]); return w; }
; #define PG8_WAIT_V(n) asm volatile("s_waitcnt vmcnt(" #n ")" ::: "memory")
; #define PG8_WAIT_L(n) asm volatile("s_waitcnt lgkmcnt(" #n ")" ::: "memory")
; #define PG8_BAR __builtin_amdgcn_s_barrier()
; template <class Epi>
; __device__ __forceinline__ void gemm_phase(PG8_LAS unsigned char* lds, const Gemm g, const StaticOrder& S, const Epi& E) {
;     ...
;             PG8_BAR; PG8_WAIT_L(0); PG8_MMA(1, 0, At, B0); PG8_BAR; PG8_SCHED;
;             PG8_STAGE(PG8_SB(1, 1), b3 + hstepB, voffB);
;             PG8_WAIT_V(6); PG8_BAR; PG8_MMA(1, 1, At, B1); PG8_BAR;
;         }
;         E(acc, cur, wr, wc, fr, fq);
;     __device__ __forceinline__ void operator()(const f32x4 (&acc)[2][2][4][2], const pg8::Unit& u, int wr, int wc, int fr, int fq) const {
;         const int row0 = u.pm * 256 + wr * 64 + fr, col0 = u.pn * 256 + wc * 32 + 8 * fq;
; #pragma unroll
;         for (int ai = 0; ai < 2; ++ai) {
;             u32x4 rb[4][2];
; #pragma unroll
;             for (int m = 0; m < 4; ++m)
; #pragma unroll
;                 for (int bj = 0; bj < 2; ++bj) rb[m][bj] = *(const u32x4*)(resb + (size_t)(row0 + ai * 128 + m * 16) * DM + col0 + bj * 128);
; #pragma unroll
;             for (int m = 0; m < 4; ++m) {
;                 const int r = row0 + ai * 128 + m * 16; float ss = 0.f;
; #pragma unroll
;                 for (int bj = 0; bj < 2; ++bj) {
;                     const size_t off = (size_t)r * DM + col0 + bj * 128;
;                     float rv[8], o[8]; unpack8(rb[m][bj], rv);
; #pragma unroll
;                     for (int n = 0; n < 2; ++n)
; #pragma unroll
;                         for (int i = 0; i < 4; ++i) o[n * 4 + i] = rv[n * 4 + i] + coef * acc[ai][bj][m][n][i];
;                     if (outf) { *(f32x4*)(outf + off) = (f32x4){o[0], o[1], o[2], o[3]}; *(f32x4*)(outf + off + 4) = (f32x4){o[4], o[5], o[6], o[7]}; }
;                     if (hb) { *(u32x4*)(hb + off) = pack8(o);
; #pragma unroll
;                         for (int i = 0; i < 8; ++i) ss += o[i] * o[i]; }
;                 }
;                 if (hb) { ss += __shfl_xor(ss, 16); ss += __shfl_xor(ss, 32); if (fq == 0) part[(size_t)r * 32 + u.pn * 4 + wc] = ss; }
	v_mfma_f32_16x16x32_bf16 v[60:63], v[128:131], v[144:147], v[60:63]
	v_mfma_f32_16x16x32_bf16 v[56:59], v[136:139], v[144:147], v[56:59]
	v_mfma_f32_16x16x32_bf16 v[40:43], v[128:131], v[170:173], v[40:43]
	v_mfma_f32_16x16x32_bf16 v[44:47], v[136:139], v[170:173], v[44:47]
	v_mfma_f32_16x16x32_bf16 v[24:27], v[128:131], v[178:181], v[24:27]
	v_mfma_f32_16x16x32_bf16 v[28:31], v[136:139], v[178:181], v[28:31]
	v_mfma_f32_16x16x32_bf16 v[8:11], v[128:131], v[194:197], v[8:11]
	v_mfma_f32_16x16x32_bf16 v[12:15], v[136:139], v[194:197], v[12:15]
	v_mfma_f32_16x16x32_bf16 v[60:63], v[132:135], v[148:151], v[60:63]
	v_mfma_f32_16x16x32_bf16 v[56:59], v[140:143], v[148:151], v[56:59]
	v_mfma_f32_16x16x32_bf16 v[40:43], v[132:135], v[174:177], v[40:43]
	v_mfma_f32_16x16x32_bf16 v[44:47], v[140:143], v[174:177], v[44:47]
	v_mfma_f32_16x16x32_bf16 v[24:27], v[132:135], v[182:185], v[24:27]
	v_mfma_f32_16x16x32_bf16 v[28:31], v[140:143], v[182:185], v[28:31]
	v_mfma_f32_16x16x32_bf16 v[8:11], v[132:135], v[198:201], v[8:11]
	v_mfma_f32_16x16x32_bf16 v[12:15], v[140:143], v[198:201], v[12:15]
	v_mfma_f32_16x16x32_bf16 v[52:55], v[202:205], v[144:147], v[52:55]
	v_mfma_f32_16x16x32_bf16 v[48:51], v[210:213], v[144:147], v[48:51]
	v_mfma_f32_16x16x32_bf16 v[36:39], v[202:205], v[170:173], v[36:39]
	v_mfma_f32_16x16x32_bf16 v[32:35], v[210:213], v[170:173], v[32:35]
	v_mfma_f32_16x16x32_bf16 v[20:23], v[202:205], v[178:181], v[20:23]
	v_mfma_f32_16x16x32_bf16 v[16:19], v[210:213], v[178:181], v[16:19]
	v_mfma_f32_16x16x32_bf16 v[4:7], v[202:205], v[194:197], v[4:7]
	v_mfma_f32_16x16x32_bf16 v[0:3], v[210:213], v[194:197], v[0:3]
	v_mfma_f32_16x16x32_bf16 v[52:55], v[206:209], v[148:151], v[52:55]
	v_mfma_f32_16x16x32_bf16 v[48:51], v[214:217], v[148:151], v[48:51]
	v_mfma_f32_16x16x32_bf16 v[36:39], v[206:209], v[174:177], v[36:39]
	v_mfma_f32_16x16x32_bf16 v[32:35], v[214:217], v[174:177], v[32:35]
	v_mfma_f32_16x16x32_bf16 v[20:23], v[206:209], v[182:185], v[20:23]
	v_mfma_f32_16x16x32_bf16 v[16:19], v[214:217], v[182:185], v[16:19]
	v_mfma_f32_16x16x32_bf16 v[4:7], v[206:209], v[198:201], v[4:7]
	v_mfma_f32_16x16x32_bf16 v[0:3], v[214:217], v[198:201], v[0:3]
	s_add_i32 s56, s56, 2
	s_add_u32 s28, s28, 0x100
	s_addc_u32 s29, s29, 0
	s_add_u32 s54, s54, 0x100
	s_addc_u32 s55, s55, 0
	s_cmp_gt_u32 s56, 29
	s_barrier
	s_cbranch_scc0 .LBB0_1003
	s_setprio 0
	v_lshl_or_b32 v170, s8, 8, v189
	v_lshl_add_u32 v172, s20, 8, v169
	v_ashrrev_i32_e32 v171, 31, v170
	v_lshlrev_b64 v[204:205], 1, v[170:171]
	v_ashrrev_i32_e32 v173, 31, v172
	v_lshl_add_u64 v[174:175], s[76:77], 0, v[204:205]
	v_lshlrev_b64 v[194:195], 12, v[172:173]
	v_lshl_add_u64 v[128:129], v[174:175], 0, v[194:195]
	global_load_dwordx4 v[196:199], v[128:129], off
	global_load_dwordx4 v[200:203], v[128:129], off offset:256
	v_or_b32_e32 v184, 16, v172
	v_or_b32_e32 v180, 32, v172
	v_or_b32_e32 v176, 48, v172
	v_ashrrev_i32_e32 v185, 31, v184
	v_ashrrev_i32_e32 v181, 31, v180
	v_ashrrev_i32_e32 v177, 31, v176
	v_lshlrev_b64 v[186:187], 12, v[184:185]
	v_lshlrev_b64 v[182:183], 12, v[180:181]
	v_lshlrev_b64 v[178:179], 12, v[176:177]
	v_lshl_add_u64 v[128:129], v[174:175], 0, v[186:187]
	v_lshl_add_u64 v[130:131], v[174:175], 0, v[182:183]
	v_lshl_add_u64 v[206:207], v[174:175], 0, v[178:179]
	global_load_dwordx4 v[148:151], v[128:129], off
	global_load_dwordx4 v[144:147], v[128:129], off offset:256
	global_load_dwordx4 v[140:143], v[130:131], off
	global_load_dwordx4 v[136:139], v[130:131], off offset:256
	global_load_dwordx4 v[132:135], v[206:207], off
	s_nop 0
	global_load_dwordx4 v[128:131], v[206:207], off offset:256
	v_and_b32_e32 v207, 64, v193
	v_xor_b32_e32 v206, 16, v193
	v_add_u32_e32 v207, 64, v207
	v_xor_b32_e32 v208, 32, v193
	v_cmp_lt_i32_e32 vcc, v206, v207
	s_lshl_b32 s20, s8, 2
	s_ashr_i32 s21, s20, 31
	v_cndmask_b32_e32 v209, v193, v206, vcc
	v_cmp_lt_i32_e32 vcc, v208, v207
	v_lshl_add_u64 v[206:207], s[76:77], 0, v[194:195]
	v_lshl_add_u64 v[204:205], v[206:207], 0, v[204:205]
	v_lshlrev_b32_e32 v194, 2, v209
	v_cndmask_b32_e32 v208, v193, v208, vcc
	s_waitcnt vmcnt(0)
	v_lshlrev_b32_e32 v195, 16, v196
	v_and_b32_e32 v196, 0xffff0000, v196
	v_lshlrev_b32_e32 v212, 16, v202
	v_add_f32_e32 v125, v125, v196
	v_lshlrev_b32_e32 v206, 16, v197
	v_add_f32_e32 v124, v124, v195
	v_add_f32_e32 v195, v112, v212
	v_cvt_pk_bf16_f32 v112, v124, v125
	v_mul_f32_e32 v125, v125, v125
	v_and_b32_e32 v197, 0xffff0000, v197
	v_add_f32_e32 v126, v126, v206
	v_fmac_f32_e32 v125, v124, v124
	v_lshlrev_b32_e32 v207, 16, v198
	v_add_f32_e32 v127, v127, v197
	v_fmac_f32_e32 v125, v126, v126
	v_and_b32_e32 v198, 0xffff0000, v198
	v_add_f32_e32 v120, v120, v207
	v_fmac_f32_e32 v125, v127, v127
	v_lshlrev_b32_e32 v209, 16, v199
	v_add_f32_e32 v121, v121, v198
	v_fmac_f32_e32 v125, v120, v120
	v_and_b32_e32 v199, 0xffff0000, v199
	v_add_f32_e32 v122, v122, v209
	v_fmac_f32_e32 v125, v121, v121
	v_lshlrev_b32_e32 v210, 16, v200
	v_add_f32_e32 v123, v123, v199
	v_fmac_f32_e32 v125, v122, v122
	v_and_b32_e32 v200, 0xffff0000, v200
	v_add_f32_e32 v116, v116, v210
	v_fmac_f32_e32 v125, v123, v123
	v_lshlrev_b32_e32 v211, 16, v201
	v_add_f32_e32 v117, v117, v200
	v_fmac_f32_e32 v125, v116, v116
	v_and_b32_e32 v201, 0xffff0000, v201
	v_add_f32_e32 v118, v118, v211
	v_fmac_f32_e32 v125, v117, v117
	v_add_f32_e32 v119, v119, v201
	v_fmac_f32_e32 v125, v118, v118
	v_and_b32_e32 v202, 0xffff0000, v202
	v_fmac_f32_e32 v125, v119, v119
	v_lshlrev_b32_e32 v213, 16, v203
	v_add_f32_e32 v196, v113, v202
	v_fmac_f32_e32 v125, v195, v195
	v_and_b32_e32 v203, 0xffff0000, v203
	v_add_f32_e32 v197, v114, v213
	v_fmac_f32_e32 v125, v196, v196
	v_add_f32_e32 v198, v115, v203
	v_fmac_f32_e32 v125, v197, v197
	v_fmac_f32_e32 v125, v198, v198
	ds_bpermute_b32 v124, v194, v125
	v_cvt_pk_bf16_f32 v113, v126, v127
	v_cvt_pk_bf16_f32 v114, v120, v121
	v_cvt_pk_bf16_f32 v115, v122, v123
	global_store_dwordx4 v[204:205], v[112:115], off
	v_cvt_pk_bf16_f32 v116, v116, v117
	v_cvt_pk_bf16_f32 v117, v118, v119
	v_cvt_pk_bf16_f32 v118, v195, v196
	v_cvt_pk_bf16_f32 v119, v197, v198
	global_store_dwordx4 v[204:205], v[116:119], off offset:256
	s_waitcnt lgkmcnt(0)
	v_add_f32_e32 v113, v125, v124
	v_lshlrev_b32_e32 v112, 2, v208
	ds_bpermute_b32 v114, v112, v113
	s_and_saveexec_b64 s[22:23], s[2:3]
	s_cbranch_execz .LBB0_1006
	v_lshlrev_b64 v[116:117], 7, v[172:173]
	v_lshl_add_u64 v[116:117], s[0:1], 0, v[116:117]
	v_lshl_add_u64 v[116:117], s[20:21], 2, v[116:117]
	s_lshl_b32 s8, s40, 2
	v_lshl_add_u64 v[116:117], v[116:117], 0, s[8:9]
	s_waitcnt lgkmcnt(0)
	v_add_f32_e32 v113, v113, v114
	global_store_dword v[116:117], v113, off

; #define PG8_STAGE(bufoff, gbase, voff) do { _Pragma("unroll") for (int _i = 0; _i < 2; ++_i) \
;         __builtin_amdgcn_global_load_lds((const unsigned*)((const char*)(gbase) + (voff)[_i]), (PG8_LAS unsigned*)(lds + (bufoff) + ldsw + _i * 8192), 16, 0, 0); } while (0)
; #define PG8_LDA(dst, b, h) do { _Pragma("unroll") for (int m = 0; m < 4; ++m) _Pragma("unroll") for (int k = 0; k < 2; ++k) dst[m][k] = *(const PG8_LAS bf16x8*)(lds + PG8_SA(b, h) + aoff + m * 2048 + k * 1024); } while (0)
; #define PG8_LDB(dst, b, h) do { _Pragma("unroll") for (int n = 0; n < 2; ++n) _Pragma("unroll") for (int k = 0; k < 2; ++k) dst[n][k] = *(const PG8_LAS bf16x8*)(lds + PG8_SB(b, h) + boff + n * 2048 + k * 1024); } while (0)
; #define PG8_MMA(ai, bj, At, Bt) do { __builtin_amdgcn_s_setprio(1); _Pragma("unroll") for (int m = 0; m < 4; ++m) _Pragma("unroll") for (int n = 0; n < 2; ++n) _Pragma("unroll") for (int k = 0; k < 2; ++k) \
;         acc[ai][bj][m][n] = __builtin_amdgcn_mfma_f32_16x16x32_bf16(Bt[n][k], At[m][k], acc[ai][bj][m][n], 0, 0, 0); __builtin_amdgcn_s_setprio(0); } while (0)
; template <class Epi>
; __device__ __forceinline__ void gemm_phase(PG8_LAS unsigned char* lds, const Gemm g, const StaticOrder& S, const Epi& E) {
;     ...
;         const bool has_next = S.next(ui + 1, nxt);
;         const char* nA = has_next ? (const char*)g.A + (size_t)nxt.pm * tstepA : cA; const char* nB = has_next ? (const char*)g.Bt + (size_t)nxt.pn * tstepB : cB;
;         for (int t = 0; t < nt; t += 2) {
;             const bool last = (t == nt - 2);
;             const char* a1 = cA + (size_t)(t + 1) * kstep;
;             const char* a2 = last ? nA : cA + (size_t)(t + 2) * kstep; const char* b2 = last ? nB : cB + (size_t)(t + 2) * kstep;
;             const char* a3 = a2 + kstep; const char* b3 = b2 + kstep;
;             PG8_LDB(B0, 0, 0); PG8_SCHED; PG8_LDA(At, 0, 0); PG8_STAGE(PG8_SA(1, 1), a1 + hstepA, voffA);
;             PG8_WAIT_L(8); PG8_BAR; PG8_WAIT_L(0); PG8_MMA(0, 0, At, B0); PG8_BAR; PG8_SCHED;
;     ...
; #pragma unroll
;         for (int a = 0; a < 2; ++a)
; #pragma unroll
;             for (int b = 0; b < 2; ++b)
; #pragma unroll
;                 for (int m = 0; m < 4; ++m)
; #pragma unroll
;                     for (int n = 0; n < 2; ++n) acc[a][b][m][n] = (f32x4){0.f, 0.f, 0.f, 0.f};
;         cur = nxt; cA = nA; cB = nB; ++ui;
.LBB0_1085:
	s_ashr_i32 s39, s38, 31
	v_cmp_lt_i64_e32 vcc, s[0:1], v[150:151]
	s_lshl_b64 s[0:1], s[38:39], 20
	s_add_u32 s40, s76, s0
	s_addc_u32 s41, s77, s1
	s_and_b64 s[0:1], vcc, exec
	s_cselect_b32 s39, s41, s7
	s_cselect_b32 s59, s40, s6
	s_ashr_i32 s37, s36, 31
	s_lshl_b64 s[0:1], s[36:37], 20
	v_readlane_b32 s42, v253, 28
	v_readlane_b32 s43, v253, 29
	s_add_u32 s42, s42, s0
	s_addc_u32 s43, s43, s1
	s_and_b64 s[0:1], vcc, exec
	s_cselect_b32 s37, s43, s5
	s_cselect_b32 s60, s42, s4
	s_add_u32 s0, s6, 0x80080
	s_addc_u32 s1, s7, 0
	s_add_u32 s61, s4, 0x100
	v_mov_b32_e32 v8, 0
	s_addc_u32 s62, s5, 0
	s_mov_b32 s63, -2
	v_mov_b32_e32 v9, v8
	v_mov_b32_e32 v10, v8
	v_mov_b32_e32 v11, v8
	v_mov_b32_e32 v16, v8
	v_mov_b32_e32 v17, v8
	v_mov_b32_e32 v18, v8
	v_mov_b32_e32 v19, v8
	v_mov_b32_e32 v24, v8
	v_mov_b32_e32 v25, v8
	v_mov_b32_e32 v26, v8
	v_mov_b32_e32 v27, v8
	v_mov_b32_e32 v32, v8
	v_mov_b32_e32 v33, v8
	v_mov_b32_e32 v34, v8
	v_mov_b32_e32 v35, v8
	v_mov_b32_e32 v40, v8
	v_mov_b32_e32 v41, v8
	v_mov_b32_e32 v42, v8
	v_mov_b32_e32 v43, v8
	v_mov_b32_e32 v48, v8
	v_mov_b32_e32 v49, v8
	v_mov_b32_e32 v50, v8
	v_mov_b32_e32 v51, v8
	v_mov_b32_e32 v56, v8
	v_mov_b32_e32 v57, v8
	v_mov_b32_e32 v58, v8
	v_mov_b32_e32 v59, v8
	v_mov_b32_e32 v64, v8
	v_mov_b32_e32 v65, v8
	v_mov_b32_e32 v66, v8
	v_mov_b32_e32 v67, v8
	v_mov_b32_e32 v12, v8
	v_mov_b32_e32 v13, v8
	v_mov_b32_e32 v14, v8
	v_mov_b32_e32 v15, v8
	v_mov_b32_e32 v20, v8
	v_mov_b32_e32 v21, v8
	v_mov_b32_e32 v22, v8
	v_mov_b32_e32 v23, v8
	v_mov_b32_e32 v28, v8
	v_mov_b32_e32 v29, v8
	v_mov_b32_e32 v30, v8
	v_mov_b32_e32 v31, v8
	v_mov_b32_e32 v36, v8
	v_mov_b32_e32 v37, v8
	v_mov_b32_e32 v38, v8
	v_mov_b32_e32 v39, v8
	v_mov_b32_e32 v44, v8
	v_mov_b32_e32 v45, v8
	v_mov_b32_e32 v46, v8
	v_mov_b32_e32 v47, v8
	v_mov_b32_e32 v52, v8
	v_mov_b32_e32 v53, v8
	v_mov_b32_e32 v54, v8
	v_mov_b32_e32 v55, v8
	v_mov_b32_e32 v60, v8
	v_mov_b32_e32 v61, v8
	v_mov_b32_e32 v62, v8
	v_mov_b32_e32 v63, v8
	v_mov_b32_e32 v68, v8
	v_mov_b32_e32 v69, v8
	v_mov_b32_e32 v70, v8
	v_mov_b32_e32 v71, v8
	v_mov_b32_e32 v72, v8
	v_mov_b32_e32 v73, v8
	v_mov_b32_e32 v74, v8
	v_mov_b32_e32 v75, v8
	v_mov_b32_e32 v80, v8
	v_mov_b32_e32 v81, v8
	v_mov_b32_e32 v82, v8
	v_mov_b32_e32 v83, v8
	v_mov_b32_e32 v88, v8
	v_mov_b32_e32 v89, v8
	v_mov_b32_e32 v90, v8
	v_mov_b32_e32 v91, v8
	v_mov_b32_e32 v96, v8
	v_mov_b32_e32 v97, v8
	v_mov_b32_e32 v98, v8
	v_mov_b32_e32 v99, v8
	v_mov_b32_e32 v104, v8
	v_mov_b32_e32 v105, v8
	v_mov_b32_e32 v106, v8
	v_mov_b32_e32 v107, v8
	v_mov_b32_e32 v112, v8
	v_mov_b32_e32 v113, v8
	v_mov_b32_e32 v114, v8
	v_mov_b32_e32 v115, v8
	v_mov_b32_e32 v120, v8
	v_mov_b32_e32 v121, v8
	v_mov_b32_e32 v122, v8
	v_mov_b32_e32 v123, v8
	v_mov_b32_e32 v128, v8
	v_mov_b32_e32 v129, v8
	v_mov_b32_e32 v130, v8
	v_mov_b32_e32 v131, v8
	v_mov_b32_e32 v76, v8
	v_mov_b32_e32 v77, v8
	v_mov_b32_e32 v78, v8
	v_mov_b32_e32 v79, v8
	v_mov_b32_e32 v84, v8
	v_mov_b32_e32 v85, v8
	v_mov_b32_e32 v86, v8
	v_mov_b32_e32 v87, v8
	v_mov_b32_e32 v92, v8
	v_mov_b32_e32 v93, v8
	v_mov_b32_e32 v94, v8
	v_mov_b32_e32 v95, v8
	v_mov_b32_e32 v100, v8
	v_mov_b32_e32 v101, v8
	v_mov_b32_e32 v102, v8
	v_mov_b32_e32 v103, v8
	v_mov_b32_e32 v108, v8
	v_mov_b32_e32 v109, v8
	v_mov_b32_e32 v110, v8
	v_mov_b32_e32 v111, v8
	v_mov_b32_e32 v116, v8
	v_mov_b32_e32 v117, v8
	v_mov_b32_e32 v118, v8
	v_mov_b32_e32 v119, v8
	v_mov_b32_e32 v124, v8
	v_mov_b32_e32 v125, v8
	v_mov_b32_e32 v126, v8
	v_mov_b32_e32 v127, v8
	v_mov_b32_e32 v132, v8
	v_mov_b32_e32 v133, v8
	v_mov_b32_e32 v134, v8
	v_mov_b32_e32 v135, v8
	s_cmp_eq_u32 s101, 1
	s_cbranch_scc0 .Lsp_6
	s_setprio 1
.Lsp_6:
.LBB0_1086:
	ds_read_b128 v[0:3], v173
	ds_read_b128 v[4:7], v173 offset:1024
	ds_read_b128 v[154:157], v173 offset:2048
	ds_read_b128 v[158:161], v173 offset:3072
	ds_read_b128 v[162:165], v174
	ds_read_b128 v[178:181], v174 offset:1024
	ds_read_b128 v[182:185], v174 offset:2048
	ds_read_b128 v[186:189], v174 offset:3072
	ds_read_b128 v[190:193], v174 offset:4096
	ds_read_b128 v[194:197], v174 offset:5120
	ds_read_b128 v[198:201], v174 offset:6144
	ds_read_b128 v[202:205], v174 offset:7168
	ds_read_b128 v[206:209], v175
	ds_read_b128 v[210:213], v175 offset:1024
	ds_read_b128 v[214:217], v175 offset:2048
	ds_read_b128 v[218:221], v175 offset:3072
	s_add_u32 s4, s0, 0xfff80080
	s_addc_u32 s5, s1, -1
	s_cmp_eq_u32 s63, 28
	s_cselect_b32 s7, s39, s5
	s_cselect_b32 s6, s59, s4
	s_cselect_b32 s5, s37, s62
	s_cselect_b32 s4, s60, s61
	v_lshl_add_u64 v[166:167], s[0:1], 0, v[146:147]
	s_add_i32 m0, s11, 0xc000
	s_nop 0
	global_load_lds_dwordx4 v[166:167], off
	v_lshl_add_u64 v[166:167], s[0:1], 0, v[148:149]
	s_add_i32 m0, s11, 0xe000
	s_nop 0
	global_load_lds_dwordx4 v[166:167], off
	s_waitcnt lgkmcnt(0)
	s_waitcnt vmcnt(8)
	s_barrier
; #define PG8_STAGE(bufoff, gbase, voff) do { _Pragma("unroll") for (int _i = 0; _i < 2; ++_i) \
;         __builtin_amdgcn_global_load_lds((const unsigned*)((const char*)(gbase) + (voff)[_i]), (PG8_LAS unsigned*)(lds + (bufoff) + ldsw + _i * 8192), 16, 0, 0); } while (0)
; #define PG8_LDA(dst, b, h) do { _Pragma("unroll") for (int m = 0; m < 4; ++m) _Pragma("unroll") for (int k = 0; k < 2; ++k) dst[m][k] = *(const PG8_LAS bf16x8*)(lds + PG8_SA(b, h) + aoff + m * 2048 + k * 1024); } while (0)
; #define PG8_LDB(dst, b, h) do { _Pragma("unroll") for (int n = 0; n < 2; ++n) _Pragma("unroll") for (int k = 0; k < 2; ++k) dst[n][k] = *(const PG8_LAS bf16x8*)(lds + PG8_SB(b, h) + boff + n * 2048 + k * 1024); } while (0)
; #define PG8_MMA(ai, bj, At, Bt) do { __builtin_amdgcn_s_setprio(1); _Pragma("unroll") for (int m = 0; m < 4; ++m) _Pragma("unroll") for (int n = 0; n < 2; ++n) _Pragma("unroll") for (int k = 0; k < 2; ++k) \
;         acc[ai][bj][m][n] = __builtin_amdgcn_mfma_f32_16x16x32_bf16(Bt[n][k], At[m][k], acc[ai][bj][m][n], 0, 0, 0); __builtin_amdgcn_s_setprio(0); } while (0)
; #define PG8_WAIT_V(n) asm volatile("s_waitcnt vmcnt(" #n ")" ::: "memory")
; #define PG8_WAIT_L(n) asm volatile("s_waitcnt lgkmcnt(" #n ")" ::: "memory")
; #define PG8_BAR __builtin_amdgcn_s_barrier()
; #define PG8_SCHED __builtin_amdgcn_sched_barrier(0)
; template <class Epi>
; __device__ __forceinline__ void gemm_phase(PG8_LAS unsigned char* lds, const Gemm g, const StaticOrder& S, const Epi& E) {
;     ...
;             PG8_WAIT_L(8); PG8_BAR; PG8_WAIT_L(0); PG8_MMA(0, 0, At, B0); PG8_BAR; PG8_SCHED;
;             PG8_LDB(B1, 0, 1); PG8_STAGE(PG8_SB(0, 0), b2, voffB);
;             PG8_BAR; PG8_WAIT_L(0); PG8_MMA(0, 1, At, B1); PG8_BAR;
;             PG8_LDA(At, 0, 1); PG8_STAGE(PG8_SA(0, 0), a2, voffA);
;             PG8_BAR; PG8_WAIT_L(0); PG8_MMA(1, 0, At, B0); PG8_BAR; PG8_SCHED;
;             PG8_STAGE(PG8_SB(0, 1), b2 + hstepB, voffB);
;             PG8_WAIT_V(6); PG8_BAR; PG8_MMA(1, 1, At, B1); PG8_BAR;
	v_mfma_f32_16x16x32_bf16 v[132:135], v[0:3], v[162:165], v[132:135]
	v_mfma_f32_16x16x32_bf16 v[124:127], v[154:157], v[162:165], v[124:127]
	v_mfma_f32_16x16x32_bf16 v[116:119], v[0:3], v[182:185], v[116:119]
	v_mfma_f32_16x16x32_bf16 v[108:111], v[154:157], v[182:185], v[108:111]
	v_mfma_f32_16x16x32_bf16 v[100:103], v[0:3], v[190:193], v[100:103]
	v_mfma_f32_16x16x32_bf16 v[92:95], v[154:157], v[190:193], v[92:95]
	v_mfma_f32_16x16x32_bf16 v[84:87], v[0:3], v[198:201], v[84:87]
	v_mfma_f32_16x16x32_bf16 v[76:79], v[154:157], v[198:201], v[76:79]
	v_mfma_f32_16x16x32_bf16 v[132:135], v[4:7], v[178:181], v[132:135]
	v_mfma_f32_16x16x32_bf16 v[124:127], v[158:161], v[178:181], v[124:127]
	v_mfma_f32_16x16x32_bf16 v[116:119], v[4:7], v[186:189], v[116:119]
	v_mfma_f32_16x16x32_bf16 v[108:111], v[158:161], v[186:189], v[108:111]
	v_mfma_f32_16x16x32_bf16 v[100:103], v[4:7], v[194:197], v[100:103]
	v_mfma_f32_16x16x32_bf16 v[92:95], v[158:161], v[194:197], v[92:95]
	v_mfma_f32_16x16x32_bf16 v[84:87], v[4:7], v[202:205], v[84:87]
	v_mfma_f32_16x16x32_bf16 v[76:79], v[158:161], v[202:205], v[76:79]
	v_mfma_f32_16x16x32_bf16 v[128:131], v[206:209], v[162:165], v[128:131]
	v_mfma_f32_16x16x32_bf16 v[120:123], v[214:217], v[162:165], v[120:123]
	v_mfma_f32_16x16x32_bf16 v[112:115], v[206:209], v[182:185], v[112:115]
	v_mfma_f32_16x16x32_bf16 v[104:107], v[214:217], v[182:185], v[104:107]
	v_mfma_f32_16x16x32_bf16 v[96:99], v[206:209], v[190:193], v[96:99]
	v_mfma_f32_16x16x32_bf16 v[88:91], v[214:217], v[190:193], v[88:91]
	v_mfma_f32_16x16x32_bf16 v[80:83], v[206:209], v[198:201], v[80:83]
	v_mfma_f32_16x16x32_bf16 v[72:75], v[214:217], v[198:201], v[72:75]
	v_mfma_f32_16x16x32_bf16 v[128:131], v[210:213], v[178:181], v[128:131]
	v_mfma_f32_16x16x32_bf16 v[120:123], v[218:221], v[178:181], v[120:123]
	v_mfma_f32_16x16x32_bf16 v[112:115], v[210:213], v[186:189], v[112:115]
	v_mfma_f32_16x16x32_bf16 v[104:107], v[218:221], v[186:189], v[104:107]
	v_mfma_f32_16x16x32_bf16 v[96:99], v[210:213], v[194:197], v[96:99]
	v_mfma_f32_16x16x32_bf16 v[88:91], v[218:221], v[194:197], v[88:91]
	v_mfma_f32_16x16x32_bf16 v[80:83], v[210:213], v[202:205], v[80:83]
	v_mfma_f32_16x16x32_bf16 v[72:75], v[218:221], v[202:205], v[72:75]
	s_barrier
	ds_read_b128 v[162:165], v174 offset:16384
	ds_read_b128 v[178:181], v174 offset:17408
	ds_read_b128 v[182:185], v174 offset:18432
	ds_read_b128 v[186:189], v174 offset:19456
	ds_read_b128 v[190:193], v174 offset:20480
	ds_read_b128 v[194:197], v174 offset:21504
	ds_read_b128 v[198:201], v174 offset:22528
	ds_read_b128 v[202:205], v174 offset:23552
	s_add_i32 s64, s52, s22
	v_lshl_add_u64 v[166:167], s[4:5], 0, v[140:141]
	s_mov_b32 m0, s64
	s_nop 0
	global_load_lds_dwordx4 v[166:167], off
	v_lshl_add_u64 v[222:223], s[4:5], 0, v[136:137]
	s_add_i32 m0, s64, 0x2000
	s_nop 0
	global_load_lds_dwordx4 v[222:223], off
	s_mov_b32 m0, s11
	v_lshl_add_u64 v[224:225], s[6:7], 0, v[142:143]
	global_load_lds_dwordx4 v[224:225], off
	v_lshl_add_u64 v[226:227], s[6:7], 0, v[138:139]
	s_mov_b32 m0, s31
	s_nop 0
	global_load_lds_dwordx4 v[226:227], off
	s_add_u32 s64, s4, 0x80000
	s_addc_u32 s65, s5, 0
	s_add_i32 s66, s53, s22
	v_lshl_add_u64 v[228:229], s[64:65], 0, v[140:141]
	s_mov_b32 m0, s66
	s_nop 0
	global_load_lds_dwordx4 v[228:229], off
	v_lshl_add_u64 v[228:229], s[64:65], 0, v[136:137]
	s_add_i32 m0, s66, 0x2000
	s_nop 0
	global_load_lds_dwordx4 v[228:229], off
	s_waitcnt lgkmcnt(0)
	s_waitcnt vmcnt(8)
	s_barrier
	v_mfma_f32_16x16x32_bf16 v[68:71], v[0:3], v[162:165], v[68:71]
	v_mfma_f32_16x16x32_bf16 v[60:63], v[154:157], v[162:165], v[60:63]
	v_mfma_f32_16x16x32_bf16 v[52:55], v[0:3], v[182:185], v[52:55]
	v_mfma_f32_16x16x32_bf16 v[44:47], v[154:157], v[182:185], v[44:47]
	v_mfma_f32_16x16x32_bf16 v[36:39], v[0:3], v[190:193], v[36:39]
	v_mfma_f32_16x16x32_bf16 v[28:31], v[154:157], v[190:193], v[28:31]
	v_mfma_f32_16x16x32_bf16 v[0:3], v[0:3], v[198:201], v[20:23]
	v_mfma_f32_16x16x32_bf16 v[68:71], v[4:7], v[178:181], v[68:71]
	v_mfma_f32_16x16x32_bf16 v[60:63], v[158:161], v[178:181], v[60:63]
	v_mfma_f32_16x16x32_bf16 v[52:55], v[4:7], v[186:189], v[52:55]
	v_mfma_f32_16x16x32_bf16 v[44:47], v[158:161], v[186:189], v[44:47]
	v_mfma_f32_16x16x32_bf16 v[36:39], v[4:7], v[194:197], v[36:39]
	v_mfma_f32_16x16x32_bf16 v[28:31], v[158:161], v[194:197], v[28:31]
	v_mfma_f32_16x16x32_bf16 v[0:3], v[4:7], v[202:205], v[0:3]
	v_mfma_f32_16x16x32_bf16 v[4:7], v[154:157], v[198:201], v[12:15]
	v_mfma_f32_16x16x32_bf16 v[4:7], v[158:161], v[202:205], v[4:7]
	v_mfma_f32_16x16x32_bf16 v[12:15], v[206:209], v[162:165], v[64:67]
	v_mfma_f32_16x16x32_bf16 v[64:67], v[210:213], v[178:181], v[12:15]
	v_mfma_f32_16x16x32_bf16 v[12:15], v[214:217], v[162:165], v[56:59]
	v_mfma_f32_16x16x32_bf16 v[56:59], v[218:221], v[178:181], v[12:15]
	v_mfma_f32_16x16x32_bf16 v[12:15], v[206:209], v[182:185], v[48:51]
	v_mfma_f32_16x16x32_bf16 v[48:51], v[210:213], v[186:189], v[12:15]
	v_mfma_f32_16x16x32_bf16 v[12:15], v[214:217], v[182:185], v[40:43]
	v_mfma_f32_16x16x32_bf16 v[40:43], v[218:221], v[186:189], v[12:15]
	v_mfma_f32_16x16x32_bf16 v[12:15], v[206:209], v[190:193], v[32:35]
	v_mfma_f32_16x16x32_bf16 v[32:35], v[210:213], v[194:197], v[12:15]
	v_mfma_f32_16x16x32_bf16 v[12:15], v[214:217], v[190:193], v[24:27]
	v_mfma_f32_16x16x32_bf16 v[24:27], v[218:221], v[194:197], v[12:15]
	v_mfma_f32_16x16x32_bf16 v[12:15], v[206:209], v[198:201], v[16:19]
	v_mfma_f32_16x16x32_bf16 v[8:11], v[214:217], v[198:201], v[8:11]
	v_mfma_f32_16x16x32_bf16 v[16:19], v[210:213], v[202:205], v[12:15]
	v_mfma_f32_16x16x32_bf16 v[8:11], v[218:221], v[202:205], v[8:11]
	s_add_i32 s64, 0, 0x18000
	v_add_u32_e32 v158, s64, v170
	s_barrier
; #define PG8_STAGE(bufoff, gbase, voff) do { _Pragma("unroll") for (int _i = 0; _i < 2; ++_i) \
;         __builtin_amdgcn_global_load_lds((const unsigned*)((const char*)(gbase) + (voff)[_i]), (PG8_LAS unsigned*)(lds + (bufoff) + ldsw + _i * 8192), 16, 0, 0); } while (0)
; #define PG8_LDA(dst, b, h) do { _Pragma("unroll") for (int m = 0; m < 4; ++m) _Pragma("unroll") for (int k = 0; k < 2; ++k) dst[m][k] = *(const PG8_LAS bf16x8*)(lds + PG8_SA(b, h) + aoff + m * 2048 + k * 1024); } while (0)
; #define PG8_LDB(dst, b, h) do { _Pragma("unroll") for (int n = 0; n < 2; ++n) _Pragma("unroll") for (int k = 0; k < 2; ++k) dst[n][k] = *(const PG8_LAS bf16x8*)(lds + PG8_SB(b, h) + boff + n * 2048 + k * 1024); } while (0)
; #define PG8_MMA(ai, bj, At, Bt) do { __builtin_amdgcn_s_setprio(1); _Pragma("unroll") for (int m = 0; m < 4; ++m) _Pragma("unroll") for (int n = 0; n < 2; ++n) _Pragma("unroll") for (int k = 0; k < 2; ++k) \
;         acc[ai][bj][m][n] = __builtin_amdgcn_mfma_f32_16x16x32_bf16(Bt[n][k], At[m][k], acc[ai][bj][m][n], 0, 0, 0); __builtin_amdgcn_s_setprio(0); } while (0)
; #define PG8_WAIT_L(n) asm volatile("s_waitcnt lgkmcnt(" #n ")" ::: "memory")
; #define PG8_BAR __builtin_amdgcn_s_barrier()
; #define PG8_SCHED __builtin_amdgcn_sched_barrier(0)
; template <class Epi>
; __device__ __forceinline__ void gemm_phase(PG8_LAS unsigned char* lds, const Gemm g, const StaticOrder& S, const Epi& E) {
;     ...
;             PG8_LDB(B0, 1, 0); PG8_SCHED; PG8_LDA(At, 1, 0); PG8_STAGE(PG8_SA(0, 1), a2 + hstepA, voffA);
;             PG8_WAIT_L(8); PG8_BAR; PG8_WAIT_L(0); PG8_MMA(0, 0, At, B0); PG8_BAR; PG8_SCHED;
;             PG8_LDB(B1, 1, 1); PG8_STAGE(PG8_SB(1, 0), b3, voffB);
;             PG8_BAR; PG8_WAIT_L(0); PG8_MMA(0, 1, At, B1); PG8_BAR;
;             PG8_LDA(At, 1, 1); PG8_STAGE(PG8_SA(1, 0), a3, voffA);
;             PG8_BAR; PG8_WAIT_L(0); PG8_MMA(1, 0, At, B0); PG8_BAR; PG8_SCHED;
	s_nop 0
	s_nop 0
	ds_read_b128 v[12:15], v158
	ds_read_b128 v[20:23], v158 offset:1024
	ds_read_b128 v[154:157], v158 offset:2048
	ds_read_b128 v[158:161], v158 offset:3072
	ds_read_b128 v[162:165], v174 offset:32768
	ds_read_b128 v[178:181], v174 offset:33792
	ds_read_b128 v[182:185], v174 offset:34816
	ds_read_b128 v[186:189], v174 offset:35840
	ds_read_b128 v[190:193], v174 offset:36864
	ds_read_b128 v[194:197], v174 offset:37888
	ds_read_b128 v[198:201], v174 offset:38912
	ds_read_b128 v[202:205], v174 offset:39936
	v_add_u32_e32 v177, 0x1c000, v170
	ds_read_b128 v[206:209], v177
	ds_read_b128 v[210:213], v177 offset:1024
	ds_read_b128 v[214:217], v177 offset:2048
	ds_read_b128 v[218:221], v177 offset:3072
	s_add_u32 s6, s6, 0x80000
	s_addc_u32 s7, s7, 0
	s_mov_b32 m0, s34
	v_lshl_add_u64 v[228:229], s[6:7], 0, v[142:143]
	global_load_lds_dwordx4 v[228:229], off
	v_lshl_add_u64 v[228:229], s[6:7], 0, v[138:139]
	s_mov_b32 m0, s35
	s_nop 0
	global_load_lds_dwordx4 v[228:229], off
	s_waitcnt lgkmcnt(0)
	s_waitcnt vmcnt(8)
	s_barrier
	v_mfma_f32_16x16x32_bf16 v[132:135], v[12:15], v[162:165], v[132:135]
	v_mfma_f32_16x16x32_bf16 v[124:127], v[154:157], v[162:165], v[124:127]
	v_mfma_f32_16x16x32_bf16 v[116:119], v[12:15], v[182:185], v[116:119]
	v_mfma_f32_16x16x32_bf16 v[108:111], v[154:157], v[182:185], v[108:111]
	v_mfma_f32_16x16x32_bf16 v[100:103], v[12:15], v[190:193], v[100:103]
	v_mfma_f32_16x16x32_bf16 v[92:95], v[154:157], v[190:193], v[92:95]
	v_mfma_f32_16x16x32_bf16 v[84:87], v[12:15], v[198:201], v[84:87]
	v_mfma_f32_16x16x32_bf16 v[76:79], v[154:157], v[198:201], v[76:79]
	v_mfma_f32_16x16x32_bf16 v[132:135], v[20:23], v[178:181], v[132:135]
	v_mfma_f32_16x16x32_bf16 v[124:127], v[158:161], v[178:181], v[124:127]
	v_mfma_f32_16x16x32_bf16 v[116:119], v[20:23], v[186:189], v[116:119]
	v_mfma_f32_16x16x32_bf16 v[108:111], v[158:161], v[186:189], v[108:111]
	v_mfma_f32_16x16x32_bf16 v[100:103], v[20:23], v[194:197], v[100:103]
	v_mfma_f32_16x16x32_bf16 v[92:95], v[158:161], v[194:197], v[92:95]
	v_mfma_f32_16x16x32_bf16 v[84:87], v[20:23], v[202:205], v[84:87]
	v_mfma_f32_16x16x32_bf16 v[76:79], v[158:161], v[202:205], v[76:79]
	v_mfma_f32_16x16x32_bf16 v[128:131], v[206:209], v[162:165], v[128:131]
	v_mfma_f32_16x16x32_bf16 v[120:123], v[214:217], v[162:165], v[120:123]
	v_mfma_f32_16x16x32_bf16 v[112:115], v[206:209], v[182:185], v[112:115]
	v_mfma_f32_16x16x32_bf16 v[104:107], v[214:217], v[182:185], v[104:107]
	v_mfma_f32_16x16x32_bf16 v[96:99], v[206:209], v[190:193], v[96:99]
	v_mfma_f32_16x16x32_bf16 v[88:91], v[214:217], v[190:193], v[88:91]
	v_mfma_f32_16x16x32_bf16 v[80:83], v[206:209], v[198:201], v[80:83]
	v_mfma_f32_16x16x32_bf16 v[72:75], v[214:217], v[198:201], v[72:75]
	v_mfma_f32_16x16x32_bf16 v[128:131], v[210:213], v[178:181], v[128:131]
	v_mfma_f32_16x16x32_bf16 v[120:123], v[218:221], v[178:181], v[120:123]
	v_mfma_f32_16x16x32_bf16 v[112:115], v[210:213], v[186:189], v[112:115]
	v_mfma_f32_16x16x32_bf16 v[104:107], v[218:221], v[186:189], v[104:107]
	v_mfma_f32_16x16x32_bf16 v[96:99], v[210:213], v[194:197], v[96:99]
	v_mfma_f32_16x16x32_bf16 v[88:91], v[218:221], v[194:197], v[88:91]
	v_mfma_f32_16x16x32_bf16 v[80:83], v[210:213], v[202:205], v[80:83]
	v_mfma_f32_16x16x32_bf16 v[72:75], v[218:221], v[202:205], v[72:75]
	s_barrier
	ds_read_b128 v[162:165], v174 offset:49152
	ds_read_b128 v[178:181], v174 offset:50176
	ds_read_b128 v[182:185], v174 offset:51200
	ds_read_b128 v[186:189], v174 offset:52224
	ds_read_b128 v[190:193], v174 offset:53248
	ds_read_b128 v[194:197], v174 offset:54272
	ds_read_b128 v[198:201], v174 offset:55296
	ds_read_b128 v[202:205], v174 offset:56320
	s_add_i32 s6, 0, 0x1c000
	s_add_i32 s7, s64, s22
	v_lshl_add_u64 v[166:167], v[166:167], 0, s[12:13]
	s_mov_b32 m0, s7
	s_nop 0
	global_load_lds_dwordx4 v[166:167], off
	v_lshl_add_u64 v[166:167], v[222:223], 0, s[12:13]
	s_add_i32 m0, s7, 0x2000
	s_nop 0
	global_load_lds_dwordx4 v[166:167], off
	s_mov_b32 m0, s48
	v_lshl_add_u64 v[166:167], v[224:225], 0, s[12:13]
	global_load_lds_dwordx4 v[166:167], off
	v_lshl_add_u64 v[166:167], v[226:227], 0, s[12:13]
	s_mov_b32 m0, s49
	s_nop 0
	global_load_lds_dwordx4 v[166:167], off
	s_add_u32 s4, s4, 0x80080
	s_addc_u32 s5, s5, 0
	s_add_i32 s6, s6, s22
	v_lshl_add_u64 v[228:229], s[4:5], 0, v[140:141]
	s_mov_b32 m0, s6
	s_nop 0
	global_load_lds_dwordx4 v[228:229], off
	v_lshl_add_u64 v[228:229], s[4:5], 0, v[136:137]
	s_add_i32 m0, s6, 0x2000
	s_nop 0
	global_load_lds_dwordx4 v[228:229], off
	s_waitcnt lgkmcnt(0)
	s_waitcnt vmcnt(8)
	s_barrier
; #define PG8_STAGE(bufoff, gbase, voff) do { _Pragma("unroll") for (int _i = 0; _i < 2; ++_i) \
;         __builtin_amdgcn_global_load_lds((const unsigned*)((const char*)(gbase) + (voff)[_i]), (PG8_LAS unsigned*)(lds + (bufoff) + ldsw + _i * 8192), 16, 0, 0); } while (0)
; #define PG8_MMA(ai, bj, At, Bt) do { __builtin_amdgcn_s_setprio(1); _Pragma("unroll") for (int m = 0; m < 4; ++m) _Pragma("unroll") for (int n = 0; n < 2; ++n) _Pragma("unroll") for (int k = 0; k < 2; ++k) \
;         acc[ai][bj][m][n] = __builtin_amdgcn_mfma_f32_16x16x32_bf16(Bt[n][k], At[m][k], acc[ai][bj][m][n], 0, 0, 0); __builtin_amdgcn_s_setprio(0); } while (0)
; #define PG8_WAIT_V(n) asm volatile("s_waitcnt vmcnt(" #n ")" ::: "memory")
; #define PG8_WAIT_L(n) asm volatile("s_waitcnt lgkmcnt(" #n ")" ::: "memory")
; #define PG8_BAR __builtin_amdgcn_s_barrier()
; #define PG8_SCHED __builtin_amdgcn_sched_barrier(0)
; __device__ __forceinline__ void rstd8(const float* part, int row0, int fq, float (&rs)[8]) {
;     f32x4 v[8][2];
; #pragma unroll
;     for (int k = 0; k < 8; ++k) { const f32x4* p = (const f32x4*)(part + (size_t)(row0 + (k >> 2) * 128 + (k & 3) * 16) * 32 + fq * 8); v[k][0] = p[0]; v[k][1] = p[1]; }
; #pragma unroll
;     for (int k = 0; k < 8; ++k) { float s = ((v[k][0][0] + v[k][0][1]) + (v[k][0][2] + v[k][0][3])) + ((v[k][1][0] + v[k][1][1]) + (v[k][1][2] + v[k][1][3]));
;         s += __shfl_xor(s, 16); s += __shfl_xor(s, 32); rs[k] = rsqrtf(s * (1.0f / 2048.0f) + EPS); }
; template <class Epi>
; __device__ __forceinline__ void gemm_phase(PG8_LAS unsigned char* lds, const Gemm g, const StaticOrder& S, const Epi& E) {
;     ...
;             PG8_BAR; PG8_WAIT_L(0); PG8_MMA(1, 0, At, B0); PG8_BAR; PG8_SCHED;
;             PG8_STAGE(PG8_SB(1, 1), b3 + hstepB, voffB);
;             PG8_WAIT_V(6); PG8_BAR; PG8_MMA(1, 1, At, B1); PG8_BAR;
;         }
;         E(acc, cur, wr, wc, fr, fq);
;         if (!has_next) break;
	v_mfma_f32_16x16x32_bf16 v[68:71], v[12:15], v[162:165], v[68:71]
	v_mfma_f32_16x16x32_bf16 v[52:55], v[12:15], v[182:185], v[52:55]
	v_mfma_f32_16x16x32_bf16 v[36:39], v[12:15], v[190:193], v[36:39]
	v_mfma_f32_16x16x32_bf16 v[0:3], v[12:15], v[198:201], v[0:3]
	v_mfma_f32_16x16x32_bf16 v[68:71], v[20:23], v[178:181], v[68:71]
	v_mfma_f32_16x16x32_bf16 v[60:63], v[154:157], v[162:165], v[60:63]
	v_mfma_f32_16x16x32_bf16 v[52:55], v[20:23], v[186:189], v[52:55]
	v_mfma_f32_16x16x32_bf16 v[44:47], v[154:157], v[182:185], v[44:47]
	v_mfma_f32_16x16x32_bf16 v[36:39], v[20:23], v[194:197], v[36:39]
	v_mfma_f32_16x16x32_bf16 v[28:31], v[154:157], v[190:193], v[28:31]
	v_mfma_f32_16x16x32_bf16 v[20:23], v[20:23], v[202:205], v[0:3]
	v_mfma_f32_16x16x32_bf16 v[0:3], v[154:157], v[198:201], v[4:7]
	v_mfma_f32_16x16x32_bf16 v[60:63], v[158:161], v[178:181], v[60:63]
	v_mfma_f32_16x16x32_bf16 v[44:47], v[158:161], v[186:189], v[44:47]
	v_mfma_f32_16x16x32_bf16 v[28:31], v[158:161], v[194:197], v[28:31]
	v_mfma_f32_16x16x32_bf16 v[12:15], v[158:161], v[202:205], v[0:3]
	v_mfma_f32_16x16x32_bf16 v[0:3], v[206:209], v[162:165], v[64:67]
	v_mfma_f32_16x16x32_bf16 v[64:67], v[210:213], v[178:181], v[0:3]
	v_mfma_f32_16x16x32_bf16 v[0:3], v[214:217], v[162:165], v[56:59]
	v_mfma_f32_16x16x32_bf16 v[56:59], v[218:221], v[178:181], v[0:3]
	v_mfma_f32_16x16x32_bf16 v[0:3], v[206:209], v[182:185], v[48:51]
	v_mfma_f32_16x16x32_bf16 v[48:51], v[210:213], v[186:189], v[0:3]
	v_mfma_f32_16x16x32_bf16 v[0:3], v[214:217], v[182:185], v[40:43]
	v_mfma_f32_16x16x32_bf16 v[40:43], v[218:221], v[186:189], v[0:3]
	v_mfma_f32_16x16x32_bf16 v[0:3], v[206:209], v[190:193], v[32:35]
	v_mfma_f32_16x16x32_bf16 v[32:35], v[210:213], v[194:197], v[0:3]
	v_mfma_f32_16x16x32_bf16 v[0:3], v[214:217], v[190:193], v[24:27]
	v_mfma_f32_16x16x32_bf16 v[24:27], v[218:221], v[194:197], v[0:3]
	v_mfma_f32_16x16x32_bf16 v[0:3], v[206:209], v[198:201], v[16:19]
	v_mfma_f32_16x16x32_bf16 v[16:19], v[210:213], v[202:205], v[0:3]
	v_mfma_f32_16x16x32_bf16 v[0:3], v[214:217], v[198:201], v[8:11]
	v_mfma_f32_16x16x32_bf16 v[8:11], v[218:221], v[202:205], v[0:3]
	s_add_i32 s63, s63, 2
	s_add_u32 s0, s0, 0x100
	s_addc_u32 s1, s1, 0
	s_add_u32 s61, s61, 0x100
	s_addc_u32 s62, s62, 0
	s_cmp_gt_u32 s63, 29
	s_barrier
	s_cbranch_scc0 .LBB0_1086
	s_setprio 0
	v_lshl_add_u32 v164, s10, 8, v169
	v_or_b32_e32 v160, 16, v164
	v_or_b32_e32 v158, 32, v164
	v_or_b32_e32 v156, 48, v164
	s_mov_b64 s[0:1], -1
	s_cmp_lg_u32 s10, s58
	v_ashrrev_i32_e32 v165, 31, v164
	v_ashrrev_i32_e32 v161, 31, v160
	v_ashrrev_i32_e32 v159, 31, v158
	v_ashrrev_i32_e32 v157, 31, v156
	v_add_u32_e32 v166, 0x80, v164
	s_cbranch_scc0 .LBB0_1089
	v_lshlrev_b64 v[0:1], 7, v[164:165]
	v_lshlrev_b64 v[4:5], 7, v[160:161]
	v_lshl_add_u64 v[162:163], v[144:145], 0, v[0:1]
	v_lshl_add_u64 v[154:155], v[144:145], 0, v[4:5]
	global_load_dwordx4 v[0:3], v[162:163], off
	global_load_dwordx4 v[4:7], v[154:155], off
	global_load_dwordx4 v[178:181], v[162:163], off offset:16
	global_load_dwordx4 v[182:185], v[154:155], off offset:16
	v_lshlrev_b64 v[154:155], 7, v[158:159]
	v_lshlrev_b64 v[186:187], 7, v[156:157]
	v_lshl_add_u64 v[154:155], v[144:145], 0, v[154:155]
	v_lshl_add_u64 v[198:199], v[144:145], 0, v[186:187]
	global_load_dwordx4 v[186:189], v[154:155], off
	global_load_dwordx4 v[190:193], v[198:199], off
	global_load_dwordx4 v[194:197], v[154:155], off offset:16
	s_nop 0
	global_load_dwordx4 v[198:201], v[198:199], off offset:16
	v_add_u32_e32 v154, 0x80, v164
	v_ashrrev_i32_e32 v155, 31, v154
	v_lshlrev_b64 v[202:203], 7, v[154:155]
	v_add_co_u32_e32 v204, vcc, s47, v162
	v_lshl_add_u64 v[210:211], v[144:145], 0, v[202:203]
	s_nop 0
	v_addc_co_u32_e32 v205, vcc, 0, v163, vcc
	global_load_dwordx4 v[202:205], v[204:205], off offset:2048
	s_nop 0
	global_load_dwordx4 v[206:209], v[210:211], off offset:16
	s_nop 0
	global_load_dwordx4 v[210:213], v[210:211], off
	v_and_b32_e32 v177, 64, v176
	v_add_co_u32_e32 v226, vcc, s54, v162
	v_xor_b32_e32 v167, 16, v176
	v_add_u32_e32 v177, 64, v177
	v_addc_co_u32_e32 v227, vcc, 0, v163, vcc
	v_xor_b32_e32 v216, 32, v176
	v_cmp_lt_i32_e32 vcc, v167, v177
	v_lshl_add_u64 v[214:215], v[162:163], 0, s[14:15]
	v_lshl_add_u64 v[222:223], v[162:163], 0, s[16:17]
	v_cndmask_b32_e32 v167, v176, v167, vcc
	v_cmp_lt_i32_e32 vcc, v216, v177
	v_lshl_add_u64 v[162:163], v[162:163], 0, s[18:19]
	v_lshlrev_b32_e32 v167, 2, v167
	v_cndmask_b32_e32 v177, v176, v216, vcc
	global_load_dwordx4 v[214:217], v[214:215], off offset:16
	s_nop 0
	global_load_dwordx4 v[218:221], v[226:227], off
	s_nop 0
	global_load_dwordx4 v[222:225], v[222:223], off offset:16
	s_nop 0
	global_load_dwordx4 v[226:229], v[226:227], off offset:2048
	s_nop 0
	global_load_dwordx4 v[230:233], v[162:163], off offset:16
	v_lshlrev_b32_e32 v177, 2, v177
	v_mov_b64_e32 v[234:235], s[28:29]
	s_waitcnt vmcnt(0)
; __device__ __forceinline__ void rstd8(const float* part, int row0, int fq, float (&rs)[8]) {
;     f32x4 v[8][2];
; #pragma unroll
;     for (int k = 0; k < 8; ++k) { const f32x4* p = (const f32x4*)(part + (size_t)(row0 + (k >> 2) * 128 + (k & 3) * 16) * 32 + fq * 8); v[k][0] = p[0]; v[k][1] = p[1]; }
; #pragma unroll
;     for (int k = 0; k < 8; ++k) { float s = ((v[k][0][0] + v[k][0][1]) + (v[k][0][2] + v[k][0][3])) + ((v[k][1][0] + v[k][1][1]) + (v[k][1][2] + v[k][1][3]));
;         s += __shfl_xor(s, 16); s += __shfl_xor(s, 32); rs[k] = rsqrtf(s * (1.0f / 2048.0f) + EPS); }
;     __device__ __forceinline__ void operator()(const f32x4 (&acc)[2][2][4][2], const pg8::Unit& u, int wr, int wc, int fr, int fq) const {
;     ...
;         if (u.pm != cached_pm) { rstd8(part, row0, fq, rsv);
; #pragma unroll
;             for (int k = 0; k < 8; ++k) mine[k * 64] = rsv[k];
;             cached_pm = u.pm; }
	v_mov_b32_e32 v163, v4
	v_mov_b32_e32 v162, v0
	v_mov_b32_e32 v4, v1
	v_mov_b32_e32 v0, v2
	v_mov_b32_e32 v1, v6
	v_mov_b32_e32 v6, v3
	v_mov_b32_e32 v2, v178
	v_mov_b32_e32 v3, v182
	v_mov_b32_e32 v182, v179
	v_mov_b32_e32 v178, v180
	v_mov_b32_e32 v179, v184
	v_mov_b32_e32 v184, v181
	v_pk_add_f32 v[4:5], v[162:163], v[4:5]
	v_pk_add_f32 v[0:1], v[0:1], v[6:7]
	v_pk_add_f32 v[2:3], v[2:3], v[182:183]
	v_pk_add_f32 v[6:7], v[178:179], v[184:185]
	v_pk_add_f32 v[0:1], v[4:5], v[0:1]
	v_pk_add_f32 v[2:3], v[2:3], v[6:7]
	v_mov_b32_e32 v180, v186
	v_pk_add_f32 v[0:1], v[0:1], v[2:3]
	ds_bpermute_b32 v2, v167, v0
	ds_bpermute_b32 v3, v167, v1
	v_mov_b32_e32 v181, v190
	v_mov_b32_e32 v190, v187
	v_mov_b32_e32 v186, v188
	v_mov_b32_e32 v187, v192
	v_mov_b32_e32 v192, v189
	v_mov_b32_e32 v188, v194
	v_mov_b32_e32 v189, v198
	v_mov_b32_e32 v198, v195
	v_mov_b32_e32 v194, v196
	v_mov_b32_e32 v195, v200
	v_mov_b32_e32 v200, v197
	s_waitcnt lgkmcnt(0)
	v_pk_add_f32 v[0:1], v[0:1], v[2:3]
	v_pk_add_f32 v[162:163], v[180:181], v[190:191]
	v_pk_add_f32 v[4:5], v[186:187], v[192:193]
	v_pk_add_f32 v[6:7], v[188:189], v[198:199]
	v_pk_add_f32 v[178:179], v[194:195], v[200:201]
	ds_bpermute_b32 v2, v177, v0
	ds_bpermute_b32 v3, v177, v1
	v_pk_add_f32 v[4:5], v[162:163], v[4:5]
	v_pk_add_f32 v[6:7], v[6:7], v[178:179]
	v_mov_b32_e32 v162, v212
	v_pk_add_f32 v[4:5], v[4:5], v[6:7]
	ds_bpermute_b32 v6, v167, v4
	ds_bpermute_b32 v7, v167, v5
	s_waitcnt lgkmcnt(2)
	v_pk_add_f32 v[0:1], v[0:1], v[2:3]
	v_mov_b32_e32 v163, v204
	v_pk_fma_f32 v[0:1], v[0:1], s[20:21], v[234:235] op_sel_hi:[1,0,0]
	v_mov_b32_e32 v204, v213
	v_mul_f32_e32 v2, 0x4b800000, v0
	v_mul_f32_e32 v3, 0x4b800000, v1
	v_cmp_gt_f32_e32 vcc, s55, v0
	v_cmp_gt_f32_e64 s[0:1], s55, v1
	v_pk_add_f32 v[162:163], v[162:163], v[204:205]
	v_cndmask_b32_e32 v0, v0, v2, vcc
	v_cndmask_b32_e64 v1, v1, v3, s[0:1]
	s_waitcnt lgkmcnt(0)
	v_pk_add_f32 v[2:3], v[4:5], v[6:7]
	ds_bpermute_b32 v4, v177, v2
	ds_bpermute_b32 v5, v177, v3
	v_rsq_f32_e32 v0, v0
	v_rsq_f32_e32 v1, v1
	v_mov_b32_e32 v178, v208
	v_mov_b32_e32 v179, v216
	s_waitcnt lgkmcnt(0)
	v_pk_add_f32 v[2:3], v[2:3], v[4:5]
	v_pk_mul_f32 v[6:7], v[0:1], s[30:31] op_sel_hi:[1,0]
	v_pk_fma_f32 v[2:3], v[2:3], s[20:21], v[234:235] op_sel_hi:[1,0,0]
	v_cndmask_b32_e64 v1, v1, v7, s[0:1]
	v_mul_f32_e32 v4, 0x4b800000, v2
	v_cmp_gt_f32_e64 s[0:1], s55, v2
	v_mov_b32_e32 v5, v202
	v_mov_b32_e32 v202, v211
	v_cndmask_b32_e64 v2, v2, v4, s[0:1]
	v_mov_b32_e32 v4, v210
	v_pk_add_f32 v[4:5], v[4:5], v[202:203]
	v_mov_b32_e32 v216, v209
	v_pk_add_f32 v[4:5], v[4:5], v[162:163]
	v_mov_b32_e32 v162, v206
	v_mov_b32_e32 v163, v214
	v_mov_b32_e32 v214, v207
	v_pk_add_f32 v[162:163], v[162:163], v[214:215]
	v_pk_add_f32 v[178:179], v[178:179], v[216:217]
	v_mul_f32_e32 v7, 0x4b800000, v3
	v_pk_add_f32 v[162:163], v[162:163], v[178:179]
	v_cmp_gt_f32_e64 s[4:5], s55, v3
	v_pk_add_f32 v[4:5], v[4:5], v[162:163]
	ds_bpermute_b32 v162, v167, v4
	ds_bpermute_b32 v163, v167, v5
	v_cndmask_b32_e64 v3, v3, v7, s[4:5]
	v_rsq_f32_e32 v2, v2
	v_rsq_f32_e32 v3, v3
	v_cndmask_b32_e32 v0, v0, v6, vcc
	s_waitcnt lgkmcnt(0)
	v_pk_add_f32 v[4:5], v[4:5], v[162:163]
	ds_bpermute_b32 v162, v177, v4
	ds_bpermute_b32 v163, v177, v5
	v_pk_mul_f32 v[6:7], v[2:3], s[30:31] op_sel_hi:[1,0]
	v_mov_b32_e32 v178, v226
	v_cndmask_b32_e64 v3, v3, v7, s[4:5]
	v_cndmask_b32_e64 v2, v2, v6, s[0:1]
	s_waitcnt lgkmcnt(0)
	v_pk_add_f32 v[4:5], v[4:5], v[162:163]
	v_mov_b32_e32 v6, v219
	v_mov_b32_e32 v7, v220
	v_mov_b32_e32 v219, v221
	v_mov_b32_e32 v162, v223
	v_mov_b32_e32 v163, v224
	v_mov_b32_e32 v223, v225
	v_mov_b32_e32 v179, v230
	v_mov_b32_e32 v230, v227
	v_mov_b32_e32 v180, v228
	v_mov_b32_e32 v181, v232
	v_mov_b32_e32 v232, v229
	v_pk_add_f32 v[6:7], v[6:7], v[218:219]
	v_pk_add_f32 v[162:163], v[162:163], v[222:223]
	v_pk_add_f32 v[178:179], v[178:179], v[230:231]
	v_pk_add_f32 v[180:181], v[180:181], v[232:233]
	v_pk_add_f32 v[6:7], v[6:7], v[6:7] op_sel:[0,1] op_sel_hi:[1,0]
	v_pk_add_f32 v[162:163], v[162:163], v[162:163] op_sel:[0,1] op_sel_hi:[1,0]
	v_pk_add_f32 v[178:179], v[178:179], v[180:181]
	v_pk_fma_f32 v[4:5], v[4:5], s[20:21], v[234:235] op_sel_hi:[1,0,0]
	v_mov_b32_e32 v7, v178
	v_mov_b32_e32 v163, v179
	v_pk_add_f32 v[6:7], v[6:7], v[162:163]
	ds_bpermute_b32 v162, v167, v6
	ds_bpermute_b32 v163, v167, v7
	v_mul_f32_e32 v167, 0x4b800000, v4
	v_cmp_gt_f32_e32 vcc, s55, v4
	v_cmp_gt_f32_e64 s[0:1], s55, v5
	s_waitcnt lgkmcnt(0)
	v_pk_add_f32 v[6:7], v[6:7], v[162:163]
	ds_bpermute_b32 v162, v177, v6
	ds_bpermute_b32 v163, v177, v7
	v_cndmask_b32_e32 v4, v4, v167, vcc
	v_mul_f32_e32 v167, 0x4b800000, v5
	v_cndmask_b32_e64 v5, v5, v167, s[0:1]
	v_rsq_f32_e32 v4, v4
	s_waitcnt lgkmcnt(0)
	v_pk_add_f32 v[6:7], v[6:7], v[162:163]
	v_rsq_f32_e32 v5, v5
	v_pk_fma_f32 v[6:7], v[6:7], s[20:21], v[234:235] op_sel_hi:[1,0,0]
	s_nop 0
	v_mul_f32_e32 v162, 0x4b800000, v6
	v_cmp_gt_f32_e64 s[4:5], s55, v6
	v_cmp_gt_f32_e64 s[6:7], s55, v7
	s_nop 0
	v_cndmask_b32_e64 v6, v6, v162, s[4:5]
	v_mul_f32_e32 v162, 0x4b800000, v7
	v_cndmask_b32_e64 v7, v7, v162, s[6:7]
	v_rsq_f32_e32 v6, v6
	v_rsq_f32_e32 v7, v7
	v_pk_mul_f32 v[162:163], v[4:5], s[30:31] op_sel_hi:[1,0]
	s_nop 0
	v_cndmask_b32_e64 v5, v5, v163, s[0:1]
	v_cndmask_b32_e32 v4, v4, v162, vcc
	v_pk_mul_f32 v[162:163], v[6:7], s[30:31] op_sel_hi:[1,0]
	s_mov_b64 s[0:1], 0
	v_cndmask_b32_e64 v7, v7, v163, s[6:7]
	v_cndmask_b32_e64 v6, v6, v162, s[4:5]
	ds_write2st64_b32 v171, v0, v1 offset1:1
	ds_write2st64_b32 v171, v2, v3 offset0:2 offset1:3
	ds_write2st64_b32 v171, v4, v5 offset0:4 offset1:5
	ds_write2st64_b32 v171, v6, v7 offset0:6 offset1:7
	v_mov_b64_e32 v[162:163], v[154:155]

; #define PG8_STAGE(bufoff, gbase, voff) do { _Pragma("unroll") for (int _i = 0; _i < 2; ++_i) \
;         __builtin_amdgcn_global_load_lds((const unsigned*)((const char*)(gbase) + (voff)[_i]), (PG8_LAS unsigned*)(lds + (bufoff) + ldsw + _i * 8192), 16, 0, 0); } while (0)
; #define PG8_LDA(dst, b, h) do { _Pragma("unroll") for (int m = 0; m < 4; ++m) _Pragma("unroll") for (int k = 0; k < 2; ++k) dst[m][k] = *(const PG8_LAS bf16x8*)(lds + PG8_SA(b, h) + aoff + m * 2048 + k * 1024); } while (0)
; #define PG8_LDB(dst, b, h) do { _Pragma("unroll") for (int n = 0; n < 2; ++n) _Pragma("unroll") for (int k = 0; k < 2; ++k) dst[n][k] = *(const PG8_LAS bf16x8*)(lds + PG8_SB(b, h) + boff + n * 2048 + k * 1024); } while (0)
; #define PG8_MMA(ai, bj, At, Bt) do { __builtin_amdgcn_s_setprio(1); _Pragma("unroll") for (int m = 0; m < 4; ++m) _Pragma("unroll") for (int n = 0; n < 2; ++n) _Pragma("unroll") for (int k = 0; k < 2; ++k) \
;         acc[ai][bj][m][n] = __builtin_amdgcn_mfma_f32_16x16x32_bf16(Bt[n][k], At[m][k], acc[ai][bj][m][n], 0, 0, 0); __builtin_amdgcn_s_setprio(0); } while (0)
; #define PG8_WAIT_L(n) asm volatile("s_waitcnt lgkmcnt(" #n ")" ::: "memory")
; #define PG8_BAR __builtin_amdgcn_s_barrier()
; #define PG8_SCHED __builtin_amdgcn_sched_barrier(0)
; template <class Epi>
; __device__ __forceinline__ void gemm_phase(PG8_LAS unsigned char* lds, const Gemm g, const StaticOrder& S, const Epi& E) {
;     ...
;     f32x4 acc[2][2][4][2];
; #pragma unroll
;     for (int a = 0; a < 2; ++a)
; #pragma unroll
;         for (int b = 0; b < 2; ++b)
; #pragma unroll
;             for (int m = 0; m < 4; ++m)
; #pragma unroll
;                 for (int n = 0; n < 2; ++n) acc[a][b][m][n] = (f32x4){0.f, 0.f, 0.f, 0.f};
;     ...
;         for (int t = 0; t < nt; t += 2) {
;             const bool last = (t == nt - 2);
;             const char* a1 = cA + (size_t)(t + 1) * kstep;
;             const char* a2 = last ? nA : cA + (size_t)(t + 2) * kstep; const char* b2 = last ? nB : cB + (size_t)(t + 2) * kstep;
;             const char* a3 = a2 + kstep; const char* b3 = b2 + kstep;
;             PG8_LDB(B0, 0, 0); PG8_SCHED; PG8_LDA(At, 0, 0); PG8_STAGE(PG8_SA(1, 1), a1 + hstepA, voffA);
;             PG8_WAIT_L(8); PG8_BAR; PG8_WAIT_L(0); PG8_MMA(0, 0, At, B0); PG8_BAR; PG8_SCHED;
.LBB0_1169:
	s_add_u32 s10, s10, 0x160080
	s_addc_u32 s11, s11, 0
	s_add_u32 s36, s12, 0x100
	v_mov_b32_e32 v4, 0
	s_addc_u32 s37, s13, 0
	s_mov_b32 s38, -2
	v_mov_b32_e32 v5, v4
	v_mov_b32_e32 v6, v4
	v_mov_b32_e32 v7, v4
	v_mov_b32_e32 v0, v4
	v_mov_b32_e32 v1, v4
	v_mov_b32_e32 v2, v4
	v_mov_b32_e32 v3, v4
	v_mov_b32_e32 v20, v4
	v_mov_b32_e32 v21, v4
	v_mov_b32_e32 v22, v4
	v_mov_b32_e32 v23, v4
	v_mov_b32_e32 v16, v4
	v_mov_b32_e32 v17, v4
	v_mov_b32_e32 v18, v4
	v_mov_b32_e32 v19, v4
	v_mov_b32_e32 v36, v4
	v_mov_b32_e32 v37, v4
	v_mov_b32_e32 v38, v4
	v_mov_b32_e32 v39, v4
	v_mov_b32_e32 v32, v4
	v_mov_b32_e32 v33, v4
	v_mov_b32_e32 v34, v4
	v_mov_b32_e32 v35, v4
	v_mov_b32_e32 v52, v4
	v_mov_b32_e32 v53, v4
	v_mov_b32_e32 v54, v4
	v_mov_b32_e32 v55, v4
	v_mov_b32_e32 v48, v4
	v_mov_b32_e32 v49, v4
	v_mov_b32_e32 v50, v4
	v_mov_b32_e32 v51, v4
	v_mov_b32_e32 v12, v4
	v_mov_b32_e32 v13, v4
	v_mov_b32_e32 v14, v4
	v_mov_b32_e32 v15, v4
	v_mov_b32_e32 v8, v4
	v_mov_b32_e32 v9, v4
	v_mov_b32_e32 v10, v4
	v_mov_b32_e32 v11, v4
	v_mov_b32_e32 v28, v4
	v_mov_b32_e32 v29, v4
	v_mov_b32_e32 v30, v4
	v_mov_b32_e32 v31, v4
	v_mov_b32_e32 v24, v4
	v_mov_b32_e32 v25, v4
	v_mov_b32_e32 v26, v4
	v_mov_b32_e32 v27, v4
	v_mov_b32_e32 v44, v4
	v_mov_b32_e32 v45, v4
	v_mov_b32_e32 v46, v4
	v_mov_b32_e32 v47, v4
	v_mov_b32_e32 v40, v4
	v_mov_b32_e32 v41, v4
	v_mov_b32_e32 v42, v4
	v_mov_b32_e32 v43, v4
	v_mov_b32_e32 v60, v4
	v_mov_b32_e32 v61, v4
	v_mov_b32_e32 v62, v4
	v_mov_b32_e32 v63, v4
	v_mov_b32_e32 v56, v4
	v_mov_b32_e32 v57, v4
	v_mov_b32_e32 v58, v4
	v_mov_b32_e32 v59, v4
	v_mov_b32_e32 v68, v4
	v_mov_b32_e32 v69, v4
	v_mov_b32_e32 v70, v4
	v_mov_b32_e32 v71, v4
	v_mov_b32_e32 v64, v4
	v_mov_b32_e32 v65, v4
	v_mov_b32_e32 v66, v4
	v_mov_b32_e32 v67, v4
	v_mov_b32_e32 v84, v4
	v_mov_b32_e32 v85, v4
	v_mov_b32_e32 v86, v4
	v_mov_b32_e32 v87, v4
	v_mov_b32_e32 v80, v4
	v_mov_b32_e32 v81, v4
	v_mov_b32_e32 v82, v4
	v_mov_b32_e32 v83, v4
	v_mov_b32_e32 v96, v4
	v_mov_b32_e32 v97, v4
	v_mov_b32_e32 v98, v4
	v_mov_b32_e32 v99, v4
	v_mov_b32_e32 v100, v4
	v_mov_b32_e32 v101, v4
	v_mov_b32_e32 v102, v4
	v_mov_b32_e32 v103, v4
	v_mov_b32_e32 v112, v4
	v_mov_b32_e32 v113, v4
	v_mov_b32_e32 v114, v4
	v_mov_b32_e32 v115, v4
	v_mov_b32_e32 v116, v4
	v_mov_b32_e32 v117, v4
	v_mov_b32_e32 v118, v4
	v_mov_b32_e32 v119, v4
	v_mov_b32_e32 v76, v4
	v_mov_b32_e32 v77, v4
	v_mov_b32_e32 v78, v4
	v_mov_b32_e32 v79, v4
	v_mov_b32_e32 v72, v4
	v_mov_b32_e32 v73, v4
	v_mov_b32_e32 v74, v4
	v_mov_b32_e32 v75, v4
	v_mov_b32_e32 v92, v4
	v_mov_b32_e32 v93, v4
	v_mov_b32_e32 v94, v4
	v_mov_b32_e32 v95, v4
	v_mov_b32_e32 v88, v4
	v_mov_b32_e32 v89, v4
	v_mov_b32_e32 v90, v4
	v_mov_b32_e32 v91, v4
	v_mov_b32_e32 v104, v4
	v_mov_b32_e32 v105, v4
	v_mov_b32_e32 v106, v4
	v_mov_b32_e32 v107, v4
	v_mov_b32_e32 v108, v4
	v_mov_b32_e32 v109, v4
	v_mov_b32_e32 v110, v4
	v_mov_b32_e32 v111, v4
	v_mov_b32_e32 v120, v4
	v_mov_b32_e32 v121, v4
	v_mov_b32_e32 v122, v4
	v_mov_b32_e32 v123, v4
	v_mov_b32_e32 v124, v4
	v_mov_b32_e32 v125, v4
	v_mov_b32_e32 v126, v4
	v_mov_b32_e32 v127, v4
	s_cmp_eq_u32 s101, 1
	s_cbranch_scc0 .Lsp_7
	s_setprio 1
.Lsp_7:
.LBB0_1170:
	ds_read_b128 v[144:147], v155
	ds_read_b128 v[148:151], v155 offset:1024
	ds_read_b128 v[158:161], v155 offset:2048
	ds_read_b128 v[162:165], v155 offset:3072
	ds_read_b128 v[166:169], v156
	ds_read_b128 v[170:173], v156 offset:1024
	ds_read_b128 v[174:177], v156 offset:2048
	ds_read_b128 v[178:181], v156 offset:3072
	ds_read_b128 v[182:185], v156 offset:4096
	ds_read_b128 v[186:189], v156 offset:5120
	ds_read_b128 v[190:193], v156 offset:6144
	ds_read_b128 v[194:197], v156 offset:7168
	ds_read_b128 v[198:201], v157
	ds_read_b128 v[202:205], v157 offset:1024
	ds_read_b128 v[206:209], v157 offset:2048
	ds_read_b128 v[210:213], v157 offset:3072
	s_add_u32 s12, s10, 0xffea0080
	s_addc_u32 s13, s11, -1
	s_cmpk_eq_i32 s38, 0x54
	s_cselect_b32 s15, s3, s13
	s_cselect_b32 s14, s2, s12
	s_cselect_b32 s13, s5, s37
	s_cselect_b32 s12, s4, s36
	v_lshl_add_u64 v[222:223], s[10:11], 0, v[136:137]
	s_add_i32 m0, s19, 0xc000
	s_nop 0
	global_load_lds_dwordx4 v[222:223], off
	v_lshl_add_u64 v[222:223], s[10:11], 0, v[138:139]
	s_add_i32 m0, s19, 0xe000
	s_nop 0
	global_load_lds_dwordx4 v[222:223], off
	s_waitcnt lgkmcnt(0)
	s_waitcnt vmcnt(8)
	s_barrier
	v_mfma_f32_16x16x32_bf16 v[124:127], v[144:147], v[166:169], v[124:127]
	v_mfma_f32_16x16x32_bf16 v[120:123], v[158:161], v[166:169], v[120:123]
	v_mfma_f32_16x16x32_bf16 v[108:111], v[144:147], v[174:177], v[108:111]
	v_mfma_f32_16x16x32_bf16 v[104:107], v[158:161], v[174:177], v[104:107]
	v_mfma_f32_16x16x32_bf16 v[88:91], v[144:147], v[182:185], v[88:91]
	v_mfma_f32_16x16x32_bf16 v[92:95], v[158:161], v[182:185], v[92:95]
	v_mfma_f32_16x16x32_bf16 v[72:75], v[144:147], v[190:193], v[72:75]
	v_mfma_f32_16x16x32_bf16 v[76:79], v[158:161], v[190:193], v[76:79]
	v_mfma_f32_16x16x32_bf16 v[124:127], v[148:151], v[170:173], v[124:127]
	v_mfma_f32_16x16x32_bf16 v[120:123], v[162:165], v[170:173], v[120:123]
	v_mfma_f32_16x16x32_bf16 v[108:111], v[148:151], v[178:181], v[108:111]
	v_mfma_f32_16x16x32_bf16 v[104:107], v[162:165], v[178:181], v[104:107]
	v_mfma_f32_16x16x32_bf16 v[88:91], v[148:151], v[186:189], v[88:91]
	v_mfma_f32_16x16x32_bf16 v[92:95], v[162:165], v[186:189], v[92:95]
	v_mfma_f32_16x16x32_bf16 v[72:75], v[148:151], v[194:197], v[72:75]
	v_mfma_f32_16x16x32_bf16 v[76:79], v[162:165], v[194:197], v[76:79]
	v_mfma_f32_16x16x32_bf16 v[116:119], v[198:201], v[166:169], v[116:119]
	v_mfma_f32_16x16x32_bf16 v[112:115], v[206:209], v[166:169], v[112:115]
	v_mfma_f32_16x16x32_bf16 v[100:103], v[198:201], v[174:177], v[100:103]
	v_mfma_f32_16x16x32_bf16 v[96:99], v[206:209], v[174:177], v[96:99]
	v_mfma_f32_16x16x32_bf16 v[80:83], v[198:201], v[182:185], v[80:83]
	v_mfma_f32_16x16x32_bf16 v[84:87], v[206:209], v[182:185], v[84:87]
	v_mfma_f32_16x16x32_bf16 v[64:67], v[198:201], v[190:193], v[64:67]
	v_mfma_f32_16x16x32_bf16 v[68:71], v[206:209], v[190:193], v[68:71]
	v_mfma_f32_16x16x32_bf16 v[116:119], v[202:205], v[170:173], v[116:119]
	v_mfma_f32_16x16x32_bf16 v[112:115], v[210:213], v[170:173], v[112:115]
	v_mfma_f32_16x16x32_bf16 v[100:103], v[202:205], v[178:181], v[100:103]
	v_mfma_f32_16x16x32_bf16 v[96:99], v[210:213], v[178:181], v[96:99]
	v_mfma_f32_16x16x32_bf16 v[80:83], v[202:205], v[186:189], v[80:83]
	v_mfma_f32_16x16x32_bf16 v[84:87], v[210:213], v[186:189], v[84:87]
	v_mfma_f32_16x16x32_bf16 v[64:67], v[202:205], v[194:197], v[64:67]
	v_mfma_f32_16x16x32_bf16 v[68:71], v[210:213], v[194:197], v[68:71]
	s_barrier
; #define PG8_STAGE(bufoff, gbase, voff) do { _Pragma("unroll") for (int _i = 0; _i < 2; ++_i) \
;         __builtin_amdgcn_global_load_lds((const unsigned*)((const char*)(gbase) + (voff)[_i]), (PG8_LAS unsigned*)(lds + (bufoff) + ldsw + _i * 8192), 16, 0, 0); } while (0)
; #define PG8_LDA(dst, b, h) do { _Pragma("unroll") for (int m = 0; m < 4; ++m) _Pragma("unroll") for (int k = 0; k < 2; ++k) dst[m][k] = *(const PG8_LAS bf16x8*)(lds + PG8_SA(b, h) + aoff + m * 2048 + k * 1024); } while (0)
; #define PG8_LDB(dst, b, h) do { _Pragma("unroll") for (int n = 0; n < 2; ++n) _Pragma("unroll") for (int k = 0; k < 2; ++k) dst[n][k] = *(const PG8_LAS bf16x8*)(lds + PG8_SB(b, h) + boff + n * 2048 + k * 1024); } while (0)
; #define PG8_MMA(ai, bj, At, Bt) do { __builtin_amdgcn_s_setprio(1); _Pragma("unroll") for (int m = 0; m < 4; ++m) _Pragma("unroll") for (int n = 0; n < 2; ++n) _Pragma("unroll") for (int k = 0; k < 2; ++k) \
;         acc[ai][bj][m][n] = __builtin_amdgcn_mfma_f32_16x16x32_bf16(Bt[n][k], At[m][k], acc[ai][bj][m][n], 0, 0, 0); __builtin_amdgcn_s_setprio(0); } while (0)
; #define PG8_WAIT_V(n) asm volatile("s_waitcnt vmcnt(" #n ")" ::: "memory")
; #define PG8_WAIT_L(n) asm volatile("s_waitcnt lgkmcnt(" #n ")" ::: "memory")
; #define PG8_BAR __builtin_amdgcn_s_barrier()
; #define PG8_SCHED __builtin_amdgcn_sched_barrier(0)
; template <class Epi>
; __device__ __forceinline__ void gemm_phase(PG8_LAS unsigned char* lds, const Gemm g, const StaticOrder& S, const Epi& E) {
;     ...
;             PG8_LDB(B1, 0, 1); PG8_STAGE(PG8_SB(0, 0), b2, voffB);
;             PG8_BAR; PG8_WAIT_L(0); PG8_MMA(0, 1, At, B1); PG8_BAR;
;             PG8_LDA(At, 0, 1); PG8_STAGE(PG8_SA(0, 0), a2, voffA);
;             PG8_BAR; PG8_WAIT_L(0); PG8_MMA(1, 0, At, B0); PG8_BAR; PG8_SCHED;
;             PG8_STAGE(PG8_SB(0, 1), b2 + hstepB, voffB);
;             PG8_WAIT_V(6); PG8_BAR; PG8_MMA(1, 1, At, B1); PG8_BAR;
;             PG8_LDB(B0, 1, 0); PG8_SCHED; PG8_LDA(At, 1, 0); PG8_STAGE(PG8_SA(0, 1), a2 + hstepA, voffA);
;             PG8_WAIT_L(8); PG8_BAR; PG8_WAIT_L(0); PG8_MMA(0, 0, At, B0); PG8_BAR; PG8_SCHED;
	ds_read_b128 v[166:169], v156 offset:16384
	ds_read_b128 v[170:173], v156 offset:17408
	ds_read_b128 v[174:177], v156 offset:18432
	ds_read_b128 v[178:181], v156 offset:19456
	ds_read_b128 v[182:185], v156 offset:20480
	ds_read_b128 v[186:189], v156 offset:21504
	ds_read_b128 v[190:193], v156 offset:22528
	ds_read_b128 v[194:197], v156 offset:23552
	s_add_i32 s39, s29, s18
	v_lshl_add_u64 v[214:215], s[12:13], 0, v[130:131]
	s_mov_b32 m0, s39
	s_nop 0
	global_load_lds_dwordx4 v[214:215], off
	v_lshl_add_u64 v[216:217], s[12:13], 0, v[134:135]
	s_add_i32 m0, s39, 0x2000
	s_nop 0
	global_load_lds_dwordx4 v[216:217], off
	s_mov_b32 m0, s19
	v_lshl_add_u64 v[218:219], s[14:15], 0, v[128:129]
	global_load_lds_dwordx4 v[218:219], off
	v_lshl_add_u64 v[220:221], s[14:15], 0, v[132:133]
	s_mov_b32 m0, s20
	s_nop 0
	global_load_lds_dwordx4 v[220:221], off
	s_add_u32 s40, s12, 0x160000
	s_addc_u32 s41, s13, 0
	s_add_i32 s39, s30, s18
	v_lshl_add_u64 v[222:223], s[40:41], 0, v[130:131]
	s_mov_b32 m0, s39
	s_nop 0
	global_load_lds_dwordx4 v[222:223], off
	v_lshl_add_u64 v[222:223], s[40:41], 0, v[134:135]
	s_add_i32 m0, s39, 0x2000
	s_nop 0
	global_load_lds_dwordx4 v[222:223], off
	s_waitcnt lgkmcnt(0)
	s_waitcnt vmcnt(8)
	s_barrier
	v_mfma_f32_16x16x32_bf16 v[56:59], v[144:147], v[166:169], v[56:59]
	v_mfma_f32_16x16x32_bf16 v[60:63], v[158:161], v[166:169], v[60:63]
	v_mfma_f32_16x16x32_bf16 v[40:43], v[144:147], v[174:177], v[40:43]
	v_mfma_f32_16x16x32_bf16 v[44:47], v[158:161], v[174:177], v[44:47]
	v_mfma_f32_16x16x32_bf16 v[24:27], v[144:147], v[182:185], v[24:27]
	v_mfma_f32_16x16x32_bf16 v[28:31], v[158:161], v[182:185], v[28:31]
	v_mfma_f32_16x16x32_bf16 v[8:11], v[144:147], v[190:193], v[8:11]
	v_mfma_f32_16x16x32_bf16 v[12:15], v[158:161], v[190:193], v[12:15]
	v_mfma_f32_16x16x32_bf16 v[56:59], v[148:151], v[170:173], v[56:59]
	v_mfma_f32_16x16x32_bf16 v[60:63], v[162:165], v[170:173], v[60:63]
	v_mfma_f32_16x16x32_bf16 v[40:43], v[148:151], v[178:181], v[40:43]
	v_mfma_f32_16x16x32_bf16 v[44:47], v[162:165], v[178:181], v[44:47]
	v_mfma_f32_16x16x32_bf16 v[24:27], v[148:151], v[186:189], v[24:27]
	v_mfma_f32_16x16x32_bf16 v[28:31], v[162:165], v[186:189], v[28:31]
	v_mfma_f32_16x16x32_bf16 v[8:11], v[148:151], v[194:197], v[8:11]
	v_mfma_f32_16x16x32_bf16 v[12:15], v[162:165], v[194:197], v[12:15]
	v_mfma_f32_16x16x32_bf16 v[48:51], v[198:201], v[166:169], v[48:51]
	v_mfma_f32_16x16x32_bf16 v[52:55], v[206:209], v[166:169], v[52:55]
	v_mfma_f32_16x16x32_bf16 v[32:35], v[198:201], v[174:177], v[32:35]
	v_mfma_f32_16x16x32_bf16 v[36:39], v[206:209], v[174:177], v[36:39]
	v_mfma_f32_16x16x32_bf16 v[16:19], v[198:201], v[182:185], v[16:19]
	v_mfma_f32_16x16x32_bf16 v[20:23], v[206:209], v[182:185], v[20:23]
	v_mfma_f32_16x16x32_bf16 v[0:3], v[198:201], v[190:193], v[0:3]
	v_mfma_f32_16x16x32_bf16 v[4:7], v[206:209], v[190:193], v[4:7]
	v_mfma_f32_16x16x32_bf16 v[48:51], v[202:205], v[170:173], v[48:51]
	v_mfma_f32_16x16x32_bf16 v[52:55], v[210:213], v[170:173], v[52:55]
	v_mfma_f32_16x16x32_bf16 v[32:35], v[202:205], v[178:181], v[32:35]
	v_mfma_f32_16x16x32_bf16 v[36:39], v[210:213], v[178:181], v[36:39]
	v_mfma_f32_16x16x32_bf16 v[16:19], v[202:205], v[186:189], v[16:19]
	v_mfma_f32_16x16x32_bf16 v[20:23], v[210:213], v[186:189], v[20:23]
	v_mfma_f32_16x16x32_bf16 v[0:3], v[202:205], v[194:197], v[0:3]
	v_mfma_f32_16x16x32_bf16 v[4:7], v[210:213], v[194:197], v[4:7]
	s_add_i32 s39, 0, 0x18000
	v_add_u32_e32 v162, s39, v153
	s_barrier
	ds_read_b128 v[144:147], v162
	ds_read_b128 v[148:151], v162 offset:1024
	ds_read_b128 v[158:161], v162 offset:2048
	ds_read_b128 v[162:165], v162 offset:3072
	ds_read_b128 v[166:169], v156 offset:32768
	ds_read_b128 v[170:173], v156 offset:33792
	ds_read_b128 v[174:177], v156 offset:34816
	ds_read_b128 v[178:181], v156 offset:35840
	ds_read_b128 v[182:185], v156 offset:36864
	ds_read_b128 v[186:189], v156 offset:37888
	ds_read_b128 v[190:193], v156 offset:38912
	ds_read_b128 v[194:197], v156 offset:39936
	v_add_u32_e32 v210, 0x1c000, v153
	ds_read_b128 v[198:201], v210
	ds_read_b128 v[202:205], v210 offset:1024
	ds_read_b128 v[206:209], v210 offset:2048
	ds_read_b128 v[210:213], v210 offset:3072
	s_add_u32 s14, s14, 0x160000
	s_addc_u32 s15, s15, 0
	s_mov_b32 m0, s21
	v_lshl_add_u64 v[222:223], s[14:15], 0, v[128:129]
	global_load_lds_dwordx4 v[222:223], off
	v_lshl_add_u64 v[222:223], s[14:15], 0, v[132:133]
	s_mov_b32 m0, s22
	s_nop 0
	global_load_lds_dwordx4 v[222:223], off
	s_waitcnt lgkmcnt(0)
	s_waitcnt vmcnt(8)
	s_barrier
; #define PG8_STAGE(bufoff, gbase, voff) do { _Pragma("unroll") for (int _i = 0; _i < 2; ++_i) \
;         __builtin_amdgcn_global_load_lds((const unsigned*)((const char*)(gbase) + (voff)[_i]), (PG8_LAS unsigned*)(lds + (bufoff) + ldsw + _i * 8192), 16, 0, 0); } while (0)
; #define PG8_LDA(dst, b, h) do { _Pragma("unroll") for (int m = 0; m < 4; ++m) _Pragma("unroll") for (int k = 0; k < 2; ++k) dst[m][k] = *(const PG8_LAS bf16x8*)(lds + PG8_SA(b, h) + aoff + m * 2048 + k * 1024); } while (0)
; #define PG8_LDB(dst, b, h) do { _Pragma("unroll") for (int n = 0; n < 2; ++n) _Pragma("unroll") for (int k = 0; k < 2; ++k) dst[n][k] = *(const PG8_LAS bf16x8*)(lds + PG8_SB(b, h) + boff + n * 2048 + k * 1024); } while (0)
; #define PG8_MMA(ai, bj, At, Bt) do { __builtin_amdgcn_s_setprio(1); _Pragma("unroll") for (int m = 0; m < 4; ++m) _Pragma("unroll") for (int n = 0; n < 2; ++n) _Pragma("unroll") for (int k = 0; k < 2; ++k) \
;         acc[ai][bj][m][n] = __builtin_amdgcn_mfma_f32_16x16x32_bf16(Bt[n][k], At[m][k], acc[ai][bj][m][n], 0, 0, 0); __builtin_amdgcn_s_setprio(0); } while (0)
; #define PG8_WAIT_V(n) asm volatile("s_waitcnt vmcnt(" #n ")" ::: "memory")
; #define PG8_WAIT_L(n) asm volatile("s_waitcnt lgkmcnt(" #n ")" ::: "memory")
; #define PG8_BAR __builtin_amdgcn_s_barrier()
; #define PG8_SCHED __builtin_amdgcn_sched_barrier(0)
; template <class Epi>
; __device__ __forceinline__ void gemm_phase(PG8_LAS unsigned char* lds, const Gemm g, const StaticOrder& S, const Epi& E) {
;     ...
;             PG8_LDB(B0, 1, 0); PG8_SCHED; PG8_LDA(At, 1, 0); PG8_STAGE(PG8_SA(0, 1), a2 + hstepA, voffA);
;             PG8_WAIT_L(8); PG8_BAR; PG8_WAIT_L(0); PG8_MMA(0, 0, At, B0); PG8_BAR; PG8_SCHED;
;             PG8_LDB(B1, 1, 1); PG8_STAGE(PG8_SB(1, 0), b3, voffB);
;             PG8_BAR; PG8_WAIT_L(0); PG8_MMA(0, 1, At, B1); PG8_BAR;
;             PG8_LDA(At, 1, 1); PG8_STAGE(PG8_SA(1, 0), a3, voffA);
;             PG8_BAR; PG8_WAIT_L(0); PG8_MMA(1, 0, At, B0); PG8_BAR; PG8_SCHED;
;             PG8_STAGE(PG8_SB(1, 1), b3 + hstepB, voffB);
;             PG8_WAIT_V(6); PG8_BAR; PG8_MMA(1, 1, At, B1); PG8_BAR;
	v_mfma_f32_16x16x32_bf16 v[124:127], v[144:147], v[166:169], v[124:127]
	v_mfma_f32_16x16x32_bf16 v[120:123], v[158:161], v[166:169], v[120:123]
	v_mfma_f32_16x16x32_bf16 v[108:111], v[144:147], v[174:177], v[108:111]
	v_mfma_f32_16x16x32_bf16 v[104:107], v[158:161], v[174:177], v[104:107]
	v_mfma_f32_16x16x32_bf16 v[88:91], v[144:147], v[182:185], v[88:91]
	v_mfma_f32_16x16x32_bf16 v[92:95], v[158:161], v[182:185], v[92:95]
	v_mfma_f32_16x16x32_bf16 v[72:75], v[144:147], v[190:193], v[72:75]
	v_mfma_f32_16x16x32_bf16 v[76:79], v[158:161], v[190:193], v[76:79]
	v_mfma_f32_16x16x32_bf16 v[124:127], v[148:151], v[170:173], v[124:127]
	v_mfma_f32_16x16x32_bf16 v[120:123], v[162:165], v[170:173], v[120:123]
	v_mfma_f32_16x16x32_bf16 v[108:111], v[148:151], v[178:181], v[108:111]
	v_mfma_f32_16x16x32_bf16 v[104:107], v[162:165], v[178:181], v[104:107]
	v_mfma_f32_16x16x32_bf16 v[88:91], v[148:151], v[186:189], v[88:91]
	v_mfma_f32_16x16x32_bf16 v[92:95], v[162:165], v[186:189], v[92:95]
	v_mfma_f32_16x16x32_bf16 v[72:75], v[148:151], v[194:197], v[72:75]
	v_mfma_f32_16x16x32_bf16 v[76:79], v[162:165], v[194:197], v[76:79]
	v_mfma_f32_16x16x32_bf16 v[116:119], v[198:201], v[166:169], v[116:119]
	v_mfma_f32_16x16x32_bf16 v[112:115], v[206:209], v[166:169], v[112:115]
	v_mfma_f32_16x16x32_bf16 v[100:103], v[198:201], v[174:177], v[100:103]
	v_mfma_f32_16x16x32_bf16 v[96:99], v[206:209], v[174:177], v[96:99]
	v_mfma_f32_16x16x32_bf16 v[80:83], v[198:201], v[182:185], v[80:83]
	v_mfma_f32_16x16x32_bf16 v[84:87], v[206:209], v[182:185], v[84:87]
	v_mfma_f32_16x16x32_bf16 v[64:67], v[198:201], v[190:193], v[64:67]
	v_mfma_f32_16x16x32_bf16 v[68:71], v[206:209], v[190:193], v[68:71]
	v_mfma_f32_16x16x32_bf16 v[116:119], v[202:205], v[170:173], v[116:119]
	v_mfma_f32_16x16x32_bf16 v[112:115], v[210:213], v[170:173], v[112:115]
	v_mfma_f32_16x16x32_bf16 v[100:103], v[202:205], v[178:181], v[100:103]
	v_mfma_f32_16x16x32_bf16 v[96:99], v[210:213], v[178:181], v[96:99]
	v_mfma_f32_16x16x32_bf16 v[80:83], v[202:205], v[186:189], v[80:83]
	v_mfma_f32_16x16x32_bf16 v[84:87], v[210:213], v[186:189], v[84:87]
	v_mfma_f32_16x16x32_bf16 v[64:67], v[202:205], v[194:197], v[64:67]
	v_mfma_f32_16x16x32_bf16 v[68:71], v[210:213], v[194:197], v[68:71]
	s_barrier
	ds_read_b128 v[166:169], v156 offset:49152
	ds_read_b128 v[170:173], v156 offset:50176
	ds_read_b128 v[174:177], v156 offset:51200
	ds_read_b128 v[178:181], v156 offset:52224
	ds_read_b128 v[182:185], v156 offset:53248
	ds_read_b128 v[186:189], v156 offset:54272
	ds_read_b128 v[190:193], v156 offset:55296
	ds_read_b128 v[194:197], v156 offset:56320
	s_add_i32 s14, 0, 0x1c000
	s_add_i32 s15, s39, s18
	v_lshl_add_u64 v[214:215], v[214:215], 0, s[6:7]
	s_mov_b32 m0, s15
	s_nop 0
	global_load_lds_dwordx4 v[214:215], off
	v_lshl_add_u64 v[214:215], v[216:217], 0, s[6:7]
	s_add_i32 m0, s15, 0x2000
	s_nop 0
	global_load_lds_dwordx4 v[214:215], off
	s_mov_b32 m0, s25
	v_lshl_add_u64 v[214:215], v[218:219], 0, s[6:7]
	global_load_lds_dwordx4 v[214:215], off
	v_lshl_add_u64 v[214:215], v[220:221], 0, s[6:7]
	s_mov_b32 m0, s27
	s_nop 0
	global_load_lds_dwordx4 v[214:215], off
	s_add_u32 s12, s12, 0x160080
	s_addc_u32 s13, s13, 0
	s_add_i32 s14, s14, s18
	v_lshl_add_u64 v[222:223], s[12:13], 0, v[130:131]
	s_mov_b32 m0, s14
	s_nop 0
	global_load_lds_dwordx4 v[222:223], off
	v_lshl_add_u64 v[222:223], s[12:13], 0, v[134:135]
	s_add_i32 m0, s14, 0x2000
	s_nop 0
	global_load_lds_dwordx4 v[222:223], off
	s_waitcnt lgkmcnt(0)
	s_waitcnt vmcnt(8)
	s_barrier
	v_mfma_f32_16x16x32_bf16 v[56:59], v[144:147], v[166:169], v[56:59]
	v_mfma_f32_16x16x32_bf16 v[60:63], v[158:161], v[166:169], v[60:63]
	v_mfma_f32_16x16x32_bf16 v[40:43], v[144:147], v[174:177], v[40:43]
	v_mfma_f32_16x16x32_bf16 v[44:47], v[158:161], v[174:177], v[44:47]
	v_mfma_f32_16x16x32_bf16 v[24:27], v[144:147], v[182:185], v[24:27]
	v_mfma_f32_16x16x32_bf16 v[28:31], v[158:161], v[182:185], v[28:31]
	v_mfma_f32_16x16x32_bf16 v[8:11], v[144:147], v[190:193], v[8:11]
	v_mfma_f32_16x16x32_bf16 v[12:15], v[158:161], v[190:193], v[12:15]
	v_mfma_f32_16x16x32_bf16 v[56:59], v[148:151], v[170:173], v[56:59]
	v_mfma_f32_16x16x32_bf16 v[60:63], v[162:165], v[170:173], v[60:63]
	v_mfma_f32_16x16x32_bf16 v[40:43], v[148:151], v[178:181], v[40:43]
	v_mfma_f32_16x16x32_bf16 v[44:47], v[162:165], v[178:181], v[44:47]
	v_mfma_f32_16x16x32_bf16 v[24:27], v[148:151], v[186:189], v[24:27]
	v_mfma_f32_16x16x32_bf16 v[28:31], v[162:165], v[186:189], v[28:31]
	v_mfma_f32_16x16x32_bf16 v[8:11], v[148:151], v[194:197], v[8:11]
	v_mfma_f32_16x16x32_bf16 v[12:15], v[162:165], v[194:197], v[12:15]
	v_mfma_f32_16x16x32_bf16 v[48:51], v[198:201], v[166:169], v[48:51]
	v_mfma_f32_16x16x32_bf16 v[52:55], v[206:209], v[166:169], v[52:55]
	v_mfma_f32_16x16x32_bf16 v[32:35], v[198:201], v[174:177], v[32:35]
	v_mfma_f32_16x16x32_bf16 v[36:39], v[206:209], v[174:177], v[36:39]
	v_mfma_f32_16x16x32_bf16 v[16:19], v[198:201], v[182:185], v[16:19]
	v_mfma_f32_16x16x32_bf16 v[20:23], v[206:209], v[182:185], v[20:23]
	v_mfma_f32_16x16x32_bf16 v[0:3], v[198:201], v[190:193], v[0:3]
	v_mfma_f32_16x16x32_bf16 v[4:7], v[206:209], v[190:193], v[4:7]
	v_mfma_f32_16x16x32_bf16 v[48:51], v[202:205], v[170:173], v[48:51]
	v_mfma_f32_16x16x32_bf16 v[52:55], v[210:213], v[170:173], v[52:55]
	v_mfma_f32_16x16x32_bf16 v[32:35], v[202:205], v[178:181], v[32:35]
	v_mfma_f32_16x16x32_bf16 v[36:39], v[210:213], v[178:181], v[36:39]
	v_mfma_f32_16x16x32_bf16 v[16:19], v[202:205], v[186:189], v[16:19]
	v_mfma_f32_16x16x32_bf16 v[20:23], v[210:213], v[186:189], v[20:23]
	v_mfma_f32_16x16x32_bf16 v[0:3], v[202:205], v[194:197], v[0:3]
	v_mfma_f32_16x16x32_bf16 v[4:7], v[210:213], v[194:197], v[4:7]
	s_add_i32 s38, s38, 2
	s_add_u32 s10, s10, 0x100
	s_addc_u32 s11, s11, 0
	s_add_u32 s36, s36, 0x100
	s_addc_u32 s37, s37, 0
	s_cmpk_gt_u32 s38, 0x55
	s_barrier
;     __device__ __forceinline__ void operator()(const f32x4 (&acc)[2][2][4][2], const pg8::Unit& u, int wr, int wc, int fr, int fq) const {
;         const int row0 = u.pm * 256 + wr * 64 + fr, col0 = u.pn * 256 + wc * 32 + 8 * fq;
; #pragma unroll
;         for (int ai = 0; ai < 2; ++ai) {
;             u32x4 rb[4][2];
; #pragma unroll
;             for (int m = 0; m < 4; ++m)
; #pragma unroll
;                 for (int bj = 0; bj < 2; ++bj) rb[m][bj] = *(const u32x4*)(resb + (size_t)(row0 + ai * 128 + m * 16) * DM + col0 + bj * 128);
; #pragma unroll
;             for (int m = 0; m < 4; ++m) {
;                 const int r = row0 + ai * 128 + m * 16; float ss = 0.f;
; #pragma unroll
;                 for (int bj = 0; bj < 2; ++bj) {
;                     const size_t off = (size_t)r * DM + col0 + bj * 128;
;                     float rv[8], o[8]; unpack8(rb[m][bj], rv);
; #pragma unroll
;                     for (int n = 0; n < 2; ++n)
; #pragma unroll
;                         for (int i = 0; i < 4; ++i) o[n * 4 + i] = rv[n * 4 + i] + coef * acc[ai][bj][m][n][i];
;                     if (outf) { *(f32x4*)(outf + off) = (f32x4){o[0], o[1], o[2], o[3]}; *(f32x4*)(outf + off + 4) = (f32x4){o[4], o[5], o[6], o[7]}; }
	s_cbranch_scc0 .LBB0_1170
	s_setprio 0
	s_andn2_b64 vcc, exec, s[8:9]
	s_cbranch_vccnz .LBB0_1158
	v_lshl_or_b32 v144, s35, 8, v154
	v_lshl_add_u32 v148, s34, 8, v152
	v_ashrrev_i32_e32 v145, 31, v144
	v_ashrrev_i32_e32 v149, 31, v148
	v_lshl_add_u64 v[146:147], v[144:145], 1, s[76:77]
	v_lshlrev_b64 v[150:151], 12, v[148:149]
	v_or_b32_e32 v182, 16, v148
	v_lshl_add_u64 v[150:151], v[146:147], 0, v[150:151]
	v_ashrrev_i32_e32 v183, 31, v182
	global_load_dwordx4 v[158:161], v[150:151], off
	global_load_dwordx4 v[162:165], v[150:151], off offset:256
	v_lshlrev_b64 v[150:151], 12, v[182:183]
	v_lshl_add_u64 v[150:151], v[146:147], 0, v[150:151]
	v_or_b32_e32 v190, 32, v148
	global_load_dwordx4 v[166:169], v[150:151], off
	global_load_dwordx4 v[170:173], v[150:151], off offset:256
	v_ashrrev_i32_e32 v191, 31, v190
	v_lshlrev_b64 v[150:151], 12, v[190:191]
	v_lshl_add_u64 v[150:151], v[146:147], 0, v[150:151]
	global_load_dwordx4 v[174:177], v[150:151], off
	global_load_dwordx4 v[178:181], v[150:151], off offset:256
	v_or_b32_e32 v150, 48, v148
	v_ashrrev_i32_e32 v151, 31, v150
	v_lshlrev_b64 v[184:185], 13, v[148:149]
	v_lshlrev_b64 v[186:187], 12, v[150:151]
	v_lshlrev_b64 v[144:145], 2, v[144:145]
	v_lshl_add_u64 v[184:185], s[42:43], 0, v[184:185]
	v_lshlrev_b64 v[182:183], 13, v[182:183]
	v_lshl_add_u64 v[186:187], v[146:147], 0, v[186:187]
	v_lshl_add_u64 v[192:193], v[184:185], 0, v[144:145]
	v_lshl_add_u64 v[194:195], s[42:43], 0, v[182:183]
	global_load_dwordx4 v[182:185], v[186:187], off offset:256
	s_nop 0
	global_load_dwordx4 v[186:189], v[186:187], off
	v_lshl_add_u64 v[194:195], v[194:195], 0, v[144:145]
	s_waitcnt vmcnt(0)
	v_lshlrev_b32_e32 v196, 16, v160
	v_and_b32_e32 v197, 0xffff0000, v160
	v_lshlrev_b32_e32 v160, 16, v161
	v_and_b32_e32 v161, 0xffff0000, v161
	v_lshlrev_b32_e32 v198, 16, v158
	v_and_b32_e32 v199, 0xffff0000, v158
	v_lshlrev_b32_e32 v158, 16, v159
	v_and_b32_e32 v159, 0xffff0000, v159
	v_lshlrev_b32_e32 v200, 16, v164
	v_and_b32_e32 v201, 0xffff0000, v164
	v_lshlrev_b32_e32 v164, 16, v165
	v_and_b32_e32 v165, 0xffff0000, v165
	v_lshlrev_b32_e32 v202, 16, v162
	v_and_b32_e32 v203, 0xffff0000, v162
	v_lshlrev_b32_e32 v162, 16, v163
	v_and_b32_e32 v163, 0xffff0000, v163
	v_pk_fma_f32 v[122:123], v[122:123], 0.5, v[160:161] op_sel_hi:[1,0,1]
	v_pk_fma_f32 v[126:127], v[126:127], 0.5, v[158:159] op_sel_hi:[1,0,1]
	v_pk_fma_f32 v[114:115], v[114:115], 0.5, v[164:165] op_sel_hi:[1,0,1]
	v_pk_fma_f32 v[118:119], v[118:119], 0.5, v[162:163] op_sel_hi:[1,0,1]
	v_lshlrev_b32_e32 v158, 16, v168
	v_and_b32_e32 v159, 0xffff0000, v168
	v_lshlrev_b32_e32 v160, 16, v169
	v_and_b32_e32 v161, 0xffff0000, v169
	v_lshlrev_b32_e32 v162, 16, v166
	v_and_b32_e32 v163, 0xffff0000, v166
	v_lshlrev_b32_e32 v164, 16, v167
	v_and_b32_e32 v165, 0xffff0000, v167
	v_lshlrev_b32_e32 v168, 16, v173
	v_and_b32_e32 v169, 0xffff0000, v173
	v_pk_fma_f32 v[124:125], v[124:125], 0.5, v[198:199] op_sel_hi:[1,0,1]
	v_lshlrev_b32_e32 v166, 16, v172
	v_and_b32_e32 v167, 0xffff0000, v172
	v_lshlrev_b32_e32 v172, 16, v170
	v_and_b32_e32 v173, 0xffff0000, v170
	v_lshlrev_b32_e32 v170, 16, v171
	v_and_b32_e32 v171, 0xffff0000, v171
	v_pk_fma_f32 v[108:109], v[108:109], 0.5, v[162:163] op_sel_hi:[1,0,1]
	v_pk_fma_f32 v[110:111], v[110:111], 0.5, v[164:165] op_sel_hi:[1,0,1]
	v_pk_fma_f32 v[98:99], v[98:99], 0.5, v[168:169] op_sel_hi:[1,0,1]
	v_pk_fma_f32 v[120:121], v[120:121], 0.5, v[196:197] op_sel_hi:[1,0,1]
	v_pk_fma_f32 v[112:113], v[112:113], 0.5, v[200:201] op_sel_hi:[1,0,1]
	v_pk_fma_f32 v[116:117], v[116:117], 0.5, v[202:203] op_sel_hi:[1,0,1]
	global_store_dwordx4 v[192:193], v[124:127], off
	global_store_dwordx4 v[192:193], v[120:123], off offset:16
	global_store_dwordx4 v[192:193], v[116:119], off offset:512
	global_store_dwordx4 v[192:193], v[112:115], off offset:528
	v_pk_fma_f32 v[104:105], v[104:105], 0.5, v[158:159] op_sel_hi:[1,0,1]
	v_pk_fma_f32 v[106:107], v[106:107], 0.5, v[160:161] op_sel_hi:[1,0,1]
	v_pk_fma_f32 v[96:97], v[96:97], 0.5, v[166:167] op_sel_hi:[1,0,1]
	v_pk_fma_f32 v[100:101], v[100:101], 0.5, v[172:173] op_sel_hi:[1,0,1]
	v_pk_fma_f32 v[102:103], v[102:103], 0.5, v[170:171] op_sel_hi:[1,0,1]
	global_store_dwordx4 v[194:195], v[108:111], off
	global_store_dwordx4 v[194:195], v[104:107], off offset:16
	global_store_dwordx4 v[194:195], v[100:103], off offset:512
	global_store_dwordx4 v[194:195], v[96:99], off offset:528
	s_nop 0
	v_add_u32_e32 v100, 0xa0, v148
	v_lshlrev_b32_e32 v98, 16, v176
	v_and_b32_e32 v99, 0xffff0000, v176
	v_pk_fma_f32 v[92:93], v[92:93], 0.5, v[98:99] op_sel_hi:[1,0,1]
	v_lshlrev_b32_e32 v98, 16, v177
	v_and_b32_e32 v99, 0xffff0000, v177
	v_lshlrev_b64 v[96:97], 13, v[190:191]
	v_pk_fma_f32 v[94:95], v[94:95], 0.5, v[98:99] op_sel_hi:[1,0,1]
	v_lshlrev_b32_e32 v98, 16, v174
	v_and_b32_e32 v99, 0xffff0000, v174
	v_lshl_add_u64 v[96:97], s[42:43], 0, v[96:97]
	v_pk_fma_f32 v[88:89], v[88:89], 0.5, v[98:99] op_sel_hi:[1,0,1]
	v_lshlrev_b32_e32 v98, 16, v175
	v_and_b32_e32 v99, 0xffff0000, v175
	v_lshl_add_u64 v[96:97], v[96:97], 0, v[144:145]
	v_pk_fma_f32 v[90:91], v[90:91], 0.5, v[98:99] op_sel_hi:[1,0,1]
	global_store_dwordx4 v[96:97], v[88:91], off
	global_store_dwordx4 v[96:97], v[92:95], off offset:16
	v_add_u32_e32 v98, 0x90, v148
	v_lshlrev_b32_e32 v88, 16, v180
	v_and_b32_e32 v89, 0xffff0000, v180
	v_pk_fma_f32 v[84:85], v[84:85], 0.5, v[88:89] op_sel_hi:[1,0,1]
	v_lshlrev_b32_e32 v88, 16, v181
	v_and_b32_e32 v89, 0xffff0000, v181
	v_pk_fma_f32 v[86:87], v[86:87], 0.5, v[88:89] op_sel_hi:[1,0,1]
	v_lshlrev_b32_e32 v88, 16, v178
	v_and_b32_e32 v89, 0xffff0000, v178
;     __device__ __forceinline__ void operator()(const f32x4 (&acc)[2][2][4][2], const pg8::Unit& u, int wr, int wc, int fr, int fq) const {
;     ...
;         for (int ai = 0; ai < 2; ++ai) {
;             u32x4 rb[4][2];
; #pragma unroll
;             for (int m = 0; m < 4; ++m)
; #pragma unroll
;                 for (int bj = 0; bj < 2; ++bj) rb[m][bj] = *(const u32x4*)(resb + (size_t)(row0 + ai * 128 + m * 16) * DM + col0 + bj * 128);
; #pragma unroll
;             for (int m = 0; m < 4; ++m) {
;                 const int r = row0 + ai * 128 + m * 16; float ss = 0.f;
; #pragma unroll
;                 for (int bj = 0; bj < 2; ++bj) {
;                     const size_t off = (size_t)r * DM + col0 + bj * 128;
;                     float rv[8], o[8]; unpack8(rb[m][bj], rv);
; #pragma unroll
;                     for (int n = 0; n < 2; ++n)
; #pragma unroll
;                         for (int i = 0; i < 4; ++i) o[n * 4 + i] = rv[n * 4 + i] + coef * acc[ai][bj][m][n][i];
;                     if (outf) { *(f32x4*)(outf + off) = (f32x4){o[0], o[1], o[2], o[3]}; *(f32x4*)(outf + off + 4) = (f32x4){o[4], o[5], o[6], o[7]}; }
	v_pk_fma_f32 v[80:81], v[80:81], 0.5, v[88:89] op_sel_hi:[1,0,1]
	v_lshlrev_b32_e32 v88, 16, v179
	v_and_b32_e32 v89, 0xffff0000, v179
	v_pk_fma_f32 v[82:83], v[82:83], 0.5, v[88:89] op_sel_hi:[1,0,1]
	global_store_dwordx4 v[96:97], v[80:83], off offset:512
	global_store_dwordx4 v[96:97], v[84:87], off offset:528
	v_add_u32_e32 v96, 0x80, v148
	v_lshlrev_b32_e32 v82, 16, v188
	v_and_b32_e32 v83, 0xffff0000, v188
	v_pk_fma_f32 v[76:77], v[76:77], 0.5, v[82:83] op_sel_hi:[1,0,1]
	v_lshlrev_b32_e32 v82, 16, v189
	v_and_b32_e32 v83, 0xffff0000, v189
	v_lshlrev_b64 v[80:81], 13, v[150:151]
	v_pk_fma_f32 v[78:79], v[78:79], 0.5, v[82:83] op_sel_hi:[1,0,1]
	v_lshlrev_b32_e32 v82, 16, v186
	v_and_b32_e32 v83, 0xffff0000, v186
	v_lshl_add_u64 v[80:81], s[42:43], 0, v[80:81]
	v_pk_fma_f32 v[72:73], v[72:73], 0.5, v[82:83] op_sel_hi:[1,0,1]
	v_lshlrev_b32_e32 v82, 16, v187
	v_and_b32_e32 v83, 0xffff0000, v187
	v_lshl_add_u64 v[80:81], v[80:81], 0, v[144:145]
	v_pk_fma_f32 v[74:75], v[74:75], 0.5, v[82:83] op_sel_hi:[1,0,1]
	global_store_dwordx4 v[80:81], v[72:75], off
	global_store_dwordx4 v[80:81], v[76:79], off offset:16
	v_ashrrev_i32_e32 v97, 31, v96
	v_lshlrev_b32_e32 v72, 16, v184
	v_and_b32_e32 v73, 0xffff0000, v184
	v_pk_fma_f32 v[68:69], v[68:69], 0.5, v[72:73] op_sel_hi:[1,0,1]
	v_lshlrev_b32_e32 v72, 16, v185
	v_and_b32_e32 v73, 0xffff0000, v185
	v_pk_fma_f32 v[70:71], v[70:71], 0.5, v[72:73] op_sel_hi:[1,0,1]
	v_lshlrev_b32_e32 v72, 16, v182
	v_and_b32_e32 v73, 0xffff0000, v182
	v_pk_fma_f32 v[64:65], v[64:65], 0.5, v[72:73] op_sel_hi:[1,0,1]
	v_lshlrev_b32_e32 v72, 16, v183
	v_and_b32_e32 v73, 0xffff0000, v183
	v_pk_fma_f32 v[66:67], v[66:67], 0.5, v[72:73] op_sel_hi:[1,0,1]
	global_store_dwordx4 v[80:81], v[64:67], off offset:512
	global_store_dwordx4 v[80:81], v[68:71], off offset:528
	v_ashrrev_i32_e32 v99, 31, v98
	v_lshlrev_b64 v[64:65], 12, v[96:97]
	v_lshl_add_u64 v[64:65], v[146:147], 0, v[64:65]
	global_load_dwordx4 v[68:71], v[64:65], off
	global_load_dwordx4 v[72:75], v[64:65], off offset:256
	v_lshlrev_b64 v[64:65], 12, v[98:99]
	v_lshl_add_u64 v[64:65], v[146:147], 0, v[64:65]
	global_load_dwordx4 v[76:79], v[64:65], off
	global_load_dwordx4 v[80:83], v[64:65], off offset:256
	v_ashrrev_i32_e32 v101, 31, v100
	v_lshlrev_b64 v[64:65], 12, v[100:101]
	v_lshl_add_u64 v[64:65], v[146:147], 0, v[64:65]
	global_load_dwordx4 v[84:87], v[64:65], off
	global_load_dwordx4 v[88:91], v[64:65], off offset:256
	v_add_u32_e32 v102, 0xb0, v148
	v_ashrrev_i32_e32 v103, 31, v102
	v_lshlrev_b64 v[64:65], 12, v[102:103]
	v_lshl_add_u64 v[92:93], v[146:147], 0, v[64:65]
	global_load_dwordx4 v[64:67], v[92:93], off offset:256
	s_nop 0
	global_load_dwordx4 v[92:95], v[92:93], off
	v_lshlrev_b64 v[96:97], 13, v[96:97]
	v_lshl_add_u64 v[96:97], s[42:43], 0, v[96:97]
	v_lshl_add_u64 v[96:97], v[96:97], 0, v[144:145]
	s_waitcnt vmcnt(0)
;     __device__ __forceinline__ void operator()(const f32x4 (&acc)[2][2][4][2], const pg8::Unit& u, int wr, int wc, int fr, int fq) const {
;     ...
;         for (int ai = 0; ai < 2; ++ai) {
;             u32x4 rb[4][2];
; #pragma unroll
;             for (int m = 0; m < 4; ++m)
; #pragma unroll
;                 for (int bj = 0; bj < 2; ++bj) rb[m][bj] = *(const u32x4*)(resb + (size_t)(row0 + ai * 128 + m * 16) * DM + col0 + bj * 128);
; #pragma unroll
;             for (int m = 0; m < 4; ++m) {
;                 const int r = row0 + ai * 128 + m * 16; float ss = 0.f;
; #pragma unroll
;                 for (int bj = 0; bj < 2; ++bj) {
;                     const size_t off = (size_t)r * DM + col0 + bj * 128;
;                     float rv[8], o[8]; unpack8(rb[m][bj], rv);
; #pragma unroll
;                     for (int n = 0; n < 2; ++n)
; #pragma unroll
;                         for (int i = 0; i < 4; ++i) o[n * 4 + i] = rv[n * 4 + i] + coef * acc[ai][bj][m][n][i];
;                     if (outf) { *(f32x4*)(outf + off) = (f32x4){o[0], o[1], o[2], o[3]}; *(f32x4*)(outf + off + 4) = (f32x4){o[4], o[5], o[6], o[7]}; }
	v_lshlrev_b32_e32 v104, 16, v70
	v_and_b32_e32 v105, 0xffff0000, v70
	v_lshlrev_b32_e32 v70, 16, v71
	v_and_b32_e32 v71, 0xffff0000, v71
	v_pk_fma_f32 v[62:63], v[62:63], 0.5, v[70:71] op_sel_hi:[1,0,1]
	v_lshlrev_b32_e32 v70, 16, v68
	v_and_b32_e32 v71, 0xffff0000, v68
	v_lshlrev_b32_e32 v68, 16, v69
	v_and_b32_e32 v69, 0xffff0000, v69
	v_pk_fma_f32 v[56:57], v[56:57], 0.5, v[70:71] op_sel_hi:[1,0,1]
	v_pk_fma_f32 v[58:59], v[58:59], 0.5, v[68:69] op_sel_hi:[1,0,1]
	v_pk_fma_f32 v[60:61], v[60:61], 0.5, v[104:105] op_sel_hi:[1,0,1]
	global_store_dwordx4 v[96:97], v[56:59], off
	global_store_dwordx4 v[96:97], v[60:63], off offset:16
	s_nop 0
	v_lshlrev_b32_e32 v56, 16, v74
	v_and_b32_e32 v57, 0xffff0000, v74
	v_pk_fma_f32 v[52:53], v[52:53], 0.5, v[56:57] op_sel_hi:[1,0,1]
	v_lshlrev_b32_e32 v56, 16, v75
	v_and_b32_e32 v57, 0xffff0000, v75
	v_pk_fma_f32 v[54:55], v[54:55], 0.5, v[56:57] op_sel_hi:[1,0,1]
	v_lshlrev_b32_e32 v56, 16, v72
	v_and_b32_e32 v57, 0xffff0000, v72
	v_pk_fma_f32 v[48:49], v[48:49], 0.5, v[56:57] op_sel_hi:[1,0,1]
	v_lshlrev_b32_e32 v56, 16, v73
	v_and_b32_e32 v57, 0xffff0000, v73
	v_pk_fma_f32 v[50:51], v[50:51], 0.5, v[56:57] op_sel_hi:[1,0,1]
	global_store_dwordx4 v[96:97], v[48:51], off offset:512
	global_store_dwordx4 v[96:97], v[52:55], off offset:528
	s_nop 0
	v_lshlrev_b32_e32 v50, 16, v78
	v_and_b32_e32 v51, 0xffff0000, v78
	v_pk_fma_f32 v[44:45], v[44:45], 0.5, v[50:51] op_sel_hi:[1,0,1]
	v_lshlrev_b32_e32 v50, 16, v79
	v_and_b32_e32 v51, 0xffff0000, v79
	v_lshlrev_b64 v[48:49], 13, v[98:99]
	v_pk_fma_f32 v[46:47], v[46:47], 0.5, v[50:51] op_sel_hi:[1,0,1]
	v_lshlrev_b32_e32 v50, 16, v76
	v_and_b32_e32 v51, 0xffff0000, v76
	v_lshl_add_u64 v[48:49], s[42:43], 0, v[48:49]
	v_pk_fma_f32 v[40:41], v[40:41], 0.5, v[50:51] op_sel_hi:[1,0,1]
	v_lshlrev_b32_e32 v50, 16, v77
	v_and_b32_e32 v51, 0xffff0000, v77
	v_lshl_add_u64 v[48:49], v[48:49], 0, v[144:145]
	v_pk_fma_f32 v[42:43], v[42:43], 0.5, v[50:51] op_sel_hi:[1,0,1]
	global_store_dwordx4 v[48:49], v[40:43], off
	global_store_dwordx4 v[48:49], v[44:47], off offset:16
	s_nop 0
	v_lshlrev_b32_e32 v40, 16, v82
	v_and_b32_e32 v41, 0xffff0000, v82
	v_pk_fma_f32 v[36:37], v[36:37], 0.5, v[40:41] op_sel_hi:[1,0,1]
	v_lshlrev_b32_e32 v40, 16, v83
	v_and_b32_e32 v41, 0xffff0000, v83
	v_pk_fma_f32 v[38:39], v[38:39], 0.5, v[40:41] op_sel_hi:[1,0,1]
	v_lshlrev_b32_e32 v40, 16, v80
	v_and_b32_e32 v41, 0xffff0000, v80
	v_pk_fma_f32 v[32:33], v[32:33], 0.5, v[40:41] op_sel_hi:[1,0,1]
	v_lshlrev_b32_e32 v40, 16, v81
	v_and_b32_e32 v41, 0xffff0000, v81
	v_pk_fma_f32 v[34:35], v[34:35], 0.5, v[40:41] op_sel_hi:[1,0,1]
	global_store_dwordx4 v[48:49], v[32:35], off offset:512
	global_store_dwordx4 v[48:49], v[36:39], off offset:528
	s_nop 0
	v_lshlrev_b32_e32 v34, 16, v86
	v_and_b32_e32 v35, 0xffff0000, v86
	v_pk_fma_f32 v[28:29], v[28:29], 0.5, v[34:35] op_sel_hi:[1,0,1]
	v_lshlrev_b32_e32 v34, 16, v87
	v_and_b32_e32 v35, 0xffff0000, v87
	v_lshlrev_b64 v[32:33], 13, v[100:101]
	v_pk_fma_f32 v[30:31], v[30:31], 0.5, v[34:35] op_sel_hi:[1,0,1]
	v_lshlrev_b32_e32 v34, 16, v84
	v_and_b32_e32 v35, 0xffff0000, v84
	v_lshl_add_u64 v[32:33], s[42:43], 0, v[32:33]
	v_pk_fma_f32 v[24:25], v[24:25], 0.5, v[34:35] op_sel_hi:[1,0,1]
	v_lshlrev_b32_e32 v34, 16, v85
	v_and_b32_e32 v35, 0xffff0000, v85
	v_lshl_add_u64 v[32:33], v[32:33], 0, v[144:145]
	v_pk_fma_f32 v[26:27], v[26:27], 0.5, v[34:35] op_sel_hi:[1,0,1]
	global_store_dwordx4 v[32:33], v[24:27], off
	global_store_dwordx4 v[32:33], v[28:31], off offset:16
	s_nop 0
	v_lshlrev_b32_e32 v24, 16, v90
	v_and_b32_e32 v25, 0xffff0000, v90
	v_pk_fma_f32 v[20:21], v[20:21], 0.5, v[24:25] op_sel_hi:[1,0,1]
	v_lshlrev_b32_e32 v24, 16, v91
	v_and_b32_e32 v25, 0xffff0000, v91
	v_pk_fma_f32 v[22:23], v[22:23], 0.5, v[24:25] op_sel_hi:[1,0,1]
	v_lshlrev_b32_e32 v24, 16, v88
	v_and_b32_e32 v25, 0xffff0000, v88
	v_pk_fma_f32 v[16:17], v[16:17], 0.5, v[24:25] op_sel_hi:[1,0,1]
	v_lshlrev_b32_e32 v24, 16, v89
	v_and_b32_e32 v25, 0xffff0000, v89
	v_pk_fma_f32 v[18:19], v[18:19], 0.5, v[24:25] op_sel_hi:[1,0,1]
	global_store_dwordx4 v[32:33], v[16:19], off offset:512
	global_store_dwordx4 v[32:33], v[20:23], off offset:528
	s_nop 0
	v_lshlrev_b32_e32 v18, 16, v94
	v_and_b32_e32 v19, 0xffff0000, v94
	v_pk_fma_f32 v[12:13], v[12:13], 0.5, v[18:19] op_sel_hi:[1,0,1]
	v_lshlrev_b32_e32 v18, 16, v95
	v_and_b32_e32 v19, 0xffff0000, v95
	v_lshlrev_b64 v[16:17], 13, v[102:103]
	v_pk_fma_f32 v[14:15], v[14:15], 0.5, v[18:19] op_sel_hi:[1,0,1]
	v_lshlrev_b32_e32 v18, 16, v92
	v_and_b32_e32 v19, 0xffff0000, v92
	v_lshl_add_u64 v[16:17], s[42:43], 0, v[16:17]
	v_pk_fma_f32 v[8:9], v[8:9], 0.5, v[18:19] op_sel_hi:[1,0,1]
	v_lshlrev_b32_e32 v18, 16, v93
	v_and_b32_e32 v19, 0xffff0000, v93
	v_lshl_add_u64 v[16:17], v[16:17], 0, v[144:145]
	v_pk_fma_f32 v[10:11], v[10:11], 0.5, v[18:19] op_sel_hi:[1,0,1]
	global_store_dwordx4 v[16:17], v[8:11], off
	global_store_dwordx4 v[16:17], v[12:15], off offset:16
	s_nop 0
	v_lshlrev_b32_e32 v8, 16, v66
	v_and_b32_e32 v9, 0xffff0000, v66
	v_pk_fma_f32 v[4:5], v[4:5], 0.5, v[8:9] op_sel_hi:[1,0,1]
	v_lshlrev_b32_e32 v8, 16, v67
	v_and_b32_e32 v9, 0xffff0000, v67
	v_pk_fma_f32 v[6:7], v[6:7], 0.5, v[8:9] op_sel_hi:[1,0,1]
	v_lshlrev_b32_e32 v8, 16, v64
	v_and_b32_e32 v9, 0xffff0000, v64
	v_pk_fma_f32 v[0:1], v[0:1], 0.5, v[8:9] op_sel_hi:[1,0,1]
	v_lshlrev_b32_e32 v8, 16, v65
	v_and_b32_e32 v9, 0xffff0000, v65
	v_pk_fma_f32 v[2:3], v[2:3], 0.5, v[8:9] op_sel_hi:[1,0,1]
	global_store_dwordx4 v[16:17], v[0:3], off offset:512
	global_store_dwordx4 v[16:17], v[4:7], off offset:528
	s_branch .LBB0_1158
